# v39: v37 + GEMM MFMA blocks without s_setprio flips and without the redundant lgkmcnt(0)
# speedup vs baseline: 1.0088x; 1.0088x over previous
.LBB0_154:
	ds_read_b128 v[180:183], v163
	ds_read_b128 v[184:187], v164
	ds_read_b128 v[188:191], v165
	ds_read_b128 v[196:199], v167
	ds_read_b128 v[200:203], v168
	ds_read_b128 v[204:207], v169
	ds_read_b128 v[208:211], v170
	ds_read_b128 v[212:215], v171
	s_add_u32 s12, s10, 0xfffc0080
	s_addc_u32 s13, s11, -1
	s_cmp_eq_u32 s54, 12
	s_cselect_b32 s37, s5, s13
	s_cselect_b32 s36, s7, s12
	s_cselect_b32 s13, s27, s39
	s_cselect_b32 s12, s29, s38
	s_mov_b32 m0, s85
	ds_read_b128 v[216:219], v145
	ds_read_b128 v[220:223], v145 offset:1024
	ds_read_b128 v[224:227], v145 offset:2048
	ds_read_b128 v[228:231], v145 offset:3072
	ds_read_b128 v[232:235], v145 offset:4096
	ds_read_b128 v[236:239], v145 offset:5120
	ds_read_b128 v[240:243], v145 offset:6144
	ds_read_b128 v[244:247], v145 offset:7168
	global_load_lds_dwordx4 v138, s[10:11]
	s_mov_b32 m0, s86
	s_nop 0
	global_load_lds_dwordx4 v140, s[10:11]
	s_waitcnt vmcnt(8)
	s_waitcnt lgkmcnt(0)
	s_barrier
	v_mfma_f32_16x16x32_bf16 v[124:127], v[180:183], v[216:219], v[124:127]
	v_mfma_f32_16x16x32_bf16 v[120:123], v[188:191], v[216:219], v[120:123]
	v_mfma_f32_16x16x32_bf16 v[108:111], v[180:183], v[224:227], v[108:111]
	v_mfma_f32_16x16x32_bf16 v[104:107], v[188:191], v[224:227], v[104:107]
	v_mfma_f32_16x16x32_bf16 v[92:95], v[180:183], v[232:235], v[92:95]
	v_mfma_f32_16x16x32_bf16 v[88:91], v[188:191], v[232:235], v[88:91]
	v_mfma_f32_16x16x32_bf16 v[76:79], v[180:183], v[240:243], v[76:79]
	v_mfma_f32_16x16x32_bf16 v[72:75], v[188:191], v[240:243], v[72:75]
	v_mfma_f32_16x16x32_bf16 v[124:127], v[184:187], v[220:223], v[124:127]
	v_mfma_f32_16x16x32_bf16 v[120:123], v[196:199], v[220:223], v[120:123]
	v_mfma_f32_16x16x32_bf16 v[108:111], v[184:187], v[228:231], v[108:111]
	v_mfma_f32_16x16x32_bf16 v[104:107], v[196:199], v[228:231], v[104:107]
	v_mfma_f32_16x16x32_bf16 v[92:95], v[184:187], v[236:239], v[92:95]
	v_mfma_f32_16x16x32_bf16 v[88:91], v[196:199], v[236:239], v[88:91]
	v_mfma_f32_16x16x32_bf16 v[76:79], v[184:187], v[244:247], v[76:79]
	v_mfma_f32_16x16x32_bf16 v[72:75], v[196:199], v[244:247], v[72:75]
	v_mfma_f32_16x16x32_bf16 v[116:119], v[200:203], v[216:219], v[116:119]
	v_mfma_f32_16x16x32_bf16 v[112:115], v[208:211], v[216:219], v[112:115]
	v_mfma_f32_16x16x32_bf16 v[100:103], v[200:203], v[224:227], v[100:103]
	v_mfma_f32_16x16x32_bf16 v[96:99], v[208:211], v[224:227], v[96:99]
	v_mfma_f32_16x16x32_bf16 v[84:87], v[200:203], v[232:235], v[84:87]
	v_mfma_f32_16x16x32_bf16 v[80:83], v[208:211], v[232:235], v[80:83]
	v_mfma_f32_16x16x32_bf16 v[68:71], v[200:203], v[240:243], v[68:71]
	v_mfma_f32_16x16x32_bf16 v[64:67], v[208:211], v[240:243], v[64:67]
	v_mfma_f32_16x16x32_bf16 v[116:119], v[204:207], v[220:223], v[116:119]
	v_mfma_f32_16x16x32_bf16 v[112:115], v[212:215], v[220:223], v[112:115]
	v_mfma_f32_16x16x32_bf16 v[100:103], v[204:207], v[228:231], v[100:103]
	v_mfma_f32_16x16x32_bf16 v[96:99], v[212:215], v[228:231], v[96:99]
	v_mfma_f32_16x16x32_bf16 v[84:87], v[204:207], v[236:239], v[84:87]
	v_mfma_f32_16x16x32_bf16 v[80:83], v[212:215], v[236:239], v[80:83]
	v_mfma_f32_16x16x32_bf16 v[68:71], v[204:207], v[244:247], v[68:71]
	v_mfma_f32_16x16x32_bf16 v[64:67], v[212:215], v[244:247], v[64:67]
	s_barrier
	s_add_u32 s98, s12, s20
	s_addc_u32 s99, s13, s21
	s_add_u32 s100, s36, s20
	s_addc_u32 s101, s37, s21
	s_mov_b32 m0, s25
	s_add_u32 s56, s12, 0x40000
	ds_read_b128 v[216:219], v145 offset:16384
	ds_read_b128 v[220:223], v145 offset:17408
	ds_read_b128 v[224:227], v145 offset:18432
	ds_read_b128 v[228:231], v145 offset:19456
	ds_read_b128 v[232:235], v145 offset:20480
	ds_read_b128 v[236:239], v145 offset:21504
	ds_read_b128 v[240:243], v145 offset:22528
	ds_read_b128 v[244:247], v145 offset:23552
	global_load_lds_dwordx4 v132, s[12:13]
	s_mov_b32 m0, s33
	s_addc_u32 s57, s13, 0
	global_load_lds_dwordx4 v134, s[12:13]
	s_mov_b32 m0, s62
	s_nop 0
	global_load_lds_dwordx4 v132, s[56:57]
	s_mov_b32 m0, s63
	s_nop 0
	global_load_lds_dwordx4 v134, s[56:57]
	s_mov_b32 m0, s2
	s_nop 0
	global_load_lds_dwordx4 v132, s[36:37]
	s_mov_b32 m0, s64
	s_nop 0
	global_load_lds_dwordx4 v134, s[36:37]
	s_waitcnt vmcnt(8)
	s_waitcnt lgkmcnt(0)
	s_barrier
	v_mfma_f32_16x16x32_bf16 v[60:63], v[180:183], v[216:219], v[60:63]
	v_mfma_f32_16x16x32_bf16 v[56:59], v[188:191], v[216:219], v[56:59]
	v_mfma_f32_16x16x32_bf16 v[44:47], v[180:183], v[224:227], v[44:47]
	v_mfma_f32_16x16x32_bf16 v[40:43], v[188:191], v[224:227], v[40:43]
	v_mfma_f32_16x16x32_bf16 v[28:31], v[180:183], v[232:235], v[28:31]
	v_mfma_f32_16x16x32_bf16 v[24:27], v[188:191], v[232:235], v[24:27]
	v_mfma_f32_16x16x32_bf16 v[12:15], v[180:183], v[240:243], v[12:15]
	v_mfma_f32_16x16x32_bf16 v[8:11], v[188:191], v[240:243], v[8:11]
	v_mfma_f32_16x16x32_bf16 v[60:63], v[184:187], v[220:223], v[60:63]
	v_mfma_f32_16x16x32_bf16 v[56:59], v[196:199], v[220:223], v[56:59]
	v_mfma_f32_16x16x32_bf16 v[44:47], v[184:187], v[228:231], v[44:47]
	v_mfma_f32_16x16x32_bf16 v[40:43], v[196:199], v[228:231], v[40:43]
	v_mfma_f32_16x16x32_bf16 v[28:31], v[184:187], v[236:239], v[28:31]
	v_mfma_f32_16x16x32_bf16 v[24:27], v[196:199], v[236:239], v[24:27]
	v_mfma_f32_16x16x32_bf16 v[12:15], v[184:187], v[244:247], v[12:15]
	v_mfma_f32_16x16x32_bf16 v[8:11], v[196:199], v[244:247], v[8:11]
	v_mfma_f32_16x16x32_bf16 v[52:55], v[200:203], v[216:219], v[52:55]
	v_mfma_f32_16x16x32_bf16 v[48:51], v[208:211], v[216:219], v[48:51]
	v_mfma_f32_16x16x32_bf16 v[36:39], v[200:203], v[224:227], v[36:39]
	v_mfma_f32_16x16x32_bf16 v[32:35], v[208:211], v[224:227], v[32:35]
	v_mfma_f32_16x16x32_bf16 v[20:23], v[200:203], v[232:235], v[20:23]
	v_mfma_f32_16x16x32_bf16 v[16:19], v[208:211], v[232:235], v[16:19]
	v_mfma_f32_16x16x32_bf16 v[4:7], v[200:203], v[240:243], v[4:7]
	v_mfma_f32_16x16x32_bf16 v[0:3], v[208:211], v[240:243], v[0:3]
	v_mfma_f32_16x16x32_bf16 v[52:55], v[204:207], v[220:223], v[52:55]
	v_mfma_f32_16x16x32_bf16 v[48:51], v[212:215], v[220:223], v[48:51]
	v_mfma_f32_16x16x32_bf16 v[36:39], v[204:207], v[228:231], v[36:39]
	v_mfma_f32_16x16x32_bf16 v[32:35], v[212:215], v[228:231], v[32:35]
	v_mfma_f32_16x16x32_bf16 v[20:23], v[204:207], v[236:239], v[20:23]
	v_mfma_f32_16x16x32_bf16 v[16:19], v[212:215], v[236:239], v[16:19]
	v_mfma_f32_16x16x32_bf16 v[4:7], v[204:207], v[244:247], v[4:7]
	v_mfma_f32_16x16x32_bf16 v[0:3], v[212:215], v[244:247], v[0:3]
	s_barrier
	ds_read_b128 v[180:183], v172
	ds_read_b128 v[184:187], v173
	ds_read_b128 v[188:191], v174
	ds_read_b128 v[196:199], v175
	ds_read_b128 v[200:203], v176
	ds_read_b128 v[204:207], v177
	ds_read_b128 v[208:211], v178
	ds_read_b128 v[212:215], v179
	s_add_u32 s36, s36, 0x40000
	s_addc_u32 s37, s37, 0
	s_mov_b32 m0, s65
	ds_read_b128 v[216:219], v145 offset:32768
	ds_read_b128 v[220:223], v145 offset:33792
	ds_read_b128 v[224:227], v145 offset:34816
	ds_read_b128 v[228:231], v145 offset:35840
	ds_read_b128 v[232:235], v145 offset:36864
	ds_read_b128 v[236:239], v145 offset:37888
	ds_read_b128 v[240:243], v145 offset:38912
	ds_read_b128 v[244:247], v145 offset:39936
	global_load_lds_dwordx4 v132, s[36:37]
	s_mov_b32 m0, s66
	s_nop 0
	global_load_lds_dwordx4 v134, s[36:37]
	s_waitcnt vmcnt(8)
	s_waitcnt lgkmcnt(0)
	s_barrier
	v_mfma_f32_16x16x32_bf16 v[124:127], v[180:183], v[216:219], v[124:127]
	v_mfma_f32_16x16x32_bf16 v[120:123], v[188:191], v[216:219], v[120:123]
	v_mfma_f32_16x16x32_bf16 v[108:111], v[180:183], v[224:227], v[108:111]
	v_mfma_f32_16x16x32_bf16 v[104:107], v[188:191], v[224:227], v[104:107]
	v_mfma_f32_16x16x32_bf16 v[92:95], v[180:183], v[232:235], v[92:95]
	v_mfma_f32_16x16x32_bf16 v[88:91], v[188:191], v[232:235], v[88:91]
	v_mfma_f32_16x16x32_bf16 v[76:79], v[180:183], v[240:243], v[76:79]
	v_mfma_f32_16x16x32_bf16 v[72:75], v[188:191], v[240:243], v[72:75]
	v_mfma_f32_16x16x32_bf16 v[124:127], v[184:187], v[220:223], v[124:127]
	v_mfma_f32_16x16x32_bf16 v[120:123], v[196:199], v[220:223], v[120:123]
	v_mfma_f32_16x16x32_bf16 v[108:111], v[184:187], v[228:231], v[108:111]
	v_mfma_f32_16x16x32_bf16 v[104:107], v[196:199], v[228:231], v[104:107]
	v_mfma_f32_16x16x32_bf16 v[92:95], v[184:187], v[236:239], v[92:95]
	v_mfma_f32_16x16x32_bf16 v[88:91], v[196:199], v[236:239], v[88:91]
	v_mfma_f32_16x16x32_bf16 v[76:79], v[184:187], v[244:247], v[76:79]
	v_mfma_f32_16x16x32_bf16 v[72:75], v[196:199], v[244:247], v[72:75]
	v_mfma_f32_16x16x32_bf16 v[116:119], v[200:203], v[216:219], v[116:119]
	v_mfma_f32_16x16x32_bf16 v[112:115], v[208:211], v[216:219], v[112:115]
	v_mfma_f32_16x16x32_bf16 v[100:103], v[200:203], v[224:227], v[100:103]
	v_mfma_f32_16x16x32_bf16 v[96:99], v[208:211], v[224:227], v[96:99]
	v_mfma_f32_16x16x32_bf16 v[84:87], v[200:203], v[232:235], v[84:87]
	v_mfma_f32_16x16x32_bf16 v[80:83], v[208:211], v[232:235], v[80:83]
	v_mfma_f32_16x16x32_bf16 v[68:71], v[200:203], v[240:243], v[68:71]
	v_mfma_f32_16x16x32_bf16 v[64:67], v[208:211], v[240:243], v[64:67]
	v_mfma_f32_16x16x32_bf16 v[116:119], v[204:207], v[220:223], v[116:119]
	v_mfma_f32_16x16x32_bf16 v[112:115], v[212:215], v[220:223], v[112:115]
	v_mfma_f32_16x16x32_bf16 v[100:103], v[204:207], v[228:231], v[100:103]
	v_mfma_f32_16x16x32_bf16 v[96:99], v[212:215], v[228:231], v[96:99]
	v_mfma_f32_16x16x32_bf16 v[84:87], v[204:207], v[236:239], v[84:87]
	v_mfma_f32_16x16x32_bf16 v[80:83], v[212:215], v[236:239], v[80:83]
	v_mfma_f32_16x16x32_bf16 v[68:71], v[204:207], v[244:247], v[68:71]
	v_mfma_f32_16x16x32_bf16 v[64:67], v[212:215], v[244:247], v[64:67]
	s_barrier
	s_mov_b32 m0, s67
	s_add_u32 s12, s12, 0x40080
	ds_read_b128 v[216:219], v145 offset:49152
	ds_read_b128 v[220:223], v145 offset:50176
	ds_read_b128 v[224:227], v145 offset:51200
	ds_read_b128 v[228:231], v145 offset:52224
	ds_read_b128 v[232:235], v145 offset:53248
	ds_read_b128 v[236:239], v145 offset:54272
	ds_read_b128 v[240:243], v145 offset:55296
	ds_read_b128 v[244:247], v145 offset:56320
	global_load_lds_dwordx4 v132, s[98:99]
	s_mov_b32 m0, s72
	s_addc_u32 s13, s13, 0
	global_load_lds_dwordx4 v134, s[98:99]
	s_mov_b32 m0, s75
	s_nop 0
	global_load_lds_dwordx4 v132, s[12:13]
	s_mov_b32 m0, s78
	s_nop 0
	global_load_lds_dwordx4 v134, s[12:13]
	s_mov_b32 m0, s73
	s_nop 0
	global_load_lds_dwordx4 v132, s[100:101]
	s_mov_b32 m0, s74
	s_nop 0
	global_load_lds_dwordx4 v134, s[100:101]
	s_waitcnt vmcnt(8)
	s_waitcnt lgkmcnt(0)
	s_barrier
	v_mfma_f32_16x16x32_bf16 v[60:63], v[180:183], v[216:219], v[60:63]
	v_mfma_f32_16x16x32_bf16 v[56:59], v[188:191], v[216:219], v[56:59]
	v_mfma_f32_16x16x32_bf16 v[44:47], v[180:183], v[224:227], v[44:47]
	v_mfma_f32_16x16x32_bf16 v[40:43], v[188:191], v[224:227], v[40:43]
	v_mfma_f32_16x16x32_bf16 v[28:31], v[180:183], v[232:235], v[28:31]
	v_mfma_f32_16x16x32_bf16 v[24:27], v[188:191], v[232:235], v[24:27]
	v_mfma_f32_16x16x32_bf16 v[12:15], v[180:183], v[240:243], v[12:15]
	v_mfma_f32_16x16x32_bf16 v[8:11], v[188:191], v[240:243], v[8:11]
	v_mfma_f32_16x16x32_bf16 v[60:63], v[184:187], v[220:223], v[60:63]
	v_mfma_f32_16x16x32_bf16 v[56:59], v[196:199], v[220:223], v[56:59]
	v_mfma_f32_16x16x32_bf16 v[44:47], v[184:187], v[228:231], v[44:47]
	v_mfma_f32_16x16x32_bf16 v[40:43], v[196:199], v[228:231], v[40:43]
	v_mfma_f32_16x16x32_bf16 v[28:31], v[184:187], v[236:239], v[28:31]
	v_mfma_f32_16x16x32_bf16 v[24:27], v[196:199], v[236:239], v[24:27]
	v_mfma_f32_16x16x32_bf16 v[12:15], v[184:187], v[244:247], v[12:15]
	v_mfma_f32_16x16x32_bf16 v[8:11], v[196:199], v[244:247], v[8:11]
	v_mfma_f32_16x16x32_bf16 v[52:55], v[200:203], v[216:219], v[52:55]
	v_mfma_f32_16x16x32_bf16 v[48:51], v[208:211], v[216:219], v[48:51]
	v_mfma_f32_16x16x32_bf16 v[36:39], v[200:203], v[224:227], v[36:39]
	v_mfma_f32_16x16x32_bf16 v[32:35], v[208:211], v[224:227], v[32:35]
	v_mfma_f32_16x16x32_bf16 v[20:23], v[200:203], v[232:235], v[20:23]
	v_mfma_f32_16x16x32_bf16 v[16:19], v[208:211], v[232:235], v[16:19]
	v_mfma_f32_16x16x32_bf16 v[4:7], v[200:203], v[240:243], v[4:7]
	v_mfma_f32_16x16x32_bf16 v[0:3], v[208:211], v[240:243], v[0:3]
	v_mfma_f32_16x16x32_bf16 v[52:55], v[204:207], v[220:223], v[52:55]
	v_mfma_f32_16x16x32_bf16 v[48:51], v[212:215], v[220:223], v[48:51]
	v_mfma_f32_16x16x32_bf16 v[36:39], v[204:207], v[228:231], v[36:39]
	v_mfma_f32_16x16x32_bf16 v[32:35], v[212:215], v[228:231], v[32:35]
	v_mfma_f32_16x16x32_bf16 v[20:23], v[204:207], v[236:239], v[20:23]
	v_mfma_f32_16x16x32_bf16 v[16:19], v[212:215], v[236:239], v[16:19]
	v_mfma_f32_16x16x32_bf16 v[4:7], v[204:207], v[244:247], v[4:7]
	v_mfma_f32_16x16x32_bf16 v[0:3], v[212:215], v[244:247], v[0:3]
	s_barrier
	s_add_i32 s54, s54, 2
	s_add_u32 s10, s10, 0x100
	s_addc_u32 s11, s11, 0
	s_add_u32 s38, s38, 0x100
	s_addc_u32 s39, s39, 0
	s_cmp_gt_u32 s54, 13
	s_cbranch_scc0 .LBB0_154
	s_and_b64 vcc, exec, s[22:23]
	s_cbranch_vccz .LBB0_157
	s_barrier

.LBB0_251:
	ds_read_b128 v[160:163], v165
	ds_read_b128 v[182:185], v167
	ds_read_b128 v[186:189], v168
	ds_read_b128 v[190:193], v169
	ds_read_b128 v[196:199], v170
	ds_read_b128 v[200:203], v171
	ds_read_b128 v[204:207], v172
	ds_read_b128 v[208:211], v173
	s_add_u32 s14, s12, 0xfffc0080
	s_addc_u32 s15, s13, -1
	s_cmp_eq_u32 s54, 12
	s_cselect_b32 s29, s7, s15
	s_cselect_b32 s28, s11, s14
	s_cselect_b32 s15, s21, s39
	s_cselect_b32 s14, s23, s38
	s_mov_b32 m0, s82
	ds_read_b128 v[212:215], v145
	ds_read_b128 v[216:219], v145 offset:1024
	ds_read_b128 v[220:223], v145 offset:2048
	ds_read_b128 v[224:227], v145 offset:3072
	ds_read_b128 v[228:231], v145 offset:4096
	ds_read_b128 v[232:235], v145 offset:5120
	ds_read_b128 v[236:239], v145 offset:6144
	ds_read_b128 v[240:243], v145 offset:7168
	global_load_lds_dwordx4 v138, s[12:13]
	s_mov_b32 m0, s83
	s_nop 0
	global_load_lds_dwordx4 v140, s[12:13]
	s_waitcnt vmcnt(8)
	s_waitcnt lgkmcnt(0)
	s_barrier
	v_mfma_f32_16x16x32_bf16 v[124:127], v[160:163], v[212:215], v[124:127]
	v_mfma_f32_16x16x32_bf16 v[120:123], v[186:189], v[212:215], v[120:123]
	v_mfma_f32_16x16x32_bf16 v[108:111], v[160:163], v[220:223], v[108:111]
	v_mfma_f32_16x16x32_bf16 v[104:107], v[186:189], v[220:223], v[104:107]
	v_mfma_f32_16x16x32_bf16 v[92:95], v[160:163], v[228:231], v[92:95]
	v_mfma_f32_16x16x32_bf16 v[88:91], v[186:189], v[228:231], v[88:91]
	v_mfma_f32_16x16x32_bf16 v[76:79], v[160:163], v[236:239], v[76:79]
	v_mfma_f32_16x16x32_bf16 v[72:75], v[186:189], v[236:239], v[72:75]
	v_mfma_f32_16x16x32_bf16 v[124:127], v[182:185], v[216:219], v[124:127]
	v_mfma_f32_16x16x32_bf16 v[120:123], v[190:193], v[216:219], v[120:123]
	v_mfma_f32_16x16x32_bf16 v[108:111], v[182:185], v[224:227], v[108:111]
	v_mfma_f32_16x16x32_bf16 v[104:107], v[190:193], v[224:227], v[104:107]
	v_mfma_f32_16x16x32_bf16 v[92:95], v[182:185], v[232:235], v[92:95]
	v_mfma_f32_16x16x32_bf16 v[88:91], v[190:193], v[232:235], v[88:91]
	v_mfma_f32_16x16x32_bf16 v[76:79], v[182:185], v[240:243], v[76:79]
	v_mfma_f32_16x16x32_bf16 v[72:75], v[190:193], v[240:243], v[72:75]
	v_mfma_f32_16x16x32_bf16 v[116:119], v[196:199], v[212:215], v[116:119]
	v_mfma_f32_16x16x32_bf16 v[112:115], v[204:207], v[212:215], v[112:115]
	v_mfma_f32_16x16x32_bf16 v[100:103], v[196:199], v[220:223], v[100:103]
	v_mfma_f32_16x16x32_bf16 v[96:99], v[204:207], v[220:223], v[96:99]
	v_mfma_f32_16x16x32_bf16 v[84:87], v[196:199], v[228:231], v[84:87]
	v_mfma_f32_16x16x32_bf16 v[80:83], v[204:207], v[228:231], v[80:83]
	v_mfma_f32_16x16x32_bf16 v[68:71], v[196:199], v[236:239], v[68:71]
	v_mfma_f32_16x16x32_bf16 v[64:67], v[204:207], v[236:239], v[64:67]
	v_mfma_f32_16x16x32_bf16 v[116:119], v[200:203], v[216:219], v[116:119]
	v_mfma_f32_16x16x32_bf16 v[112:115], v[208:211], v[216:219], v[112:115]
	v_mfma_f32_16x16x32_bf16 v[100:103], v[200:203], v[224:227], v[100:103]
	v_mfma_f32_16x16x32_bf16 v[96:99], v[208:211], v[224:227], v[96:99]
	v_mfma_f32_16x16x32_bf16 v[84:87], v[200:203], v[232:235], v[84:87]
	v_mfma_f32_16x16x32_bf16 v[80:83], v[208:211], v[232:235], v[80:83]
	v_mfma_f32_16x16x32_bf16 v[68:71], v[200:203], v[240:243], v[68:71]
	v_mfma_f32_16x16x32_bf16 v[64:67], v[208:211], v[240:243], v[64:67]
	s_barrier
	s_add_u32 s98, s14, s16
	s_addc_u32 s99, s15, s17
	s_add_u32 s100, s28, s16
	s_addc_u32 s101, s29, s17
	s_mov_b32 m0, s33
	s_add_u32 s56, s14, 0x40000
	ds_read_b128 v[212:215], v145 offset:16384
	ds_read_b128 v[216:219], v145 offset:17408
	ds_read_b128 v[220:223], v145 offset:18432
	ds_read_b128 v[224:227], v145 offset:19456
	ds_read_b128 v[228:231], v145 offset:20480
	ds_read_b128 v[232:235], v145 offset:21504
	ds_read_b128 v[236:239], v145 offset:22528
	ds_read_b128 v[240:243], v145 offset:23552
	global_load_lds_dwordx4 v132, s[14:15]
	s_mov_b32 m0, s34
	s_addc_u32 s57, s15, 0
	global_load_lds_dwordx4 v134, s[14:15]
	s_mov_b32 m0, s35
	s_nop 0
	global_load_lds_dwordx4 v132, s[56:57]
	s_mov_b32 m0, s36
	s_nop 0
	global_load_lds_dwordx4 v134, s[56:57]
	s_mov_b32 m0, s31
	s_nop 0
	global_load_lds_dwordx4 v132, s[28:29]
	s_mov_b32 m0, s37
	s_nop 0
	global_load_lds_dwordx4 v134, s[28:29]
	s_waitcnt vmcnt(8)
	s_waitcnt lgkmcnt(0)
	s_barrier
	v_mfma_f32_16x16x32_bf16 v[60:63], v[160:163], v[212:215], v[60:63]
	v_mfma_f32_16x16x32_bf16 v[56:59], v[186:189], v[212:215], v[56:59]
	v_mfma_f32_16x16x32_bf16 v[44:47], v[160:163], v[220:223], v[44:47]
	v_mfma_f32_16x16x32_bf16 v[40:43], v[186:189], v[220:223], v[40:43]
	v_mfma_f32_16x16x32_bf16 v[28:31], v[160:163], v[228:231], v[28:31]
	v_mfma_f32_16x16x32_bf16 v[24:27], v[186:189], v[228:231], v[24:27]
	v_mfma_f32_16x16x32_bf16 v[12:15], v[160:163], v[236:239], v[12:15]
	v_mfma_f32_16x16x32_bf16 v[8:11], v[186:189], v[236:239], v[8:11]
	v_mfma_f32_16x16x32_bf16 v[60:63], v[182:185], v[216:219], v[60:63]
	v_mfma_f32_16x16x32_bf16 v[56:59], v[190:193], v[216:219], v[56:59]
	v_mfma_f32_16x16x32_bf16 v[44:47], v[182:185], v[224:227], v[44:47]
	v_mfma_f32_16x16x32_bf16 v[40:43], v[190:193], v[224:227], v[40:43]
	v_mfma_f32_16x16x32_bf16 v[28:31], v[182:185], v[232:235], v[28:31]
	v_mfma_f32_16x16x32_bf16 v[24:27], v[190:193], v[232:235], v[24:27]
	v_mfma_f32_16x16x32_bf16 v[12:15], v[182:185], v[240:243], v[12:15]
	v_mfma_f32_16x16x32_bf16 v[8:11], v[190:193], v[240:243], v[8:11]
	v_mfma_f32_16x16x32_bf16 v[52:55], v[196:199], v[212:215], v[52:55]
	v_mfma_f32_16x16x32_bf16 v[48:51], v[204:207], v[212:215], v[48:51]
	v_mfma_f32_16x16x32_bf16 v[36:39], v[196:199], v[220:223], v[36:39]
	v_mfma_f32_16x16x32_bf16 v[32:35], v[204:207], v[220:223], v[32:35]
	v_mfma_f32_16x16x32_bf16 v[20:23], v[196:199], v[228:231], v[20:23]
	v_mfma_f32_16x16x32_bf16 v[16:19], v[204:207], v[228:231], v[16:19]
	v_mfma_f32_16x16x32_bf16 v[4:7], v[196:199], v[236:239], v[4:7]
	v_mfma_f32_16x16x32_bf16 v[0:3], v[204:207], v[236:239], v[0:3]
	v_mfma_f32_16x16x32_bf16 v[52:55], v[200:203], v[216:219], v[52:55]
	v_mfma_f32_16x16x32_bf16 v[48:51], v[208:211], v[216:219], v[48:51]
	v_mfma_f32_16x16x32_bf16 v[36:39], v[200:203], v[224:227], v[36:39]
	v_mfma_f32_16x16x32_bf16 v[32:35], v[208:211], v[224:227], v[32:35]
	v_mfma_f32_16x16x32_bf16 v[20:23], v[200:203], v[232:235], v[20:23]
	v_mfma_f32_16x16x32_bf16 v[16:19], v[208:211], v[232:235], v[16:19]
	v_mfma_f32_16x16x32_bf16 v[4:7], v[200:203], v[240:243], v[4:7]
	v_mfma_f32_16x16x32_bf16 v[0:3], v[208:211], v[240:243], v[0:3]
	s_barrier
	ds_read_b128 v[160:163], v174
	ds_read_b128 v[182:185], v175
	ds_read_b128 v[186:189], v176
	ds_read_b128 v[190:193], v177
	ds_read_b128 v[196:199], v178
	ds_read_b128 v[200:203], v179
	ds_read_b128 v[204:207], v180
	ds_read_b128 v[208:211], v181
	s_add_u32 s28, s28, 0x40000
	s_addc_u32 s29, s29, 0
	s_mov_b32 m0, s62
	ds_read_b128 v[212:215], v145 offset:32768
	ds_read_b128 v[216:219], v145 offset:33792
	ds_read_b128 v[220:223], v145 offset:34816
	ds_read_b128 v[224:227], v145 offset:35840
	ds_read_b128 v[228:231], v145 offset:36864
	ds_read_b128 v[232:235], v145 offset:37888
	ds_read_b128 v[236:239], v145 offset:38912
	ds_read_b128 v[240:243], v145 offset:39936
	global_load_lds_dwordx4 v132, s[28:29]
	s_mov_b32 m0, s63
	s_nop 0
	global_load_lds_dwordx4 v134, s[28:29]
	s_waitcnt vmcnt(8)
	s_waitcnt lgkmcnt(0)
	s_barrier
	v_mfma_f32_16x16x32_bf16 v[124:127], v[160:163], v[212:215], v[124:127]
	v_mfma_f32_16x16x32_bf16 v[120:123], v[186:189], v[212:215], v[120:123]
	v_mfma_f32_16x16x32_bf16 v[108:111], v[160:163], v[220:223], v[108:111]
	v_mfma_f32_16x16x32_bf16 v[104:107], v[186:189], v[220:223], v[104:107]
	v_mfma_f32_16x16x32_bf16 v[92:95], v[160:163], v[228:231], v[92:95]
	v_mfma_f32_16x16x32_bf16 v[88:91], v[186:189], v[228:231], v[88:91]
	v_mfma_f32_16x16x32_bf16 v[76:79], v[160:163], v[236:239], v[76:79]
	v_mfma_f32_16x16x32_bf16 v[72:75], v[186:189], v[236:239], v[72:75]
	v_mfma_f32_16x16x32_bf16 v[124:127], v[182:185], v[216:219], v[124:127]
	v_mfma_f32_16x16x32_bf16 v[120:123], v[190:193], v[216:219], v[120:123]
	v_mfma_f32_16x16x32_bf16 v[108:111], v[182:185], v[224:227], v[108:111]
	v_mfma_f32_16x16x32_bf16 v[104:107], v[190:193], v[224:227], v[104:107]
	v_mfma_f32_16x16x32_bf16 v[92:95], v[182:185], v[232:235], v[92:95]
	v_mfma_f32_16x16x32_bf16 v[88:91], v[190:193], v[232:235], v[88:91]
	v_mfma_f32_16x16x32_bf16 v[76:79], v[182:185], v[240:243], v[76:79]
	v_mfma_f32_16x16x32_bf16 v[72:75], v[190:193], v[240:243], v[72:75]
	v_mfma_f32_16x16x32_bf16 v[116:119], v[196:199], v[212:215], v[116:119]
	v_mfma_f32_16x16x32_bf16 v[112:115], v[204:207], v[212:215], v[112:115]
	v_mfma_f32_16x16x32_bf16 v[100:103], v[196:199], v[220:223], v[100:103]
	v_mfma_f32_16x16x32_bf16 v[96:99], v[204:207], v[220:223], v[96:99]
	v_mfma_f32_16x16x32_bf16 v[84:87], v[196:199], v[228:231], v[84:87]
	v_mfma_f32_16x16x32_bf16 v[80:83], v[204:207], v[228:231], v[80:83]
	v_mfma_f32_16x16x32_bf16 v[68:71], v[196:199], v[236:239], v[68:71]
	v_mfma_f32_16x16x32_bf16 v[64:67], v[204:207], v[236:239], v[64:67]
	v_mfma_f32_16x16x32_bf16 v[116:119], v[200:203], v[216:219], v[116:119]
	v_mfma_f32_16x16x32_bf16 v[112:115], v[208:211], v[216:219], v[112:115]
	v_mfma_f32_16x16x32_bf16 v[100:103], v[200:203], v[224:227], v[100:103]
	v_mfma_f32_16x16x32_bf16 v[96:99], v[208:211], v[224:227], v[96:99]
	v_mfma_f32_16x16x32_bf16 v[84:87], v[200:203], v[232:235], v[84:87]
	v_mfma_f32_16x16x32_bf16 v[80:83], v[208:211], v[232:235], v[80:83]
	v_mfma_f32_16x16x32_bf16 v[68:71], v[200:203], v[240:243], v[68:71]
	v_mfma_f32_16x16x32_bf16 v[64:67], v[208:211], v[240:243], v[64:67]
	s_barrier
	s_mov_b32 m0, s64
	s_add_u32 s14, s14, 0x40080
	ds_read_b128 v[212:215], v145 offset:49152
	ds_read_b128 v[216:219], v145 offset:50176
	ds_read_b128 v[220:223], v145 offset:51200
	ds_read_b128 v[224:227], v145 offset:52224
	ds_read_b128 v[228:231], v145 offset:53248
	ds_read_b128 v[232:235], v145 offset:54272
	ds_read_b128 v[236:239], v145 offset:55296
	ds_read_b128 v[240:243], v145 offset:56320
	global_load_lds_dwordx4 v132, s[98:99]
	s_mov_b32 m0, s65
	s_addc_u32 s15, s15, 0
	global_load_lds_dwordx4 v134, s[98:99]
	s_mov_b32 m0, s72
	s_nop 0
	global_load_lds_dwordx4 v132, s[14:15]
	s_mov_b32 m0, s73
	s_nop 0
	global_load_lds_dwordx4 v134, s[14:15]
	s_mov_b32 m0, s66
	s_nop 0
	global_load_lds_dwordx4 v132, s[100:101]
	s_mov_b32 m0, s67
	s_nop 0
	global_load_lds_dwordx4 v134, s[100:101]
	s_waitcnt vmcnt(8)
	s_waitcnt lgkmcnt(0)
	s_barrier
	v_mfma_f32_16x16x32_bf16 v[60:63], v[160:163], v[212:215], v[60:63]
	v_mfma_f32_16x16x32_bf16 v[56:59], v[186:189], v[212:215], v[56:59]
	v_mfma_f32_16x16x32_bf16 v[44:47], v[160:163], v[220:223], v[44:47]
	v_mfma_f32_16x16x32_bf16 v[40:43], v[186:189], v[220:223], v[40:43]
	v_mfma_f32_16x16x32_bf16 v[28:31], v[160:163], v[228:231], v[28:31]
	v_mfma_f32_16x16x32_bf16 v[24:27], v[186:189], v[228:231], v[24:27]
	v_mfma_f32_16x16x32_bf16 v[12:15], v[160:163], v[236:239], v[12:15]
	v_mfma_f32_16x16x32_bf16 v[8:11], v[186:189], v[236:239], v[8:11]
	v_mfma_f32_16x16x32_bf16 v[60:63], v[182:185], v[216:219], v[60:63]
	v_mfma_f32_16x16x32_bf16 v[56:59], v[190:193], v[216:219], v[56:59]
	v_mfma_f32_16x16x32_bf16 v[44:47], v[182:185], v[224:227], v[44:47]
	v_mfma_f32_16x16x32_bf16 v[40:43], v[190:193], v[224:227], v[40:43]
	v_mfma_f32_16x16x32_bf16 v[28:31], v[182:185], v[232:235], v[28:31]
	v_mfma_f32_16x16x32_bf16 v[24:27], v[190:193], v[232:235], v[24:27]
	v_mfma_f32_16x16x32_bf16 v[12:15], v[182:185], v[240:243], v[12:15]
	v_mfma_f32_16x16x32_bf16 v[8:11], v[190:193], v[240:243], v[8:11]
	v_mfma_f32_16x16x32_bf16 v[52:55], v[196:199], v[212:215], v[52:55]
	v_mfma_f32_16x16x32_bf16 v[48:51], v[204:207], v[212:215], v[48:51]
	v_mfma_f32_16x16x32_bf16 v[36:39], v[196:199], v[220:223], v[36:39]
	v_mfma_f32_16x16x32_bf16 v[32:35], v[204:207], v[220:223], v[32:35]
	v_mfma_f32_16x16x32_bf16 v[20:23], v[196:199], v[228:231], v[20:23]
	v_mfma_f32_16x16x32_bf16 v[16:19], v[204:207], v[228:231], v[16:19]
	v_mfma_f32_16x16x32_bf16 v[4:7], v[196:199], v[236:239], v[4:7]
	v_mfma_f32_16x16x32_bf16 v[0:3], v[204:207], v[236:239], v[0:3]
	v_mfma_f32_16x16x32_bf16 v[52:55], v[200:203], v[216:219], v[52:55]
	v_mfma_f32_16x16x32_bf16 v[48:51], v[208:211], v[216:219], v[48:51]
	v_mfma_f32_16x16x32_bf16 v[36:39], v[200:203], v[224:227], v[36:39]
	v_mfma_f32_16x16x32_bf16 v[32:35], v[208:211], v[224:227], v[32:35]
	v_mfma_f32_16x16x32_bf16 v[20:23], v[200:203], v[232:235], v[20:23]
	v_mfma_f32_16x16x32_bf16 v[16:19], v[208:211], v[232:235], v[16:19]
	v_mfma_f32_16x16x32_bf16 v[4:7], v[200:203], v[240:243], v[4:7]
	v_mfma_f32_16x16x32_bf16 v[0:3], v[208:211], v[240:243], v[0:3]
	s_barrier
	s_add_i32 s54, s54, 2
	s_add_u32 s12, s12, 0x100
	s_addc_u32 s13, s13, 0
	s_add_u32 s38, s38, 0x100
	s_addc_u32 s39, s39, 0
	s_cmp_gt_u32 s54, 13
	s_cbranch_scc0 .LBB0_251
	s_and_b64 vcc, exec, s[18:19]
	s_cbranch_vccz .LBB0_254
	s_barrier

.LBB0_586:
	ds_read_b128 v[160:163], v165
	ds_read_b128 v[182:185], v167
	ds_read_b128 v[186:189], v168
	ds_read_b128 v[190:193], v169
	ds_read_b128 v[196:199], v170
	ds_read_b128 v[200:203], v171
	ds_read_b128 v[204:207], v172
	ds_read_b128 v[208:211], v173
	s_add_u32 s12, s10, 0xfffc0080
	s_addc_u32 s13, s11, -1
	s_cmp_eq_u32 s54, 12
	s_cselect_b32 s15, s7, s13
	s_cselect_b32 s14, s9, s12
	s_cselect_b32 s13, s21, s39
	s_cselect_b32 s12, s23, s38
	s_mov_b32 m0, s82
	ds_read_b128 v[212:215], v145
	ds_read_b128 v[216:219], v145 offset:1024
	ds_read_b128 v[220:223], v145 offset:2048
	ds_read_b128 v[224:227], v145 offset:3072
	ds_read_b128 v[228:231], v145 offset:4096
	ds_read_b128 v[232:235], v145 offset:5120
	ds_read_b128 v[236:239], v145 offset:6144
	ds_read_b128 v[240:243], v145 offset:7168
	global_load_lds_dwordx4 v138, s[10:11]
	s_mov_b32 m0, s83
	s_nop 0
	global_load_lds_dwordx4 v140, s[10:11]
	s_waitcnt vmcnt(8)
	s_waitcnt lgkmcnt(0)
	s_barrier
	v_mfma_f32_16x16x32_bf16 v[124:127], v[160:163], v[212:215], v[124:127]
	v_mfma_f32_16x16x32_bf16 v[120:123], v[186:189], v[212:215], v[120:123]
	v_mfma_f32_16x16x32_bf16 v[108:111], v[160:163], v[220:223], v[108:111]
	v_mfma_f32_16x16x32_bf16 v[104:107], v[186:189], v[220:223], v[104:107]
	v_mfma_f32_16x16x32_bf16 v[92:95], v[160:163], v[228:231], v[92:95]
	v_mfma_f32_16x16x32_bf16 v[88:91], v[186:189], v[228:231], v[88:91]
	v_mfma_f32_16x16x32_bf16 v[76:79], v[160:163], v[236:239], v[76:79]
	v_mfma_f32_16x16x32_bf16 v[72:75], v[186:189], v[236:239], v[72:75]
	v_mfma_f32_16x16x32_bf16 v[124:127], v[182:185], v[216:219], v[124:127]
	v_mfma_f32_16x16x32_bf16 v[120:123], v[190:193], v[216:219], v[120:123]
	v_mfma_f32_16x16x32_bf16 v[108:111], v[182:185], v[224:227], v[108:111]
	v_mfma_f32_16x16x32_bf16 v[104:107], v[190:193], v[224:227], v[104:107]
	v_mfma_f32_16x16x32_bf16 v[92:95], v[182:185], v[232:235], v[92:95]
	v_mfma_f32_16x16x32_bf16 v[88:91], v[190:193], v[232:235], v[88:91]
	v_mfma_f32_16x16x32_bf16 v[76:79], v[182:185], v[240:243], v[76:79]
	v_mfma_f32_16x16x32_bf16 v[72:75], v[190:193], v[240:243], v[72:75]
	v_mfma_f32_16x16x32_bf16 v[116:119], v[196:199], v[212:215], v[116:119]
	v_mfma_f32_16x16x32_bf16 v[112:115], v[204:207], v[212:215], v[112:115]
	v_mfma_f32_16x16x32_bf16 v[100:103], v[196:199], v[220:223], v[100:103]
	v_mfma_f32_16x16x32_bf16 v[96:99], v[204:207], v[220:223], v[96:99]
	v_mfma_f32_16x16x32_bf16 v[84:87], v[196:199], v[228:231], v[84:87]
	v_mfma_f32_16x16x32_bf16 v[80:83], v[204:207], v[228:231], v[80:83]
	v_mfma_f32_16x16x32_bf16 v[68:71], v[196:199], v[236:239], v[68:71]
	v_mfma_f32_16x16x32_bf16 v[64:67], v[204:207], v[236:239], v[64:67]
	v_mfma_f32_16x16x32_bf16 v[116:119], v[200:203], v[216:219], v[116:119]
	v_mfma_f32_16x16x32_bf16 v[112:115], v[208:211], v[216:219], v[112:115]
	v_mfma_f32_16x16x32_bf16 v[100:103], v[200:203], v[224:227], v[100:103]
	v_mfma_f32_16x16x32_bf16 v[96:99], v[208:211], v[224:227], v[96:99]
	v_mfma_f32_16x16x32_bf16 v[84:87], v[200:203], v[232:235], v[84:87]
	v_mfma_f32_16x16x32_bf16 v[80:83], v[208:211], v[232:235], v[80:83]
	v_mfma_f32_16x16x32_bf16 v[68:71], v[200:203], v[240:243], v[68:71]
	v_mfma_f32_16x16x32_bf16 v[64:67], v[208:211], v[240:243], v[64:67]
	s_barrier
	s_add_u32 s98, s12, s16
	s_addc_u32 s99, s13, s17
	s_add_u32 s100, s14, s16
	s_addc_u32 s101, s15, s17
	s_mov_b32 m0, s30
	s_add_u32 s56, s12, 0x40000
	ds_read_b128 v[212:215], v145 offset:16384
	ds_read_b128 v[216:219], v145 offset:17408
	ds_read_b128 v[220:223], v145 offset:18432
	ds_read_b128 v[224:227], v145 offset:19456
	ds_read_b128 v[228:231], v145 offset:20480
	ds_read_b128 v[232:235], v145 offset:21504
	ds_read_b128 v[236:239], v145 offset:22528
	ds_read_b128 v[240:243], v145 offset:23552
	global_load_lds_dwordx4 v132, s[12:13]
	s_mov_b32 m0, s31
	s_addc_u32 s57, s13, 0
	global_load_lds_dwordx4 v134, s[12:13]
	s_mov_b32 m0, s33
	s_nop 0
	global_load_lds_dwordx4 v132, s[56:57]
	s_mov_b32 m0, s34
	s_nop 0
	global_load_lds_dwordx4 v134, s[56:57]
	s_mov_b32 m0, s29
	s_nop 0
	global_load_lds_dwordx4 v132, s[14:15]
	s_mov_b32 m0, s35
	s_nop 0
	global_load_lds_dwordx4 v134, s[14:15]
	s_waitcnt vmcnt(8)
	s_waitcnt lgkmcnt(0)
	s_barrier
	v_mfma_f32_16x16x32_bf16 v[60:63], v[160:163], v[212:215], v[60:63]
	v_mfma_f32_16x16x32_bf16 v[56:59], v[186:189], v[212:215], v[56:59]
	v_mfma_f32_16x16x32_bf16 v[44:47], v[160:163], v[220:223], v[44:47]
	v_mfma_f32_16x16x32_bf16 v[40:43], v[186:189], v[220:223], v[40:43]
	v_mfma_f32_16x16x32_bf16 v[28:31], v[160:163], v[228:231], v[28:31]
	v_mfma_f32_16x16x32_bf16 v[24:27], v[186:189], v[228:231], v[24:27]
	v_mfma_f32_16x16x32_bf16 v[12:15], v[160:163], v[236:239], v[12:15]
	v_mfma_f32_16x16x32_bf16 v[8:11], v[186:189], v[236:239], v[8:11]
	v_mfma_f32_16x16x32_bf16 v[60:63], v[182:185], v[216:219], v[60:63]
	v_mfma_f32_16x16x32_bf16 v[56:59], v[190:193], v[216:219], v[56:59]
	v_mfma_f32_16x16x32_bf16 v[44:47], v[182:185], v[224:227], v[44:47]
	v_mfma_f32_16x16x32_bf16 v[40:43], v[190:193], v[224:227], v[40:43]
	v_mfma_f32_16x16x32_bf16 v[28:31], v[182:185], v[232:235], v[28:31]
	v_mfma_f32_16x16x32_bf16 v[24:27], v[190:193], v[232:235], v[24:27]
	v_mfma_f32_16x16x32_bf16 v[12:15], v[182:185], v[240:243], v[12:15]
	v_mfma_f32_16x16x32_bf16 v[8:11], v[190:193], v[240:243], v[8:11]
	v_mfma_f32_16x16x32_bf16 v[52:55], v[196:199], v[212:215], v[52:55]
	v_mfma_f32_16x16x32_bf16 v[48:51], v[204:207], v[212:215], v[48:51]
	v_mfma_f32_16x16x32_bf16 v[36:39], v[196:199], v[220:223], v[36:39]
	v_mfma_f32_16x16x32_bf16 v[32:35], v[204:207], v[220:223], v[32:35]
	v_mfma_f32_16x16x32_bf16 v[20:23], v[196:199], v[228:231], v[20:23]
	v_mfma_f32_16x16x32_bf16 v[16:19], v[204:207], v[228:231], v[16:19]
	v_mfma_f32_16x16x32_bf16 v[4:7], v[196:199], v[236:239], v[4:7]
	v_mfma_f32_16x16x32_bf16 v[0:3], v[204:207], v[236:239], v[0:3]
	v_mfma_f32_16x16x32_bf16 v[52:55], v[200:203], v[216:219], v[52:55]
	v_mfma_f32_16x16x32_bf16 v[48:51], v[208:211], v[216:219], v[48:51]
	v_mfma_f32_16x16x32_bf16 v[36:39], v[200:203], v[224:227], v[36:39]
	v_mfma_f32_16x16x32_bf16 v[32:35], v[208:211], v[224:227], v[32:35]
	v_mfma_f32_16x16x32_bf16 v[20:23], v[200:203], v[232:235], v[20:23]
	v_mfma_f32_16x16x32_bf16 v[16:19], v[208:211], v[232:235], v[16:19]
	v_mfma_f32_16x16x32_bf16 v[4:7], v[200:203], v[240:243], v[4:7]
	v_mfma_f32_16x16x32_bf16 v[0:3], v[208:211], v[240:243], v[0:3]
	s_barrier
	ds_read_b128 v[160:163], v174
	ds_read_b128 v[182:185], v175
	ds_read_b128 v[186:189], v176
	ds_read_b128 v[190:193], v177
	ds_read_b128 v[196:199], v178
	ds_read_b128 v[200:203], v179
	ds_read_b128 v[204:207], v180
	ds_read_b128 v[208:211], v181
	s_add_u32 s14, s14, 0x40000
	s_addc_u32 s15, s15, 0
	s_mov_b32 m0, s36
	ds_read_b128 v[212:215], v145 offset:32768
	ds_read_b128 v[216:219], v145 offset:33792
	ds_read_b128 v[220:223], v145 offset:34816
	ds_read_b128 v[224:227], v145 offset:35840
	ds_read_b128 v[228:231], v145 offset:36864
	ds_read_b128 v[232:235], v145 offset:37888
	ds_read_b128 v[236:239], v145 offset:38912
	ds_read_b128 v[240:243], v145 offset:39936
	global_load_lds_dwordx4 v132, s[14:15]
	s_mov_b32 m0, s37
	s_nop 0
	global_load_lds_dwordx4 v134, s[14:15]
	s_waitcnt vmcnt(8)
	s_waitcnt lgkmcnt(0)
	s_barrier
	v_mfma_f32_16x16x32_bf16 v[124:127], v[160:163], v[212:215], v[124:127]
	v_mfma_f32_16x16x32_bf16 v[120:123], v[186:189], v[212:215], v[120:123]
	v_mfma_f32_16x16x32_bf16 v[108:111], v[160:163], v[220:223], v[108:111]
	v_mfma_f32_16x16x32_bf16 v[104:107], v[186:189], v[220:223], v[104:107]
	v_mfma_f32_16x16x32_bf16 v[92:95], v[160:163], v[228:231], v[92:95]
	v_mfma_f32_16x16x32_bf16 v[88:91], v[186:189], v[228:231], v[88:91]
	v_mfma_f32_16x16x32_bf16 v[76:79], v[160:163], v[236:239], v[76:79]
	v_mfma_f32_16x16x32_bf16 v[72:75], v[186:189], v[236:239], v[72:75]
	v_mfma_f32_16x16x32_bf16 v[124:127], v[182:185], v[216:219], v[124:127]
	v_mfma_f32_16x16x32_bf16 v[120:123], v[190:193], v[216:219], v[120:123]
	v_mfma_f32_16x16x32_bf16 v[108:111], v[182:185], v[224:227], v[108:111]
	v_mfma_f32_16x16x32_bf16 v[104:107], v[190:193], v[224:227], v[104:107]
	v_mfma_f32_16x16x32_bf16 v[92:95], v[182:185], v[232:235], v[92:95]
	v_mfma_f32_16x16x32_bf16 v[88:91], v[190:193], v[232:235], v[88:91]
	v_mfma_f32_16x16x32_bf16 v[76:79], v[182:185], v[240:243], v[76:79]
	v_mfma_f32_16x16x32_bf16 v[72:75], v[190:193], v[240:243], v[72:75]
	v_mfma_f32_16x16x32_bf16 v[116:119], v[196:199], v[212:215], v[116:119]
	v_mfma_f32_16x16x32_bf16 v[112:115], v[204:207], v[212:215], v[112:115]
	v_mfma_f32_16x16x32_bf16 v[100:103], v[196:199], v[220:223], v[100:103]
	v_mfma_f32_16x16x32_bf16 v[96:99], v[204:207], v[220:223], v[96:99]
	v_mfma_f32_16x16x32_bf16 v[84:87], v[196:199], v[228:231], v[84:87]
	v_mfma_f32_16x16x32_bf16 v[80:83], v[204:207], v[228:231], v[80:83]
	v_mfma_f32_16x16x32_bf16 v[68:71], v[196:199], v[236:239], v[68:71]
	v_mfma_f32_16x16x32_bf16 v[64:67], v[204:207], v[236:239], v[64:67]
	v_mfma_f32_16x16x32_bf16 v[116:119], v[200:203], v[216:219], v[116:119]
	v_mfma_f32_16x16x32_bf16 v[112:115], v[208:211], v[216:219], v[112:115]
	v_mfma_f32_16x16x32_bf16 v[100:103], v[200:203], v[224:227], v[100:103]
	v_mfma_f32_16x16x32_bf16 v[96:99], v[208:211], v[224:227], v[96:99]
	v_mfma_f32_16x16x32_bf16 v[84:87], v[200:203], v[232:235], v[84:87]
	v_mfma_f32_16x16x32_bf16 v[80:83], v[208:211], v[232:235], v[80:83]
	v_mfma_f32_16x16x32_bf16 v[68:71], v[200:203], v[240:243], v[68:71]
	v_mfma_f32_16x16x32_bf16 v[64:67], v[208:211], v[240:243], v[64:67]
	s_barrier
	s_mov_b32 m0, s64
	s_add_u32 s12, s12, 0x40080
	ds_read_b128 v[212:215], v145 offset:49152
	ds_read_b128 v[216:219], v145 offset:50176
	ds_read_b128 v[220:223], v145 offset:51200
	ds_read_b128 v[224:227], v145 offset:52224
	ds_read_b128 v[228:231], v145 offset:53248
	ds_read_b128 v[232:235], v145 offset:54272
	ds_read_b128 v[236:239], v145 offset:55296
	ds_read_b128 v[240:243], v145 offset:56320
	global_load_lds_dwordx4 v132, s[98:99]
	s_mov_b32 m0, s65
	s_addc_u32 s13, s13, 0
	global_load_lds_dwordx4 v134, s[98:99]
	s_mov_b32 m0, s72
	s_nop 0
	global_load_lds_dwordx4 v132, s[12:13]
	s_mov_b32 m0, s73
	s_nop 0
	global_load_lds_dwordx4 v134, s[12:13]
	s_mov_b32 m0, s66
	s_nop 0
	global_load_lds_dwordx4 v132, s[100:101]
	s_mov_b32 m0, s67
	s_nop 0
	global_load_lds_dwordx4 v134, s[100:101]
	s_waitcnt vmcnt(8)
	s_waitcnt lgkmcnt(0)
	s_barrier
	v_mfma_f32_16x16x32_bf16 v[60:63], v[160:163], v[212:215], v[60:63]
	v_mfma_f32_16x16x32_bf16 v[56:59], v[186:189], v[212:215], v[56:59]
	v_mfma_f32_16x16x32_bf16 v[44:47], v[160:163], v[220:223], v[44:47]
	v_mfma_f32_16x16x32_bf16 v[40:43], v[186:189], v[220:223], v[40:43]
	v_mfma_f32_16x16x32_bf16 v[28:31], v[160:163], v[228:231], v[28:31]
	v_mfma_f32_16x16x32_bf16 v[24:27], v[186:189], v[228:231], v[24:27]
	v_mfma_f32_16x16x32_bf16 v[12:15], v[160:163], v[236:239], v[12:15]
	v_mfma_f32_16x16x32_bf16 v[8:11], v[186:189], v[236:239], v[8:11]
	v_mfma_f32_16x16x32_bf16 v[60:63], v[182:185], v[216:219], v[60:63]
	v_mfma_f32_16x16x32_bf16 v[56:59], v[190:193], v[216:219], v[56:59]
	v_mfma_f32_16x16x32_bf16 v[44:47], v[182:185], v[224:227], v[44:47]
	v_mfma_f32_16x16x32_bf16 v[40:43], v[190:193], v[224:227], v[40:43]
	v_mfma_f32_16x16x32_bf16 v[28:31], v[182:185], v[232:235], v[28:31]
	v_mfma_f32_16x16x32_bf16 v[24:27], v[190:193], v[232:235], v[24:27]
	v_mfma_f32_16x16x32_bf16 v[12:15], v[182:185], v[240:243], v[12:15]
	v_mfma_f32_16x16x32_bf16 v[8:11], v[190:193], v[240:243], v[8:11]
	v_mfma_f32_16x16x32_bf16 v[52:55], v[196:199], v[212:215], v[52:55]
	v_mfma_f32_16x16x32_bf16 v[48:51], v[204:207], v[212:215], v[48:51]
	v_mfma_f32_16x16x32_bf16 v[36:39], v[196:199], v[220:223], v[36:39]
	v_mfma_f32_16x16x32_bf16 v[32:35], v[204:207], v[220:223], v[32:35]
	v_mfma_f32_16x16x32_bf16 v[20:23], v[196:199], v[228:231], v[20:23]
	v_mfma_f32_16x16x32_bf16 v[16:19], v[204:207], v[228:231], v[16:19]
	v_mfma_f32_16x16x32_bf16 v[4:7], v[196:199], v[236:239], v[4:7]
	v_mfma_f32_16x16x32_bf16 v[0:3], v[204:207], v[236:239], v[0:3]
	v_mfma_f32_16x16x32_bf16 v[52:55], v[200:203], v[216:219], v[52:55]
	v_mfma_f32_16x16x32_bf16 v[48:51], v[208:211], v[216:219], v[48:51]
	v_mfma_f32_16x16x32_bf16 v[36:39], v[200:203], v[224:227], v[36:39]
	v_mfma_f32_16x16x32_bf16 v[32:35], v[208:211], v[224:227], v[32:35]
	v_mfma_f32_16x16x32_bf16 v[20:23], v[200:203], v[232:235], v[20:23]
	v_mfma_f32_16x16x32_bf16 v[16:19], v[208:211], v[232:235], v[16:19]
	v_mfma_f32_16x16x32_bf16 v[4:7], v[200:203], v[240:243], v[4:7]
	v_mfma_f32_16x16x32_bf16 v[0:3], v[208:211], v[240:243], v[0:3]
	s_barrier
	s_add_i32 s54, s54, 2
	s_add_u32 s10, s10, 0x100
	s_addc_u32 s11, s11, 0
	s_add_u32 s38, s38, 0x100
	s_addc_u32 s39, s39, 0
	s_cmp_gt_u32 s54, 13
	s_cbranch_scc0 .LBB0_586
	s_and_b64 vcc, exec, s[18:19]
	s_cbranch_vccz .LBB0_589
	s_barrier

.LBB0_856:
	ds_read_b128 v[178:181], v160
	ds_read_b128 v[182:185], v161
	ds_read_b128 v[186:189], v162
	ds_read_b128 v[190:193], v163
	ds_read_b128 v[198:201], v164
	ds_read_b128 v[202:205], v165
	ds_read_b128 v[206:209], v167
	ds_read_b128 v[210:213], v168
	s_add_u32 s28, s10, 0x100
	s_addc_u32 s29, s11, 0
	s_cmp_eq_u32 s56, 28
	s_cselect_b32 s35, s4, s29
	s_cselect_b32 s34, s5, s28
	s_cselect_b32 s31, s21, vcc_hi
	s_cselect_b32 s30, s23, vcc_lo
	s_mov_b32 m0, s55
	ds_read_b128 v[214:217], v152
	ds_read_b128 v[218:221], v152 offset:1024
	ds_read_b128 v[222:225], v152 offset:2048
	ds_read_b128 v[226:229], v152 offset:3072
	ds_read_b128 v[230:233], v152 offset:4096
	ds_read_b128 v[234:237], v152 offset:5120
	ds_read_b128 v[238:241], v152 offset:6144
	ds_read_b128 v[242:245], v152 offset:7168
	global_load_lds_dwordx4 v136, s[10:11]
	s_mov_b32 m0, s36
	s_nop 0
	global_load_lds_dwordx4 v138, s[10:11]
	s_waitcnt vmcnt(8)
	s_waitcnt lgkmcnt(0)
	s_barrier
	v_mfma_f32_16x16x32_bf16 v[124:127], v[178:181], v[214:217], v[124:127]
	v_mfma_f32_16x16x32_bf16 v[120:123], v[186:189], v[214:217], v[120:123]
	v_mfma_f32_16x16x32_bf16 v[108:111], v[178:181], v[222:225], v[108:111]
	v_mfma_f32_16x16x32_bf16 v[104:107], v[186:189], v[222:225], v[104:107]
	v_mfma_f32_16x16x32_bf16 v[92:95], v[178:181], v[230:233], v[92:95]
	v_mfma_f32_16x16x32_bf16 v[88:91], v[186:189], v[230:233], v[88:91]
	v_mfma_f32_16x16x32_bf16 v[76:79], v[178:181], v[238:241], v[76:79]
	v_mfma_f32_16x16x32_bf16 v[72:75], v[186:189], v[238:241], v[72:75]
	v_mfma_f32_16x16x32_bf16 v[124:127], v[182:185], v[218:221], v[124:127]
	v_mfma_f32_16x16x32_bf16 v[120:123], v[190:193], v[218:221], v[120:123]
	v_mfma_f32_16x16x32_bf16 v[108:111], v[182:185], v[226:229], v[108:111]
	v_mfma_f32_16x16x32_bf16 v[104:107], v[190:193], v[226:229], v[104:107]
	v_mfma_f32_16x16x32_bf16 v[92:95], v[182:185], v[234:237], v[92:95]
	v_mfma_f32_16x16x32_bf16 v[88:91], v[190:193], v[234:237], v[88:91]
	v_mfma_f32_16x16x32_bf16 v[76:79], v[182:185], v[242:245], v[76:79]
	v_mfma_f32_16x16x32_bf16 v[72:75], v[190:193], v[242:245], v[72:75]
	v_mfma_f32_16x16x32_bf16 v[116:119], v[198:201], v[214:217], v[116:119]
	v_mfma_f32_16x16x32_bf16 v[112:115], v[206:209], v[214:217], v[112:115]
	v_mfma_f32_16x16x32_bf16 v[100:103], v[198:201], v[222:225], v[100:103]
	v_mfma_f32_16x16x32_bf16 v[96:99], v[206:209], v[222:225], v[96:99]
	v_mfma_f32_16x16x32_bf16 v[84:87], v[198:201], v[230:233], v[84:87]
	v_mfma_f32_16x16x32_bf16 v[80:83], v[206:209], v[230:233], v[80:83]
	v_mfma_f32_16x16x32_bf16 v[68:71], v[198:201], v[238:241], v[68:71]
	v_mfma_f32_16x16x32_bf16 v[64:67], v[206:209], v[238:241], v[64:67]
	v_mfma_f32_16x16x32_bf16 v[116:119], v[202:205], v[218:221], v[116:119]
	v_mfma_f32_16x16x32_bf16 v[112:115], v[210:213], v[218:221], v[112:115]
	v_mfma_f32_16x16x32_bf16 v[100:103], v[202:205], v[226:229], v[100:103]
	v_mfma_f32_16x16x32_bf16 v[96:99], v[210:213], v[226:229], v[96:99]
	v_mfma_f32_16x16x32_bf16 v[84:87], v[202:205], v[234:237], v[84:87]
	v_mfma_f32_16x16x32_bf16 v[80:83], v[210:213], v[234:237], v[80:83]
	v_mfma_f32_16x16x32_bf16 v[68:71], v[202:205], v[242:245], v[68:71]
	v_mfma_f32_16x16x32_bf16 v[64:67], v[210:213], v[242:245], v[64:67]
	s_barrier
	s_add_u32 s98, s30, s14
	s_addc_u32 s99, s31, s15
	s_add_u32 s100, s34, s14
	s_addc_u32 s101, s35, s15
	s_mov_b32 m0, s37
	s_add_u32 s10, s30, 0x80000
	ds_read_b128 v[214:217], v152 offset:16384
	ds_read_b128 v[218:221], v152 offset:17408
	ds_read_b128 v[222:225], v152 offset:18432
	ds_read_b128 v[226:229], v152 offset:19456
	ds_read_b128 v[230:233], v152 offset:20480
	ds_read_b128 v[234:237], v152 offset:21504
	ds_read_b128 v[238:241], v152 offset:22528
	ds_read_b128 v[242:245], v152 offset:23552
	global_load_lds_dwordx4 v132, s[30:31]
	s_mov_b32 m0, s41
	s_addc_u32 s11, s31, 0
	global_load_lds_dwordx4 v134, s[30:31]
	s_mov_b32 m0, s42
	s_nop 0
	global_load_lds_dwordx4 v132, s[10:11]
	s_mov_b32 m0, s43
	s_nop 0
	global_load_lds_dwordx4 v134, s[10:11]
	s_mov_b32 m0, s40
	s_nop 0
	global_load_lds_dwordx4 v132, s[34:35]
	s_mov_b32 m0, s72
	s_nop 0
	global_load_lds_dwordx4 v134, s[34:35]
	s_waitcnt vmcnt(8)
	s_waitcnt lgkmcnt(0)
	s_barrier
	v_mfma_f32_16x16x32_bf16 v[60:63], v[178:181], v[214:217], v[60:63]
	v_mfma_f32_16x16x32_bf16 v[56:59], v[186:189], v[214:217], v[56:59]
	v_mfma_f32_16x16x32_bf16 v[44:47], v[178:181], v[222:225], v[44:47]
	v_mfma_f32_16x16x32_bf16 v[40:43], v[186:189], v[222:225], v[40:43]
	v_mfma_f32_16x16x32_bf16 v[28:31], v[178:181], v[230:233], v[28:31]
	v_mfma_f32_16x16x32_bf16 v[24:27], v[186:189], v[230:233], v[24:27]
	v_mfma_f32_16x16x32_bf16 v[16:19], v[178:181], v[238:241], v[16:19]
	v_mfma_f32_16x16x32_bf16 v[8:11], v[186:189], v[238:241], v[8:11]
	v_mfma_f32_16x16x32_bf16 v[60:63], v[182:185], v[218:221], v[60:63]
	v_mfma_f32_16x16x32_bf16 v[56:59], v[190:193], v[218:221], v[56:59]
	v_mfma_f32_16x16x32_bf16 v[44:47], v[182:185], v[226:229], v[44:47]
	v_mfma_f32_16x16x32_bf16 v[40:43], v[190:193], v[226:229], v[40:43]
	v_mfma_f32_16x16x32_bf16 v[28:31], v[182:185], v[234:237], v[28:31]
	v_mfma_f32_16x16x32_bf16 v[24:27], v[190:193], v[234:237], v[24:27]
	v_mfma_f32_16x16x32_bf16 v[16:19], v[182:185], v[242:245], v[16:19]
	v_mfma_f32_16x16x32_bf16 v[8:11], v[190:193], v[242:245], v[8:11]
	v_mfma_f32_16x16x32_bf16 v[52:55], v[198:201], v[214:217], v[52:55]
	v_mfma_f32_16x16x32_bf16 v[48:51], v[206:209], v[214:217], v[48:51]
	v_mfma_f32_16x16x32_bf16 v[36:39], v[198:201], v[222:225], v[36:39]
	v_mfma_f32_16x16x32_bf16 v[32:35], v[206:209], v[222:225], v[32:35]
	v_mfma_f32_16x16x32_bf16 v[20:23], v[198:201], v[230:233], v[20:23]
	v_mfma_f32_16x16x32_bf16 v[12:15], v[206:209], v[230:233], v[12:15]
	v_mfma_f32_16x16x32_bf16 v[4:7], v[198:201], v[238:241], v[4:7]
	v_mfma_f32_16x16x32_bf16 v[0:3], v[206:209], v[238:241], v[0:3]
	v_mfma_f32_16x16x32_bf16 v[52:55], v[202:205], v[218:221], v[52:55]
	v_mfma_f32_16x16x32_bf16 v[48:51], v[210:213], v[218:221], v[48:51]
	v_mfma_f32_16x16x32_bf16 v[36:39], v[202:205], v[226:229], v[36:39]
	v_mfma_f32_16x16x32_bf16 v[32:35], v[210:213], v[226:229], v[32:35]
	v_mfma_f32_16x16x32_bf16 v[20:23], v[202:205], v[234:237], v[20:23]
	v_mfma_f32_16x16x32_bf16 v[12:15], v[210:213], v[234:237], v[12:15]
	v_mfma_f32_16x16x32_bf16 v[4:7], v[202:205], v[242:245], v[4:7]
	v_mfma_f32_16x16x32_bf16 v[0:3], v[210:213], v[242:245], v[0:3]
	s_barrier
	ds_read_b128 v[178:181], v169
	ds_read_b128 v[182:185], v170
	ds_read_b128 v[186:189], v171
	ds_read_b128 v[190:193], v172
	ds_read_b128 v[198:201], v173
	ds_read_b128 v[202:205], v174
	ds_read_b128 v[206:209], v175
	ds_read_b128 v[210:213], v176
	s_add_u32 s10, s34, 0x80000
	s_addc_u32 s11, s35, 0
	s_mov_b32 m0, s73
	ds_read_b128 v[214:217], v152 offset:32768
	ds_read_b128 v[218:221], v152 offset:33792
	ds_read_b128 v[222:225], v152 offset:34816
	ds_read_b128 v[226:229], v152 offset:35840
	ds_read_b128 v[230:233], v152 offset:36864
	ds_read_b128 v[234:237], v152 offset:37888
	ds_read_b128 v[238:241], v152 offset:38912
	ds_read_b128 v[242:245], v152 offset:39936
	global_load_lds_dwordx4 v132, s[10:11]
	s_mov_b32 m0, s74
	s_nop 0
	global_load_lds_dwordx4 v134, s[10:11]
	s_waitcnt vmcnt(8)
	s_waitcnt lgkmcnt(0)
	s_barrier
	v_mfma_f32_16x16x32_bf16 v[124:127], v[178:181], v[214:217], v[124:127]
	v_mfma_f32_16x16x32_bf16 v[120:123], v[186:189], v[214:217], v[120:123]
	v_mfma_f32_16x16x32_bf16 v[108:111], v[178:181], v[222:225], v[108:111]
	v_mfma_f32_16x16x32_bf16 v[104:107], v[186:189], v[222:225], v[104:107]
	v_mfma_f32_16x16x32_bf16 v[92:95], v[178:181], v[230:233], v[92:95]
	v_mfma_f32_16x16x32_bf16 v[88:91], v[186:189], v[230:233], v[88:91]
	v_mfma_f32_16x16x32_bf16 v[76:79], v[178:181], v[238:241], v[76:79]
	v_mfma_f32_16x16x32_bf16 v[72:75], v[186:189], v[238:241], v[72:75]
	v_mfma_f32_16x16x32_bf16 v[124:127], v[182:185], v[218:221], v[124:127]
	v_mfma_f32_16x16x32_bf16 v[120:123], v[190:193], v[218:221], v[120:123]
	v_mfma_f32_16x16x32_bf16 v[108:111], v[182:185], v[226:229], v[108:111]
	v_mfma_f32_16x16x32_bf16 v[104:107], v[190:193], v[226:229], v[104:107]
	v_mfma_f32_16x16x32_bf16 v[92:95], v[182:185], v[234:237], v[92:95]
	v_mfma_f32_16x16x32_bf16 v[88:91], v[190:193], v[234:237], v[88:91]
	v_mfma_f32_16x16x32_bf16 v[76:79], v[182:185], v[242:245], v[76:79]
	v_mfma_f32_16x16x32_bf16 v[72:75], v[190:193], v[242:245], v[72:75]
	v_mfma_f32_16x16x32_bf16 v[116:119], v[198:201], v[214:217], v[116:119]
	v_mfma_f32_16x16x32_bf16 v[112:115], v[206:209], v[214:217], v[112:115]
	v_mfma_f32_16x16x32_bf16 v[100:103], v[198:201], v[222:225], v[100:103]
	v_mfma_f32_16x16x32_bf16 v[96:99], v[206:209], v[222:225], v[96:99]
	v_mfma_f32_16x16x32_bf16 v[84:87], v[198:201], v[230:233], v[84:87]
	v_mfma_f32_16x16x32_bf16 v[80:83], v[206:209], v[230:233], v[80:83]
	v_mfma_f32_16x16x32_bf16 v[68:71], v[198:201], v[238:241], v[68:71]
	v_mfma_f32_16x16x32_bf16 v[64:67], v[206:209], v[238:241], v[64:67]
	v_mfma_f32_16x16x32_bf16 v[116:119], v[202:205], v[218:221], v[116:119]
	v_mfma_f32_16x16x32_bf16 v[112:115], v[210:213], v[218:221], v[112:115]
	v_mfma_f32_16x16x32_bf16 v[100:103], v[202:205], v[226:229], v[100:103]
	v_mfma_f32_16x16x32_bf16 v[96:99], v[210:213], v[226:229], v[96:99]
	v_mfma_f32_16x16x32_bf16 v[84:87], v[202:205], v[234:237], v[84:87]
	v_mfma_f32_16x16x32_bf16 v[80:83], v[210:213], v[234:237], v[80:83]
	v_mfma_f32_16x16x32_bf16 v[68:71], v[202:205], v[242:245], v[68:71]
	v_mfma_f32_16x16x32_bf16 v[64:67], v[210:213], v[242:245], v[64:67]
	s_barrier
	s_mov_b32 m0, s75
	s_add_u32 s10, s30, 0x80080
	ds_read_b128 v[214:217], v152 offset:49152
	ds_read_b128 v[218:221], v152 offset:50176
	ds_read_b128 v[222:225], v152 offset:51200
	ds_read_b128 v[226:229], v152 offset:52224
	ds_read_b128 v[230:233], v152 offset:53248
	ds_read_b128 v[234:237], v152 offset:54272
	ds_read_b128 v[238:241], v152 offset:55296
	ds_read_b128 v[242:245], v152 offset:56320
	global_load_lds_dwordx4 v132, s[98:99]
	s_mov_b32 m0, s78
	s_addc_u32 s11, s31, 0
	global_load_lds_dwordx4 v134, s[98:99]
	s_mov_b32 m0, s83
	s_nop 0
	global_load_lds_dwordx4 v132, s[10:11]
	s_mov_b32 m0, s84
	s_nop 0
	global_load_lds_dwordx4 v134, s[10:11]
	s_mov_b32 m0, s79
	s_nop 0
	global_load_lds_dwordx4 v132, s[100:101]
	s_mov_b32 m0, s82
	s_nop 0
	global_load_lds_dwordx4 v134, s[100:101]
	s_waitcnt vmcnt(8)
	s_waitcnt lgkmcnt(0)
	s_barrier
	v_mfma_f32_16x16x32_bf16 v[60:63], v[178:181], v[214:217], v[60:63]
	v_mfma_f32_16x16x32_bf16 v[56:59], v[186:189], v[214:217], v[56:59]
	v_mfma_f32_16x16x32_bf16 v[44:47], v[178:181], v[222:225], v[44:47]
	v_mfma_f32_16x16x32_bf16 v[40:43], v[186:189], v[222:225], v[40:43]
	v_mfma_f32_16x16x32_bf16 v[28:31], v[178:181], v[230:233], v[28:31]
	v_mfma_f32_16x16x32_bf16 v[24:27], v[186:189], v[230:233], v[24:27]
	v_mfma_f32_16x16x32_bf16 v[16:19], v[178:181], v[238:241], v[16:19]
	v_mfma_f32_16x16x32_bf16 v[8:11], v[186:189], v[238:241], v[8:11]
	v_mfma_f32_16x16x32_bf16 v[60:63], v[182:185], v[218:221], v[60:63]
	v_mfma_f32_16x16x32_bf16 v[56:59], v[190:193], v[218:221], v[56:59]
	v_mfma_f32_16x16x32_bf16 v[44:47], v[182:185], v[226:229], v[44:47]
	v_mfma_f32_16x16x32_bf16 v[40:43], v[190:193], v[226:229], v[40:43]
	v_mfma_f32_16x16x32_bf16 v[28:31], v[182:185], v[234:237], v[28:31]
	v_mfma_f32_16x16x32_bf16 v[24:27], v[190:193], v[234:237], v[24:27]
	v_mfma_f32_16x16x32_bf16 v[16:19], v[182:185], v[242:245], v[16:19]
	v_mfma_f32_16x16x32_bf16 v[8:11], v[190:193], v[242:245], v[8:11]
	v_mfma_f32_16x16x32_bf16 v[52:55], v[198:201], v[214:217], v[52:55]
	v_mfma_f32_16x16x32_bf16 v[48:51], v[206:209], v[214:217], v[48:51]
	v_mfma_f32_16x16x32_bf16 v[36:39], v[198:201], v[222:225], v[36:39]
	v_mfma_f32_16x16x32_bf16 v[32:35], v[206:209], v[222:225], v[32:35]
	v_mfma_f32_16x16x32_bf16 v[20:23], v[198:201], v[230:233], v[20:23]
	v_mfma_f32_16x16x32_bf16 v[12:15], v[206:209], v[230:233], v[12:15]
	v_mfma_f32_16x16x32_bf16 v[4:7], v[198:201], v[238:241], v[4:7]
	v_mfma_f32_16x16x32_bf16 v[0:3], v[206:209], v[238:241], v[0:3]
	v_mfma_f32_16x16x32_bf16 v[52:55], v[202:205], v[218:221], v[52:55]
	v_mfma_f32_16x16x32_bf16 v[48:51], v[210:213], v[218:221], v[48:51]
	v_mfma_f32_16x16x32_bf16 v[36:39], v[202:205], v[226:229], v[36:39]
	v_mfma_f32_16x16x32_bf16 v[32:35], v[210:213], v[226:229], v[32:35]
	v_mfma_f32_16x16x32_bf16 v[20:23], v[202:205], v[234:237], v[20:23]
	v_mfma_f32_16x16x32_bf16 v[12:15], v[210:213], v[234:237], v[12:15]
	v_mfma_f32_16x16x32_bf16 v[4:7], v[202:205], v[242:245], v[4:7]
	v_mfma_f32_16x16x32_bf16 v[0:3], v[210:213], v[242:245], v[0:3]
	s_barrier
	s_add_i32 s56, s56, 2
	s_add_u32 vcc_lo, vcc_lo, 0x100
	s_addc_u32 vcc_hi, vcc_hi, 0
	s_cmp_gt_u32 s56, 29
	s_mov_b64 s[10:11], s[28:29]
	s_cbranch_scc0 .LBB0_856
	s_and_b64 vcc, exec, s[16:17]
	s_cbranch_vccz .LBB0_859
	s_barrier

.LBB0_1096:
	ds_read_b128 v[174:177], v143
	ds_read_b128 v[178:181], v153
	ds_read_b128 v[182:185], v159
	ds_read_b128 v[186:189], v160
	ds_read_b128 v[190:193], v161
	ds_read_b128 v[198:201], v162
	ds_read_b128 v[202:205], v163
	ds_read_b128 v[206:209], v164
	s_add_u32 s48, s24, 0xfffc0080
	s_addc_u32 s49, s25, -1
	s_cmp_eq_u32 s55, 12
	s_cselect_b32 s51, s4, s49
	s_cselect_b32 s50, s5, s48
	s_cselect_b32 s49, s15, s54
	s_cselect_b32 s48, s27, s39
	s_mov_b32 m0, s65
	ds_read_b128 v[210:213], v141
	ds_read_b128 v[214:217], v141 offset:1024
	ds_read_b128 v[218:221], v141 offset:2048
	ds_read_b128 v[222:225], v141 offset:3072
	ds_read_b128 v[226:229], v141 offset:4096
	ds_read_b128 v[230:233], v141 offset:5120
	ds_read_b128 v[234:237], v141 offset:6144
	ds_read_b128 v[238:241], v141 offset:7168
	global_load_lds_dwordx4 v132, s[24:25]
	s_mov_b32 m0, s67
	s_nop 0
	global_load_lds_dwordx4 v134, s[24:25]
	s_waitcnt vmcnt(8)
	s_waitcnt lgkmcnt(0)
	s_barrier
	v_mfma_f32_16x16x32_bf16 v[124:127], v[174:177], v[210:213], v[124:127]
	v_mfma_f32_16x16x32_bf16 v[120:123], v[182:185], v[210:213], v[120:123]
	v_mfma_f32_16x16x32_bf16 v[108:111], v[174:177], v[218:221], v[108:111]
	v_mfma_f32_16x16x32_bf16 v[104:107], v[182:185], v[218:221], v[104:107]
	v_mfma_f32_16x16x32_bf16 v[92:95], v[174:177], v[226:229], v[92:95]
	v_mfma_f32_16x16x32_bf16 v[88:91], v[182:185], v[226:229], v[88:91]
	v_mfma_f32_16x16x32_bf16 v[76:79], v[174:177], v[234:237], v[76:79]
	v_mfma_f32_16x16x32_bf16 v[72:75], v[182:185], v[234:237], v[72:75]
	v_mfma_f32_16x16x32_bf16 v[124:127], v[178:181], v[214:217], v[124:127]
	v_mfma_f32_16x16x32_bf16 v[120:123], v[186:189], v[214:217], v[120:123]
	v_mfma_f32_16x16x32_bf16 v[108:111], v[178:181], v[222:225], v[108:111]
	v_mfma_f32_16x16x32_bf16 v[104:107], v[186:189], v[222:225], v[104:107]
	v_mfma_f32_16x16x32_bf16 v[92:95], v[178:181], v[230:233], v[92:95]
	v_mfma_f32_16x16x32_bf16 v[88:91], v[186:189], v[230:233], v[88:91]
	v_mfma_f32_16x16x32_bf16 v[76:79], v[178:181], v[238:241], v[76:79]
	v_mfma_f32_16x16x32_bf16 v[72:75], v[186:189], v[238:241], v[72:75]
	v_mfma_f32_16x16x32_bf16 v[116:119], v[190:193], v[210:213], v[116:119]
	v_mfma_f32_16x16x32_bf16 v[112:115], v[202:205], v[210:213], v[112:115]
	v_mfma_f32_16x16x32_bf16 v[100:103], v[190:193], v[218:221], v[100:103]
	v_mfma_f32_16x16x32_bf16 v[96:99], v[202:205], v[218:221], v[96:99]
	v_mfma_f32_16x16x32_bf16 v[84:87], v[190:193], v[226:229], v[84:87]
	v_mfma_f32_16x16x32_bf16 v[80:83], v[202:205], v[226:229], v[80:83]
	v_mfma_f32_16x16x32_bf16 v[68:71], v[190:193], v[234:237], v[68:71]
	v_mfma_f32_16x16x32_bf16 v[64:67], v[202:205], v[234:237], v[64:67]
	v_mfma_f32_16x16x32_bf16 v[116:119], v[198:201], v[214:217], v[116:119]
	v_mfma_f32_16x16x32_bf16 v[112:115], v[206:209], v[214:217], v[112:115]
	v_mfma_f32_16x16x32_bf16 v[100:103], v[198:201], v[222:225], v[100:103]
	v_mfma_f32_16x16x32_bf16 v[96:99], v[206:209], v[222:225], v[96:99]
	v_mfma_f32_16x16x32_bf16 v[84:87], v[198:201], v[230:233], v[84:87]
	v_mfma_f32_16x16x32_bf16 v[80:83], v[206:209], v[230:233], v[80:83]
	v_mfma_f32_16x16x32_bf16 v[68:71], v[198:201], v[238:241], v[68:71]
	v_mfma_f32_16x16x32_bf16 v[64:67], v[206:209], v[238:241], v[64:67]
	s_barrier
	s_add_u32 s98, s48, s8
	s_addc_u32 s99, s49, s9
	s_add_u32 s100, s50, s8
	s_addc_u32 s101, s51, s9
	s_mov_b32 m0, s28
	s_add_u32 s68, s48, 0x40000
	ds_read_b128 v[210:213], v141 offset:16384
	ds_read_b128 v[214:217], v141 offset:17408
	ds_read_b128 v[218:221], v141 offset:18432
	ds_read_b128 v[222:225], v141 offset:19456
	ds_read_b128 v[226:229], v141 offset:20480
	ds_read_b128 v[230:233], v141 offset:21504
	ds_read_b128 v[234:237], v141 offset:22528
	ds_read_b128 v[238:241], v141 offset:23552
	global_load_lds_dwordx4 v130, s[48:49]
	s_mov_b32 m0, s29
	s_addc_u32 s69, s49, 0
	global_load_lds_dwordx4 v128, s[48:49]
	s_mov_b32 m0, s30
	s_nop 0
	global_load_lds_dwordx4 v130, s[68:69]
	s_mov_b32 m0, s31
	s_nop 0
	global_load_lds_dwordx4 v128, s[68:69]
	s_mov_b32 m0, s2
	s_nop 0
	global_load_lds_dwordx4 v130, s[50:51]
	s_mov_b32 m0, s33
	s_nop 0
	global_load_lds_dwordx4 v128, s[50:51]
	s_waitcnt vmcnt(8)
	s_waitcnt lgkmcnt(0)
	s_barrier
	v_mfma_f32_16x16x32_bf16 v[60:63], v[174:177], v[210:213], v[60:63]
	v_mfma_f32_16x16x32_bf16 v[56:59], v[182:185], v[210:213], v[56:59]
	v_mfma_f32_16x16x32_bf16 v[44:47], v[174:177], v[218:221], v[44:47]
	v_mfma_f32_16x16x32_bf16 v[40:43], v[182:185], v[218:221], v[40:43]
	v_mfma_f32_16x16x32_bf16 v[28:31], v[174:177], v[226:229], v[28:31]
	v_mfma_f32_16x16x32_bf16 v[24:27], v[182:185], v[226:229], v[24:27]
	v_mfma_f32_16x16x32_bf16 v[12:15], v[174:177], v[234:237], v[12:15]
	v_mfma_f32_16x16x32_bf16 v[8:11], v[182:185], v[234:237], v[8:11]
	v_mfma_f32_16x16x32_bf16 v[60:63], v[178:181], v[214:217], v[60:63]
	v_mfma_f32_16x16x32_bf16 v[56:59], v[186:189], v[214:217], v[56:59]
	v_mfma_f32_16x16x32_bf16 v[44:47], v[178:181], v[222:225], v[44:47]
	v_mfma_f32_16x16x32_bf16 v[40:43], v[186:189], v[222:225], v[40:43]
	v_mfma_f32_16x16x32_bf16 v[28:31], v[178:181], v[230:233], v[28:31]
	v_mfma_f32_16x16x32_bf16 v[24:27], v[186:189], v[230:233], v[24:27]
	v_mfma_f32_16x16x32_bf16 v[12:15], v[178:181], v[238:241], v[12:15]
	v_mfma_f32_16x16x32_bf16 v[8:11], v[186:189], v[238:241], v[8:11]
	v_mfma_f32_16x16x32_bf16 v[52:55], v[190:193], v[210:213], v[52:55]
	v_mfma_f32_16x16x32_bf16 v[48:51], v[202:205], v[210:213], v[48:51]
	v_mfma_f32_16x16x32_bf16 v[36:39], v[190:193], v[218:221], v[36:39]
	v_mfma_f32_16x16x32_bf16 v[32:35], v[202:205], v[218:221], v[32:35]
	v_mfma_f32_16x16x32_bf16 v[20:23], v[190:193], v[226:229], v[20:23]
	v_mfma_f32_16x16x32_bf16 v[16:19], v[202:205], v[226:229], v[16:19]
	v_mfma_f32_16x16x32_bf16 v[4:7], v[190:193], v[234:237], v[4:7]
	v_mfma_f32_16x16x32_bf16 v[0:3], v[202:205], v[234:237], v[0:3]
	v_mfma_f32_16x16x32_bf16 v[52:55], v[198:201], v[214:217], v[52:55]
	v_mfma_f32_16x16x32_bf16 v[48:51], v[206:209], v[214:217], v[48:51]
	v_mfma_f32_16x16x32_bf16 v[36:39], v[198:201], v[222:225], v[36:39]
	v_mfma_f32_16x16x32_bf16 v[32:35], v[206:209], v[222:225], v[32:35]
	v_mfma_f32_16x16x32_bf16 v[20:23], v[198:201], v[230:233], v[20:23]
	v_mfma_f32_16x16x32_bf16 v[16:19], v[206:209], v[230:233], v[16:19]
	v_mfma_f32_16x16x32_bf16 v[4:7], v[198:201], v[238:241], v[4:7]
	v_mfma_f32_16x16x32_bf16 v[0:3], v[206:209], v[238:241], v[0:3]
	s_barrier
	ds_read_b128 v[174:177], v165
	ds_read_b128 v[178:181], v166
	ds_read_b128 v[182:185], v167
	ds_read_b128 v[186:189], v168
	ds_read_b128 v[190:193], v169
	ds_read_b128 v[198:201], v170
	ds_read_b128 v[202:205], v171
	ds_read_b128 v[206:209], v172
	s_add_u32 s50, s50, 0x40000
	s_addc_u32 s51, s51, 0
	s_mov_b32 m0, s34
	ds_read_b128 v[210:213], v141 offset:32768
	ds_read_b128 v[214:217], v141 offset:33792
	ds_read_b128 v[218:221], v141 offset:34816
	ds_read_b128 v[222:225], v141 offset:35840
	ds_read_b128 v[226:229], v141 offset:36864
	ds_read_b128 v[230:233], v141 offset:37888
	ds_read_b128 v[234:237], v141 offset:38912
	ds_read_b128 v[238:241], v141 offset:39936
	global_load_lds_dwordx4 v130, s[50:51]
	s_mov_b32 m0, s35
	s_nop 0
	global_load_lds_dwordx4 v128, s[50:51]
	s_waitcnt vmcnt(8)
	s_waitcnt lgkmcnt(0)
	s_barrier
	v_mfma_f32_16x16x32_bf16 v[124:127], v[174:177], v[210:213], v[124:127]
	v_mfma_f32_16x16x32_bf16 v[120:123], v[182:185], v[210:213], v[120:123]
	v_mfma_f32_16x16x32_bf16 v[108:111], v[174:177], v[218:221], v[108:111]
	v_mfma_f32_16x16x32_bf16 v[104:107], v[182:185], v[218:221], v[104:107]
	v_mfma_f32_16x16x32_bf16 v[92:95], v[174:177], v[226:229], v[92:95]
	v_mfma_f32_16x16x32_bf16 v[88:91], v[182:185], v[226:229], v[88:91]
	v_mfma_f32_16x16x32_bf16 v[76:79], v[174:177], v[234:237], v[76:79]
	v_mfma_f32_16x16x32_bf16 v[72:75], v[182:185], v[234:237], v[72:75]
	v_mfma_f32_16x16x32_bf16 v[124:127], v[178:181], v[214:217], v[124:127]
	v_mfma_f32_16x16x32_bf16 v[120:123], v[186:189], v[214:217], v[120:123]
	v_mfma_f32_16x16x32_bf16 v[108:111], v[178:181], v[222:225], v[108:111]
	v_mfma_f32_16x16x32_bf16 v[104:107], v[186:189], v[222:225], v[104:107]
	v_mfma_f32_16x16x32_bf16 v[92:95], v[178:181], v[230:233], v[92:95]
	v_mfma_f32_16x16x32_bf16 v[88:91], v[186:189], v[230:233], v[88:91]
	v_mfma_f32_16x16x32_bf16 v[76:79], v[178:181], v[238:241], v[76:79]
	v_mfma_f32_16x16x32_bf16 v[72:75], v[186:189], v[238:241], v[72:75]
	v_mfma_f32_16x16x32_bf16 v[116:119], v[190:193], v[210:213], v[116:119]
	v_mfma_f32_16x16x32_bf16 v[112:115], v[202:205], v[210:213], v[112:115]
	v_mfma_f32_16x16x32_bf16 v[100:103], v[190:193], v[218:221], v[100:103]
	v_mfma_f32_16x16x32_bf16 v[96:99], v[202:205], v[218:221], v[96:99]
	v_mfma_f32_16x16x32_bf16 v[84:87], v[190:193], v[226:229], v[84:87]
	v_mfma_f32_16x16x32_bf16 v[80:83], v[202:205], v[226:229], v[80:83]
	v_mfma_f32_16x16x32_bf16 v[68:71], v[190:193], v[234:237], v[68:71]
	v_mfma_f32_16x16x32_bf16 v[64:67], v[202:205], v[234:237], v[64:67]
	v_mfma_f32_16x16x32_bf16 v[116:119], v[198:201], v[214:217], v[116:119]
	v_mfma_f32_16x16x32_bf16 v[112:115], v[206:209], v[214:217], v[112:115]
	v_mfma_f32_16x16x32_bf16 v[100:103], v[198:201], v[222:225], v[100:103]
	v_mfma_f32_16x16x32_bf16 v[96:99], v[206:209], v[222:225], v[96:99]
	v_mfma_f32_16x16x32_bf16 v[84:87], v[198:201], v[230:233], v[84:87]
	v_mfma_f32_16x16x32_bf16 v[80:83], v[206:209], v[230:233], v[80:83]
	v_mfma_f32_16x16x32_bf16 v[68:71], v[198:201], v[238:241], v[68:71]
	v_mfma_f32_16x16x32_bf16 v[64:67], v[206:209], v[238:241], v[64:67]
	s_barrier
	s_mov_b32 m0, s40
	s_add_u32 s48, s48, 0x40080
	ds_read_b128 v[210:213], v141 offset:49152
	ds_read_b128 v[214:217], v141 offset:50176
	ds_read_b128 v[218:221], v141 offset:51200
	ds_read_b128 v[222:225], v141 offset:52224
	ds_read_b128 v[226:229], v141 offset:53248
	ds_read_b128 v[230:233], v141 offset:54272
	ds_read_b128 v[234:237], v141 offset:55296
	ds_read_b128 v[238:241], v141 offset:56320
	global_load_lds_dwordx4 v130, s[98:99]
	s_mov_b32 m0, s41
	s_addc_u32 s49, s49, 0
	global_load_lds_dwordx4 v128, s[98:99]
	s_mov_b32 m0, s53
	s_nop 0
	global_load_lds_dwordx4 v130, s[48:49]
	s_mov_b32 m0, s60
	s_nop 0
	global_load_lds_dwordx4 v128, s[48:49]
	s_mov_b32 m0, s47
	s_nop 0
	global_load_lds_dwordx4 v130, s[100:101]
	s_mov_b32 m0, s52
	s_nop 0
	global_load_lds_dwordx4 v128, s[100:101]
	s_waitcnt vmcnt(8)
	s_waitcnt lgkmcnt(0)
	s_barrier
	v_mfma_f32_16x16x32_bf16 v[60:63], v[174:177], v[210:213], v[60:63]
	v_mfma_f32_16x16x32_bf16 v[56:59], v[182:185], v[210:213], v[56:59]
	v_mfma_f32_16x16x32_bf16 v[44:47], v[174:177], v[218:221], v[44:47]
	v_mfma_f32_16x16x32_bf16 v[40:43], v[182:185], v[218:221], v[40:43]
	v_mfma_f32_16x16x32_bf16 v[28:31], v[174:177], v[226:229], v[28:31]
	v_mfma_f32_16x16x32_bf16 v[24:27], v[182:185], v[226:229], v[24:27]
	v_mfma_f32_16x16x32_bf16 v[12:15], v[174:177], v[234:237], v[12:15]
	v_mfma_f32_16x16x32_bf16 v[8:11], v[182:185], v[234:237], v[8:11]
	v_mfma_f32_16x16x32_bf16 v[60:63], v[178:181], v[214:217], v[60:63]
	v_mfma_f32_16x16x32_bf16 v[56:59], v[186:189], v[214:217], v[56:59]
	v_mfma_f32_16x16x32_bf16 v[44:47], v[178:181], v[222:225], v[44:47]
	v_mfma_f32_16x16x32_bf16 v[40:43], v[186:189], v[222:225], v[40:43]
	v_mfma_f32_16x16x32_bf16 v[28:31], v[178:181], v[230:233], v[28:31]
	v_mfma_f32_16x16x32_bf16 v[24:27], v[186:189], v[230:233], v[24:27]
	v_mfma_f32_16x16x32_bf16 v[12:15], v[178:181], v[238:241], v[12:15]
	v_mfma_f32_16x16x32_bf16 v[8:11], v[186:189], v[238:241], v[8:11]
	v_mfma_f32_16x16x32_bf16 v[52:55], v[190:193], v[210:213], v[52:55]
	v_mfma_f32_16x16x32_bf16 v[48:51], v[202:205], v[210:213], v[48:51]
	v_mfma_f32_16x16x32_bf16 v[36:39], v[190:193], v[218:221], v[36:39]
	v_mfma_f32_16x16x32_bf16 v[32:35], v[202:205], v[218:221], v[32:35]
	v_mfma_f32_16x16x32_bf16 v[20:23], v[190:193], v[226:229], v[20:23]
	v_mfma_f32_16x16x32_bf16 v[16:19], v[202:205], v[226:229], v[16:19]
	v_mfma_f32_16x16x32_bf16 v[4:7], v[190:193], v[234:237], v[4:7]
	v_mfma_f32_16x16x32_bf16 v[0:3], v[202:205], v[234:237], v[0:3]
	v_mfma_f32_16x16x32_bf16 v[52:55], v[198:201], v[214:217], v[52:55]
	v_mfma_f32_16x16x32_bf16 v[48:51], v[206:209], v[214:217], v[48:51]
	v_mfma_f32_16x16x32_bf16 v[36:39], v[198:201], v[222:225], v[36:39]
	v_mfma_f32_16x16x32_bf16 v[32:35], v[206:209], v[222:225], v[32:35]
	v_mfma_f32_16x16x32_bf16 v[20:23], v[198:201], v[230:233], v[20:23]
	v_mfma_f32_16x16x32_bf16 v[16:19], v[206:209], v[230:233], v[16:19]
	v_mfma_f32_16x16x32_bf16 v[4:7], v[198:201], v[238:241], v[4:7]
	v_mfma_f32_16x16x32_bf16 v[0:3], v[206:209], v[238:241], v[0:3]
	s_barrier
	s_add_i32 s55, s55, 2
	s_add_u32 s24, s24, 0x100
	s_addc_u32 s25, s25, 0
	s_add_u32 s39, s39, 0x100
	s_addc_u32 s54, s54, 0
	s_cmp_gt_u32 s55, 13
	s_cbranch_scc0 .LBB0_1096
	s_and_b64 vcc, exec, s[12:13]
	s_cbranch_vccz .LBB0_1099
	s_barrier

.LBB0_1176:
	ds_read_b128 v[128:131], v183
	ds_read_b128 v[132:135], v184
	ds_read_b128 v[136:139], v185
	ds_read_b128 v[168:171], v186
	ds_read_b128 v[172:175], v187
	ds_read_b128 v[176:179], v188
	ds_read_b128 v[204:207], v189
	ds_read_b128 v[208:211], v190
	s_add_u32 s46, s24, 0x100
	s_addc_u32 s47, s25, 0
	s_cmp_eq_u32 s66, 40
	s_cselect_b32 s51, s13, s47
	s_cselect_b32 s50, s12, s46
	s_cselect_b32 s49, s45, s5
	s_cselect_b32 s48, s44, s4
	s_mov_b32 m0, s60
	ds_read_b128 v[212:215], v159
	ds_read_b128 v[216:219], v159 offset:1024
	ds_read_b128 v[220:223], v159 offset:2048
	ds_read_b128 v[224:227], v159 offset:3072
	ds_read_b128 v[228:231], v159 offset:4096
	ds_read_b128 v[232:235], v159 offset:5120
	ds_read_b128 v[236:239], v159 offset:6144
	ds_read_b128 v[240:243], v159 offset:7168
	global_load_lds_dwordx4 v160, s[24:25]
	s_mov_b32 m0, s61
	s_nop 0
	global_load_lds_dwordx4 v162, s[24:25]
	s_waitcnt vmcnt(8)
	s_waitcnt lgkmcnt(0)
	s_barrier
	v_mfma_f32_16x16x32_bf16 v[124:127], v[128:131], v[212:215], v[124:127]
	v_mfma_f32_16x16x32_bf16 v[120:123], v[136:139], v[212:215], v[120:123]
	v_mfma_f32_16x16x32_bf16 v[108:111], v[128:131], v[220:223], v[108:111]
	v_mfma_f32_16x16x32_bf16 v[104:107], v[136:139], v[220:223], v[104:107]
	v_mfma_f32_16x16x32_bf16 v[92:95], v[128:131], v[228:231], v[92:95]
	v_mfma_f32_16x16x32_bf16 v[88:91], v[136:139], v[228:231], v[88:91]
	v_mfma_f32_16x16x32_bf16 v[76:79], v[128:131], v[236:239], v[76:79]
	v_mfma_f32_16x16x32_bf16 v[72:75], v[136:139], v[236:239], v[72:75]
	v_mfma_f32_16x16x32_bf16 v[124:127], v[132:135], v[216:219], v[124:127]
	v_mfma_f32_16x16x32_bf16 v[120:123], v[168:171], v[216:219], v[120:123]
	v_mfma_f32_16x16x32_bf16 v[108:111], v[132:135], v[224:227], v[108:111]
	v_mfma_f32_16x16x32_bf16 v[104:107], v[168:171], v[224:227], v[104:107]
	v_mfma_f32_16x16x32_bf16 v[92:95], v[132:135], v[232:235], v[92:95]
	v_mfma_f32_16x16x32_bf16 v[88:91], v[168:171], v[232:235], v[88:91]
	v_mfma_f32_16x16x32_bf16 v[76:79], v[132:135], v[240:243], v[76:79]
	v_mfma_f32_16x16x32_bf16 v[72:75], v[168:171], v[240:243], v[72:75]
	v_mfma_f32_16x16x32_bf16 v[116:119], v[172:175], v[212:215], v[116:119]
	v_mfma_f32_16x16x32_bf16 v[112:115], v[204:207], v[212:215], v[112:115]
	v_mfma_f32_16x16x32_bf16 v[100:103], v[172:175], v[220:223], v[100:103]
	v_mfma_f32_16x16x32_bf16 v[96:99], v[204:207], v[220:223], v[96:99]
	v_mfma_f32_16x16x32_bf16 v[84:87], v[172:175], v[228:231], v[84:87]
	v_mfma_f32_16x16x32_bf16 v[80:83], v[204:207], v[228:231], v[80:83]
	v_mfma_f32_16x16x32_bf16 v[68:71], v[172:175], v[236:239], v[68:71]
	v_mfma_f32_16x16x32_bf16 v[64:67], v[204:207], v[236:239], v[64:67]
	v_mfma_f32_16x16x32_bf16 v[116:119], v[176:179], v[216:219], v[116:119]
	v_mfma_f32_16x16x32_bf16 v[112:115], v[208:211], v[216:219], v[112:115]
	v_mfma_f32_16x16x32_bf16 v[100:103], v[176:179], v[224:227], v[100:103]
	v_mfma_f32_16x16x32_bf16 v[96:99], v[208:211], v[224:227], v[96:99]
	v_mfma_f32_16x16x32_bf16 v[84:87], v[176:179], v[232:235], v[84:87]
	v_mfma_f32_16x16x32_bf16 v[80:83], v[208:211], v[232:235], v[80:83]
	v_mfma_f32_16x16x32_bf16 v[68:71], v[176:179], v[240:243], v[68:71]
	v_mfma_f32_16x16x32_bf16 v[64:67], v[208:211], v[240:243], v[64:67]
	s_barrier
	s_add_u32 s98, s48, s14
	s_addc_u32 s99, s49, s15
	s_add_u32 s100, s50, s14
	s_addc_u32 s101, s51, s15
	s_mov_b32 m0, s7
	s_add_u32 s24, s48, 0xb0000
	ds_read_b128 v[212:215], v159 offset:16384
	ds_read_b128 v[216:219], v159 offset:17408
	ds_read_b128 v[220:223], v159 offset:18432
	ds_read_b128 v[224:227], v159 offset:19456
	ds_read_b128 v[228:231], v159 offset:20480
	ds_read_b128 v[232:235], v159 offset:21504
	ds_read_b128 v[236:239], v159 offset:22528
	ds_read_b128 v[240:243], v159 offset:23552
	global_load_lds_dwordx4 v140, s[48:49]
	s_mov_b32 m0, s28
	s_addc_u32 s25, s49, 0
	global_load_lds_dwordx4 v142, s[48:49]
	s_mov_b32 m0, s29
	s_nop 0
	global_load_lds_dwordx4 v140, s[24:25]
	s_mov_b32 m0, s30
	s_nop 0
	global_load_lds_dwordx4 v142, s[24:25]
	s_mov_b32 m0, s6
	s_nop 0
	global_load_lds_dwordx4 v140, s[50:51]
	s_mov_b32 m0, s31
	s_nop 0
	global_load_lds_dwordx4 v142, s[50:51]
	s_waitcnt vmcnt(8)
	s_waitcnt lgkmcnt(0)
	s_barrier
	v_mfma_f32_16x16x32_bf16 v[60:63], v[128:131], v[212:215], v[60:63]
	v_mfma_f32_16x16x32_bf16 v[56:59], v[136:139], v[212:215], v[56:59]
	v_mfma_f32_16x16x32_bf16 v[44:47], v[128:131], v[220:223], v[44:47]
	v_mfma_f32_16x16x32_bf16 v[40:43], v[136:139], v[220:223], v[40:43]
	v_mfma_f32_16x16x32_bf16 v[28:31], v[128:131], v[228:231], v[28:31]
	v_mfma_f32_16x16x32_bf16 v[24:27], v[136:139], v[228:231], v[24:27]
	v_mfma_f32_16x16x32_bf16 v[12:15], v[128:131], v[236:239], v[12:15]
	v_mfma_f32_16x16x32_bf16 v[8:11], v[136:139], v[236:239], v[8:11]
	v_mfma_f32_16x16x32_bf16 v[60:63], v[132:135], v[216:219], v[60:63]
	v_mfma_f32_16x16x32_bf16 v[56:59], v[168:171], v[216:219], v[56:59]
	v_mfma_f32_16x16x32_bf16 v[44:47], v[132:135], v[224:227], v[44:47]
	v_mfma_f32_16x16x32_bf16 v[40:43], v[168:171], v[224:227], v[40:43]
	v_mfma_f32_16x16x32_bf16 v[28:31], v[132:135], v[232:235], v[28:31]
	v_mfma_f32_16x16x32_bf16 v[24:27], v[168:171], v[232:235], v[24:27]
	v_mfma_f32_16x16x32_bf16 v[12:15], v[132:135], v[240:243], v[12:15]
	v_mfma_f32_16x16x32_bf16 v[8:11], v[168:171], v[240:243], v[8:11]
	v_mfma_f32_16x16x32_bf16 v[52:55], v[172:175], v[212:215], v[52:55]
	v_mfma_f32_16x16x32_bf16 v[48:51], v[204:207], v[212:215], v[48:51]
	v_mfma_f32_16x16x32_bf16 v[36:39], v[172:175], v[220:223], v[36:39]
	v_mfma_f32_16x16x32_bf16 v[32:35], v[204:207], v[220:223], v[32:35]
	v_mfma_f32_16x16x32_bf16 v[20:23], v[172:175], v[228:231], v[20:23]
	v_mfma_f32_16x16x32_bf16 v[16:19], v[204:207], v[228:231], v[16:19]
	v_mfma_f32_16x16x32_bf16 v[4:7], v[172:175], v[236:239], v[4:7]
	v_mfma_f32_16x16x32_bf16 v[0:3], v[204:207], v[236:239], v[0:3]
	v_mfma_f32_16x16x32_bf16 v[52:55], v[176:179], v[216:219], v[52:55]
	v_mfma_f32_16x16x32_bf16 v[48:51], v[208:211], v[216:219], v[48:51]
	v_mfma_f32_16x16x32_bf16 v[36:39], v[176:179], v[224:227], v[36:39]
	v_mfma_f32_16x16x32_bf16 v[32:35], v[208:211], v[224:227], v[32:35]
	v_mfma_f32_16x16x32_bf16 v[20:23], v[176:179], v[232:235], v[20:23]
	v_mfma_f32_16x16x32_bf16 v[16:19], v[208:211], v[232:235], v[16:19]
	v_mfma_f32_16x16x32_bf16 v[4:7], v[176:179], v[240:243], v[4:7]
	v_mfma_f32_16x16x32_bf16 v[0:3], v[208:211], v[240:243], v[0:3]
	s_barrier
	ds_read_b128 v[128:131], v191
	ds_read_b128 v[132:135], v192
	ds_read_b128 v[136:139], v193
	ds_read_b128 v[168:171], v197
	ds_read_b128 v[172:175], v198
	ds_read_b128 v[176:179], v199
	ds_read_b128 v[204:207], v200
	ds_read_b128 v[208:211], v201
	s_add_u32 s24, s50, 0xb0000
	s_addc_u32 s25, s51, 0
	s_mov_b32 m0, s33
	ds_read_b128 v[212:215], v159 offset:32768
	ds_read_b128 v[216:219], v159 offset:33792
	ds_read_b128 v[220:223], v159 offset:34816
	ds_read_b128 v[224:227], v159 offset:35840
	ds_read_b128 v[228:231], v159 offset:36864
	ds_read_b128 v[232:235], v159 offset:37888
	ds_read_b128 v[236:239], v159 offset:38912
	ds_read_b128 v[240:243], v159 offset:39936
	global_load_lds_dwordx4 v140, s[24:25]
	s_mov_b32 m0, s34
	s_nop 0
	global_load_lds_dwordx4 v142, s[24:25]
	s_waitcnt vmcnt(8)
	s_waitcnt lgkmcnt(0)
	s_barrier
	v_mfma_f32_16x16x32_bf16 v[124:127], v[128:131], v[212:215], v[124:127]
	v_mfma_f32_16x16x32_bf16 v[120:123], v[136:139], v[212:215], v[120:123]
	v_mfma_f32_16x16x32_bf16 v[108:111], v[128:131], v[220:223], v[108:111]
	v_mfma_f32_16x16x32_bf16 v[104:107], v[136:139], v[220:223], v[104:107]
	v_mfma_f32_16x16x32_bf16 v[92:95], v[128:131], v[228:231], v[92:95]
	v_mfma_f32_16x16x32_bf16 v[88:91], v[136:139], v[228:231], v[88:91]
	v_mfma_f32_16x16x32_bf16 v[76:79], v[128:131], v[236:239], v[76:79]
	v_mfma_f32_16x16x32_bf16 v[72:75], v[136:139], v[236:239], v[72:75]
	v_mfma_f32_16x16x32_bf16 v[124:127], v[132:135], v[216:219], v[124:127]
	v_mfma_f32_16x16x32_bf16 v[120:123], v[168:171], v[216:219], v[120:123]
	v_mfma_f32_16x16x32_bf16 v[108:111], v[132:135], v[224:227], v[108:111]
	v_mfma_f32_16x16x32_bf16 v[104:107], v[168:171], v[224:227], v[104:107]
	v_mfma_f32_16x16x32_bf16 v[92:95], v[132:135], v[232:235], v[92:95]
	v_mfma_f32_16x16x32_bf16 v[88:91], v[168:171], v[232:235], v[88:91]
	v_mfma_f32_16x16x32_bf16 v[76:79], v[132:135], v[240:243], v[76:79]
	v_mfma_f32_16x16x32_bf16 v[72:75], v[168:171], v[240:243], v[72:75]
	v_mfma_f32_16x16x32_bf16 v[116:119], v[172:175], v[212:215], v[116:119]
	v_mfma_f32_16x16x32_bf16 v[112:115], v[204:207], v[212:215], v[112:115]
	v_mfma_f32_16x16x32_bf16 v[100:103], v[172:175], v[220:223], v[100:103]
	v_mfma_f32_16x16x32_bf16 v[96:99], v[204:207], v[220:223], v[96:99]
	v_mfma_f32_16x16x32_bf16 v[84:87], v[172:175], v[228:231], v[84:87]
	v_mfma_f32_16x16x32_bf16 v[80:83], v[204:207], v[228:231], v[80:83]
	v_mfma_f32_16x16x32_bf16 v[68:71], v[172:175], v[236:239], v[68:71]
	v_mfma_f32_16x16x32_bf16 v[64:67], v[204:207], v[236:239], v[64:67]
	v_mfma_f32_16x16x32_bf16 v[116:119], v[176:179], v[216:219], v[116:119]
	v_mfma_f32_16x16x32_bf16 v[112:115], v[208:211], v[216:219], v[112:115]
	v_mfma_f32_16x16x32_bf16 v[100:103], v[176:179], v[224:227], v[100:103]
	v_mfma_f32_16x16x32_bf16 v[96:99], v[208:211], v[224:227], v[96:99]
	v_mfma_f32_16x16x32_bf16 v[84:87], v[176:179], v[232:235], v[84:87]
	v_mfma_f32_16x16x32_bf16 v[80:83], v[208:211], v[232:235], v[80:83]
	v_mfma_f32_16x16x32_bf16 v[68:71], v[176:179], v[240:243], v[68:71]
	v_mfma_f32_16x16x32_bf16 v[64:67], v[208:211], v[240:243], v[64:67]
	s_barrier
	s_mov_b32 m0, s35
	s_add_u32 s24, s48, 0xb0080
	ds_read_b128 v[212:215], v159 offset:49152
	ds_read_b128 v[216:219], v159 offset:50176
	ds_read_b128 v[220:223], v159 offset:51200
	ds_read_b128 v[224:227], v159 offset:52224
	ds_read_b128 v[228:231], v159 offset:53248
	ds_read_b128 v[232:235], v159 offset:54272
	ds_read_b128 v[236:239], v159 offset:55296
	ds_read_b128 v[240:243], v159 offset:56320
	global_load_lds_dwordx4 v140, s[98:99]
	s_mov_b32 m0, s36
	s_addc_u32 s25, s49, 0
	global_load_lds_dwordx4 v142, s[98:99]
	s_mov_b32 m0, s41
	s_nop 0
	global_load_lds_dwordx4 v140, s[24:25]
	s_mov_b32 m0, s43
	s_nop 0
	global_load_lds_dwordx4 v142, s[24:25]
	s_mov_b32 m0, s37
	s_nop 0
	global_load_lds_dwordx4 v140, s[100:101]
	s_mov_b32 m0, s40
	s_nop 0
	global_load_lds_dwordx4 v142, s[100:101]
	s_waitcnt vmcnt(8)
	s_waitcnt lgkmcnt(0)
	s_barrier
	v_mfma_f32_16x16x32_bf16 v[60:63], v[128:131], v[212:215], v[60:63]
	v_mfma_f32_16x16x32_bf16 v[56:59], v[136:139], v[212:215], v[56:59]
	v_mfma_f32_16x16x32_bf16 v[44:47], v[128:131], v[220:223], v[44:47]
	v_mfma_f32_16x16x32_bf16 v[40:43], v[136:139], v[220:223], v[40:43]
	v_mfma_f32_16x16x32_bf16 v[28:31], v[128:131], v[228:231], v[28:31]
	v_mfma_f32_16x16x32_bf16 v[24:27], v[136:139], v[228:231], v[24:27]
	v_mfma_f32_16x16x32_bf16 v[12:15], v[128:131], v[236:239], v[12:15]
	v_mfma_f32_16x16x32_bf16 v[8:11], v[136:139], v[236:239], v[8:11]
	v_mfma_f32_16x16x32_bf16 v[60:63], v[132:135], v[216:219], v[60:63]
	v_mfma_f32_16x16x32_bf16 v[56:59], v[168:171], v[216:219], v[56:59]
	v_mfma_f32_16x16x32_bf16 v[44:47], v[132:135], v[224:227], v[44:47]
	v_mfma_f32_16x16x32_bf16 v[40:43], v[168:171], v[224:227], v[40:43]
	v_mfma_f32_16x16x32_bf16 v[28:31], v[132:135], v[232:235], v[28:31]
	v_mfma_f32_16x16x32_bf16 v[24:27], v[168:171], v[232:235], v[24:27]
	v_mfma_f32_16x16x32_bf16 v[12:15], v[132:135], v[240:243], v[12:15]
	v_mfma_f32_16x16x32_bf16 v[8:11], v[168:171], v[240:243], v[8:11]
	v_mfma_f32_16x16x32_bf16 v[52:55], v[172:175], v[212:215], v[52:55]
	v_mfma_f32_16x16x32_bf16 v[48:51], v[204:207], v[212:215], v[48:51]
	v_mfma_f32_16x16x32_bf16 v[36:39], v[172:175], v[220:223], v[36:39]
	v_mfma_f32_16x16x32_bf16 v[32:35], v[204:207], v[220:223], v[32:35]
	v_mfma_f32_16x16x32_bf16 v[20:23], v[172:175], v[228:231], v[20:23]
	v_mfma_f32_16x16x32_bf16 v[16:19], v[204:207], v[228:231], v[16:19]
	v_mfma_f32_16x16x32_bf16 v[4:7], v[172:175], v[236:239], v[4:7]
	v_mfma_f32_16x16x32_bf16 v[0:3], v[204:207], v[236:239], v[0:3]
	v_mfma_f32_16x16x32_bf16 v[52:55], v[176:179], v[216:219], v[52:55]
	v_mfma_f32_16x16x32_bf16 v[48:51], v[208:211], v[216:219], v[48:51]
	v_mfma_f32_16x16x32_bf16 v[36:39], v[176:179], v[224:227], v[36:39]
	v_mfma_f32_16x16x32_bf16 v[32:35], v[208:211], v[224:227], v[32:35]
	v_mfma_f32_16x16x32_bf16 v[20:23], v[176:179], v[232:235], v[20:23]
	v_mfma_f32_16x16x32_bf16 v[16:19], v[208:211], v[232:235], v[16:19]
	v_mfma_f32_16x16x32_bf16 v[4:7], v[176:179], v[240:243], v[4:7]
	v_mfma_f32_16x16x32_bf16 v[0:3], v[208:211], v[240:243], v[0:3]
	s_barrier
	s_add_i32 s66, s66, 2
	s_add_u32 s4, s4, 0x100
	s_addc_u32 s5, s5, 0
	s_cmp_gt_u32 s66, 41
	s_mov_b64 s[24:25], s[46:47]
	s_cbranch_scc0 .LBB0_1176
	s_mov_b64 s[88:89], s[78:79]
	s_and_b64 vcc, exec, s[26:27]
	s_cbranch_vccz .LBB0_1179
	s_barrier

.LBB0_1334:
	ds_read_b128 v[160:163], v167
	ds_read_b128 v[184:187], v168
	ds_read_b128 v[188:191], v169
	ds_read_b128 v[198:201], v170
	ds_read_b128 v[202:205], v171
	ds_read_b128 v[206:209], v172
	ds_read_b128 v[210:213], v173
	ds_read_b128 v[214:217], v174
	s_add_u32 s24, s14, 0xfffc0080
	s_addc_u32 s25, s15, -1
	s_cmp_eq_u32 s66, 12
	s_cselect_b32 s65, s4, s25
	s_cselect_b32 s64, s5, s24
	s_cselect_b32 s25, s11, s49
	s_cselect_b32 s24, s13, s47
	s_mov_b32 m0, s61
	ds_read_b128 v[218:221], v159
	ds_read_b128 v[222:225], v159 offset:1024
	ds_read_b128 v[226:229], v159 offset:2048
	ds_read_b128 v[230:233], v159 offset:3072
	ds_read_b128 v[234:237], v159 offset:4096
	ds_read_b128 v[238:241], v159 offset:5120
	ds_read_b128 v[242:245], v159 offset:6144
	ds_read_b128 v[246:249], v159 offset:7168
	global_load_lds_dwordx4 v134, s[14:15]
	s_mov_b32 m0, s67
	s_nop 0
	global_load_lds_dwordx4 v136, s[14:15]
	s_waitcnt vmcnt(8)
	s_waitcnt lgkmcnt(0)
	s_barrier
	v_mfma_f32_16x16x32_bf16 v[124:127], v[160:163], v[218:221], v[124:127]
	v_mfma_f32_16x16x32_bf16 v[120:123], v[188:191], v[218:221], v[120:123]
	v_mfma_f32_16x16x32_bf16 v[108:111], v[160:163], v[226:229], v[108:111]
	v_mfma_f32_16x16x32_bf16 v[104:107], v[188:191], v[226:229], v[104:107]
	v_mfma_f32_16x16x32_bf16 v[92:95], v[160:163], v[234:237], v[92:95]
	v_mfma_f32_16x16x32_bf16 v[88:91], v[188:191], v[234:237], v[88:91]
	v_mfma_f32_16x16x32_bf16 v[76:79], v[160:163], v[242:245], v[76:79]
	v_mfma_f32_16x16x32_bf16 v[72:75], v[188:191], v[242:245], v[72:75]
	v_mfma_f32_16x16x32_bf16 v[124:127], v[184:187], v[222:225], v[124:127]
	v_mfma_f32_16x16x32_bf16 v[120:123], v[198:201], v[222:225], v[120:123]
	v_mfma_f32_16x16x32_bf16 v[108:111], v[184:187], v[230:233], v[108:111]
	v_mfma_f32_16x16x32_bf16 v[104:107], v[198:201], v[230:233], v[104:107]
	v_mfma_f32_16x16x32_bf16 v[92:95], v[184:187], v[238:241], v[92:95]
	v_mfma_f32_16x16x32_bf16 v[88:91], v[198:201], v[238:241], v[88:91]
	v_mfma_f32_16x16x32_bf16 v[76:79], v[184:187], v[246:249], v[76:79]
	v_mfma_f32_16x16x32_bf16 v[72:75], v[198:201], v[246:249], v[72:75]
	v_mfma_f32_16x16x32_bf16 v[116:119], v[202:205], v[218:221], v[116:119]
	v_mfma_f32_16x16x32_bf16 v[112:115], v[210:213], v[218:221], v[112:115]
	v_mfma_f32_16x16x32_bf16 v[100:103], v[202:205], v[226:229], v[100:103]
	v_mfma_f32_16x16x32_bf16 v[96:99], v[210:213], v[226:229], v[96:99]
	v_mfma_f32_16x16x32_bf16 v[84:87], v[202:205], v[234:237], v[84:87]
	v_mfma_f32_16x16x32_bf16 v[80:83], v[210:213], v[234:237], v[80:83]
	v_mfma_f32_16x16x32_bf16 v[68:71], v[202:205], v[242:245], v[68:71]
	v_mfma_f32_16x16x32_bf16 v[64:67], v[210:213], v[242:245], v[64:67]
	v_mfma_f32_16x16x32_bf16 v[116:119], v[206:209], v[222:225], v[116:119]
	v_mfma_f32_16x16x32_bf16 v[112:115], v[214:217], v[222:225], v[112:115]
	v_mfma_f32_16x16x32_bf16 v[100:103], v[206:209], v[230:233], v[100:103]
	v_mfma_f32_16x16x32_bf16 v[96:99], v[214:217], v[230:233], v[96:99]
	v_mfma_f32_16x16x32_bf16 v[84:87], v[206:209], v[238:241], v[84:87]
	v_mfma_f32_16x16x32_bf16 v[80:83], v[214:217], v[238:241], v[80:83]
	v_mfma_f32_16x16x32_bf16 v[68:71], v[206:209], v[246:249], v[68:71]
	v_mfma_f32_16x16x32_bf16 v[64:67], v[214:217], v[246:249], v[64:67]
	s_barrier
	s_add_u32 s98, s24, s38
	s_addc_u32 s99, s25, s39
	s_add_u32 s100, s64, s38
	s_addc_u32 s101, s65, s39
	s_mov_b32 m0, s6
	s_add_u32 s68, s24, 0x40000
	ds_read_b128 v[218:221], v159 offset:16384
	ds_read_b128 v[222:225], v159 offset:17408
	ds_read_b128 v[226:229], v159 offset:18432
	ds_read_b128 v[230:233], v159 offset:19456
	ds_read_b128 v[234:237], v159 offset:20480
	ds_read_b128 v[238:241], v159 offset:21504
	ds_read_b128 v[242:245], v159 offset:22528
	ds_read_b128 v[246:249], v159 offset:23552
	global_load_lds_dwordx4 v128, s[24:25]
	s_mov_b32 m0, s7
	s_addc_u32 s69, s25, 0
	global_load_lds_dwordx4 v130, s[24:25]
	s_mov_b32 m0, s28
	s_nop 0
	global_load_lds_dwordx4 v128, s[68:69]
	s_mov_b32 m0, s29
	s_nop 0
	global_load_lds_dwordx4 v130, s[68:69]
	s_mov_b32 m0, s2
	s_nop 0
	global_load_lds_dwordx4 v128, s[64:65]
	s_mov_b32 m0, s30
	s_nop 0
	global_load_lds_dwordx4 v130, s[64:65]
	s_waitcnt vmcnt(8)
	s_waitcnt lgkmcnt(0)
	s_barrier
	v_mfma_f32_16x16x32_bf16 v[60:63], v[160:163], v[218:221], v[60:63]
	v_mfma_f32_16x16x32_bf16 v[56:59], v[188:191], v[218:221], v[56:59]
	v_mfma_f32_16x16x32_bf16 v[44:47], v[160:163], v[226:229], v[44:47]
	v_mfma_f32_16x16x32_bf16 v[40:43], v[188:191], v[226:229], v[40:43]
	v_mfma_f32_16x16x32_bf16 v[28:31], v[160:163], v[234:237], v[28:31]
	v_mfma_f32_16x16x32_bf16 v[24:27], v[188:191], v[234:237], v[24:27]
	v_mfma_f32_16x16x32_bf16 v[12:15], v[160:163], v[242:245], v[12:15]
	v_mfma_f32_16x16x32_bf16 v[8:11], v[188:191], v[242:245], v[8:11]
	v_mfma_f32_16x16x32_bf16 v[60:63], v[184:187], v[222:225], v[60:63]
	v_mfma_f32_16x16x32_bf16 v[56:59], v[198:201], v[222:225], v[56:59]
	v_mfma_f32_16x16x32_bf16 v[44:47], v[184:187], v[230:233], v[44:47]
	v_mfma_f32_16x16x32_bf16 v[40:43], v[198:201], v[230:233], v[40:43]
	v_mfma_f32_16x16x32_bf16 v[28:31], v[184:187], v[238:241], v[28:31]
	v_mfma_f32_16x16x32_bf16 v[24:27], v[198:201], v[238:241], v[24:27]
	v_mfma_f32_16x16x32_bf16 v[12:15], v[184:187], v[246:249], v[12:15]
	v_mfma_f32_16x16x32_bf16 v[8:11], v[198:201], v[246:249], v[8:11]
	v_mfma_f32_16x16x32_bf16 v[52:55], v[202:205], v[218:221], v[52:55]
	v_mfma_f32_16x16x32_bf16 v[48:51], v[210:213], v[218:221], v[48:51]
	v_mfma_f32_16x16x32_bf16 v[36:39], v[202:205], v[226:229], v[36:39]
	v_mfma_f32_16x16x32_bf16 v[32:35], v[210:213], v[226:229], v[32:35]
	v_mfma_f32_16x16x32_bf16 v[20:23], v[202:205], v[234:237], v[20:23]
	v_mfma_f32_16x16x32_bf16 v[16:19], v[210:213], v[234:237], v[16:19]
	v_mfma_f32_16x16x32_bf16 v[4:7], v[202:205], v[242:245], v[4:7]
	v_mfma_f32_16x16x32_bf16 v[0:3], v[210:213], v[242:245], v[0:3]
	v_mfma_f32_16x16x32_bf16 v[52:55], v[206:209], v[222:225], v[52:55]
	v_mfma_f32_16x16x32_bf16 v[48:51], v[214:217], v[222:225], v[48:51]
	v_mfma_f32_16x16x32_bf16 v[36:39], v[206:209], v[230:233], v[36:39]
	v_mfma_f32_16x16x32_bf16 v[32:35], v[214:217], v[230:233], v[32:35]
	v_mfma_f32_16x16x32_bf16 v[20:23], v[206:209], v[238:241], v[20:23]
	v_mfma_f32_16x16x32_bf16 v[16:19], v[214:217], v[238:241], v[16:19]
	v_mfma_f32_16x16x32_bf16 v[4:7], v[206:209], v[246:249], v[4:7]
	v_mfma_f32_16x16x32_bf16 v[0:3], v[214:217], v[246:249], v[0:3]
	s_barrier
	ds_read_b128 v[160:163], v175
	ds_read_b128 v[184:187], v176
	ds_read_b128 v[188:191], v177
	ds_read_b128 v[198:201], v178
	ds_read_b128 v[202:205], v179
	ds_read_b128 v[206:209], v180
	ds_read_b128 v[210:213], v181
	ds_read_b128 v[214:217], v182
	s_add_u32 s64, s64, 0x40000
	s_addc_u32 s65, s65, 0
	s_mov_b32 m0, s31
	ds_read_b128 v[218:221], v159 offset:32768
	ds_read_b128 v[222:225], v159 offset:33792
	ds_read_b128 v[226:229], v159 offset:34816
	ds_read_b128 v[230:233], v159 offset:35840
	ds_read_b128 v[234:237], v159 offset:36864
	ds_read_b128 v[238:241], v159 offset:37888
	ds_read_b128 v[242:245], v159 offset:38912
	ds_read_b128 v[246:249], v159 offset:39936
	global_load_lds_dwordx4 v128, s[64:65]
	s_mov_b32 m0, s33
	s_nop 0
	global_load_lds_dwordx4 v130, s[64:65]
	s_waitcnt vmcnt(8)
	s_waitcnt lgkmcnt(0)
	s_barrier
	v_mfma_f32_16x16x32_bf16 v[124:127], v[160:163], v[218:221], v[124:127]
	v_mfma_f32_16x16x32_bf16 v[120:123], v[188:191], v[218:221], v[120:123]
	v_mfma_f32_16x16x32_bf16 v[108:111], v[160:163], v[226:229], v[108:111]
	v_mfma_f32_16x16x32_bf16 v[104:107], v[188:191], v[226:229], v[104:107]
	v_mfma_f32_16x16x32_bf16 v[92:95], v[160:163], v[234:237], v[92:95]
	v_mfma_f32_16x16x32_bf16 v[88:91], v[188:191], v[234:237], v[88:91]
	v_mfma_f32_16x16x32_bf16 v[76:79], v[160:163], v[242:245], v[76:79]
	v_mfma_f32_16x16x32_bf16 v[72:75], v[188:191], v[242:245], v[72:75]
	v_mfma_f32_16x16x32_bf16 v[124:127], v[184:187], v[222:225], v[124:127]
	v_mfma_f32_16x16x32_bf16 v[120:123], v[198:201], v[222:225], v[120:123]
	v_mfma_f32_16x16x32_bf16 v[108:111], v[184:187], v[230:233], v[108:111]
	v_mfma_f32_16x16x32_bf16 v[104:107], v[198:201], v[230:233], v[104:107]
	v_mfma_f32_16x16x32_bf16 v[92:95], v[184:187], v[238:241], v[92:95]
	v_mfma_f32_16x16x32_bf16 v[88:91], v[198:201], v[238:241], v[88:91]
	v_mfma_f32_16x16x32_bf16 v[76:79], v[184:187], v[246:249], v[76:79]
	v_mfma_f32_16x16x32_bf16 v[72:75], v[198:201], v[246:249], v[72:75]
	v_mfma_f32_16x16x32_bf16 v[116:119], v[202:205], v[218:221], v[116:119]
	v_mfma_f32_16x16x32_bf16 v[112:115], v[210:213], v[218:221], v[112:115]
	v_mfma_f32_16x16x32_bf16 v[100:103], v[202:205], v[226:229], v[100:103]
	v_mfma_f32_16x16x32_bf16 v[96:99], v[210:213], v[226:229], v[96:99]
	v_mfma_f32_16x16x32_bf16 v[84:87], v[202:205], v[234:237], v[84:87]
	v_mfma_f32_16x16x32_bf16 v[80:83], v[210:213], v[234:237], v[80:83]
	v_mfma_f32_16x16x32_bf16 v[68:71], v[202:205], v[242:245], v[68:71]
	v_mfma_f32_16x16x32_bf16 v[64:67], v[210:213], v[242:245], v[64:67]
	v_mfma_f32_16x16x32_bf16 v[116:119], v[206:209], v[222:225], v[116:119]
	v_mfma_f32_16x16x32_bf16 v[112:115], v[214:217], v[222:225], v[112:115]
	v_mfma_f32_16x16x32_bf16 v[100:103], v[206:209], v[230:233], v[100:103]
	v_mfma_f32_16x16x32_bf16 v[96:99], v[214:217], v[230:233], v[96:99]
	v_mfma_f32_16x16x32_bf16 v[84:87], v[206:209], v[238:241], v[84:87]
	v_mfma_f32_16x16x32_bf16 v[80:83], v[214:217], v[238:241], v[80:83]
	v_mfma_f32_16x16x32_bf16 v[68:71], v[206:209], v[246:249], v[68:71]
	v_mfma_f32_16x16x32_bf16 v[64:67], v[214:217], v[246:249], v[64:67]
	s_barrier
	s_mov_b32 m0, s34
	s_add_u32 s24, s24, 0x40080
	ds_read_b128 v[218:221], v159 offset:49152
	ds_read_b128 v[222:225], v159 offset:50176
	ds_read_b128 v[226:229], v159 offset:51200
	ds_read_b128 v[230:233], v159 offset:52224
	ds_read_b128 v[234:237], v159 offset:53248
	ds_read_b128 v[238:241], v159 offset:54272
	ds_read_b128 v[242:245], v159 offset:55296
	ds_read_b128 v[246:249], v159 offset:56320
	global_load_lds_dwordx4 v128, s[98:99]
	s_mov_b32 m0, s35
	s_addc_u32 s25, s25, 0
	global_load_lds_dwordx4 v130, s[98:99]
	s_mov_b32 m0, s40
	s_nop 0
	global_load_lds_dwordx4 v128, s[24:25]
	s_mov_b32 m0, s41
	s_nop 0
	global_load_lds_dwordx4 v130, s[24:25]
	s_mov_b32 m0, s36
	s_nop 0
	global_load_lds_dwordx4 v128, s[100:101]
	s_mov_b32 m0, s37
	s_nop 0
	global_load_lds_dwordx4 v130, s[100:101]
	s_waitcnt vmcnt(8)
	s_waitcnt lgkmcnt(0)
	s_barrier
	v_mfma_f32_16x16x32_bf16 v[60:63], v[160:163], v[218:221], v[60:63]
	v_mfma_f32_16x16x32_bf16 v[56:59], v[188:191], v[218:221], v[56:59]
	v_mfma_f32_16x16x32_bf16 v[44:47], v[160:163], v[226:229], v[44:47]
	v_mfma_f32_16x16x32_bf16 v[40:43], v[188:191], v[226:229], v[40:43]
	v_mfma_f32_16x16x32_bf16 v[28:31], v[160:163], v[234:237], v[28:31]
	v_mfma_f32_16x16x32_bf16 v[24:27], v[188:191], v[234:237], v[24:27]
	v_mfma_f32_16x16x32_bf16 v[12:15], v[160:163], v[242:245], v[12:15]
	v_mfma_f32_16x16x32_bf16 v[8:11], v[188:191], v[242:245], v[8:11]
	v_mfma_f32_16x16x32_bf16 v[60:63], v[184:187], v[222:225], v[60:63]
	v_mfma_f32_16x16x32_bf16 v[56:59], v[198:201], v[222:225], v[56:59]
	v_mfma_f32_16x16x32_bf16 v[44:47], v[184:187], v[230:233], v[44:47]
	v_mfma_f32_16x16x32_bf16 v[40:43], v[198:201], v[230:233], v[40:43]
	v_mfma_f32_16x16x32_bf16 v[28:31], v[184:187], v[238:241], v[28:31]
	v_mfma_f32_16x16x32_bf16 v[24:27], v[198:201], v[238:241], v[24:27]
	v_mfma_f32_16x16x32_bf16 v[12:15], v[184:187], v[246:249], v[12:15]
	v_mfma_f32_16x16x32_bf16 v[8:11], v[198:201], v[246:249], v[8:11]
	v_mfma_f32_16x16x32_bf16 v[52:55], v[202:205], v[218:221], v[52:55]
	v_mfma_f32_16x16x32_bf16 v[48:51], v[210:213], v[218:221], v[48:51]
	v_mfma_f32_16x16x32_bf16 v[36:39], v[202:205], v[226:229], v[36:39]
	v_mfma_f32_16x16x32_bf16 v[32:35], v[210:213], v[226:229], v[32:35]
	v_mfma_f32_16x16x32_bf16 v[20:23], v[202:205], v[234:237], v[20:23]
	v_mfma_f32_16x16x32_bf16 v[16:19], v[210:213], v[234:237], v[16:19]
	v_mfma_f32_16x16x32_bf16 v[4:7], v[202:205], v[242:245], v[4:7]
	v_mfma_f32_16x16x32_bf16 v[0:3], v[210:213], v[242:245], v[0:3]
	v_mfma_f32_16x16x32_bf16 v[52:55], v[206:209], v[222:225], v[52:55]
	v_mfma_f32_16x16x32_bf16 v[48:51], v[214:217], v[222:225], v[48:51]
	v_mfma_f32_16x16x32_bf16 v[36:39], v[206:209], v[230:233], v[36:39]
	v_mfma_f32_16x16x32_bf16 v[32:35], v[214:217], v[230:233], v[32:35]
	v_mfma_f32_16x16x32_bf16 v[20:23], v[206:209], v[238:241], v[20:23]
	v_mfma_f32_16x16x32_bf16 v[16:19], v[214:217], v[238:241], v[16:19]
	v_mfma_f32_16x16x32_bf16 v[4:7], v[206:209], v[246:249], v[4:7]
	v_mfma_f32_16x16x32_bf16 v[0:3], v[214:217], v[246:249], v[0:3]
	s_barrier
	s_add_i32 s66, s66, 2
	s_add_u32 s14, s14, 0x100
	s_addc_u32 s15, s15, 0
	s_add_u32 s47, s47, 0x100
	s_addc_u32 s49, s49, 0
	s_cmp_gt_u32 s66, 13
	s_cbranch_scc0 .LBB0_1334
	s_and_b64 vcc, exec, s[42:43]
	s_cbranch_vccz .LBB0_1337
	s_barrier

.LBB0_1497:
	ds_read_b128 v[176:179], v159
	ds_read_b128 v[180:183], v160
	ds_read_b128 v[184:187], v161
	ds_read_b128 v[188:191], v162
	ds_read_b128 v[198:201], v163
	ds_read_b128 v[202:205], v164
	ds_read_b128 v[206:209], v165
	ds_read_b128 v[210:213], v166
	s_add_u32 s50, s24, 0x100
	s_addc_u32 s51, s25, 0
	s_cmp_eq_u32 s68, 12
	s_cselect_b32 s65, s4, s51
	s_cselect_b32 s64, s5, s50
	s_cselect_b32 s55, s39, s87
	s_cselect_b32 s54, s43, s86
	s_mov_b32 m0, s76
	ds_read_b128 v[214:217], v143
	ds_read_b128 v[218:221], v143 offset:1024
	ds_read_b128 v[222:225], v143 offset:2048
	ds_read_b128 v[226:229], v143 offset:3072
	ds_read_b128 v[230:233], v143 offset:4096
	ds_read_b128 v[234:237], v143 offset:5120
	ds_read_b128 v[238:241], v143 offset:6144
	ds_read_b128 v[242:245], v143 offset:7168
	global_load_lds_dwordx4 v132, s[24:25]
	s_mov_b32 m0, s77
	s_nop 0
	global_load_lds_dwordx4 v134, s[24:25]
	s_waitcnt vmcnt(8)
	s_waitcnt lgkmcnt(0)
	s_barrier
	v_mfma_f32_16x16x32_bf16 v[124:127], v[176:179], v[214:217], v[124:127]
	v_mfma_f32_16x16x32_bf16 v[120:123], v[184:187], v[214:217], v[120:123]
	v_mfma_f32_16x16x32_bf16 v[108:111], v[176:179], v[222:225], v[108:111]
	v_mfma_f32_16x16x32_bf16 v[104:107], v[184:187], v[222:225], v[104:107]
	v_mfma_f32_16x16x32_bf16 v[92:95], v[176:179], v[230:233], v[92:95]
	v_mfma_f32_16x16x32_bf16 v[88:91], v[184:187], v[230:233], v[88:91]
	v_mfma_f32_16x16x32_bf16 v[76:79], v[176:179], v[238:241], v[76:79]
	v_mfma_f32_16x16x32_bf16 v[72:75], v[184:187], v[238:241], v[72:75]
	v_mfma_f32_16x16x32_bf16 v[124:127], v[180:183], v[218:221], v[124:127]
	v_mfma_f32_16x16x32_bf16 v[120:123], v[188:191], v[218:221], v[120:123]
	v_mfma_f32_16x16x32_bf16 v[108:111], v[180:183], v[226:229], v[108:111]
	v_mfma_f32_16x16x32_bf16 v[104:107], v[188:191], v[226:229], v[104:107]
	v_mfma_f32_16x16x32_bf16 v[92:95], v[180:183], v[234:237], v[92:95]
	v_mfma_f32_16x16x32_bf16 v[88:91], v[188:191], v[234:237], v[88:91]
	v_mfma_f32_16x16x32_bf16 v[76:79], v[180:183], v[242:245], v[76:79]
	v_mfma_f32_16x16x32_bf16 v[72:75], v[188:191], v[242:245], v[72:75]
	v_mfma_f32_16x16x32_bf16 v[116:119], v[198:201], v[214:217], v[116:119]
	v_mfma_f32_16x16x32_bf16 v[112:115], v[206:209], v[214:217], v[112:115]
	v_mfma_f32_16x16x32_bf16 v[100:103], v[198:201], v[222:225], v[100:103]
	v_mfma_f32_16x16x32_bf16 v[96:99], v[206:209], v[222:225], v[96:99]
	v_mfma_f32_16x16x32_bf16 v[84:87], v[198:201], v[230:233], v[84:87]
	v_mfma_f32_16x16x32_bf16 v[80:83], v[206:209], v[230:233], v[80:83]
	v_mfma_f32_16x16x32_bf16 v[68:71], v[198:201], v[238:241], v[68:71]
	v_mfma_f32_16x16x32_bf16 v[64:67], v[206:209], v[238:241], v[64:67]
	v_mfma_f32_16x16x32_bf16 v[116:119], v[202:205], v[218:221], v[116:119]
	v_mfma_f32_16x16x32_bf16 v[112:115], v[210:213], v[218:221], v[112:115]
	v_mfma_f32_16x16x32_bf16 v[100:103], v[202:205], v[226:229], v[100:103]
	v_mfma_f32_16x16x32_bf16 v[96:99], v[210:213], v[226:229], v[96:99]
	v_mfma_f32_16x16x32_bf16 v[84:87], v[202:205], v[234:237], v[84:87]
	v_mfma_f32_16x16x32_bf16 v[80:83], v[210:213], v[234:237], v[80:83]
	v_mfma_f32_16x16x32_bf16 v[68:71], v[202:205], v[242:245], v[68:71]
	v_mfma_f32_16x16x32_bf16 v[64:67], v[210:213], v[242:245], v[64:67]
	s_barrier
	s_add_u32 s98, s54, s10
	s_addc_u32 s99, s55, s11
	s_add_u32 s100, s64, s10
	s_addc_u32 s101, s65, s11
	s_mov_b32 m0, s29
	s_add_u32 s24, s54, 0x40000
	ds_read_b128 v[214:217], v143 offset:16384
	ds_read_b128 v[218:221], v143 offset:17408
	ds_read_b128 v[222:225], v143 offset:18432
	ds_read_b128 v[226:229], v143 offset:19456
	ds_read_b128 v[230:233], v143 offset:20480
	ds_read_b128 v[234:237], v143 offset:21504
	ds_read_b128 v[238:241], v143 offset:22528
	ds_read_b128 v[242:245], v143 offset:23552
	global_load_lds_dwordx4 v128, s[54:55]
	s_mov_b32 m0, s30
	s_addc_u32 s25, s55, 0
	global_load_lds_dwordx4 v130, s[54:55]
	s_mov_b32 m0, s31
	s_nop 0
	global_load_lds_dwordx4 v128, s[24:25]
	s_mov_b32 m0, s33
	s_nop 0
	global_load_lds_dwordx4 v130, s[24:25]
	s_mov_b32 m0, s28
	s_nop 0
	global_load_lds_dwordx4 v128, s[64:65]
	s_mov_b32 m0, s34
	s_nop 0
	global_load_lds_dwordx4 v130, s[64:65]
	s_waitcnt vmcnt(8)
	s_waitcnt lgkmcnt(0)
	s_barrier
	v_mfma_f32_16x16x32_bf16 v[60:63], v[176:179], v[214:217], v[60:63]
	v_mfma_f32_16x16x32_bf16 v[56:59], v[184:187], v[214:217], v[56:59]
	v_mfma_f32_16x16x32_bf16 v[44:47], v[176:179], v[222:225], v[44:47]
	v_mfma_f32_16x16x32_bf16 v[40:43], v[184:187], v[222:225], v[40:43]
	v_mfma_f32_16x16x32_bf16 v[28:31], v[176:179], v[230:233], v[28:31]
	v_mfma_f32_16x16x32_bf16 v[24:27], v[184:187], v[230:233], v[24:27]
	v_mfma_f32_16x16x32_bf16 v[12:15], v[176:179], v[238:241], v[12:15]
	v_mfma_f32_16x16x32_bf16 v[8:11], v[184:187], v[238:241], v[8:11]
	v_mfma_f32_16x16x32_bf16 v[60:63], v[180:183], v[218:221], v[60:63]
	v_mfma_f32_16x16x32_bf16 v[56:59], v[188:191], v[218:221], v[56:59]
	v_mfma_f32_16x16x32_bf16 v[44:47], v[180:183], v[226:229], v[44:47]
	v_mfma_f32_16x16x32_bf16 v[40:43], v[188:191], v[226:229], v[40:43]
	v_mfma_f32_16x16x32_bf16 v[28:31], v[180:183], v[234:237], v[28:31]
	v_mfma_f32_16x16x32_bf16 v[24:27], v[188:191], v[234:237], v[24:27]
	v_mfma_f32_16x16x32_bf16 v[12:15], v[180:183], v[242:245], v[12:15]
	v_mfma_f32_16x16x32_bf16 v[8:11], v[188:191], v[242:245], v[8:11]
	v_mfma_f32_16x16x32_bf16 v[52:55], v[198:201], v[214:217], v[52:55]
	v_mfma_f32_16x16x32_bf16 v[48:51], v[206:209], v[214:217], v[48:51]
	v_mfma_f32_16x16x32_bf16 v[36:39], v[198:201], v[222:225], v[36:39]
	v_mfma_f32_16x16x32_bf16 v[32:35], v[206:209], v[222:225], v[32:35]
	v_mfma_f32_16x16x32_bf16 v[20:23], v[198:201], v[230:233], v[20:23]
	v_mfma_f32_16x16x32_bf16 v[16:19], v[206:209], v[230:233], v[16:19]
	v_mfma_f32_16x16x32_bf16 v[4:7], v[198:201], v[238:241], v[4:7]
	v_mfma_f32_16x16x32_bf16 v[0:3], v[206:209], v[238:241], v[0:3]
	v_mfma_f32_16x16x32_bf16 v[52:55], v[202:205], v[218:221], v[52:55]
	v_mfma_f32_16x16x32_bf16 v[48:51], v[210:213], v[218:221], v[48:51]
	v_mfma_f32_16x16x32_bf16 v[36:39], v[202:205], v[226:229], v[36:39]
	v_mfma_f32_16x16x32_bf16 v[32:35], v[210:213], v[226:229], v[32:35]
	v_mfma_f32_16x16x32_bf16 v[20:23], v[202:205], v[234:237], v[20:23]
	v_mfma_f32_16x16x32_bf16 v[16:19], v[210:213], v[234:237], v[16:19]
	v_mfma_f32_16x16x32_bf16 v[4:7], v[202:205], v[242:245], v[4:7]
	v_mfma_f32_16x16x32_bf16 v[0:3], v[210:213], v[242:245], v[0:3]
	s_barrier
	ds_read_b128 v[176:179], v167
	ds_read_b128 v[180:183], v168
	ds_read_b128 v[184:187], v169
	ds_read_b128 v[188:191], v170
	ds_read_b128 v[198:201], v171
	ds_read_b128 v[202:205], v172
	ds_read_b128 v[206:209], v173
	ds_read_b128 v[210:213], v174
	s_add_u32 s24, s64, 0x40000
	s_addc_u32 s25, s65, 0
	s_mov_b32 m0, s35
	ds_read_b128 v[214:217], v143 offset:32768
	ds_read_b128 v[218:221], v143 offset:33792
	ds_read_b128 v[222:225], v143 offset:34816
	ds_read_b128 v[226:229], v143 offset:35840
	ds_read_b128 v[230:233], v143 offset:36864
	ds_read_b128 v[234:237], v143 offset:37888
	ds_read_b128 v[238:241], v143 offset:38912
	ds_read_b128 v[242:245], v143 offset:39936
	global_load_lds_dwordx4 v128, s[24:25]
	s_mov_b32 m0, s36
	s_nop 0
	global_load_lds_dwordx4 v130, s[24:25]
	s_waitcnt vmcnt(8)
	s_waitcnt lgkmcnt(0)
	s_barrier
	v_mfma_f32_16x16x32_bf16 v[124:127], v[176:179], v[214:217], v[124:127]
	v_mfma_f32_16x16x32_bf16 v[120:123], v[184:187], v[214:217], v[120:123]
	v_mfma_f32_16x16x32_bf16 v[108:111], v[176:179], v[222:225], v[108:111]
	v_mfma_f32_16x16x32_bf16 v[104:107], v[184:187], v[222:225], v[104:107]
	v_mfma_f32_16x16x32_bf16 v[92:95], v[176:179], v[230:233], v[92:95]
	v_mfma_f32_16x16x32_bf16 v[88:91], v[184:187], v[230:233], v[88:91]
	v_mfma_f32_16x16x32_bf16 v[76:79], v[176:179], v[238:241], v[76:79]
	v_mfma_f32_16x16x32_bf16 v[72:75], v[184:187], v[238:241], v[72:75]
	v_mfma_f32_16x16x32_bf16 v[124:127], v[180:183], v[218:221], v[124:127]
	v_mfma_f32_16x16x32_bf16 v[120:123], v[188:191], v[218:221], v[120:123]
	v_mfma_f32_16x16x32_bf16 v[108:111], v[180:183], v[226:229], v[108:111]
	v_mfma_f32_16x16x32_bf16 v[104:107], v[188:191], v[226:229], v[104:107]
	v_mfma_f32_16x16x32_bf16 v[92:95], v[180:183], v[234:237], v[92:95]
	v_mfma_f32_16x16x32_bf16 v[88:91], v[188:191], v[234:237], v[88:91]
	v_mfma_f32_16x16x32_bf16 v[76:79], v[180:183], v[242:245], v[76:79]
	v_mfma_f32_16x16x32_bf16 v[72:75], v[188:191], v[242:245], v[72:75]
	v_mfma_f32_16x16x32_bf16 v[116:119], v[198:201], v[214:217], v[116:119]
	v_mfma_f32_16x16x32_bf16 v[112:115], v[206:209], v[214:217], v[112:115]
	v_mfma_f32_16x16x32_bf16 v[100:103], v[198:201], v[222:225], v[100:103]
	v_mfma_f32_16x16x32_bf16 v[96:99], v[206:209], v[222:225], v[96:99]
	v_mfma_f32_16x16x32_bf16 v[84:87], v[198:201], v[230:233], v[84:87]
	v_mfma_f32_16x16x32_bf16 v[80:83], v[206:209], v[230:233], v[80:83]
	v_mfma_f32_16x16x32_bf16 v[68:71], v[198:201], v[238:241], v[68:71]
	v_mfma_f32_16x16x32_bf16 v[64:67], v[206:209], v[238:241], v[64:67]
	v_mfma_f32_16x16x32_bf16 v[116:119], v[202:205], v[218:221], v[116:119]
	v_mfma_f32_16x16x32_bf16 v[112:115], v[210:213], v[218:221], v[112:115]
	v_mfma_f32_16x16x32_bf16 v[100:103], v[202:205], v[226:229], v[100:103]
	v_mfma_f32_16x16x32_bf16 v[96:99], v[210:213], v[226:229], v[96:99]
	v_mfma_f32_16x16x32_bf16 v[84:87], v[202:205], v[234:237], v[84:87]
	v_mfma_f32_16x16x32_bf16 v[80:83], v[210:213], v[234:237], v[80:83]
	v_mfma_f32_16x16x32_bf16 v[68:71], v[202:205], v[242:245], v[68:71]
	v_mfma_f32_16x16x32_bf16 v[64:67], v[210:213], v[242:245], v[64:67]
	s_barrier
	s_mov_b32 m0, s40
	s_add_u32 s24, s54, 0x40080
	ds_read_b128 v[214:217], v143 offset:49152
	ds_read_b128 v[218:221], v143 offset:50176
	ds_read_b128 v[222:225], v143 offset:51200
	ds_read_b128 v[226:229], v143 offset:52224
	ds_read_b128 v[230:233], v143 offset:53248
	ds_read_b128 v[234:237], v143 offset:54272
	ds_read_b128 v[238:241], v143 offset:55296
	ds_read_b128 v[242:245], v143 offset:56320
	global_load_lds_dwordx4 v128, s[98:99]
	s_mov_b32 m0, s41
	s_addc_u32 s25, s55, 0
	global_load_lds_dwordx4 v130, s[98:99]
	s_mov_b32 m0, s53
	s_nop 0
	global_load_lds_dwordx4 v128, s[24:25]
	s_mov_b32 m0, s60
	s_nop 0
	global_load_lds_dwordx4 v130, s[24:25]
	s_mov_b32 m0, s49
	s_nop 0
	global_load_lds_dwordx4 v128, s[100:101]
	s_mov_b32 m0, s52
	s_nop 0
	global_load_lds_dwordx4 v130, s[100:101]
	s_waitcnt vmcnt(8)
	s_waitcnt lgkmcnt(0)
	s_barrier
	v_mfma_f32_16x16x32_bf16 v[60:63], v[176:179], v[214:217], v[60:63]
	v_mfma_f32_16x16x32_bf16 v[56:59], v[184:187], v[214:217], v[56:59]
	v_mfma_f32_16x16x32_bf16 v[44:47], v[176:179], v[222:225], v[44:47]
	v_mfma_f32_16x16x32_bf16 v[40:43], v[184:187], v[222:225], v[40:43]
	v_mfma_f32_16x16x32_bf16 v[28:31], v[176:179], v[230:233], v[28:31]
	v_mfma_f32_16x16x32_bf16 v[24:27], v[184:187], v[230:233], v[24:27]
	v_mfma_f32_16x16x32_bf16 v[12:15], v[176:179], v[238:241], v[12:15]
	v_mfma_f32_16x16x32_bf16 v[8:11], v[184:187], v[238:241], v[8:11]
	v_mfma_f32_16x16x32_bf16 v[60:63], v[180:183], v[218:221], v[60:63]
	v_mfma_f32_16x16x32_bf16 v[56:59], v[188:191], v[218:221], v[56:59]
	v_mfma_f32_16x16x32_bf16 v[44:47], v[180:183], v[226:229], v[44:47]
	v_mfma_f32_16x16x32_bf16 v[40:43], v[188:191], v[226:229], v[40:43]
	v_mfma_f32_16x16x32_bf16 v[28:31], v[180:183], v[234:237], v[28:31]
	v_mfma_f32_16x16x32_bf16 v[24:27], v[188:191], v[234:237], v[24:27]
	v_mfma_f32_16x16x32_bf16 v[12:15], v[180:183], v[242:245], v[12:15]
	v_mfma_f32_16x16x32_bf16 v[8:11], v[188:191], v[242:245], v[8:11]
	v_mfma_f32_16x16x32_bf16 v[52:55], v[198:201], v[214:217], v[52:55]
	v_mfma_f32_16x16x32_bf16 v[48:51], v[206:209], v[214:217], v[48:51]
	v_mfma_f32_16x16x32_bf16 v[36:39], v[198:201], v[222:225], v[36:39]
	v_mfma_f32_16x16x32_bf16 v[32:35], v[206:209], v[222:225], v[32:35]
	v_mfma_f32_16x16x32_bf16 v[20:23], v[198:201], v[230:233], v[20:23]
	v_mfma_f32_16x16x32_bf16 v[16:19], v[206:209], v[230:233], v[16:19]
	v_mfma_f32_16x16x32_bf16 v[4:7], v[198:201], v[238:241], v[4:7]
	v_mfma_f32_16x16x32_bf16 v[0:3], v[206:209], v[238:241], v[0:3]
	v_mfma_f32_16x16x32_bf16 v[52:55], v[202:205], v[218:221], v[52:55]
	v_mfma_f32_16x16x32_bf16 v[48:51], v[210:213], v[218:221], v[48:51]
	v_mfma_f32_16x16x32_bf16 v[36:39], v[202:205], v[226:229], v[36:39]
	v_mfma_f32_16x16x32_bf16 v[32:35], v[210:213], v[226:229], v[32:35]
	v_mfma_f32_16x16x32_bf16 v[20:23], v[202:205], v[234:237], v[20:23]
	v_mfma_f32_16x16x32_bf16 v[16:19], v[210:213], v[234:237], v[16:19]
	v_mfma_f32_16x16x32_bf16 v[4:7], v[202:205], v[242:245], v[4:7]
	v_mfma_f32_16x16x32_bf16 v[0:3], v[210:213], v[242:245], v[0:3]
	s_barrier
	s_add_i32 s68, s68, 2
	s_add_u32 s86, s86, 0x100
	s_addc_u32 s87, s87, 0
	s_cmp_gt_u32 s68, 13
	s_mov_b64 s[24:25], s[50:51]
	s_cbranch_scc0 .LBB0_1497
	s_and_b64 vcc, exec, s[14:15]
	s_cbranch_vccz .LBB0_1500
	s_barrier

.LBB0_1766:
	ds_read_b128 v[128:131], v199
	ds_read_b128 v[132:135], v200
	ds_read_b128 v[136:139], v201
	ds_read_b128 v[140:143], v202
	ds_read_b128 v[172:175], v203
	ds_read_b128 v[176:179], v204
	ds_read_b128 v[180:183], v205
	ds_read_b128 v[184:187], v206
	s_add_u32 s74, s24, 0x100
	s_addc_u32 s75, s25, 0
	s_cmp_eq_u32 s68, 12
	s_cselect_b32 s85, s4, s75
	s_cselect_b32 s84, s5, s74
	s_cselect_b32 s81, s47, s87
	s_cselect_b32 s80, s49, s86
	s_mov_b32 m0, s65
	ds_read_b128 v[188:191], v159
	ds_read_b128 v[216:219], v159 offset:1024
	ds_read_b128 v[220:223], v159 offset:2048
	ds_read_b128 v[224:227], v159 offset:3072
	ds_read_b128 v[228:231], v159 offset:4096
	ds_read_b128 v[232:235], v159 offset:5120
	ds_read_b128 v[236:239], v159 offset:6144
	ds_read_b128 v[240:243], v159 offset:7168
	global_load_lds_dwordx4 v164, s[24:25]
	s_mov_b32 m0, s67
	s_nop 0
	global_load_lds_dwordx4 v166, s[24:25]
	s_waitcnt vmcnt(8)
	s_waitcnt lgkmcnt(0)
	s_barrier
	v_mfma_f32_16x16x32_bf16 v[124:127], v[128:131], v[188:191], v[124:127]
	v_mfma_f32_16x16x32_bf16 v[120:123], v[136:139], v[188:191], v[120:123]
	v_mfma_f32_16x16x32_bf16 v[108:111], v[128:131], v[220:223], v[108:111]
	v_mfma_f32_16x16x32_bf16 v[104:107], v[136:139], v[220:223], v[104:107]
	v_mfma_f32_16x16x32_bf16 v[92:95], v[128:131], v[228:231], v[92:95]
	v_mfma_f32_16x16x32_bf16 v[88:91], v[136:139], v[228:231], v[88:91]
	v_mfma_f32_16x16x32_bf16 v[76:79], v[128:131], v[236:239], v[76:79]
	v_mfma_f32_16x16x32_bf16 v[72:75], v[136:139], v[236:239], v[72:75]
	v_mfma_f32_16x16x32_bf16 v[124:127], v[132:135], v[216:219], v[124:127]
	v_mfma_f32_16x16x32_bf16 v[120:123], v[140:143], v[216:219], v[120:123]
	v_mfma_f32_16x16x32_bf16 v[108:111], v[132:135], v[224:227], v[108:111]
	v_mfma_f32_16x16x32_bf16 v[104:107], v[140:143], v[224:227], v[104:107]
	v_mfma_f32_16x16x32_bf16 v[92:95], v[132:135], v[232:235], v[92:95]
	v_mfma_f32_16x16x32_bf16 v[88:91], v[140:143], v[232:235], v[88:91]
	v_mfma_f32_16x16x32_bf16 v[76:79], v[132:135], v[240:243], v[76:79]
	v_mfma_f32_16x16x32_bf16 v[72:75], v[140:143], v[240:243], v[72:75]
	v_mfma_f32_16x16x32_bf16 v[116:119], v[172:175], v[188:191], v[116:119]
	v_mfma_f32_16x16x32_bf16 v[112:115], v[180:183], v[188:191], v[112:115]
	v_mfma_f32_16x16x32_bf16 v[100:103], v[172:175], v[220:223], v[100:103]
	v_mfma_f32_16x16x32_bf16 v[96:99], v[180:183], v[220:223], v[96:99]
	v_mfma_f32_16x16x32_bf16 v[84:87], v[172:175], v[228:231], v[84:87]
	v_mfma_f32_16x16x32_bf16 v[80:83], v[180:183], v[228:231], v[80:83]
	v_mfma_f32_16x16x32_bf16 v[68:71], v[172:175], v[236:239], v[68:71]
	v_mfma_f32_16x16x32_bf16 v[64:67], v[180:183], v[236:239], v[64:67]
	v_mfma_f32_16x16x32_bf16 v[116:119], v[176:179], v[216:219], v[116:119]
	v_mfma_f32_16x16x32_bf16 v[112:115], v[184:187], v[216:219], v[112:115]
	v_mfma_f32_16x16x32_bf16 v[100:103], v[176:179], v[224:227], v[100:103]
	v_mfma_f32_16x16x32_bf16 v[96:99], v[184:187], v[224:227], v[96:99]
	v_mfma_f32_16x16x32_bf16 v[84:87], v[176:179], v[232:235], v[84:87]
	v_mfma_f32_16x16x32_bf16 v[80:83], v[184:187], v[232:235], v[80:83]
	v_mfma_f32_16x16x32_bf16 v[68:71], v[176:179], v[240:243], v[68:71]
	v_mfma_f32_16x16x32_bf16 v[64:67], v[184:187], v[240:243], v[64:67]
	s_barrier
	s_add_u32 s98, s80, s38
	s_addc_u32 s99, s81, s39
	s_add_u32 s100, s84, s38
	s_addc_u32 s101, s85, s39
	s_mov_b32 m0, s7
	s_add_u32 s24, s80, 0x40000
	ds_read_b128 v[188:191], v159 offset:16384
	ds_read_b128 v[216:219], v159 offset:17408
	ds_read_b128 v[220:223], v159 offset:18432
	ds_read_b128 v[224:227], v159 offset:19456
	ds_read_b128 v[228:231], v159 offset:20480
	ds_read_b128 v[232:235], v159 offset:21504
	ds_read_b128 v[236:239], v159 offset:22528
	ds_read_b128 v[240:243], v159 offset:23552
	global_load_lds_dwordx4 v160, s[80:81]
	s_mov_b32 m0, s28
	s_addc_u32 s25, s81, 0
	global_load_lds_dwordx4 v162, s[80:81]
	s_mov_b32 m0, s29
	s_nop 0
	global_load_lds_dwordx4 v160, s[24:25]
	s_mov_b32 m0, s30
	s_nop 0
	global_load_lds_dwordx4 v162, s[24:25]
	s_mov_b32 m0, s6
	s_nop 0
	global_load_lds_dwordx4 v160, s[84:85]
	s_mov_b32 m0, s31
	s_nop 0
	global_load_lds_dwordx4 v162, s[84:85]
	s_waitcnt vmcnt(8)
	s_waitcnt lgkmcnt(0)
	s_barrier
	v_mfma_f32_16x16x32_bf16 v[60:63], v[128:131], v[188:191], v[60:63]
	v_mfma_f32_16x16x32_bf16 v[56:59], v[136:139], v[188:191], v[56:59]
	v_mfma_f32_16x16x32_bf16 v[44:47], v[128:131], v[220:223], v[44:47]
	v_mfma_f32_16x16x32_bf16 v[40:43], v[136:139], v[220:223], v[40:43]
	v_mfma_f32_16x16x32_bf16 v[28:31], v[128:131], v[228:231], v[28:31]
	v_mfma_f32_16x16x32_bf16 v[24:27], v[136:139], v[228:231], v[24:27]
	v_mfma_f32_16x16x32_bf16 v[12:15], v[128:131], v[236:239], v[12:15]
	v_mfma_f32_16x16x32_bf16 v[8:11], v[136:139], v[236:239], v[8:11]
	v_mfma_f32_16x16x32_bf16 v[60:63], v[132:135], v[216:219], v[60:63]
	v_mfma_f32_16x16x32_bf16 v[56:59], v[140:143], v[216:219], v[56:59]
	v_mfma_f32_16x16x32_bf16 v[44:47], v[132:135], v[224:227], v[44:47]
	v_mfma_f32_16x16x32_bf16 v[40:43], v[140:143], v[224:227], v[40:43]
	v_mfma_f32_16x16x32_bf16 v[28:31], v[132:135], v[232:235], v[28:31]
	v_mfma_f32_16x16x32_bf16 v[24:27], v[140:143], v[232:235], v[24:27]
	v_mfma_f32_16x16x32_bf16 v[12:15], v[132:135], v[240:243], v[12:15]
	v_mfma_f32_16x16x32_bf16 v[8:11], v[140:143], v[240:243], v[8:11]
	v_mfma_f32_16x16x32_bf16 v[52:55], v[172:175], v[188:191], v[52:55]
	v_mfma_f32_16x16x32_bf16 v[48:51], v[180:183], v[188:191], v[48:51]
	v_mfma_f32_16x16x32_bf16 v[36:39], v[172:175], v[220:223], v[36:39]
	v_mfma_f32_16x16x32_bf16 v[32:35], v[180:183], v[220:223], v[32:35]
	v_mfma_f32_16x16x32_bf16 v[20:23], v[172:175], v[228:231], v[20:23]
	v_mfma_f32_16x16x32_bf16 v[16:19], v[180:183], v[228:231], v[16:19]
	v_mfma_f32_16x16x32_bf16 v[4:7], v[172:175], v[236:239], v[4:7]
	v_mfma_f32_16x16x32_bf16 v[0:3], v[180:183], v[236:239], v[0:3]
	v_mfma_f32_16x16x32_bf16 v[52:55], v[176:179], v[216:219], v[52:55]
	v_mfma_f32_16x16x32_bf16 v[48:51], v[184:187], v[216:219], v[48:51]
	v_mfma_f32_16x16x32_bf16 v[36:39], v[176:179], v[224:227], v[36:39]
	v_mfma_f32_16x16x32_bf16 v[32:35], v[184:187], v[224:227], v[32:35]
	v_mfma_f32_16x16x32_bf16 v[20:23], v[176:179], v[232:235], v[20:23]
	v_mfma_f32_16x16x32_bf16 v[16:19], v[184:187], v[232:235], v[16:19]
	v_mfma_f32_16x16x32_bf16 v[4:7], v[176:179], v[240:243], v[4:7]
	v_mfma_f32_16x16x32_bf16 v[0:3], v[184:187], v[240:243], v[0:3]
	s_barrier
	ds_read_b128 v[128:131], v207
	ds_read_b128 v[132:135], v208
	ds_read_b128 v[136:139], v209
	ds_read_b128 v[140:143], v210
	ds_read_b128 v[172:175], v211
	ds_read_b128 v[176:179], v212
	ds_read_b128 v[180:183], v213
	ds_read_b128 v[184:187], v214
	s_add_u32 s24, s84, 0x40000
	s_addc_u32 s25, s85, 0
	s_mov_b32 m0, s33
	ds_read_b128 v[188:191], v159 offset:32768
	ds_read_b128 v[216:219], v159 offset:33792
	ds_read_b128 v[220:223], v159 offset:34816
	ds_read_b128 v[224:227], v159 offset:35840
	ds_read_b128 v[228:231], v159 offset:36864
	ds_read_b128 v[232:235], v159 offset:37888
	ds_read_b128 v[236:239], v159 offset:38912
	ds_read_b128 v[240:243], v159 offset:39936
	global_load_lds_dwordx4 v160, s[24:25]
	s_mov_b32 m0, s34
	s_nop 0
	global_load_lds_dwordx4 v162, s[24:25]
	s_waitcnt vmcnt(8)
	s_waitcnt lgkmcnt(0)
	s_barrier
	v_mfma_f32_16x16x32_bf16 v[124:127], v[128:131], v[188:191], v[124:127]
	v_mfma_f32_16x16x32_bf16 v[120:123], v[136:139], v[188:191], v[120:123]
	v_mfma_f32_16x16x32_bf16 v[108:111], v[128:131], v[220:223], v[108:111]
	v_mfma_f32_16x16x32_bf16 v[104:107], v[136:139], v[220:223], v[104:107]
	v_mfma_f32_16x16x32_bf16 v[92:95], v[128:131], v[228:231], v[92:95]
	v_mfma_f32_16x16x32_bf16 v[88:91], v[136:139], v[228:231], v[88:91]
	v_mfma_f32_16x16x32_bf16 v[76:79], v[128:131], v[236:239], v[76:79]
	v_mfma_f32_16x16x32_bf16 v[72:75], v[136:139], v[236:239], v[72:75]
	v_mfma_f32_16x16x32_bf16 v[124:127], v[132:135], v[216:219], v[124:127]
	v_mfma_f32_16x16x32_bf16 v[120:123], v[140:143], v[216:219], v[120:123]
	v_mfma_f32_16x16x32_bf16 v[108:111], v[132:135], v[224:227], v[108:111]
	v_mfma_f32_16x16x32_bf16 v[104:107], v[140:143], v[224:227], v[104:107]
	v_mfma_f32_16x16x32_bf16 v[92:95], v[132:135], v[232:235], v[92:95]
	v_mfma_f32_16x16x32_bf16 v[88:91], v[140:143], v[232:235], v[88:91]
	v_mfma_f32_16x16x32_bf16 v[76:79], v[132:135], v[240:243], v[76:79]
	v_mfma_f32_16x16x32_bf16 v[72:75], v[140:143], v[240:243], v[72:75]
	v_mfma_f32_16x16x32_bf16 v[116:119], v[172:175], v[188:191], v[116:119]
	v_mfma_f32_16x16x32_bf16 v[112:115], v[180:183], v[188:191], v[112:115]
	v_mfma_f32_16x16x32_bf16 v[100:103], v[172:175], v[220:223], v[100:103]
	v_mfma_f32_16x16x32_bf16 v[96:99], v[180:183], v[220:223], v[96:99]
	v_mfma_f32_16x16x32_bf16 v[84:87], v[172:175], v[228:231], v[84:87]
	v_mfma_f32_16x16x32_bf16 v[80:83], v[180:183], v[228:231], v[80:83]
	v_mfma_f32_16x16x32_bf16 v[68:71], v[172:175], v[236:239], v[68:71]
	v_mfma_f32_16x16x32_bf16 v[64:67], v[180:183], v[236:239], v[64:67]
	v_mfma_f32_16x16x32_bf16 v[116:119], v[176:179], v[216:219], v[116:119]
	v_mfma_f32_16x16x32_bf16 v[112:115], v[184:187], v[216:219], v[112:115]
	v_mfma_f32_16x16x32_bf16 v[100:103], v[176:179], v[224:227], v[100:103]
	v_mfma_f32_16x16x32_bf16 v[96:99], v[184:187], v[224:227], v[96:99]
	v_mfma_f32_16x16x32_bf16 v[84:87], v[176:179], v[232:235], v[84:87]
	v_mfma_f32_16x16x32_bf16 v[80:83], v[184:187], v[232:235], v[80:83]
	v_mfma_f32_16x16x32_bf16 v[68:71], v[176:179], v[240:243], v[68:71]
	v_mfma_f32_16x16x32_bf16 v[64:67], v[184:187], v[240:243], v[64:67]
	s_barrier
	s_mov_b32 m0, s35
	s_add_u32 s24, s80, 0x40080
	ds_read_b128 v[188:191], v159 offset:49152
	ds_read_b128 v[216:219], v159 offset:50176
	ds_read_b128 v[220:223], v159 offset:51200
	ds_read_b128 v[224:227], v159 offset:52224
	ds_read_b128 v[228:231], v159 offset:53248
	ds_read_b128 v[232:235], v159 offset:54272
	ds_read_b128 v[236:239], v159 offset:55296
	ds_read_b128 v[240:243], v159 offset:56320
	global_load_lds_dwordx4 v160, s[98:99]
	s_mov_b32 m0, s36
	s_addc_u32 s25, s81, 0
	global_load_lds_dwordx4 v162, s[98:99]
	s_mov_b32 m0, s41
	s_nop 0
	global_load_lds_dwordx4 v160, s[24:25]
	s_mov_b32 m0, s45
	s_nop 0
	global_load_lds_dwordx4 v162, s[24:25]
	s_mov_b32 m0, s37
	s_nop 0
	global_load_lds_dwordx4 v160, s[100:101]
	s_mov_b32 m0, s40
	s_nop 0
	global_load_lds_dwordx4 v162, s[100:101]
	s_waitcnt vmcnt(8)
	s_waitcnt lgkmcnt(0)
	s_barrier
	v_mfma_f32_16x16x32_bf16 v[60:63], v[128:131], v[188:191], v[60:63]
	v_mfma_f32_16x16x32_bf16 v[56:59], v[136:139], v[188:191], v[56:59]
	v_mfma_f32_16x16x32_bf16 v[44:47], v[128:131], v[220:223], v[44:47]
	v_mfma_f32_16x16x32_bf16 v[40:43], v[136:139], v[220:223], v[40:43]
	v_mfma_f32_16x16x32_bf16 v[28:31], v[128:131], v[228:231], v[28:31]
	v_mfma_f32_16x16x32_bf16 v[24:27], v[136:139], v[228:231], v[24:27]
	v_mfma_f32_16x16x32_bf16 v[12:15], v[128:131], v[236:239], v[12:15]
	v_mfma_f32_16x16x32_bf16 v[8:11], v[136:139], v[236:239], v[8:11]
	v_mfma_f32_16x16x32_bf16 v[60:63], v[132:135], v[216:219], v[60:63]
	v_mfma_f32_16x16x32_bf16 v[56:59], v[140:143], v[216:219], v[56:59]
	v_mfma_f32_16x16x32_bf16 v[44:47], v[132:135], v[224:227], v[44:47]
	v_mfma_f32_16x16x32_bf16 v[40:43], v[140:143], v[224:227], v[40:43]
	v_mfma_f32_16x16x32_bf16 v[28:31], v[132:135], v[232:235], v[28:31]
	v_mfma_f32_16x16x32_bf16 v[24:27], v[140:143], v[232:235], v[24:27]
	v_mfma_f32_16x16x32_bf16 v[12:15], v[132:135], v[240:243], v[12:15]
	v_mfma_f32_16x16x32_bf16 v[8:11], v[140:143], v[240:243], v[8:11]
	v_mfma_f32_16x16x32_bf16 v[52:55], v[172:175], v[188:191], v[52:55]
	v_mfma_f32_16x16x32_bf16 v[48:51], v[180:183], v[188:191], v[48:51]
	v_mfma_f32_16x16x32_bf16 v[36:39], v[172:175], v[220:223], v[36:39]
	v_mfma_f32_16x16x32_bf16 v[32:35], v[180:183], v[220:223], v[32:35]
	v_mfma_f32_16x16x32_bf16 v[20:23], v[172:175], v[228:231], v[20:23]
	v_mfma_f32_16x16x32_bf16 v[16:19], v[180:183], v[228:231], v[16:19]
	v_mfma_f32_16x16x32_bf16 v[4:7], v[172:175], v[236:239], v[4:7]
	v_mfma_f32_16x16x32_bf16 v[0:3], v[180:183], v[236:239], v[0:3]
	v_mfma_f32_16x16x32_bf16 v[52:55], v[176:179], v[216:219], v[52:55]
	v_mfma_f32_16x16x32_bf16 v[48:51], v[184:187], v[216:219], v[48:51]
	v_mfma_f32_16x16x32_bf16 v[36:39], v[176:179], v[224:227], v[36:39]
	v_mfma_f32_16x16x32_bf16 v[32:35], v[184:187], v[224:227], v[32:35]
	v_mfma_f32_16x16x32_bf16 v[20:23], v[176:179], v[232:235], v[20:23]
	v_mfma_f32_16x16x32_bf16 v[16:19], v[184:187], v[232:235], v[16:19]
	v_mfma_f32_16x16x32_bf16 v[4:7], v[176:179], v[240:243], v[4:7]
	v_mfma_f32_16x16x32_bf16 v[0:3], v[184:187], v[240:243], v[0:3]
	s_barrier
	s_add_i32 s68, s68, 2
	s_add_u32 s86, s86, 0x100
	s_addc_u32 s87, s87, 0
	s_cmp_gt_u32 s68, 13
	s_mov_b64 s[24:25], s[74:75]
	s_cbranch_scc0 .LBB0_1766
	s_and_b64 vcc, exec, s[42:43]
	s_cbranch_vccz .LBB0_1769
	s_barrier

.LBB0_1914:
	ds_read_b128 v[174:177], v143
	ds_read_b128 v[178:181], v153
	ds_read_b128 v[182:185], v159
	ds_read_b128 v[186:189], v160
	ds_read_b128 v[190:193], v161
	ds_read_b128 v[198:201], v162
	ds_read_b128 v[202:205], v163
	ds_read_b128 v[206:209], v164
	s_add_u32 s48, s24, 0xfffc0080
	s_addc_u32 s49, s25, -1
	s_cmp_eq_u32 s75, 12
	s_cselect_b32 s51, s4, s49
	s_cselect_b32 s50, s5, s48
	s_cselect_b32 s49, s39, s74
	s_cselect_b32 s48, s41, s67
	s_mov_b32 m0, s61
	ds_read_b128 v[210:213], v141
	ds_read_b128 v[214:217], v141 offset:1024
	ds_read_b128 v[218:221], v141 offset:2048
	ds_read_b128 v[222:225], v141 offset:3072
	ds_read_b128 v[226:229], v141 offset:4096
	ds_read_b128 v[230:233], v141 offset:5120
	ds_read_b128 v[234:237], v141 offset:6144
	ds_read_b128 v[238:241], v141 offset:7168
	global_load_lds_dwordx4 v132, s[24:25]
	s_mov_b32 m0, s64
	s_nop 0
	global_load_lds_dwordx4 v134, s[24:25]
	s_waitcnt vmcnt(8)
	s_waitcnt lgkmcnt(0)
	s_barrier
	v_mfma_f32_16x16x32_bf16 v[124:127], v[174:177], v[210:213], v[124:127]
	v_mfma_f32_16x16x32_bf16 v[120:123], v[182:185], v[210:213], v[120:123]
	v_mfma_f32_16x16x32_bf16 v[108:111], v[174:177], v[218:221], v[108:111]
	v_mfma_f32_16x16x32_bf16 v[104:107], v[182:185], v[218:221], v[104:107]
	v_mfma_f32_16x16x32_bf16 v[92:95], v[174:177], v[226:229], v[92:95]
	v_mfma_f32_16x16x32_bf16 v[88:91], v[182:185], v[226:229], v[88:91]
	v_mfma_f32_16x16x32_bf16 v[76:79], v[174:177], v[234:237], v[76:79]
	v_mfma_f32_16x16x32_bf16 v[72:75], v[182:185], v[234:237], v[72:75]
	v_mfma_f32_16x16x32_bf16 v[124:127], v[178:181], v[214:217], v[124:127]
	v_mfma_f32_16x16x32_bf16 v[120:123], v[186:189], v[214:217], v[120:123]
	v_mfma_f32_16x16x32_bf16 v[108:111], v[178:181], v[222:225], v[108:111]
	v_mfma_f32_16x16x32_bf16 v[104:107], v[186:189], v[222:225], v[104:107]
	v_mfma_f32_16x16x32_bf16 v[92:95], v[178:181], v[230:233], v[92:95]
	v_mfma_f32_16x16x32_bf16 v[88:91], v[186:189], v[230:233], v[88:91]
	v_mfma_f32_16x16x32_bf16 v[76:79], v[178:181], v[238:241], v[76:79]
	v_mfma_f32_16x16x32_bf16 v[72:75], v[186:189], v[238:241], v[72:75]
	v_mfma_f32_16x16x32_bf16 v[116:119], v[190:193], v[210:213], v[116:119]
	v_mfma_f32_16x16x32_bf16 v[112:115], v[202:205], v[210:213], v[112:115]
	v_mfma_f32_16x16x32_bf16 v[100:103], v[190:193], v[218:221], v[100:103]
	v_mfma_f32_16x16x32_bf16 v[96:99], v[202:205], v[218:221], v[96:99]
	v_mfma_f32_16x16x32_bf16 v[84:87], v[190:193], v[226:229], v[84:87]
	v_mfma_f32_16x16x32_bf16 v[80:83], v[202:205], v[226:229], v[80:83]
	v_mfma_f32_16x16x32_bf16 v[68:71], v[190:193], v[234:237], v[68:71]
	v_mfma_f32_16x16x32_bf16 v[64:67], v[202:205], v[234:237], v[64:67]
	v_mfma_f32_16x16x32_bf16 v[116:119], v[198:201], v[214:217], v[116:119]
	v_mfma_f32_16x16x32_bf16 v[112:115], v[206:209], v[214:217], v[112:115]
	v_mfma_f32_16x16x32_bf16 v[100:103], v[198:201], v[222:225], v[100:103]
	v_mfma_f32_16x16x32_bf16 v[96:99], v[206:209], v[222:225], v[96:99]
	v_mfma_f32_16x16x32_bf16 v[84:87], v[198:201], v[230:233], v[84:87]
	v_mfma_f32_16x16x32_bf16 v[80:83], v[206:209], v[230:233], v[80:83]
	v_mfma_f32_16x16x32_bf16 v[68:71], v[198:201], v[238:241], v[68:71]
	v_mfma_f32_16x16x32_bf16 v[64:67], v[206:209], v[238:241], v[64:67]
	s_barrier
	s_add_u32 s98, s48, s12
	s_addc_u32 s99, s49, s13
	s_add_u32 s100, s50, s12
	s_addc_u32 s101, s51, s13
	s_mov_b32 m0, s8
	s_add_u32 s68, s48, 0x40000
	ds_read_b128 v[210:213], v141 offset:16384
	ds_read_b128 v[214:217], v141 offset:17408
	ds_read_b128 v[218:221], v141 offset:18432
	ds_read_b128 v[222:225], v141 offset:19456
	ds_read_b128 v[226:229], v141 offset:20480
	ds_read_b128 v[230:233], v141 offset:21504
	ds_read_b128 v[234:237], v141 offset:22528
	ds_read_b128 v[238:241], v141 offset:23552
	global_load_lds_dwordx4 v130, s[48:49]
	s_mov_b32 m0, s9
	s_addc_u32 s69, s49, 0
	global_load_lds_dwordx4 v128, s[48:49]
	s_mov_b32 m0, s28
	s_nop 0
	global_load_lds_dwordx4 v130, s[68:69]
	s_mov_b32 m0, s29
	s_nop 0
	global_load_lds_dwordx4 v128, s[68:69]
	s_mov_b32 m0, s2
	s_nop 0
	global_load_lds_dwordx4 v130, s[50:51]
	s_mov_b32 m0, s30
	s_nop 0
	global_load_lds_dwordx4 v128, s[50:51]
	s_waitcnt vmcnt(8)
	s_waitcnt lgkmcnt(0)
	s_barrier
	v_mfma_f32_16x16x32_bf16 v[60:63], v[174:177], v[210:213], v[60:63]
	v_mfma_f32_16x16x32_bf16 v[56:59], v[182:185], v[210:213], v[56:59]
	v_mfma_f32_16x16x32_bf16 v[44:47], v[174:177], v[218:221], v[44:47]
	v_mfma_f32_16x16x32_bf16 v[40:43], v[182:185], v[218:221], v[40:43]
	v_mfma_f32_16x16x32_bf16 v[28:31], v[174:177], v[226:229], v[28:31]
	v_mfma_f32_16x16x32_bf16 v[24:27], v[182:185], v[226:229], v[24:27]
	v_mfma_f32_16x16x32_bf16 v[12:15], v[174:177], v[234:237], v[12:15]
	v_mfma_f32_16x16x32_bf16 v[8:11], v[182:185], v[234:237], v[8:11]
	v_mfma_f32_16x16x32_bf16 v[60:63], v[178:181], v[214:217], v[60:63]
	v_mfma_f32_16x16x32_bf16 v[56:59], v[186:189], v[214:217], v[56:59]
	v_mfma_f32_16x16x32_bf16 v[44:47], v[178:181], v[222:225], v[44:47]
	v_mfma_f32_16x16x32_bf16 v[40:43], v[186:189], v[222:225], v[40:43]
	v_mfma_f32_16x16x32_bf16 v[28:31], v[178:181], v[230:233], v[28:31]
	v_mfma_f32_16x16x32_bf16 v[24:27], v[186:189], v[230:233], v[24:27]
	v_mfma_f32_16x16x32_bf16 v[12:15], v[178:181], v[238:241], v[12:15]
	v_mfma_f32_16x16x32_bf16 v[8:11], v[186:189], v[238:241], v[8:11]
	v_mfma_f32_16x16x32_bf16 v[52:55], v[190:193], v[210:213], v[52:55]
	v_mfma_f32_16x16x32_bf16 v[48:51], v[202:205], v[210:213], v[48:51]
	v_mfma_f32_16x16x32_bf16 v[36:39], v[190:193], v[218:221], v[36:39]
	v_mfma_f32_16x16x32_bf16 v[32:35], v[202:205], v[218:221], v[32:35]
	v_mfma_f32_16x16x32_bf16 v[20:23], v[190:193], v[226:229], v[20:23]
	v_mfma_f32_16x16x32_bf16 v[16:19], v[202:205], v[226:229], v[16:19]
	v_mfma_f32_16x16x32_bf16 v[4:7], v[190:193], v[234:237], v[4:7]
	v_mfma_f32_16x16x32_bf16 v[0:3], v[202:205], v[234:237], v[0:3]
	v_mfma_f32_16x16x32_bf16 v[52:55], v[198:201], v[214:217], v[52:55]
	v_mfma_f32_16x16x32_bf16 v[48:51], v[206:209], v[214:217], v[48:51]
	v_mfma_f32_16x16x32_bf16 v[36:39], v[198:201], v[222:225], v[36:39]
	v_mfma_f32_16x16x32_bf16 v[32:35], v[206:209], v[222:225], v[32:35]
	v_mfma_f32_16x16x32_bf16 v[20:23], v[198:201], v[230:233], v[20:23]
	v_mfma_f32_16x16x32_bf16 v[16:19], v[206:209], v[230:233], v[16:19]
	v_mfma_f32_16x16x32_bf16 v[4:7], v[198:201], v[238:241], v[4:7]
	v_mfma_f32_16x16x32_bf16 v[0:3], v[206:209], v[238:241], v[0:3]
	s_barrier
	ds_read_b128 v[174:177], v165
	ds_read_b128 v[178:181], v166
	ds_read_b128 v[182:185], v167
	ds_read_b128 v[186:189], v168
	ds_read_b128 v[190:193], v169
	ds_read_b128 v[198:201], v170
	ds_read_b128 v[202:205], v171
	ds_read_b128 v[206:209], v172
	s_add_u32 s50, s50, 0x40000
	s_addc_u32 s51, s51, 0
	s_mov_b32 m0, s31
	ds_read_b128 v[210:213], v141 offset:32768
	ds_read_b128 v[214:217], v141 offset:33792
	ds_read_b128 v[218:221], v141 offset:34816
	ds_read_b128 v[222:225], v141 offset:35840
	ds_read_b128 v[226:229], v141 offset:36864
	ds_read_b128 v[230:233], v141 offset:37888
	ds_read_b128 v[234:237], v141 offset:38912
	ds_read_b128 v[238:241], v141 offset:39936
	global_load_lds_dwordx4 v130, s[50:51]
	s_mov_b32 m0, s33
	s_nop 0
	global_load_lds_dwordx4 v128, s[50:51]
	s_waitcnt vmcnt(8)
	s_waitcnt lgkmcnt(0)
	s_barrier
	v_mfma_f32_16x16x32_bf16 v[124:127], v[174:177], v[210:213], v[124:127]
	v_mfma_f32_16x16x32_bf16 v[120:123], v[182:185], v[210:213], v[120:123]
	v_mfma_f32_16x16x32_bf16 v[108:111], v[174:177], v[218:221], v[108:111]
	v_mfma_f32_16x16x32_bf16 v[104:107], v[182:185], v[218:221], v[104:107]
	v_mfma_f32_16x16x32_bf16 v[92:95], v[174:177], v[226:229], v[92:95]
	v_mfma_f32_16x16x32_bf16 v[88:91], v[182:185], v[226:229], v[88:91]
	v_mfma_f32_16x16x32_bf16 v[76:79], v[174:177], v[234:237], v[76:79]
	v_mfma_f32_16x16x32_bf16 v[72:75], v[182:185], v[234:237], v[72:75]
	v_mfma_f32_16x16x32_bf16 v[124:127], v[178:181], v[214:217], v[124:127]
	v_mfma_f32_16x16x32_bf16 v[120:123], v[186:189], v[214:217], v[120:123]
	v_mfma_f32_16x16x32_bf16 v[108:111], v[178:181], v[222:225], v[108:111]
	v_mfma_f32_16x16x32_bf16 v[104:107], v[186:189], v[222:225], v[104:107]
	v_mfma_f32_16x16x32_bf16 v[92:95], v[178:181], v[230:233], v[92:95]
	v_mfma_f32_16x16x32_bf16 v[88:91], v[186:189], v[230:233], v[88:91]
	v_mfma_f32_16x16x32_bf16 v[76:79], v[178:181], v[238:241], v[76:79]
	v_mfma_f32_16x16x32_bf16 v[72:75], v[186:189], v[238:241], v[72:75]
	v_mfma_f32_16x16x32_bf16 v[116:119], v[190:193], v[210:213], v[116:119]
	v_mfma_f32_16x16x32_bf16 v[112:115], v[202:205], v[210:213], v[112:115]
	v_mfma_f32_16x16x32_bf16 v[100:103], v[190:193], v[218:221], v[100:103]
	v_mfma_f32_16x16x32_bf16 v[96:99], v[202:205], v[218:221], v[96:99]
	v_mfma_f32_16x16x32_bf16 v[84:87], v[190:193], v[226:229], v[84:87]
	v_mfma_f32_16x16x32_bf16 v[80:83], v[202:205], v[226:229], v[80:83]
	v_mfma_f32_16x16x32_bf16 v[68:71], v[190:193], v[234:237], v[68:71]
	v_mfma_f32_16x16x32_bf16 v[64:67], v[202:205], v[234:237], v[64:67]
	v_mfma_f32_16x16x32_bf16 v[116:119], v[198:201], v[214:217], v[116:119]
	v_mfma_f32_16x16x32_bf16 v[112:115], v[206:209], v[214:217], v[112:115]
	v_mfma_f32_16x16x32_bf16 v[100:103], v[198:201], v[222:225], v[100:103]
	v_mfma_f32_16x16x32_bf16 v[96:99], v[206:209], v[222:225], v[96:99]
	v_mfma_f32_16x16x32_bf16 v[84:87], v[198:201], v[230:233], v[84:87]
	v_mfma_f32_16x16x32_bf16 v[80:83], v[206:209], v[230:233], v[80:83]
	v_mfma_f32_16x16x32_bf16 v[68:71], v[198:201], v[238:241], v[68:71]
	v_mfma_f32_16x16x32_bf16 v[64:67], v[206:209], v[238:241], v[64:67]
	s_barrier
	s_mov_b32 m0, s36
	s_add_u32 s48, s48, 0x40080
	ds_read_b128 v[210:213], v141 offset:49152
	ds_read_b128 v[214:217], v141 offset:50176
	ds_read_b128 v[218:221], v141 offset:51200
	ds_read_b128 v[222:225], v141 offset:52224
	ds_read_b128 v[226:229], v141 offset:53248
	ds_read_b128 v[230:233], v141 offset:54272
	ds_read_b128 v[234:237], v141 offset:55296
	ds_read_b128 v[238:241], v141 offset:56320
	global_load_lds_dwordx4 v130, s[98:99]
	s_mov_b32 m0, s37
	s_addc_u32 s49, s49, 0
	global_load_lds_dwordx4 v128, s[98:99]
	s_mov_b32 m0, s53
	s_nop 0
	global_load_lds_dwordx4 v130, s[48:49]
	s_mov_b32 m0, s54
	s_nop 0
	global_load_lds_dwordx4 v128, s[48:49]
	s_mov_b32 m0, s47
	s_nop 0
	global_load_lds_dwordx4 v130, s[100:101]
	s_mov_b32 m0, s52
	s_nop 0
	global_load_lds_dwordx4 v128, s[100:101]
	s_waitcnt vmcnt(8)
	s_waitcnt lgkmcnt(0)
	s_barrier
	v_mfma_f32_16x16x32_bf16 v[60:63], v[174:177], v[210:213], v[60:63]
	v_mfma_f32_16x16x32_bf16 v[56:59], v[182:185], v[210:213], v[56:59]
	v_mfma_f32_16x16x32_bf16 v[44:47], v[174:177], v[218:221], v[44:47]
	v_mfma_f32_16x16x32_bf16 v[40:43], v[182:185], v[218:221], v[40:43]
	v_mfma_f32_16x16x32_bf16 v[28:31], v[174:177], v[226:229], v[28:31]
	v_mfma_f32_16x16x32_bf16 v[24:27], v[182:185], v[226:229], v[24:27]
	v_mfma_f32_16x16x32_bf16 v[12:15], v[174:177], v[234:237], v[12:15]
	v_mfma_f32_16x16x32_bf16 v[8:11], v[182:185], v[234:237], v[8:11]
	v_mfma_f32_16x16x32_bf16 v[60:63], v[178:181], v[214:217], v[60:63]
	v_mfma_f32_16x16x32_bf16 v[56:59], v[186:189], v[214:217], v[56:59]
	v_mfma_f32_16x16x32_bf16 v[44:47], v[178:181], v[222:225], v[44:47]
	v_mfma_f32_16x16x32_bf16 v[40:43], v[186:189], v[222:225], v[40:43]
	v_mfma_f32_16x16x32_bf16 v[28:31], v[178:181], v[230:233], v[28:31]
	v_mfma_f32_16x16x32_bf16 v[24:27], v[186:189], v[230:233], v[24:27]
	v_mfma_f32_16x16x32_bf16 v[12:15], v[178:181], v[238:241], v[12:15]
	v_mfma_f32_16x16x32_bf16 v[8:11], v[186:189], v[238:241], v[8:11]
	v_mfma_f32_16x16x32_bf16 v[52:55], v[190:193], v[210:213], v[52:55]
	v_mfma_f32_16x16x32_bf16 v[48:51], v[202:205], v[210:213], v[48:51]
	v_mfma_f32_16x16x32_bf16 v[36:39], v[190:193], v[218:221], v[36:39]
	v_mfma_f32_16x16x32_bf16 v[32:35], v[202:205], v[218:221], v[32:35]
	v_mfma_f32_16x16x32_bf16 v[20:23], v[190:193], v[226:229], v[20:23]
	v_mfma_f32_16x16x32_bf16 v[16:19], v[202:205], v[226:229], v[16:19]
	v_mfma_f32_16x16x32_bf16 v[4:7], v[190:193], v[234:237], v[4:7]
	v_mfma_f32_16x16x32_bf16 v[0:3], v[202:205], v[234:237], v[0:3]
	v_mfma_f32_16x16x32_bf16 v[52:55], v[198:201], v[214:217], v[52:55]
	v_mfma_f32_16x16x32_bf16 v[48:51], v[206:209], v[214:217], v[48:51]
	v_mfma_f32_16x16x32_bf16 v[36:39], v[198:201], v[222:225], v[36:39]
	v_mfma_f32_16x16x32_bf16 v[32:35], v[206:209], v[222:225], v[32:35]
	v_mfma_f32_16x16x32_bf16 v[20:23], v[198:201], v[230:233], v[20:23]
	v_mfma_f32_16x16x32_bf16 v[16:19], v[206:209], v[230:233], v[16:19]
	v_mfma_f32_16x16x32_bf16 v[4:7], v[198:201], v[238:241], v[4:7]
	v_mfma_f32_16x16x32_bf16 v[0:3], v[206:209], v[238:241], v[0:3]
	s_barrier
	s_add_i32 s75, s75, 2
	s_add_u32 s24, s24, 0x100
	s_addc_u32 s25, s25, 0
	s_add_u32 s67, s67, 0x100
	s_addc_u32 s74, s74, 0
	s_cmp_gt_u32 s75, 13
	s_cbranch_scc0 .LBB0_1914
	s_and_b64 vcc, exec, s[14:15]
	s_cbranch_vccz .LBB0_1917
	s_barrier

.LBB0_1994:
	ds_read_b128 v[128:131], v199
	ds_read_b128 v[132:135], v200
	ds_read_b128 v[136:139], v201
	ds_read_b128 v[140:143], v202
	ds_read_b128 v[172:175], v203
	ds_read_b128 v[176:179], v204
	ds_read_b128 v[180:183], v205
	ds_read_b128 v[184:187], v206
	s_add_u32 s48, s24, 0x100
	s_addc_u32 s49, s25, 0
	s_cmp_eq_u32 s68, 40
	s_cselect_b32 s55, s13, s49
	s_cselect_b32 s54, s12, s48
	s_cselect_b32 s51, s47, s5
	s_cselect_b32 s50, s46, s4
	s_mov_b32 m0, s64
	ds_read_b128 v[188:191], v159
	ds_read_b128 v[216:219], v159 offset:1024
	ds_read_b128 v[220:223], v159 offset:2048
	ds_read_b128 v[224:227], v159 offset:3072
	ds_read_b128 v[228:231], v159 offset:4096
	ds_read_b128 v[232:235], v159 offset:5120
	ds_read_b128 v[236:239], v159 offset:6144
	ds_read_b128 v[240:243], v159 offset:7168
	global_load_lds_dwordx4 v164, s[24:25]
	s_mov_b32 m0, s65
	s_nop 0
	global_load_lds_dwordx4 v166, s[24:25]
	s_waitcnt vmcnt(8)
	s_waitcnt lgkmcnt(0)
	s_barrier
	v_mfma_f32_16x16x32_bf16 v[124:127], v[128:131], v[188:191], v[124:127]
	v_mfma_f32_16x16x32_bf16 v[120:123], v[136:139], v[188:191], v[120:123]
	v_mfma_f32_16x16x32_bf16 v[108:111], v[128:131], v[220:223], v[108:111]
	v_mfma_f32_16x16x32_bf16 v[104:107], v[136:139], v[220:223], v[104:107]
	v_mfma_f32_16x16x32_bf16 v[92:95], v[128:131], v[228:231], v[92:95]
	v_mfma_f32_16x16x32_bf16 v[88:91], v[136:139], v[228:231], v[88:91]
	v_mfma_f32_16x16x32_bf16 v[76:79], v[128:131], v[236:239], v[76:79]
	v_mfma_f32_16x16x32_bf16 v[72:75], v[136:139], v[236:239], v[72:75]
	v_mfma_f32_16x16x32_bf16 v[124:127], v[132:135], v[216:219], v[124:127]
	v_mfma_f32_16x16x32_bf16 v[120:123], v[140:143], v[216:219], v[120:123]
	v_mfma_f32_16x16x32_bf16 v[108:111], v[132:135], v[224:227], v[108:111]
	v_mfma_f32_16x16x32_bf16 v[104:107], v[140:143], v[224:227], v[104:107]
	v_mfma_f32_16x16x32_bf16 v[92:95], v[132:135], v[232:235], v[92:95]
	v_mfma_f32_16x16x32_bf16 v[88:91], v[140:143], v[232:235], v[88:91]
	v_mfma_f32_16x16x32_bf16 v[76:79], v[132:135], v[240:243], v[76:79]
	v_mfma_f32_16x16x32_bf16 v[72:75], v[140:143], v[240:243], v[72:75]
	v_mfma_f32_16x16x32_bf16 v[116:119], v[172:175], v[188:191], v[116:119]
	v_mfma_f32_16x16x32_bf16 v[112:115], v[180:183], v[188:191], v[112:115]
	v_mfma_f32_16x16x32_bf16 v[100:103], v[172:175], v[220:223], v[100:103]
	v_mfma_f32_16x16x32_bf16 v[96:99], v[180:183], v[220:223], v[96:99]
	v_mfma_f32_16x16x32_bf16 v[84:87], v[172:175], v[228:231], v[84:87]
	v_mfma_f32_16x16x32_bf16 v[80:83], v[180:183], v[228:231], v[80:83]
	v_mfma_f32_16x16x32_bf16 v[68:71], v[172:175], v[236:239], v[68:71]
	v_mfma_f32_16x16x32_bf16 v[64:67], v[180:183], v[236:239], v[64:67]
	v_mfma_f32_16x16x32_bf16 v[116:119], v[176:179], v[216:219], v[116:119]
	v_mfma_f32_16x16x32_bf16 v[112:115], v[184:187], v[216:219], v[112:115]
	v_mfma_f32_16x16x32_bf16 v[100:103], v[176:179], v[224:227], v[100:103]
	v_mfma_f32_16x16x32_bf16 v[96:99], v[184:187], v[224:227], v[96:99]
	v_mfma_f32_16x16x32_bf16 v[84:87], v[176:179], v[232:235], v[84:87]
	v_mfma_f32_16x16x32_bf16 v[80:83], v[184:187], v[232:235], v[80:83]
	v_mfma_f32_16x16x32_bf16 v[68:71], v[176:179], v[240:243], v[68:71]
	v_mfma_f32_16x16x32_bf16 v[64:67], v[184:187], v[240:243], v[64:67]
	s_barrier
	s_add_u32 s98, s50, s40
	s_addc_u32 s99, s51, s41
	s_add_u32 s100, s54, s40
	s_addc_u32 s101, s55, s41
	s_mov_b32 m0, s7
	s_add_u32 s24, s50, 0xb0000
	ds_read_b128 v[188:191], v159 offset:16384
	ds_read_b128 v[216:219], v159 offset:17408
	ds_read_b128 v[220:223], v159 offset:18432
	ds_read_b128 v[224:227], v159 offset:19456
	ds_read_b128 v[228:231], v159 offset:20480
	ds_read_b128 v[232:235], v159 offset:21504
	ds_read_b128 v[236:239], v159 offset:22528
	ds_read_b128 v[240:243], v159 offset:23552
	global_load_lds_dwordx4 v160, s[50:51]
	s_mov_b32 m0, s8
	s_addc_u32 s25, s51, 0
	global_load_lds_dwordx4 v162, s[50:51]
	s_mov_b32 m0, s9
	s_nop 0
	global_load_lds_dwordx4 v160, s[24:25]
	s_mov_b32 m0, s28
	s_nop 0
	global_load_lds_dwordx4 v162, s[24:25]
	s_mov_b32 m0, s6
	s_nop 0
	global_load_lds_dwordx4 v160, s[54:55]
	s_mov_b32 m0, s29
	s_nop 0
	global_load_lds_dwordx4 v162, s[54:55]
	s_waitcnt vmcnt(8)
	s_waitcnt lgkmcnt(0)
	s_barrier
	v_mfma_f32_16x16x32_bf16 v[60:63], v[128:131], v[188:191], v[60:63]
	v_mfma_f32_16x16x32_bf16 v[56:59], v[136:139], v[188:191], v[56:59]
	v_mfma_f32_16x16x32_bf16 v[44:47], v[128:131], v[220:223], v[44:47]
	v_mfma_f32_16x16x32_bf16 v[40:43], v[136:139], v[220:223], v[40:43]
	v_mfma_f32_16x16x32_bf16 v[28:31], v[128:131], v[228:231], v[28:31]
	v_mfma_f32_16x16x32_bf16 v[24:27], v[136:139], v[228:231], v[24:27]
	v_mfma_f32_16x16x32_bf16 v[12:15], v[128:131], v[236:239], v[12:15]
	v_mfma_f32_16x16x32_bf16 v[8:11], v[136:139], v[236:239], v[8:11]
	v_mfma_f32_16x16x32_bf16 v[60:63], v[132:135], v[216:219], v[60:63]
	v_mfma_f32_16x16x32_bf16 v[56:59], v[140:143], v[216:219], v[56:59]
	v_mfma_f32_16x16x32_bf16 v[44:47], v[132:135], v[224:227], v[44:47]
	v_mfma_f32_16x16x32_bf16 v[40:43], v[140:143], v[224:227], v[40:43]
	v_mfma_f32_16x16x32_bf16 v[28:31], v[132:135], v[232:235], v[28:31]
	v_mfma_f32_16x16x32_bf16 v[24:27], v[140:143], v[232:235], v[24:27]
	v_mfma_f32_16x16x32_bf16 v[12:15], v[132:135], v[240:243], v[12:15]
	v_mfma_f32_16x16x32_bf16 v[8:11], v[140:143], v[240:243], v[8:11]
	v_mfma_f32_16x16x32_bf16 v[52:55], v[172:175], v[188:191], v[52:55]
	v_mfma_f32_16x16x32_bf16 v[48:51], v[180:183], v[188:191], v[48:51]
	v_mfma_f32_16x16x32_bf16 v[36:39], v[172:175], v[220:223], v[36:39]
	v_mfma_f32_16x16x32_bf16 v[32:35], v[180:183], v[220:223], v[32:35]
	v_mfma_f32_16x16x32_bf16 v[20:23], v[172:175], v[228:231], v[20:23]
	v_mfma_f32_16x16x32_bf16 v[16:19], v[180:183], v[228:231], v[16:19]
	v_mfma_f32_16x16x32_bf16 v[4:7], v[172:175], v[236:239], v[4:7]
	v_mfma_f32_16x16x32_bf16 v[0:3], v[180:183], v[236:239], v[0:3]
	v_mfma_f32_16x16x32_bf16 v[52:55], v[176:179], v[216:219], v[52:55]
	v_mfma_f32_16x16x32_bf16 v[48:51], v[184:187], v[216:219], v[48:51]
	v_mfma_f32_16x16x32_bf16 v[36:39], v[176:179], v[224:227], v[36:39]
	v_mfma_f32_16x16x32_bf16 v[32:35], v[184:187], v[224:227], v[32:35]
	v_mfma_f32_16x16x32_bf16 v[20:23], v[176:179], v[232:235], v[20:23]
	v_mfma_f32_16x16x32_bf16 v[16:19], v[184:187], v[232:235], v[16:19]
	v_mfma_f32_16x16x32_bf16 v[4:7], v[176:179], v[240:243], v[4:7]
	v_mfma_f32_16x16x32_bf16 v[0:3], v[184:187], v[240:243], v[0:3]
	s_barrier
	ds_read_b128 v[128:131], v207
	ds_read_b128 v[132:135], v208
	ds_read_b128 v[136:139], v209
	ds_read_b128 v[140:143], v210
	ds_read_b128 v[172:175], v211
	ds_read_b128 v[176:179], v212
	ds_read_b128 v[180:183], v213
	ds_read_b128 v[184:187], v214
	s_add_u32 s24, s54, 0xb0000
	s_addc_u32 s25, s55, 0
	s_mov_b32 m0, s30
	ds_read_b128 v[188:191], v159 offset:32768
	ds_read_b128 v[216:219], v159 offset:33792
	ds_read_b128 v[220:223], v159 offset:34816
	ds_read_b128 v[224:227], v159 offset:35840
	ds_read_b128 v[228:231], v159 offset:36864
	ds_read_b128 v[232:235], v159 offset:37888
	ds_read_b128 v[236:239], v159 offset:38912
	ds_read_b128 v[240:243], v159 offset:39936
	global_load_lds_dwordx4 v160, s[24:25]
	s_mov_b32 m0, s31
	s_nop 0
	global_load_lds_dwordx4 v162, s[24:25]
	s_waitcnt vmcnt(8)
	s_waitcnt lgkmcnt(0)
	s_barrier
	v_mfma_f32_16x16x32_bf16 v[124:127], v[128:131], v[188:191], v[124:127]
	v_mfma_f32_16x16x32_bf16 v[120:123], v[136:139], v[188:191], v[120:123]
	v_mfma_f32_16x16x32_bf16 v[108:111], v[128:131], v[220:223], v[108:111]
	v_mfma_f32_16x16x32_bf16 v[104:107], v[136:139], v[220:223], v[104:107]
	v_mfma_f32_16x16x32_bf16 v[92:95], v[128:131], v[228:231], v[92:95]
	v_mfma_f32_16x16x32_bf16 v[88:91], v[136:139], v[228:231], v[88:91]
	v_mfma_f32_16x16x32_bf16 v[76:79], v[128:131], v[236:239], v[76:79]
	v_mfma_f32_16x16x32_bf16 v[72:75], v[136:139], v[236:239], v[72:75]
	v_mfma_f32_16x16x32_bf16 v[124:127], v[132:135], v[216:219], v[124:127]
	v_mfma_f32_16x16x32_bf16 v[120:123], v[140:143], v[216:219], v[120:123]
	v_mfma_f32_16x16x32_bf16 v[108:111], v[132:135], v[224:227], v[108:111]
	v_mfma_f32_16x16x32_bf16 v[104:107], v[140:143], v[224:227], v[104:107]
	v_mfma_f32_16x16x32_bf16 v[92:95], v[132:135], v[232:235], v[92:95]
	v_mfma_f32_16x16x32_bf16 v[88:91], v[140:143], v[232:235], v[88:91]
	v_mfma_f32_16x16x32_bf16 v[76:79], v[132:135], v[240:243], v[76:79]
	v_mfma_f32_16x16x32_bf16 v[72:75], v[140:143], v[240:243], v[72:75]
	v_mfma_f32_16x16x32_bf16 v[116:119], v[172:175], v[188:191], v[116:119]
	v_mfma_f32_16x16x32_bf16 v[112:115], v[180:183], v[188:191], v[112:115]
	v_mfma_f32_16x16x32_bf16 v[100:103], v[172:175], v[220:223], v[100:103]
	v_mfma_f32_16x16x32_bf16 v[96:99], v[180:183], v[220:223], v[96:99]
	v_mfma_f32_16x16x32_bf16 v[84:87], v[172:175], v[228:231], v[84:87]
	v_mfma_f32_16x16x32_bf16 v[80:83], v[180:183], v[228:231], v[80:83]
	v_mfma_f32_16x16x32_bf16 v[68:71], v[172:175], v[236:239], v[68:71]
	v_mfma_f32_16x16x32_bf16 v[64:67], v[180:183], v[236:239], v[64:67]
	v_mfma_f32_16x16x32_bf16 v[116:119], v[176:179], v[216:219], v[116:119]
	v_mfma_f32_16x16x32_bf16 v[112:115], v[184:187], v[216:219], v[112:115]
	v_mfma_f32_16x16x32_bf16 v[100:103], v[176:179], v[224:227], v[100:103]
	v_mfma_f32_16x16x32_bf16 v[96:99], v[184:187], v[224:227], v[96:99]
	v_mfma_f32_16x16x32_bf16 v[84:87], v[176:179], v[232:235], v[84:87]
	v_mfma_f32_16x16x32_bf16 v[80:83], v[184:187], v[232:235], v[80:83]
	v_mfma_f32_16x16x32_bf16 v[68:71], v[176:179], v[240:243], v[68:71]
	v_mfma_f32_16x16x32_bf16 v[64:67], v[184:187], v[240:243], v[64:67]
	s_barrier
	s_mov_b32 m0, s33
	s_add_u32 s24, s50, 0xb0080
	ds_read_b128 v[188:191], v159 offset:49152
	ds_read_b128 v[216:219], v159 offset:50176
	ds_read_b128 v[220:223], v159 offset:51200
	ds_read_b128 v[224:227], v159 offset:52224
	ds_read_b128 v[228:231], v159 offset:53248
	ds_read_b128 v[232:235], v159 offset:54272
	ds_read_b128 v[236:239], v159 offset:55296
	ds_read_b128 v[240:243], v159 offset:56320
	global_load_lds_dwordx4 v160, s[98:99]
	s_mov_b32 m0, s34
	s_addc_u32 s25, s51, 0
	global_load_lds_dwordx4 v162, s[98:99]
	s_mov_b32 m0, s37
	s_nop 0
	global_load_lds_dwordx4 v160, s[24:25]
	s_mov_b32 m0, s45
	s_nop 0
	global_load_lds_dwordx4 v162, s[24:25]
	s_mov_b32 m0, s35
	s_nop 0
	global_load_lds_dwordx4 v160, s[100:101]
	s_mov_b32 m0, s36
	s_nop 0
	global_load_lds_dwordx4 v162, s[100:101]
	s_waitcnt vmcnt(8)
	s_waitcnt lgkmcnt(0)
	s_barrier
	v_mfma_f32_16x16x32_bf16 v[60:63], v[128:131], v[188:191], v[60:63]
	v_mfma_f32_16x16x32_bf16 v[56:59], v[136:139], v[188:191], v[56:59]
	v_mfma_f32_16x16x32_bf16 v[44:47], v[128:131], v[220:223], v[44:47]
	v_mfma_f32_16x16x32_bf16 v[40:43], v[136:139], v[220:223], v[40:43]
	v_mfma_f32_16x16x32_bf16 v[28:31], v[128:131], v[228:231], v[28:31]
	v_mfma_f32_16x16x32_bf16 v[24:27], v[136:139], v[228:231], v[24:27]
	v_mfma_f32_16x16x32_bf16 v[12:15], v[128:131], v[236:239], v[12:15]
	v_mfma_f32_16x16x32_bf16 v[8:11], v[136:139], v[236:239], v[8:11]
	v_mfma_f32_16x16x32_bf16 v[60:63], v[132:135], v[216:219], v[60:63]
	v_mfma_f32_16x16x32_bf16 v[56:59], v[140:143], v[216:219], v[56:59]
	v_mfma_f32_16x16x32_bf16 v[44:47], v[132:135], v[224:227], v[44:47]
	v_mfma_f32_16x16x32_bf16 v[40:43], v[140:143], v[224:227], v[40:43]
	v_mfma_f32_16x16x32_bf16 v[28:31], v[132:135], v[232:235], v[28:31]
	v_mfma_f32_16x16x32_bf16 v[24:27], v[140:143], v[232:235], v[24:27]
	v_mfma_f32_16x16x32_bf16 v[12:15], v[132:135], v[240:243], v[12:15]
	v_mfma_f32_16x16x32_bf16 v[8:11], v[140:143], v[240:243], v[8:11]
	v_mfma_f32_16x16x32_bf16 v[52:55], v[172:175], v[188:191], v[52:55]
	v_mfma_f32_16x16x32_bf16 v[48:51], v[180:183], v[188:191], v[48:51]
	v_mfma_f32_16x16x32_bf16 v[36:39], v[172:175], v[220:223], v[36:39]
	v_mfma_f32_16x16x32_bf16 v[32:35], v[180:183], v[220:223], v[32:35]
	v_mfma_f32_16x16x32_bf16 v[20:23], v[172:175], v[228:231], v[20:23]
	v_mfma_f32_16x16x32_bf16 v[16:19], v[180:183], v[228:231], v[16:19]
	v_mfma_f32_16x16x32_bf16 v[4:7], v[172:175], v[236:239], v[4:7]
	v_mfma_f32_16x16x32_bf16 v[0:3], v[180:183], v[236:239], v[0:3]
	v_mfma_f32_16x16x32_bf16 v[52:55], v[176:179], v[216:219], v[52:55]
	v_mfma_f32_16x16x32_bf16 v[48:51], v[184:187], v[216:219], v[48:51]
	v_mfma_f32_16x16x32_bf16 v[36:39], v[176:179], v[224:227], v[36:39]
	v_mfma_f32_16x16x32_bf16 v[32:35], v[184:187], v[224:227], v[32:35]
	v_mfma_f32_16x16x32_bf16 v[20:23], v[176:179], v[232:235], v[20:23]
	v_mfma_f32_16x16x32_bf16 v[16:19], v[184:187], v[232:235], v[16:19]
	v_mfma_f32_16x16x32_bf16 v[4:7], v[176:179], v[240:243], v[4:7]
	v_mfma_f32_16x16x32_bf16 v[0:3], v[184:187], v[240:243], v[0:3]
	s_barrier
	s_add_i32 s68, s68, 2
	s_add_u32 s4, s4, 0x100
	s_addc_u32 s5, s5, 0
	s_cmp_gt_u32 s68, 41
	s_mov_b64 s[24:25], s[48:49]
	s_cbranch_scc0 .LBB0_1994
	s_and_b64 vcc, exec, s[42:43]
	s_cbranch_vccz .LBB0_1997
	s_barrier

.LBB0_2152:
	ds_read_b128 v[160:163], v169
	ds_read_b128 v[164:167], v170
	ds_read_b128 v[186:189], v171
	ds_read_b128 v[190:193], v172
	ds_read_b128 v[198:201], v173
	ds_read_b128 v[202:205], v174
	ds_read_b128 v[206:209], v175
	ds_read_b128 v[210:213], v176
	s_add_u32 s18, s16, 0xfffc0080
	s_addc_u32 s19, s17, -1
	s_cmp_eq_u32 s66, 12
	s_cselect_b32 s25, s4, s19
	s_cselect_b32 s24, s5, s18
	s_cselect_b32 s19, s13, s49
	s_cselect_b32 s18, s15, s47
	s_mov_b32 m0, s64
	ds_read_b128 v[214:217], v159
	ds_read_b128 v[218:221], v159 offset:1024
	ds_read_b128 v[222:225], v159 offset:2048
	ds_read_b128 v[226:229], v159 offset:3072
	ds_read_b128 v[230:233], v159 offset:4096
	ds_read_b128 v[234:237], v159 offset:5120
	ds_read_b128 v[238:241], v159 offset:6144
	ds_read_b128 v[242:245], v159 offset:7168
	global_load_lds_dwordx4 v134, s[16:17]
	s_mov_b32 m0, s65
	s_nop 0
	global_load_lds_dwordx4 v136, s[16:17]
	s_waitcnt vmcnt(8)
	s_waitcnt lgkmcnt(0)
	s_barrier
	v_mfma_f32_16x16x32_bf16 v[124:127], v[160:163], v[214:217], v[124:127]
	v_mfma_f32_16x16x32_bf16 v[120:123], v[186:189], v[214:217], v[120:123]
	v_mfma_f32_16x16x32_bf16 v[108:111], v[160:163], v[222:225], v[108:111]
	v_mfma_f32_16x16x32_bf16 v[104:107], v[186:189], v[222:225], v[104:107]
	v_mfma_f32_16x16x32_bf16 v[92:95], v[160:163], v[230:233], v[92:95]
	v_mfma_f32_16x16x32_bf16 v[88:91], v[186:189], v[230:233], v[88:91]
	v_mfma_f32_16x16x32_bf16 v[76:79], v[160:163], v[238:241], v[76:79]
	v_mfma_f32_16x16x32_bf16 v[72:75], v[186:189], v[238:241], v[72:75]
	v_mfma_f32_16x16x32_bf16 v[124:127], v[164:167], v[218:221], v[124:127]
	v_mfma_f32_16x16x32_bf16 v[120:123], v[190:193], v[218:221], v[120:123]
	v_mfma_f32_16x16x32_bf16 v[108:111], v[164:167], v[226:229], v[108:111]
	v_mfma_f32_16x16x32_bf16 v[104:107], v[190:193], v[226:229], v[104:107]
	v_mfma_f32_16x16x32_bf16 v[92:95], v[164:167], v[234:237], v[92:95]
	v_mfma_f32_16x16x32_bf16 v[88:91], v[190:193], v[234:237], v[88:91]
	v_mfma_f32_16x16x32_bf16 v[76:79], v[164:167], v[242:245], v[76:79]
	v_mfma_f32_16x16x32_bf16 v[72:75], v[190:193], v[242:245], v[72:75]
	v_mfma_f32_16x16x32_bf16 v[116:119], v[198:201], v[214:217], v[116:119]
	v_mfma_f32_16x16x32_bf16 v[112:115], v[206:209], v[214:217], v[112:115]
	v_mfma_f32_16x16x32_bf16 v[100:103], v[198:201], v[222:225], v[100:103]
	v_mfma_f32_16x16x32_bf16 v[96:99], v[206:209], v[222:225], v[96:99]
	v_mfma_f32_16x16x32_bf16 v[84:87], v[198:201], v[230:233], v[84:87]
	v_mfma_f32_16x16x32_bf16 v[80:83], v[206:209], v[230:233], v[80:83]
	v_mfma_f32_16x16x32_bf16 v[68:71], v[198:201], v[238:241], v[68:71]
	v_mfma_f32_16x16x32_bf16 v[64:67], v[206:209], v[238:241], v[64:67]
	v_mfma_f32_16x16x32_bf16 v[116:119], v[202:205], v[218:221], v[116:119]
	v_mfma_f32_16x16x32_bf16 v[112:115], v[210:213], v[218:221], v[112:115]
	v_mfma_f32_16x16x32_bf16 v[100:103], v[202:205], v[226:229], v[100:103]
	v_mfma_f32_16x16x32_bf16 v[96:99], v[210:213], v[226:229], v[96:99]
	v_mfma_f32_16x16x32_bf16 v[84:87], v[202:205], v[234:237], v[84:87]
	v_mfma_f32_16x16x32_bf16 v[80:83], v[210:213], v[234:237], v[80:83]
	v_mfma_f32_16x16x32_bf16 v[68:71], v[202:205], v[242:245], v[68:71]
	v_mfma_f32_16x16x32_bf16 v[64:67], v[210:213], v[242:245], v[64:67]
	s_barrier
	s_add_u32 s98, s18, s42
	s_addc_u32 s99, s19, s43
	s_add_u32 s100, s24, s42
	s_addc_u32 s101, s25, s43
	s_mov_b32 m0, s6
	s_add_u32 s68, s18, 0x40000
	ds_read_b128 v[214:217], v159 offset:16384
	ds_read_b128 v[218:221], v159 offset:17408
	ds_read_b128 v[222:225], v159 offset:18432
	ds_read_b128 v[226:229], v159 offset:19456
	ds_read_b128 v[230:233], v159 offset:20480
	ds_read_b128 v[234:237], v159 offset:21504
	ds_read_b128 v[238:241], v159 offset:22528
	ds_read_b128 v[242:245], v159 offset:23552
	global_load_lds_dwordx4 v128, s[18:19]
	s_mov_b32 m0, s7
	s_addc_u32 s69, s19, 0
	global_load_lds_dwordx4 v130, s[18:19]
	s_mov_b32 m0, s8
	s_nop 0
	global_load_lds_dwordx4 v128, s[68:69]
	s_mov_b32 m0, s9
	s_nop 0
	global_load_lds_dwordx4 v130, s[68:69]
	s_mov_b32 m0, s2
	s_nop 0
	global_load_lds_dwordx4 v128, s[24:25]
	s_mov_b32 m0, s28
	s_nop 0
	global_load_lds_dwordx4 v130, s[24:25]
	s_waitcnt vmcnt(8)
	s_waitcnt lgkmcnt(0)
	s_barrier
	v_mfma_f32_16x16x32_bf16 v[60:63], v[160:163], v[214:217], v[60:63]
	v_mfma_f32_16x16x32_bf16 v[56:59], v[186:189], v[214:217], v[56:59]
	v_mfma_f32_16x16x32_bf16 v[44:47], v[160:163], v[222:225], v[44:47]
	v_mfma_f32_16x16x32_bf16 v[40:43], v[186:189], v[222:225], v[40:43]
	v_mfma_f32_16x16x32_bf16 v[28:31], v[160:163], v[230:233], v[28:31]
	v_mfma_f32_16x16x32_bf16 v[24:27], v[186:189], v[230:233], v[24:27]
	v_mfma_f32_16x16x32_bf16 v[12:15], v[160:163], v[238:241], v[12:15]
	v_mfma_f32_16x16x32_bf16 v[8:11], v[186:189], v[238:241], v[8:11]
	v_mfma_f32_16x16x32_bf16 v[60:63], v[164:167], v[218:221], v[60:63]
	v_mfma_f32_16x16x32_bf16 v[56:59], v[190:193], v[218:221], v[56:59]
	v_mfma_f32_16x16x32_bf16 v[44:47], v[164:167], v[226:229], v[44:47]
	v_mfma_f32_16x16x32_bf16 v[40:43], v[190:193], v[226:229], v[40:43]
	v_mfma_f32_16x16x32_bf16 v[28:31], v[164:167], v[234:237], v[28:31]
	v_mfma_f32_16x16x32_bf16 v[24:27], v[190:193], v[234:237], v[24:27]
	v_mfma_f32_16x16x32_bf16 v[12:15], v[164:167], v[242:245], v[12:15]
	v_mfma_f32_16x16x32_bf16 v[8:11], v[190:193], v[242:245], v[8:11]
	v_mfma_f32_16x16x32_bf16 v[52:55], v[198:201], v[214:217], v[52:55]
	v_mfma_f32_16x16x32_bf16 v[48:51], v[206:209], v[214:217], v[48:51]
	v_mfma_f32_16x16x32_bf16 v[36:39], v[198:201], v[222:225], v[36:39]
	v_mfma_f32_16x16x32_bf16 v[32:35], v[206:209], v[222:225], v[32:35]
	v_mfma_f32_16x16x32_bf16 v[20:23], v[198:201], v[230:233], v[20:23]
	v_mfma_f32_16x16x32_bf16 v[16:19], v[206:209], v[230:233], v[16:19]
	v_mfma_f32_16x16x32_bf16 v[4:7], v[198:201], v[238:241], v[4:7]
	v_mfma_f32_16x16x32_bf16 v[0:3], v[206:209], v[238:241], v[0:3]
	v_mfma_f32_16x16x32_bf16 v[52:55], v[202:205], v[218:221], v[52:55]
	v_mfma_f32_16x16x32_bf16 v[48:51], v[210:213], v[218:221], v[48:51]
	v_mfma_f32_16x16x32_bf16 v[36:39], v[202:205], v[226:229], v[36:39]
	v_mfma_f32_16x16x32_bf16 v[32:35], v[210:213], v[226:229], v[32:35]
	v_mfma_f32_16x16x32_bf16 v[20:23], v[202:205], v[234:237], v[20:23]
	v_mfma_f32_16x16x32_bf16 v[16:19], v[210:213], v[234:237], v[16:19]
	v_mfma_f32_16x16x32_bf16 v[4:7], v[202:205], v[242:245], v[4:7]
	v_mfma_f32_16x16x32_bf16 v[0:3], v[210:213], v[242:245], v[0:3]
	s_barrier
	ds_read_b128 v[160:163], v177
	ds_read_b128 v[164:167], v178
	ds_read_b128 v[186:189], v179
	ds_read_b128 v[190:193], v180
	ds_read_b128 v[198:201], v181
	ds_read_b128 v[202:205], v182
	ds_read_b128 v[206:209], v183
	ds_read_b128 v[210:213], v184
	s_add_u32 s24, s24, 0x40000
	s_addc_u32 s25, s25, 0
	s_mov_b32 m0, s29
	ds_read_b128 v[214:217], v159 offset:32768
	ds_read_b128 v[218:221], v159 offset:33792
	ds_read_b128 v[222:225], v159 offset:34816
	ds_read_b128 v[226:229], v159 offset:35840
	ds_read_b128 v[230:233], v159 offset:36864
	ds_read_b128 v[234:237], v159 offset:37888
	ds_read_b128 v[238:241], v159 offset:38912
	ds_read_b128 v[242:245], v159 offset:39936
	global_load_lds_dwordx4 v128, s[24:25]
	s_mov_b32 m0, s30
	s_nop 0
	global_load_lds_dwordx4 v130, s[24:25]
	s_waitcnt vmcnt(8)
	s_waitcnt lgkmcnt(0)
	s_barrier
	v_mfma_f32_16x16x32_bf16 v[124:127], v[160:163], v[214:217], v[124:127]
	v_mfma_f32_16x16x32_bf16 v[120:123], v[186:189], v[214:217], v[120:123]
	v_mfma_f32_16x16x32_bf16 v[108:111], v[160:163], v[222:225], v[108:111]
	v_mfma_f32_16x16x32_bf16 v[104:107], v[186:189], v[222:225], v[104:107]
	v_mfma_f32_16x16x32_bf16 v[92:95], v[160:163], v[230:233], v[92:95]
	v_mfma_f32_16x16x32_bf16 v[88:91], v[186:189], v[230:233], v[88:91]
	v_mfma_f32_16x16x32_bf16 v[76:79], v[160:163], v[238:241], v[76:79]
	v_mfma_f32_16x16x32_bf16 v[72:75], v[186:189], v[238:241], v[72:75]
	v_mfma_f32_16x16x32_bf16 v[124:127], v[164:167], v[218:221], v[124:127]
	v_mfma_f32_16x16x32_bf16 v[120:123], v[190:193], v[218:221], v[120:123]
	v_mfma_f32_16x16x32_bf16 v[108:111], v[164:167], v[226:229], v[108:111]
	v_mfma_f32_16x16x32_bf16 v[104:107], v[190:193], v[226:229], v[104:107]
	v_mfma_f32_16x16x32_bf16 v[92:95], v[164:167], v[234:237], v[92:95]
	v_mfma_f32_16x16x32_bf16 v[88:91], v[190:193], v[234:237], v[88:91]
	v_mfma_f32_16x16x32_bf16 v[76:79], v[164:167], v[242:245], v[76:79]
	v_mfma_f32_16x16x32_bf16 v[72:75], v[190:193], v[242:245], v[72:75]
	v_mfma_f32_16x16x32_bf16 v[116:119], v[198:201], v[214:217], v[116:119]
	v_mfma_f32_16x16x32_bf16 v[112:115], v[206:209], v[214:217], v[112:115]
	v_mfma_f32_16x16x32_bf16 v[100:103], v[198:201], v[222:225], v[100:103]
	v_mfma_f32_16x16x32_bf16 v[96:99], v[206:209], v[222:225], v[96:99]
	v_mfma_f32_16x16x32_bf16 v[84:87], v[198:201], v[230:233], v[84:87]
	v_mfma_f32_16x16x32_bf16 v[80:83], v[206:209], v[230:233], v[80:83]
	v_mfma_f32_16x16x32_bf16 v[68:71], v[198:201], v[238:241], v[68:71]
	v_mfma_f32_16x16x32_bf16 v[64:67], v[206:209], v[238:241], v[64:67]
	v_mfma_f32_16x16x32_bf16 v[116:119], v[202:205], v[218:221], v[116:119]
	v_mfma_f32_16x16x32_bf16 v[112:115], v[210:213], v[218:221], v[112:115]
	v_mfma_f32_16x16x32_bf16 v[100:103], v[202:205], v[226:229], v[100:103]
	v_mfma_f32_16x16x32_bf16 v[96:99], v[210:213], v[226:229], v[96:99]
	v_mfma_f32_16x16x32_bf16 v[84:87], v[202:205], v[234:237], v[84:87]
	v_mfma_f32_16x16x32_bf16 v[80:83], v[210:213], v[234:237], v[80:83]
	v_mfma_f32_16x16x32_bf16 v[68:71], v[202:205], v[242:245], v[68:71]
	v_mfma_f32_16x16x32_bf16 v[64:67], v[210:213], v[242:245], v[64:67]
	s_barrier
	s_mov_b32 m0, s31
	s_add_u32 s18, s18, 0x40080
	ds_read_b128 v[214:217], v159 offset:49152
	ds_read_b128 v[218:221], v159 offset:50176
	ds_read_b128 v[222:225], v159 offset:51200
	ds_read_b128 v[226:229], v159 offset:52224
	ds_read_b128 v[230:233], v159 offset:53248
	ds_read_b128 v[234:237], v159 offset:54272
	ds_read_b128 v[238:241], v159 offset:55296
	ds_read_b128 v[242:245], v159 offset:56320
	global_load_lds_dwordx4 v128, s[98:99]
	s_mov_b32 m0, s33
	s_addc_u32 s19, s19, 0
	global_load_lds_dwordx4 v130, s[98:99]
	s_mov_b32 m0, s36
	s_nop 0
	global_load_lds_dwordx4 v128, s[18:19]
	s_mov_b32 m0, s37
	s_nop 0
	global_load_lds_dwordx4 v130, s[18:19]
	s_mov_b32 m0, s34
	s_nop 0
	global_load_lds_dwordx4 v128, s[100:101]
	s_mov_b32 m0, s35
	s_nop 0
	global_load_lds_dwordx4 v130, s[100:101]
	s_waitcnt vmcnt(8)
	s_waitcnt lgkmcnt(0)
	s_barrier
	v_mfma_f32_16x16x32_bf16 v[60:63], v[160:163], v[214:217], v[60:63]
	v_mfma_f32_16x16x32_bf16 v[56:59], v[186:189], v[214:217], v[56:59]
	v_mfma_f32_16x16x32_bf16 v[44:47], v[160:163], v[222:225], v[44:47]
	v_mfma_f32_16x16x32_bf16 v[40:43], v[186:189], v[222:225], v[40:43]
	v_mfma_f32_16x16x32_bf16 v[28:31], v[160:163], v[230:233], v[28:31]
	v_mfma_f32_16x16x32_bf16 v[24:27], v[186:189], v[230:233], v[24:27]
	v_mfma_f32_16x16x32_bf16 v[12:15], v[160:163], v[238:241], v[12:15]
	v_mfma_f32_16x16x32_bf16 v[8:11], v[186:189], v[238:241], v[8:11]
	v_mfma_f32_16x16x32_bf16 v[60:63], v[164:167], v[218:221], v[60:63]
	v_mfma_f32_16x16x32_bf16 v[56:59], v[190:193], v[218:221], v[56:59]
	v_mfma_f32_16x16x32_bf16 v[44:47], v[164:167], v[226:229], v[44:47]
	v_mfma_f32_16x16x32_bf16 v[40:43], v[190:193], v[226:229], v[40:43]
	v_mfma_f32_16x16x32_bf16 v[28:31], v[164:167], v[234:237], v[28:31]
	v_mfma_f32_16x16x32_bf16 v[24:27], v[190:193], v[234:237], v[24:27]
	v_mfma_f32_16x16x32_bf16 v[12:15], v[164:167], v[242:245], v[12:15]
	v_mfma_f32_16x16x32_bf16 v[8:11], v[190:193], v[242:245], v[8:11]
	v_mfma_f32_16x16x32_bf16 v[52:55], v[198:201], v[214:217], v[52:55]
	v_mfma_f32_16x16x32_bf16 v[48:51], v[206:209], v[214:217], v[48:51]
	v_mfma_f32_16x16x32_bf16 v[36:39], v[198:201], v[222:225], v[36:39]
	v_mfma_f32_16x16x32_bf16 v[32:35], v[206:209], v[222:225], v[32:35]
	v_mfma_f32_16x16x32_bf16 v[20:23], v[198:201], v[230:233], v[20:23]
	v_mfma_f32_16x16x32_bf16 v[16:19], v[206:209], v[230:233], v[16:19]
	v_mfma_f32_16x16x32_bf16 v[4:7], v[198:201], v[238:241], v[4:7]
	v_mfma_f32_16x16x32_bf16 v[0:3], v[206:209], v[238:241], v[0:3]
	v_mfma_f32_16x16x32_bf16 v[52:55], v[202:205], v[218:221], v[52:55]
	v_mfma_f32_16x16x32_bf16 v[48:51], v[210:213], v[218:221], v[48:51]
	v_mfma_f32_16x16x32_bf16 v[36:39], v[202:205], v[226:229], v[36:39]
	v_mfma_f32_16x16x32_bf16 v[32:35], v[210:213], v[226:229], v[32:35]
	v_mfma_f32_16x16x32_bf16 v[20:23], v[202:205], v[234:237], v[20:23]
	v_mfma_f32_16x16x32_bf16 v[16:19], v[210:213], v[234:237], v[16:19]
	v_mfma_f32_16x16x32_bf16 v[4:7], v[202:205], v[242:245], v[4:7]
	v_mfma_f32_16x16x32_bf16 v[0:3], v[210:213], v[242:245], v[0:3]
	s_barrier
	s_add_i32 s66, s66, 2
	s_add_u32 s16, s16, 0x100
	s_addc_u32 s17, s17, 0
	s_add_u32 s47, s47, 0x100
	s_addc_u32 s49, s49, 0
	s_cmp_gt_u32 s66, 13
	s_cbranch_scc0 .LBB0_2152
	s_and_b64 vcc, exec, s[44:45]
	s_cbranch_vccz .LBB0_2155
	s_barrier

.LBB0_2530:
	ds_read_b128 v[140:143], v162
	ds_read_b128 v[178:181], v163
	ds_read_b128 v[182:185], v164
	ds_read_b128 v[186:189], v165
	ds_read_b128 v[190:193], v166
	ds_read_b128 v[198:201], v167
	ds_read_b128 v[202:205], v168
	ds_read_b128 v[206:209], v169
	s_add_u32 s16, s0, 0xfffe0080
	s_addc_u32 s17, s1, -1
	s_cmp_eq_u32 s64, 4
	s_cselect_b32 s19, s4, s17
	s_cselect_b32 s18, s5, s16
	s_cselect_b32 s17, s13, s51
	s_cselect_b32 s16, s15, s49
	s_mov_b32 m0, s77
	ds_read_b128 v[210:213], v160
	ds_read_b128 v[214:217], v160 offset:1024
	ds_read_b128 v[218:221], v160 offset:2048
	ds_read_b128 v[222:225], v160 offset:3072
	ds_read_b128 v[226:229], v160 offset:4096
	ds_read_b128 v[230:233], v160 offset:5120
	ds_read_b128 v[234:237], v160 offset:6144
	ds_read_b128 v[238:241], v160 offset:7168
	global_load_lds_dwordx4 v132, s[0:1]
	s_mov_b32 m0, s78
	s_nop 0
	global_load_lds_dwordx4 v134, s[0:1]
	s_waitcnt vmcnt(8)
	s_waitcnt lgkmcnt(0)
	s_barrier
	v_mfma_f32_16x16x32_bf16 v[124:127], v[140:143], v[210:213], v[124:127]
	v_mfma_f32_16x16x32_bf16 v[120:123], v[182:185], v[210:213], v[120:123]
	v_mfma_f32_16x16x32_bf16 v[108:111], v[140:143], v[218:221], v[108:111]
	v_mfma_f32_16x16x32_bf16 v[104:107], v[182:185], v[218:221], v[104:107]
	v_mfma_f32_16x16x32_bf16 v[92:95], v[140:143], v[226:229], v[92:95]
	v_mfma_f32_16x16x32_bf16 v[88:91], v[182:185], v[226:229], v[88:91]
	v_mfma_f32_16x16x32_bf16 v[76:79], v[140:143], v[234:237], v[76:79]
	v_mfma_f32_16x16x32_bf16 v[72:75], v[182:185], v[234:237], v[72:75]
	v_mfma_f32_16x16x32_bf16 v[124:127], v[178:181], v[214:217], v[124:127]
	v_mfma_f32_16x16x32_bf16 v[120:123], v[186:189], v[214:217], v[120:123]
	v_mfma_f32_16x16x32_bf16 v[108:111], v[178:181], v[222:225], v[108:111]
	v_mfma_f32_16x16x32_bf16 v[104:107], v[186:189], v[222:225], v[104:107]
	v_mfma_f32_16x16x32_bf16 v[92:95], v[178:181], v[230:233], v[92:95]
	v_mfma_f32_16x16x32_bf16 v[88:91], v[186:189], v[230:233], v[88:91]
	v_mfma_f32_16x16x32_bf16 v[76:79], v[178:181], v[238:241], v[76:79]
	v_mfma_f32_16x16x32_bf16 v[72:75], v[186:189], v[238:241], v[72:75]
	v_mfma_f32_16x16x32_bf16 v[116:119], v[190:193], v[210:213], v[116:119]
	v_mfma_f32_16x16x32_bf16 v[112:115], v[202:205], v[210:213], v[112:115]
	v_mfma_f32_16x16x32_bf16 v[100:103], v[190:193], v[218:221], v[100:103]
	v_mfma_f32_16x16x32_bf16 v[96:99], v[202:205], v[218:221], v[96:99]
	v_mfma_f32_16x16x32_bf16 v[84:87], v[190:193], v[226:229], v[84:87]
	v_mfma_f32_16x16x32_bf16 v[80:83], v[202:205], v[226:229], v[80:83]
	v_mfma_f32_16x16x32_bf16 v[68:71], v[190:193], v[234:237], v[68:71]
	v_mfma_f32_16x16x32_bf16 v[64:67], v[202:205], v[234:237], v[64:67]
	v_mfma_f32_16x16x32_bf16 v[116:119], v[198:201], v[214:217], v[116:119]
	v_mfma_f32_16x16x32_bf16 v[112:115], v[206:209], v[214:217], v[112:115]
	v_mfma_f32_16x16x32_bf16 v[100:103], v[198:201], v[222:225], v[100:103]
	v_mfma_f32_16x16x32_bf16 v[96:99], v[206:209], v[222:225], v[96:99]
	v_mfma_f32_16x16x32_bf16 v[84:87], v[198:201], v[230:233], v[84:87]
	v_mfma_f32_16x16x32_bf16 v[80:83], v[206:209], v[230:233], v[80:83]
	v_mfma_f32_16x16x32_bf16 v[68:71], v[198:201], v[238:241], v[68:71]
	v_mfma_f32_16x16x32_bf16 v[64:67], v[206:209], v[238:241], v[64:67]
	s_barrier
	s_add_u32 s98, s16, s44
	s_addc_u32 s99, s17, s45
	s_add_u32 s100, s18, s44
	s_addc_u32 s101, s19, s45
	s_mov_b32 m0, s6
	s_add_u32 s68, s16, 0x20000
	ds_read_b128 v[210:213], v160 offset:16384
	ds_read_b128 v[214:217], v160 offset:17408
	ds_read_b128 v[218:221], v160 offset:18432
	ds_read_b128 v[222:225], v160 offset:19456
	ds_read_b128 v[226:229], v160 offset:20480
	ds_read_b128 v[230:233], v160 offset:21504
	ds_read_b128 v[234:237], v160 offset:22528
	ds_read_b128 v[238:241], v160 offset:23552
	global_load_lds_dwordx4 v128, s[16:17]
	s_mov_b32 m0, s7
	s_addc_u32 s69, s17, 0
	global_load_lds_dwordx4 v130, s[16:17]
	s_mov_b32 m0, s8
	s_nop 0
	global_load_lds_dwordx4 v128, s[68:69]
	s_mov_b32 m0, s9
	s_nop 0
	global_load_lds_dwordx4 v130, s[68:69]
	s_mov_b32 m0, s2
	s_nop 0
	global_load_lds_dwordx4 v128, s[18:19]
	s_mov_b32 m0, s28
	s_nop 0
	global_load_lds_dwordx4 v130, s[18:19]
	s_waitcnt vmcnt(8)
	s_waitcnt lgkmcnt(0)
	s_barrier
	v_mfma_f32_16x16x32_bf16 v[60:63], v[140:143], v[210:213], v[60:63]
	v_mfma_f32_16x16x32_bf16 v[56:59], v[182:185], v[210:213], v[56:59]
	v_mfma_f32_16x16x32_bf16 v[44:47], v[140:143], v[218:221], v[44:47]
	v_mfma_f32_16x16x32_bf16 v[40:43], v[182:185], v[218:221], v[40:43]
	v_mfma_f32_16x16x32_bf16 v[28:31], v[140:143], v[226:229], v[28:31]
	v_mfma_f32_16x16x32_bf16 v[24:27], v[182:185], v[226:229], v[24:27]
	v_mfma_f32_16x16x32_bf16 v[12:15], v[140:143], v[234:237], v[12:15]
	v_mfma_f32_16x16x32_bf16 v[8:11], v[182:185], v[234:237], v[8:11]
	v_mfma_f32_16x16x32_bf16 v[60:63], v[178:181], v[214:217], v[60:63]
	v_mfma_f32_16x16x32_bf16 v[56:59], v[186:189], v[214:217], v[56:59]
	v_mfma_f32_16x16x32_bf16 v[44:47], v[178:181], v[222:225], v[44:47]
	v_mfma_f32_16x16x32_bf16 v[40:43], v[186:189], v[222:225], v[40:43]
	v_mfma_f32_16x16x32_bf16 v[28:31], v[178:181], v[230:233], v[28:31]
	v_mfma_f32_16x16x32_bf16 v[24:27], v[186:189], v[230:233], v[24:27]
	v_mfma_f32_16x16x32_bf16 v[12:15], v[178:181], v[238:241], v[12:15]
	v_mfma_f32_16x16x32_bf16 v[8:11], v[186:189], v[238:241], v[8:11]
	v_mfma_f32_16x16x32_bf16 v[52:55], v[190:193], v[210:213], v[52:55]
	v_mfma_f32_16x16x32_bf16 v[48:51], v[202:205], v[210:213], v[48:51]
	v_mfma_f32_16x16x32_bf16 v[36:39], v[190:193], v[218:221], v[36:39]
	v_mfma_f32_16x16x32_bf16 v[32:35], v[202:205], v[218:221], v[32:35]
	v_mfma_f32_16x16x32_bf16 v[20:23], v[190:193], v[226:229], v[20:23]
	v_mfma_f32_16x16x32_bf16 v[16:19], v[202:205], v[226:229], v[16:19]
	v_mfma_f32_16x16x32_bf16 v[4:7], v[190:193], v[234:237], v[4:7]
	v_mfma_f32_16x16x32_bf16 v[0:3], v[202:205], v[234:237], v[0:3]
	v_mfma_f32_16x16x32_bf16 v[52:55], v[198:201], v[214:217], v[52:55]
	v_mfma_f32_16x16x32_bf16 v[48:51], v[206:209], v[214:217], v[48:51]
	v_mfma_f32_16x16x32_bf16 v[36:39], v[198:201], v[222:225], v[36:39]
	v_mfma_f32_16x16x32_bf16 v[32:35], v[206:209], v[222:225], v[32:35]
	v_mfma_f32_16x16x32_bf16 v[20:23], v[198:201], v[230:233], v[20:23]
	v_mfma_f32_16x16x32_bf16 v[16:19], v[206:209], v[230:233], v[16:19]
	v_mfma_f32_16x16x32_bf16 v[4:7], v[198:201], v[238:241], v[4:7]
	v_mfma_f32_16x16x32_bf16 v[0:3], v[206:209], v[238:241], v[0:3]
	s_barrier
	ds_read_b128 v[140:143], v170
	ds_read_b128 v[178:181], v171
	ds_read_b128 v[182:185], v172
	ds_read_b128 v[186:189], v173
	ds_read_b128 v[190:193], v174
	ds_read_b128 v[198:201], v175
	ds_read_b128 v[202:205], v176
	ds_read_b128 v[206:209], v177
	s_add_u32 s18, s18, 0x20000
	s_addc_u32 s19, s19, 0
	s_mov_b32 m0, s29
	ds_read_b128 v[210:213], v160 offset:32768
	ds_read_b128 v[214:217], v160 offset:33792
	ds_read_b128 v[218:221], v160 offset:34816
	ds_read_b128 v[222:225], v160 offset:35840
	ds_read_b128 v[226:229], v160 offset:36864
	ds_read_b128 v[230:233], v160 offset:37888
	ds_read_b128 v[234:237], v160 offset:38912
	ds_read_b128 v[238:241], v160 offset:39936
	global_load_lds_dwordx4 v128, s[18:19]
	s_mov_b32 m0, s30
	s_nop 0
	global_load_lds_dwordx4 v130, s[18:19]
	s_waitcnt vmcnt(8)
	s_waitcnt lgkmcnt(0)
	s_barrier
	v_mfma_f32_16x16x32_bf16 v[124:127], v[140:143], v[210:213], v[124:127]
	v_mfma_f32_16x16x32_bf16 v[120:123], v[182:185], v[210:213], v[120:123]
	v_mfma_f32_16x16x32_bf16 v[108:111], v[140:143], v[218:221], v[108:111]
	v_mfma_f32_16x16x32_bf16 v[104:107], v[182:185], v[218:221], v[104:107]
	v_mfma_f32_16x16x32_bf16 v[92:95], v[140:143], v[226:229], v[92:95]
	v_mfma_f32_16x16x32_bf16 v[88:91], v[182:185], v[226:229], v[88:91]
	v_mfma_f32_16x16x32_bf16 v[76:79], v[140:143], v[234:237], v[76:79]
	v_mfma_f32_16x16x32_bf16 v[72:75], v[182:185], v[234:237], v[72:75]
	v_mfma_f32_16x16x32_bf16 v[124:127], v[178:181], v[214:217], v[124:127]
	v_mfma_f32_16x16x32_bf16 v[120:123], v[186:189], v[214:217], v[120:123]
	v_mfma_f32_16x16x32_bf16 v[108:111], v[178:181], v[222:225], v[108:111]
	v_mfma_f32_16x16x32_bf16 v[104:107], v[186:189], v[222:225], v[104:107]
	v_mfma_f32_16x16x32_bf16 v[92:95], v[178:181], v[230:233], v[92:95]
	v_mfma_f32_16x16x32_bf16 v[88:91], v[186:189], v[230:233], v[88:91]
	v_mfma_f32_16x16x32_bf16 v[76:79], v[178:181], v[238:241], v[76:79]
	v_mfma_f32_16x16x32_bf16 v[72:75], v[186:189], v[238:241], v[72:75]
	v_mfma_f32_16x16x32_bf16 v[116:119], v[190:193], v[210:213], v[116:119]
	v_mfma_f32_16x16x32_bf16 v[112:115], v[202:205], v[210:213], v[112:115]
	v_mfma_f32_16x16x32_bf16 v[100:103], v[190:193], v[218:221], v[100:103]
	v_mfma_f32_16x16x32_bf16 v[96:99], v[202:205], v[218:221], v[96:99]
	v_mfma_f32_16x16x32_bf16 v[84:87], v[190:193], v[226:229], v[84:87]
	v_mfma_f32_16x16x32_bf16 v[80:83], v[202:205], v[226:229], v[80:83]
	v_mfma_f32_16x16x32_bf16 v[68:71], v[190:193], v[234:237], v[68:71]
	v_mfma_f32_16x16x32_bf16 v[64:67], v[202:205], v[234:237], v[64:67]
	v_mfma_f32_16x16x32_bf16 v[116:119], v[198:201], v[214:217], v[116:119]
	v_mfma_f32_16x16x32_bf16 v[112:115], v[206:209], v[214:217], v[112:115]
	v_mfma_f32_16x16x32_bf16 v[100:103], v[198:201], v[222:225], v[100:103]
	v_mfma_f32_16x16x32_bf16 v[96:99], v[206:209], v[222:225], v[96:99]
	v_mfma_f32_16x16x32_bf16 v[84:87], v[198:201], v[230:233], v[84:87]
	v_mfma_f32_16x16x32_bf16 v[80:83], v[206:209], v[230:233], v[80:83]
	v_mfma_f32_16x16x32_bf16 v[68:71], v[198:201], v[238:241], v[68:71]
	v_mfma_f32_16x16x32_bf16 v[64:67], v[206:209], v[238:241], v[64:67]
	s_barrier
	s_mov_b32 m0, s31
	s_add_u32 s16, s16, 0x20080
	ds_read_b128 v[210:213], v160 offset:49152
	ds_read_b128 v[214:217], v160 offset:50176
	ds_read_b128 v[218:221], v160 offset:51200
	ds_read_b128 v[222:225], v160 offset:52224
	ds_read_b128 v[226:229], v160 offset:53248
	ds_read_b128 v[230:233], v160 offset:54272
	ds_read_b128 v[234:237], v160 offset:55296
	ds_read_b128 v[238:241], v160 offset:56320
	global_load_lds_dwordx4 v128, s[98:99]
	s_mov_b32 m0, s33
	s_addc_u32 s17, s17, 0
	global_load_lds_dwordx4 v130, s[98:99]
	s_mov_b32 m0, s36
	s_nop 0
	global_load_lds_dwordx4 v128, s[16:17]
	s_mov_b32 m0, s37
	s_nop 0
	global_load_lds_dwordx4 v130, s[16:17]
	s_mov_b32 m0, s34
	s_nop 0
	global_load_lds_dwordx4 v128, s[100:101]
	s_mov_b32 m0, s35
	s_nop 0
	global_load_lds_dwordx4 v130, s[100:101]
	s_waitcnt vmcnt(8)
	s_waitcnt lgkmcnt(0)
	s_barrier
	v_mfma_f32_16x16x32_bf16 v[60:63], v[140:143], v[210:213], v[60:63]
	v_mfma_f32_16x16x32_bf16 v[56:59], v[182:185], v[210:213], v[56:59]
	v_mfma_f32_16x16x32_bf16 v[44:47], v[140:143], v[218:221], v[44:47]
	v_mfma_f32_16x16x32_bf16 v[40:43], v[182:185], v[218:221], v[40:43]
	v_mfma_f32_16x16x32_bf16 v[28:31], v[140:143], v[226:229], v[28:31]
	v_mfma_f32_16x16x32_bf16 v[24:27], v[182:185], v[226:229], v[24:27]
	v_mfma_f32_16x16x32_bf16 v[12:15], v[140:143], v[234:237], v[12:15]
	v_mfma_f32_16x16x32_bf16 v[8:11], v[182:185], v[234:237], v[8:11]
	v_mfma_f32_16x16x32_bf16 v[60:63], v[178:181], v[214:217], v[60:63]
	v_mfma_f32_16x16x32_bf16 v[56:59], v[186:189], v[214:217], v[56:59]
	v_mfma_f32_16x16x32_bf16 v[44:47], v[178:181], v[222:225], v[44:47]
	v_mfma_f32_16x16x32_bf16 v[40:43], v[186:189], v[222:225], v[40:43]
	v_mfma_f32_16x16x32_bf16 v[28:31], v[178:181], v[230:233], v[28:31]
	v_mfma_f32_16x16x32_bf16 v[24:27], v[186:189], v[230:233], v[24:27]
	v_mfma_f32_16x16x32_bf16 v[12:15], v[178:181], v[238:241], v[12:15]
	v_mfma_f32_16x16x32_bf16 v[8:11], v[186:189], v[238:241], v[8:11]
	v_mfma_f32_16x16x32_bf16 v[52:55], v[190:193], v[210:213], v[52:55]
	v_mfma_f32_16x16x32_bf16 v[48:51], v[202:205], v[210:213], v[48:51]
	v_mfma_f32_16x16x32_bf16 v[36:39], v[190:193], v[218:221], v[36:39]
	v_mfma_f32_16x16x32_bf16 v[32:35], v[202:205], v[218:221], v[32:35]
	v_mfma_f32_16x16x32_bf16 v[20:23], v[190:193], v[226:229], v[20:23]
	v_mfma_f32_16x16x32_bf16 v[16:19], v[202:205], v[226:229], v[16:19]
	v_mfma_f32_16x16x32_bf16 v[4:7], v[190:193], v[234:237], v[4:7]
	v_mfma_f32_16x16x32_bf16 v[0:3], v[202:205], v[234:237], v[0:3]
	v_mfma_f32_16x16x32_bf16 v[52:55], v[198:201], v[214:217], v[52:55]
	v_mfma_f32_16x16x32_bf16 v[48:51], v[206:209], v[214:217], v[48:51]
	v_mfma_f32_16x16x32_bf16 v[36:39], v[198:201], v[222:225], v[36:39]
	v_mfma_f32_16x16x32_bf16 v[32:35], v[206:209], v[222:225], v[32:35]
	v_mfma_f32_16x16x32_bf16 v[20:23], v[198:201], v[230:233], v[20:23]
	v_mfma_f32_16x16x32_bf16 v[16:19], v[206:209], v[230:233], v[16:19]
	v_mfma_f32_16x16x32_bf16 v[4:7], v[198:201], v[238:241], v[4:7]
	v_mfma_f32_16x16x32_bf16 v[0:3], v[206:209], v[238:241], v[0:3]
	s_barrier
	s_add_i32 s64, s64, 2
	s_add_u32 s0, s0, 0x100
	s_addc_u32 s1, s1, 0
	s_add_u32 s49, s49, 0x100
	s_addc_u32 s51, s51, 0
	s_cmp_gt_u32 s64, 5
	s_cbranch_scc0 .LBB0_2530
	s_and_b64 vcc, exec, s[46:47]
	s_cbranch_vccz .LBB0_2533
	s_barrier

.LBB0_2628:
	s_add_u32 s65, s48, s64
	s_addc_u32 s70, s49, 0
	s_add_u32 s71, s65, 0x100
	s_addc_u32 s74, s70, 0
	s_and_b64 s[68:69], s[54:55], exec
	s_cselect_b32 s75, s4, s74
	s_cselect_b32 s74, s5, s71
	s_add_u32 s64, s46, s64
	s_addc_u32 s68, s47, 0
	s_add_u32 s64, s64, 0x100
	ds_read_b128 v[170:173], v141
	ds_read_b128 v[174:177], v142
	ds_read_b128 v[178:181], v143
	ds_read_b128 v[182:185], v153
	ds_read_b128 v[186:189], v158
	ds_read_b128 v[190:193], v159
	ds_read_b128 v[196:199], v160
	ds_read_b128 v[200:203], v161
	s_addc_u32 s68, s68, 0
	s_and_b64 s[54:55], s[54:55], exec
	s_cselect_b32 s79, s21, s68
	s_cselect_b32 s78, s23, s64
	s_add_u32 s82, s65, 0x10080
	s_addc_u32 s83, s70, 0
	s_add_u32 s80, s78, 0x10000
	s_addc_u32 s81, s79, 0
	s_add_u32 s64, s74, 0x10000
	s_addc_u32 s65, s75, 0
	s_add_u32 s54, s78, 0x10080
	s_addc_u32 s55, s79, 0
	s_mov_b32 m0, s35
	ds_read_b128 v[204:207], v139
	ds_read_b128 v[208:211], v139 offset:1024
	ds_read_b128 v[212:215], v139 offset:2048
	ds_read_b128 v[216:219], v139 offset:3072
	ds_read_b128 v[220:223], v139 offset:4096
	ds_read_b128 v[224:227], v139 offset:5120
	ds_read_b128 v[228:231], v139 offset:6144
	ds_read_b128 v[232:235], v139 offset:7168
	global_load_lds_dwordx4 v128, s[82:83]
	s_mov_b32 m0, s60
	s_nop 0
	global_load_lds_dwordx4 v130, s[82:83]
	s_waitcnt vmcnt(8)
	s_waitcnt lgkmcnt(0)
	s_barrier
	v_mfma_f32_16x16x32_bf16 v[124:127], v[170:173], v[204:207], v[124:127]
	v_mfma_f32_16x16x32_bf16 v[120:123], v[178:181], v[204:207], v[120:123]
	v_mfma_f32_16x16x32_bf16 v[108:111], v[170:173], v[212:215], v[108:111]
	v_mfma_f32_16x16x32_bf16 v[104:107], v[178:181], v[212:215], v[104:107]
	v_mfma_f32_16x16x32_bf16 v[92:95], v[170:173], v[220:223], v[92:95]
	v_mfma_f32_16x16x32_bf16 v[88:91], v[178:181], v[220:223], v[88:91]
	v_mfma_f32_16x16x32_bf16 v[76:79], v[170:173], v[228:231], v[76:79]
	v_mfma_f32_16x16x32_bf16 v[72:75], v[178:181], v[228:231], v[72:75]
	v_mfma_f32_16x16x32_bf16 v[124:127], v[174:177], v[208:211], v[124:127]
	v_mfma_f32_16x16x32_bf16 v[120:123], v[182:185], v[208:211], v[120:123]
	v_mfma_f32_16x16x32_bf16 v[108:111], v[174:177], v[216:219], v[108:111]
	v_mfma_f32_16x16x32_bf16 v[104:107], v[182:185], v[216:219], v[104:107]
	v_mfma_f32_16x16x32_bf16 v[92:95], v[174:177], v[224:227], v[92:95]
	v_mfma_f32_16x16x32_bf16 v[88:91], v[182:185], v[224:227], v[88:91]
	v_mfma_f32_16x16x32_bf16 v[76:79], v[174:177], v[232:235], v[76:79]
	v_mfma_f32_16x16x32_bf16 v[72:75], v[182:185], v[232:235], v[72:75]
	v_mfma_f32_16x16x32_bf16 v[116:119], v[186:189], v[204:207], v[116:119]
	v_mfma_f32_16x16x32_bf16 v[112:115], v[196:199], v[204:207], v[112:115]
	v_mfma_f32_16x16x32_bf16 v[100:103], v[186:189], v[212:215], v[100:103]
	v_mfma_f32_16x16x32_bf16 v[96:99], v[196:199], v[212:215], v[96:99]
	v_mfma_f32_16x16x32_bf16 v[84:87], v[186:189], v[220:223], v[84:87]
	v_mfma_f32_16x16x32_bf16 v[80:83], v[196:199], v[220:223], v[80:83]
	v_mfma_f32_16x16x32_bf16 v[68:71], v[186:189], v[228:231], v[68:71]
	v_mfma_f32_16x16x32_bf16 v[64:67], v[196:199], v[228:231], v[64:67]
	v_mfma_f32_16x16x32_bf16 v[116:119], v[190:193], v[208:211], v[116:119]
	v_mfma_f32_16x16x32_bf16 v[112:115], v[200:203], v[208:211], v[112:115]
	v_mfma_f32_16x16x32_bf16 v[100:103], v[190:193], v[216:219], v[100:103]
	v_mfma_f32_16x16x32_bf16 v[96:99], v[200:203], v[216:219], v[96:99]
	v_mfma_f32_16x16x32_bf16 v[84:87], v[190:193], v[224:227], v[84:87]
	v_mfma_f32_16x16x32_bf16 v[80:83], v[200:203], v[224:227], v[80:83]
	v_mfma_f32_16x16x32_bf16 v[68:71], v[190:193], v[232:235], v[68:71]
	v_mfma_f32_16x16x32_bf16 v[64:67], v[200:203], v[232:235], v[64:67]
	s_barrier
	s_add_u32 s98, s78, s16
	s_addc_u32 s99, s79, s17
	s_add_u32 s100, s74, s16
	s_addc_u32 s101, s75, s17
	s_mov_b32 m0, s45
	ds_read_b128 v[204:207], v139 offset:16384
	ds_read_b128 v[208:211], v139 offset:17408
	ds_read_b128 v[212:215], v139 offset:18432
	ds_read_b128 v[216:219], v139 offset:19456
	ds_read_b128 v[220:223], v139 offset:20480
	ds_read_b128 v[224:227], v139 offset:21504
	ds_read_b128 v[228:231], v139 offset:22528
	ds_read_b128 v[232:235], v139 offset:23552
	global_load_lds_dwordx4 v128, s[78:79]
	s_mov_b32 m0, s67
	s_nop 0
	global_load_lds_dwordx4 v130, s[78:79]
	s_mov_b32 m0, s84
	s_nop 0
	global_load_lds_dwordx4 v128, s[80:81]
	s_mov_b32 m0, s85
	s_nop 0
	global_load_lds_dwordx4 v130, s[80:81]
	s_mov_b32 m0, s30
	s_nop 0
	global_load_lds_dwordx4 v128, s[74:75]
	s_mov_b32 m0, s86
	s_nop 0
	global_load_lds_dwordx4 v130, s[74:75]
	s_waitcnt vmcnt(8)
	s_waitcnt lgkmcnt(0)
	s_barrier
	v_mfma_f32_16x16x32_bf16 v[60:63], v[170:173], v[204:207], v[60:63]
	v_mfma_f32_16x16x32_bf16 v[56:59], v[178:181], v[204:207], v[56:59]
	v_mfma_f32_16x16x32_bf16 v[44:47], v[170:173], v[212:215], v[44:47]
	v_mfma_f32_16x16x32_bf16 v[40:43], v[178:181], v[212:215], v[40:43]
	v_mfma_f32_16x16x32_bf16 v[28:31], v[170:173], v[220:223], v[28:31]
	v_mfma_f32_16x16x32_bf16 v[24:27], v[178:181], v[220:223], v[24:27]
	v_mfma_f32_16x16x32_bf16 v[12:15], v[170:173], v[228:231], v[12:15]
	v_mfma_f32_16x16x32_bf16 v[8:11], v[178:181], v[228:231], v[8:11]
	v_mfma_f32_16x16x32_bf16 v[60:63], v[174:177], v[208:211], v[60:63]
	v_mfma_f32_16x16x32_bf16 v[56:59], v[182:185], v[208:211], v[56:59]
	v_mfma_f32_16x16x32_bf16 v[44:47], v[174:177], v[216:219], v[44:47]
	v_mfma_f32_16x16x32_bf16 v[40:43], v[182:185], v[216:219], v[40:43]
	v_mfma_f32_16x16x32_bf16 v[28:31], v[174:177], v[224:227], v[28:31]
	v_mfma_f32_16x16x32_bf16 v[24:27], v[182:185], v[224:227], v[24:27]
	v_mfma_f32_16x16x32_bf16 v[12:15], v[174:177], v[232:235], v[12:15]
	v_mfma_f32_16x16x32_bf16 v[8:11], v[182:185], v[232:235], v[8:11]
	v_mfma_f32_16x16x32_bf16 v[52:55], v[186:189], v[204:207], v[52:55]
	v_mfma_f32_16x16x32_bf16 v[48:51], v[196:199], v[204:207], v[48:51]
	v_mfma_f32_16x16x32_bf16 v[36:39], v[186:189], v[212:215], v[36:39]
	v_mfma_f32_16x16x32_bf16 v[32:35], v[196:199], v[212:215], v[32:35]
	v_mfma_f32_16x16x32_bf16 v[20:23], v[186:189], v[220:223], v[20:23]
	v_mfma_f32_16x16x32_bf16 v[16:19], v[196:199], v[220:223], v[16:19]
	v_mfma_f32_16x16x32_bf16 v[4:7], v[186:189], v[228:231], v[4:7]
	v_mfma_f32_16x16x32_bf16 v[0:3], v[196:199], v[228:231], v[0:3]
	v_mfma_f32_16x16x32_bf16 v[52:55], v[190:193], v[208:211], v[52:55]
	v_mfma_f32_16x16x32_bf16 v[48:51], v[200:203], v[208:211], v[48:51]
	v_mfma_f32_16x16x32_bf16 v[36:39], v[190:193], v[216:219], v[36:39]
	v_mfma_f32_16x16x32_bf16 v[32:35], v[200:203], v[216:219], v[32:35]
	v_mfma_f32_16x16x32_bf16 v[20:23], v[190:193], v[224:227], v[20:23]
	v_mfma_f32_16x16x32_bf16 v[16:19], v[200:203], v[224:227], v[16:19]
	v_mfma_f32_16x16x32_bf16 v[4:7], v[190:193], v[232:235], v[4:7]
	v_mfma_f32_16x16x32_bf16 v[0:3], v[200:203], v[232:235], v[0:3]
	s_barrier
	ds_read_b128 v[170:173], v162
	ds_read_b128 v[174:177], v163
	ds_read_b128 v[178:181], v164
	ds_read_b128 v[182:185], v165
	ds_read_b128 v[186:189], v166
	ds_read_b128 v[190:193], v167
	ds_read_b128 v[196:199], v168
	ds_read_b128 v[200:203], v169
	s_mov_b32 m0, s87
	ds_read_b128 v[204:207], v139 offset:32768
	ds_read_b128 v[208:211], v139 offset:33792
	ds_read_b128 v[212:215], v139 offset:34816
	ds_read_b128 v[216:219], v139 offset:35840
	ds_read_b128 v[220:223], v139 offset:36864
	ds_read_b128 v[224:227], v139 offset:37888
	ds_read_b128 v[228:231], v139 offset:38912
	ds_read_b128 v[232:235], v139 offset:39936
	global_load_lds_dwordx4 v128, s[64:65]
	s_mov_b32 m0, s90
	s_nop 0
	global_load_lds_dwordx4 v130, s[64:65]
	s_waitcnt vmcnt(8)
	s_waitcnt lgkmcnt(0)
	s_barrier
	v_mfma_f32_16x16x32_bf16 v[124:127], v[170:173], v[204:207], v[124:127]
	v_mfma_f32_16x16x32_bf16 v[120:123], v[178:181], v[204:207], v[120:123]
	v_mfma_f32_16x16x32_bf16 v[108:111], v[170:173], v[212:215], v[108:111]
	v_mfma_f32_16x16x32_bf16 v[104:107], v[178:181], v[212:215], v[104:107]
	v_mfma_f32_16x16x32_bf16 v[92:95], v[170:173], v[220:223], v[92:95]
	v_mfma_f32_16x16x32_bf16 v[88:91], v[178:181], v[220:223], v[88:91]
	v_mfma_f32_16x16x32_bf16 v[76:79], v[170:173], v[228:231], v[76:79]
	v_mfma_f32_16x16x32_bf16 v[72:75], v[178:181], v[228:231], v[72:75]
	v_mfma_f32_16x16x32_bf16 v[124:127], v[174:177], v[208:211], v[124:127]
	v_mfma_f32_16x16x32_bf16 v[120:123], v[182:185], v[208:211], v[120:123]
	v_mfma_f32_16x16x32_bf16 v[108:111], v[174:177], v[216:219], v[108:111]
	v_mfma_f32_16x16x32_bf16 v[104:107], v[182:185], v[216:219], v[104:107]
	v_mfma_f32_16x16x32_bf16 v[92:95], v[174:177], v[224:227], v[92:95]
	v_mfma_f32_16x16x32_bf16 v[88:91], v[182:185], v[224:227], v[88:91]
	v_mfma_f32_16x16x32_bf16 v[76:79], v[174:177], v[232:235], v[76:79]
	v_mfma_f32_16x16x32_bf16 v[72:75], v[182:185], v[232:235], v[72:75]
	v_mfma_f32_16x16x32_bf16 v[116:119], v[186:189], v[204:207], v[116:119]
	v_mfma_f32_16x16x32_bf16 v[112:115], v[196:199], v[204:207], v[112:115]
	v_mfma_f32_16x16x32_bf16 v[100:103], v[186:189], v[212:215], v[100:103]
	v_mfma_f32_16x16x32_bf16 v[96:99], v[196:199], v[212:215], v[96:99]
	v_mfma_f32_16x16x32_bf16 v[84:87], v[186:189], v[220:223], v[84:87]
	v_mfma_f32_16x16x32_bf16 v[80:83], v[196:199], v[220:223], v[80:83]
	v_mfma_f32_16x16x32_bf16 v[68:71], v[186:189], v[228:231], v[68:71]
	v_mfma_f32_16x16x32_bf16 v[64:67], v[196:199], v[228:231], v[64:67]
	v_mfma_f32_16x16x32_bf16 v[116:119], v[190:193], v[208:211], v[116:119]
	v_mfma_f32_16x16x32_bf16 v[112:115], v[200:203], v[208:211], v[112:115]
	v_mfma_f32_16x16x32_bf16 v[100:103], v[190:193], v[216:219], v[100:103]
	v_mfma_f32_16x16x32_bf16 v[96:99], v[200:203], v[216:219], v[96:99]
	v_mfma_f32_16x16x32_bf16 v[84:87], v[190:193], v[224:227], v[84:87]
	v_mfma_f32_16x16x32_bf16 v[80:83], v[200:203], v[224:227], v[80:83]
	v_mfma_f32_16x16x32_bf16 v[68:71], v[190:193], v[232:235], v[68:71]
	v_mfma_f32_16x16x32_bf16 v[64:67], v[200:203], v[232:235], v[64:67]
	s_barrier
	s_mov_b32 m0, s33
	ds_read_b128 v[204:207], v139 offset:49152
	ds_read_b128 v[208:211], v139 offset:50176
	ds_read_b128 v[212:215], v139 offset:51200
	ds_read_b128 v[216:219], v139 offset:52224
	ds_read_b128 v[220:223], v139 offset:53248
	ds_read_b128 v[224:227], v139 offset:54272
	ds_read_b128 v[228:231], v139 offset:55296
	ds_read_b128 v[232:235], v139 offset:56320
	global_load_lds_dwordx4 v128, s[98:99]
	s_mov_b32 m0, s9
	s_nop 0
	global_load_lds_dwordx4 v130, s[98:99]
	s_mov_b32 m0, s52
	s_nop 0
	global_load_lds_dwordx4 v128, s[54:55]
	s_mov_b32 m0, s61
	s_nop 0
	global_load_lds_dwordx4 v130, s[54:55]
	s_mov_b32 m0, s8
	s_nop 0
	global_load_lds_dwordx4 v128, s[100:101]
	s_mov_b32 m0, s53
	s_nop 0
	global_load_lds_dwordx4 v130, s[100:101]
	s_waitcnt vmcnt(8)
	s_waitcnt lgkmcnt(0)
	s_barrier
	v_mfma_f32_16x16x32_bf16 v[60:63], v[170:173], v[204:207], v[60:63]
	v_mfma_f32_16x16x32_bf16 v[56:59], v[178:181], v[204:207], v[56:59]
	v_mfma_f32_16x16x32_bf16 v[44:47], v[170:173], v[212:215], v[44:47]
	v_mfma_f32_16x16x32_bf16 v[40:43], v[178:181], v[212:215], v[40:43]
	v_mfma_f32_16x16x32_bf16 v[28:31], v[170:173], v[220:223], v[28:31]
	v_mfma_f32_16x16x32_bf16 v[24:27], v[178:181], v[220:223], v[24:27]
	v_mfma_f32_16x16x32_bf16 v[12:15], v[170:173], v[228:231], v[12:15]
	v_mfma_f32_16x16x32_bf16 v[8:11], v[178:181], v[228:231], v[8:11]
	v_mfma_f32_16x16x32_bf16 v[60:63], v[174:177], v[208:211], v[60:63]
	v_mfma_f32_16x16x32_bf16 v[56:59], v[182:185], v[208:211], v[56:59]
	v_mfma_f32_16x16x32_bf16 v[44:47], v[174:177], v[216:219], v[44:47]
	v_mfma_f32_16x16x32_bf16 v[40:43], v[182:185], v[216:219], v[40:43]
	v_mfma_f32_16x16x32_bf16 v[28:31], v[174:177], v[224:227], v[28:31]
	v_mfma_f32_16x16x32_bf16 v[24:27], v[182:185], v[224:227], v[24:27]
	v_mfma_f32_16x16x32_bf16 v[12:15], v[174:177], v[232:235], v[12:15]
	v_mfma_f32_16x16x32_bf16 v[8:11], v[182:185], v[232:235], v[8:11]
	v_mfma_f32_16x16x32_bf16 v[52:55], v[186:189], v[204:207], v[52:55]
	v_mfma_f32_16x16x32_bf16 v[48:51], v[196:199], v[204:207], v[48:51]
	v_mfma_f32_16x16x32_bf16 v[36:39], v[186:189], v[212:215], v[36:39]
	v_mfma_f32_16x16x32_bf16 v[32:35], v[196:199], v[212:215], v[32:35]
	v_mfma_f32_16x16x32_bf16 v[20:23], v[186:189], v[220:223], v[20:23]
	v_mfma_f32_16x16x32_bf16 v[16:19], v[196:199], v[220:223], v[16:19]
	v_mfma_f32_16x16x32_bf16 v[4:7], v[186:189], v[228:231], v[4:7]
	v_mfma_f32_16x16x32_bf16 v[0:3], v[196:199], v[228:231], v[0:3]
	v_mfma_f32_16x16x32_bf16 v[52:55], v[190:193], v[208:211], v[52:55]
	v_mfma_f32_16x16x32_bf16 v[48:51], v[200:203], v[208:211], v[48:51]
	v_mfma_f32_16x16x32_bf16 v[36:39], v[190:193], v[216:219], v[36:39]
	v_mfma_f32_16x16x32_bf16 v[32:35], v[200:203], v[216:219], v[32:35]
	v_mfma_f32_16x16x32_bf16 v[20:23], v[190:193], v[224:227], v[20:23]
	v_mfma_f32_16x16x32_bf16 v[16:19], v[200:203], v[224:227], v[16:19]
	v_mfma_f32_16x16x32_bf16 v[4:7], v[190:193], v[232:235], v[4:7]
	v_mfma_f32_16x16x32_bf16 v[0:3], v[200:203], v[232:235], v[0:3]
	s_barrier
	s_movk_i32 s64, 0x100
	s_andn2_b64 vcc, exec, s[50:51]
	s_mov_b64 s[54:55], -1
	s_mov_b64 s[50:51], 0
	s_cbranch_vccz .LBB0_2628
	s_and_b64 vcc, exec, s[18:19]
	s_cbranch_vccz .LBB0_2631
	s_barrier

.LBB0_2801:
	ds_read_b128 v[128:131], v195
	ds_read_b128 v[132:135], v196
	ds_read_b128 v[136:139], v197
	ds_read_b128 v[140:143], v198
	ds_read_b128 v[170:173], v199
	ds_read_b128 v[174:177], v200
	ds_read_b128 v[178:181], v201
	ds_read_b128 v[182:185], v202
	s_add_u32 s46, s44, 0x100
	s_addc_u32 s47, s45, 0
	s_cmp_eq_u32 s68, 12
	s_cselect_b32 s51, s4, s47
	s_cselect_b32 s50, s5, s46
	s_cselect_b32 s49, s25, s67
	s_cselect_b32 s48, s27, s66
	s_mov_b32 m0, s55
	ds_read_b128 v[186:189], v192
	ds_read_b128 v[212:215], v192 offset:1024
	ds_read_b128 v[216:219], v192 offset:2048
	ds_read_b128 v[220:223], v192 offset:3072
	ds_read_b128 v[224:227], v192 offset:4096
	ds_read_b128 v[228:231], v192 offset:5120
	ds_read_b128 v[232:235], v192 offset:6144
	ds_read_b128 v[236:239], v192 offset:7168
	global_load_lds_dwordx4 v162, s[44:45]
	s_mov_b32 m0, s60
	s_nop 0
	global_load_lds_dwordx4 v164, s[44:45]
	s_waitcnt vmcnt(8)
	s_waitcnt lgkmcnt(0)
	s_barrier
	v_mfma_f32_16x16x32_bf16 v[124:127], v[128:131], v[186:189], v[124:127]
	v_mfma_f32_16x16x32_bf16 v[120:123], v[136:139], v[186:189], v[120:123]
	v_mfma_f32_16x16x32_bf16 v[108:111], v[128:131], v[216:219], v[108:111]
	v_mfma_f32_16x16x32_bf16 v[104:107], v[136:139], v[216:219], v[104:107]
	v_mfma_f32_16x16x32_bf16 v[92:95], v[128:131], v[224:227], v[92:95]
	v_mfma_f32_16x16x32_bf16 v[88:91], v[136:139], v[224:227], v[88:91]
	v_mfma_f32_16x16x32_bf16 v[76:79], v[128:131], v[232:235], v[76:79]
	v_mfma_f32_16x16x32_bf16 v[72:75], v[136:139], v[232:235], v[72:75]
	v_mfma_f32_16x16x32_bf16 v[124:127], v[132:135], v[212:215], v[124:127]
	v_mfma_f32_16x16x32_bf16 v[120:123], v[140:143], v[212:215], v[120:123]
	v_mfma_f32_16x16x32_bf16 v[108:111], v[132:135], v[220:223], v[108:111]
	v_mfma_f32_16x16x32_bf16 v[104:107], v[140:143], v[220:223], v[104:107]
	v_mfma_f32_16x16x32_bf16 v[92:95], v[132:135], v[228:231], v[92:95]
	v_mfma_f32_16x16x32_bf16 v[88:91], v[140:143], v[228:231], v[88:91]
	v_mfma_f32_16x16x32_bf16 v[76:79], v[132:135], v[236:239], v[76:79]
	v_mfma_f32_16x16x32_bf16 v[72:75], v[140:143], v[236:239], v[72:75]
	v_mfma_f32_16x16x32_bf16 v[116:119], v[170:173], v[186:189], v[116:119]
	v_mfma_f32_16x16x32_bf16 v[112:115], v[178:181], v[186:189], v[112:115]
	v_mfma_f32_16x16x32_bf16 v[100:103], v[170:173], v[216:219], v[100:103]
	v_mfma_f32_16x16x32_bf16 v[96:99], v[178:181], v[216:219], v[96:99]
	v_mfma_f32_16x16x32_bf16 v[84:87], v[170:173], v[224:227], v[84:87]
	v_mfma_f32_16x16x32_bf16 v[80:83], v[178:181], v[224:227], v[80:83]
	v_mfma_f32_16x16x32_bf16 v[68:71], v[170:173], v[232:235], v[68:71]
	v_mfma_f32_16x16x32_bf16 v[64:67], v[178:181], v[232:235], v[64:67]
	v_mfma_f32_16x16x32_bf16 v[116:119], v[174:177], v[212:215], v[116:119]
	v_mfma_f32_16x16x32_bf16 v[112:115], v[182:185], v[212:215], v[112:115]
	v_mfma_f32_16x16x32_bf16 v[100:103], v[174:177], v[220:223], v[100:103]
	v_mfma_f32_16x16x32_bf16 v[96:99], v[182:185], v[220:223], v[96:99]
	v_mfma_f32_16x16x32_bf16 v[84:87], v[174:177], v[228:231], v[84:87]
	v_mfma_f32_16x16x32_bf16 v[80:83], v[182:185], v[228:231], v[80:83]
	v_mfma_f32_16x16x32_bf16 v[68:71], v[174:177], v[236:239], v[68:71]
	v_mfma_f32_16x16x32_bf16 v[64:67], v[182:185], v[236:239], v[64:67]
	s_barrier
	s_add_u32 s98, s48, s18
	s_addc_u32 s99, s49, s19
	s_add_u32 s100, s50, s18
	s_addc_u32 s101, s51, s19
	s_mov_b32 m0, s7
	s_add_u32 s44, s48, 0x40000
	ds_read_b128 v[186:189], v192 offset:16384
	ds_read_b128 v[212:215], v192 offset:17408
	ds_read_b128 v[216:219], v192 offset:18432
	ds_read_b128 v[220:223], v192 offset:19456
	ds_read_b128 v[224:227], v192 offset:20480
	ds_read_b128 v[228:231], v192 offset:21504
	ds_read_b128 v[232:235], v192 offset:22528
	ds_read_b128 v[236:239], v192 offset:23552
	global_load_lds_dwordx4 v158, s[48:49]
	s_mov_b32 m0, s8
	s_addc_u32 s45, s49, 0
	global_load_lds_dwordx4 v160, s[48:49]
	s_mov_b32 m0, s9
	s_nop 0
	global_load_lds_dwordx4 v158, s[44:45]
	s_mov_b32 m0, s23
	s_nop 0
	global_load_lds_dwordx4 v160, s[44:45]
	s_mov_b32 m0, s6
	s_nop 0
	global_load_lds_dwordx4 v158, s[50:51]
	s_mov_b32 m0, s28
	s_nop 0
	global_load_lds_dwordx4 v160, s[50:51]
	s_waitcnt vmcnt(8)
	s_waitcnt lgkmcnt(0)
	s_barrier
	v_mfma_f32_16x16x32_bf16 v[60:63], v[128:131], v[186:189], v[60:63]
	v_mfma_f32_16x16x32_bf16 v[56:59], v[136:139], v[186:189], v[56:59]
	v_mfma_f32_16x16x32_bf16 v[44:47], v[128:131], v[216:219], v[44:47]
	v_mfma_f32_16x16x32_bf16 v[40:43], v[136:139], v[216:219], v[40:43]
	v_mfma_f32_16x16x32_bf16 v[28:31], v[128:131], v[224:227], v[28:31]
	v_mfma_f32_16x16x32_bf16 v[24:27], v[136:139], v[224:227], v[24:27]
	v_mfma_f32_16x16x32_bf16 v[12:15], v[128:131], v[232:235], v[12:15]
	v_mfma_f32_16x16x32_bf16 v[8:11], v[136:139], v[232:235], v[8:11]
	v_mfma_f32_16x16x32_bf16 v[60:63], v[132:135], v[212:215], v[60:63]
	v_mfma_f32_16x16x32_bf16 v[56:59], v[140:143], v[212:215], v[56:59]
	v_mfma_f32_16x16x32_bf16 v[44:47], v[132:135], v[220:223], v[44:47]
	v_mfma_f32_16x16x32_bf16 v[40:43], v[140:143], v[220:223], v[40:43]
	v_mfma_f32_16x16x32_bf16 v[28:31], v[132:135], v[228:231], v[28:31]
	v_mfma_f32_16x16x32_bf16 v[24:27], v[140:143], v[228:231], v[24:27]
	v_mfma_f32_16x16x32_bf16 v[12:15], v[132:135], v[236:239], v[12:15]
	v_mfma_f32_16x16x32_bf16 v[8:11], v[140:143], v[236:239], v[8:11]
	v_mfma_f32_16x16x32_bf16 v[52:55], v[170:173], v[186:189], v[52:55]
	v_mfma_f32_16x16x32_bf16 v[48:51], v[178:181], v[186:189], v[48:51]
	v_mfma_f32_16x16x32_bf16 v[36:39], v[170:173], v[216:219], v[36:39]
	v_mfma_f32_16x16x32_bf16 v[32:35], v[178:181], v[216:219], v[32:35]
	v_mfma_f32_16x16x32_bf16 v[20:23], v[170:173], v[224:227], v[20:23]
	v_mfma_f32_16x16x32_bf16 v[16:19], v[178:181], v[224:227], v[16:19]
	v_mfma_f32_16x16x32_bf16 v[4:7], v[170:173], v[232:235], v[4:7]
	v_mfma_f32_16x16x32_bf16 v[0:3], v[178:181], v[232:235], v[0:3]
	v_mfma_f32_16x16x32_bf16 v[52:55], v[174:177], v[212:215], v[52:55]
	v_mfma_f32_16x16x32_bf16 v[48:51], v[182:185], v[212:215], v[48:51]
	v_mfma_f32_16x16x32_bf16 v[36:39], v[174:177], v[220:223], v[36:39]
	v_mfma_f32_16x16x32_bf16 v[32:35], v[182:185], v[220:223], v[32:35]
	v_mfma_f32_16x16x32_bf16 v[20:23], v[174:177], v[228:231], v[20:23]
	v_mfma_f32_16x16x32_bf16 v[16:19], v[182:185], v[228:231], v[16:19]
	v_mfma_f32_16x16x32_bf16 v[4:7], v[174:177], v[236:239], v[4:7]
	v_mfma_f32_16x16x32_bf16 v[0:3], v[182:185], v[236:239], v[0:3]
	s_barrier
	ds_read_b128 v[128:131], v203
	ds_read_b128 v[132:135], v204
	ds_read_b128 v[136:139], v205
	ds_read_b128 v[140:143], v206
	ds_read_b128 v[170:173], v207
	ds_read_b128 v[174:177], v208
	ds_read_b128 v[178:181], v209
	ds_read_b128 v[182:185], v210
	s_add_u32 s44, s50, 0x40000
	s_addc_u32 s45, s51, 0
	s_mov_b32 m0, s29
	ds_read_b128 v[186:189], v192 offset:32768
	ds_read_b128 v[212:215], v192 offset:33792
	ds_read_b128 v[216:219], v192 offset:34816
	ds_read_b128 v[220:223], v192 offset:35840
	ds_read_b128 v[224:227], v192 offset:36864
	ds_read_b128 v[228:231], v192 offset:37888
	ds_read_b128 v[232:235], v192 offset:38912
	ds_read_b128 v[236:239], v192 offset:39936
	global_load_lds_dwordx4 v158, s[44:45]
	s_mov_b32 m0, s30
	s_nop 0
	global_load_lds_dwordx4 v160, s[44:45]
	s_waitcnt vmcnt(8)
	s_waitcnt lgkmcnt(0)
	s_barrier
	v_mfma_f32_16x16x32_bf16 v[124:127], v[128:131], v[186:189], v[124:127]
	v_mfma_f32_16x16x32_bf16 v[120:123], v[136:139], v[186:189], v[120:123]
	v_mfma_f32_16x16x32_bf16 v[108:111], v[128:131], v[216:219], v[108:111]
	v_mfma_f32_16x16x32_bf16 v[104:107], v[136:139], v[216:219], v[104:107]
	v_mfma_f32_16x16x32_bf16 v[92:95], v[128:131], v[224:227], v[92:95]
	v_mfma_f32_16x16x32_bf16 v[88:91], v[136:139], v[224:227], v[88:91]
	v_mfma_f32_16x16x32_bf16 v[76:79], v[128:131], v[232:235], v[76:79]
	v_mfma_f32_16x16x32_bf16 v[72:75], v[136:139], v[232:235], v[72:75]
	v_mfma_f32_16x16x32_bf16 v[124:127], v[132:135], v[212:215], v[124:127]
	v_mfma_f32_16x16x32_bf16 v[120:123], v[140:143], v[212:215], v[120:123]
	v_mfma_f32_16x16x32_bf16 v[108:111], v[132:135], v[220:223], v[108:111]
	v_mfma_f32_16x16x32_bf16 v[104:107], v[140:143], v[220:223], v[104:107]
	v_mfma_f32_16x16x32_bf16 v[92:95], v[132:135], v[228:231], v[92:95]
	v_mfma_f32_16x16x32_bf16 v[88:91], v[140:143], v[228:231], v[88:91]
	v_mfma_f32_16x16x32_bf16 v[76:79], v[132:135], v[236:239], v[76:79]
	v_mfma_f32_16x16x32_bf16 v[72:75], v[140:143], v[236:239], v[72:75]
	v_mfma_f32_16x16x32_bf16 v[116:119], v[170:173], v[186:189], v[116:119]
	v_mfma_f32_16x16x32_bf16 v[112:115], v[178:181], v[186:189], v[112:115]
	v_mfma_f32_16x16x32_bf16 v[100:103], v[170:173], v[216:219], v[100:103]
	v_mfma_f32_16x16x32_bf16 v[96:99], v[178:181], v[216:219], v[96:99]
	v_mfma_f32_16x16x32_bf16 v[84:87], v[170:173], v[224:227], v[84:87]
	v_mfma_f32_16x16x32_bf16 v[80:83], v[178:181], v[224:227], v[80:83]
	v_mfma_f32_16x16x32_bf16 v[68:71], v[170:173], v[232:235], v[68:71]
	v_mfma_f32_16x16x32_bf16 v[64:67], v[178:181], v[232:235], v[64:67]
	v_mfma_f32_16x16x32_bf16 v[116:119], v[174:177], v[212:215], v[116:119]
	v_mfma_f32_16x16x32_bf16 v[112:115], v[182:185], v[212:215], v[112:115]
	v_mfma_f32_16x16x32_bf16 v[100:103], v[174:177], v[220:223], v[100:103]
	v_mfma_f32_16x16x32_bf16 v[96:99], v[182:185], v[220:223], v[96:99]
	v_mfma_f32_16x16x32_bf16 v[84:87], v[174:177], v[228:231], v[84:87]
	v_mfma_f32_16x16x32_bf16 v[80:83], v[182:185], v[228:231], v[80:83]
	v_mfma_f32_16x16x32_bf16 v[68:71], v[174:177], v[236:239], v[68:71]
	v_mfma_f32_16x16x32_bf16 v[64:67], v[182:185], v[236:239], v[64:67]
	s_barrier
	s_mov_b32 m0, s31
	s_add_u32 s44, s48, 0x40080
	ds_read_b128 v[186:189], v192 offset:49152
	ds_read_b128 v[212:215], v192 offset:50176
	ds_read_b128 v[216:219], v192 offset:51200
	ds_read_b128 v[220:223], v192 offset:52224
	ds_read_b128 v[224:227], v192 offset:53248
	ds_read_b128 v[228:231], v192 offset:54272
	ds_read_b128 v[232:235], v192 offset:55296
	ds_read_b128 v[236:239], v192 offset:56320
	global_load_lds_dwordx4 v158, s[98:99]
	s_mov_b32 m0, s33
	s_addc_u32 s45, s49, 0
	global_load_lds_dwordx4 v160, s[98:99]
	s_mov_b32 m0, s36
	s_nop 0
	global_load_lds_dwordx4 v158, s[44:45]
	s_mov_b32 m0, s37
	s_nop 0
	global_load_lds_dwordx4 v160, s[44:45]
	s_mov_b32 m0, s34
	s_nop 0
	global_load_lds_dwordx4 v158, s[100:101]
	s_mov_b32 m0, s35
	s_nop 0
	global_load_lds_dwordx4 v160, s[100:101]
	s_waitcnt vmcnt(8)
	s_waitcnt lgkmcnt(0)
	s_barrier
	v_mfma_f32_16x16x32_bf16 v[60:63], v[128:131], v[186:189], v[60:63]
	v_mfma_f32_16x16x32_bf16 v[56:59], v[136:139], v[186:189], v[56:59]
	v_mfma_f32_16x16x32_bf16 v[44:47], v[128:131], v[216:219], v[44:47]
	v_mfma_f32_16x16x32_bf16 v[40:43], v[136:139], v[216:219], v[40:43]
	v_mfma_f32_16x16x32_bf16 v[28:31], v[128:131], v[224:227], v[28:31]
	v_mfma_f32_16x16x32_bf16 v[24:27], v[136:139], v[224:227], v[24:27]
	v_mfma_f32_16x16x32_bf16 v[12:15], v[128:131], v[232:235], v[12:15]
	v_mfma_f32_16x16x32_bf16 v[8:11], v[136:139], v[232:235], v[8:11]
	v_mfma_f32_16x16x32_bf16 v[60:63], v[132:135], v[212:215], v[60:63]
	v_mfma_f32_16x16x32_bf16 v[56:59], v[140:143], v[212:215], v[56:59]
	v_mfma_f32_16x16x32_bf16 v[44:47], v[132:135], v[220:223], v[44:47]
	v_mfma_f32_16x16x32_bf16 v[40:43], v[140:143], v[220:223], v[40:43]
	v_mfma_f32_16x16x32_bf16 v[28:31], v[132:135], v[228:231], v[28:31]
	v_mfma_f32_16x16x32_bf16 v[24:27], v[140:143], v[228:231], v[24:27]
	v_mfma_f32_16x16x32_bf16 v[12:15], v[132:135], v[236:239], v[12:15]
	v_mfma_f32_16x16x32_bf16 v[8:11], v[140:143], v[236:239], v[8:11]
	v_mfma_f32_16x16x32_bf16 v[52:55], v[170:173], v[186:189], v[52:55]
	v_mfma_f32_16x16x32_bf16 v[48:51], v[178:181], v[186:189], v[48:51]
	v_mfma_f32_16x16x32_bf16 v[36:39], v[170:173], v[216:219], v[36:39]
	v_mfma_f32_16x16x32_bf16 v[32:35], v[178:181], v[216:219], v[32:35]
	v_mfma_f32_16x16x32_bf16 v[20:23], v[170:173], v[224:227], v[20:23]
	v_mfma_f32_16x16x32_bf16 v[16:19], v[178:181], v[224:227], v[16:19]
	v_mfma_f32_16x16x32_bf16 v[4:7], v[170:173], v[232:235], v[4:7]
	v_mfma_f32_16x16x32_bf16 v[0:3], v[178:181], v[232:235], v[0:3]
	v_mfma_f32_16x16x32_bf16 v[52:55], v[174:177], v[212:215], v[52:55]
	v_mfma_f32_16x16x32_bf16 v[48:51], v[182:185], v[212:215], v[48:51]
	v_mfma_f32_16x16x32_bf16 v[36:39], v[174:177], v[220:223], v[36:39]
	v_mfma_f32_16x16x32_bf16 v[32:35], v[182:185], v[220:223], v[32:35]
	v_mfma_f32_16x16x32_bf16 v[20:23], v[174:177], v[228:231], v[20:23]
	v_mfma_f32_16x16x32_bf16 v[16:19], v[182:185], v[228:231], v[16:19]
	v_mfma_f32_16x16x32_bf16 v[4:7], v[174:177], v[236:239], v[4:7]
	v_mfma_f32_16x16x32_bf16 v[0:3], v[182:185], v[236:239], v[0:3]
	s_barrier
	s_add_i32 s68, s68, 2
	s_add_u32 s66, s66, 0x100
	s_addc_u32 s67, s67, 0
	s_cmp_gt_u32 s68, 13
	s_mov_b64 s[44:45], s[46:47]
	s_cbranch_scc0 .LBB0_2801
	s_and_b64 vcc, exec, s[20:21]
	s_cbranch_vccz .LBB0_2804
	s_barrier

.LBB0_2949:
	ds_read_b128 v[172:175], v143
	ds_read_b128 v[176:179], v153
	ds_read_b128 v[180:183], v158
	ds_read_b128 v[184:187], v159
	ds_read_b128 v[188:191], v160
	ds_read_b128 v[196:199], v161
	ds_read_b128 v[200:203], v162
	ds_read_b128 v[204:207], v163
	s_add_u32 s26, s24, 0xfffc0080
	s_addc_u32 s27, s25, -1
	s_cmp_eq_u32 s53, 12
	s_cselect_b32 s37, s4, s27
	s_cselect_b32 s36, s5, s26
	s_cselect_b32 s27, s15, s52
	s_cselect_b32 s26, s17, s51
	s_mov_b32 m0, s47
	ds_read_b128 v[208:211], v141
	ds_read_b128 v[212:215], v141 offset:1024
	ds_read_b128 v[216:219], v141 offset:2048
	ds_read_b128 v[220:223], v141 offset:3072
	ds_read_b128 v[224:227], v141 offset:4096
	ds_read_b128 v[228:231], v141 offset:5120
	ds_read_b128 v[232:235], v141 offset:6144
	ds_read_b128 v[236:239], v141 offset:7168
	global_load_lds_dwordx4 v132, s[24:25]
	s_mov_b32 m0, s48
	s_nop 0
	global_load_lds_dwordx4 v134, s[24:25]
	s_waitcnt vmcnt(8)
	s_waitcnt lgkmcnt(0)
	s_barrier
	v_mfma_f32_16x16x32_bf16 v[124:127], v[172:175], v[208:211], v[124:127]
	v_mfma_f32_16x16x32_bf16 v[120:123], v[180:183], v[208:211], v[120:123]
	v_mfma_f32_16x16x32_bf16 v[108:111], v[172:175], v[216:219], v[108:111]
	v_mfma_f32_16x16x32_bf16 v[104:107], v[180:183], v[216:219], v[104:107]
	v_mfma_f32_16x16x32_bf16 v[92:95], v[172:175], v[224:227], v[92:95]
	v_mfma_f32_16x16x32_bf16 v[88:91], v[180:183], v[224:227], v[88:91]
	v_mfma_f32_16x16x32_bf16 v[76:79], v[172:175], v[232:235], v[76:79]
	v_mfma_f32_16x16x32_bf16 v[72:75], v[180:183], v[232:235], v[72:75]
	v_mfma_f32_16x16x32_bf16 v[124:127], v[176:179], v[212:215], v[124:127]
	v_mfma_f32_16x16x32_bf16 v[120:123], v[184:187], v[212:215], v[120:123]
	v_mfma_f32_16x16x32_bf16 v[108:111], v[176:179], v[220:223], v[108:111]
	v_mfma_f32_16x16x32_bf16 v[104:107], v[184:187], v[220:223], v[104:107]
	v_mfma_f32_16x16x32_bf16 v[92:95], v[176:179], v[228:231], v[92:95]
	v_mfma_f32_16x16x32_bf16 v[88:91], v[184:187], v[228:231], v[88:91]
	v_mfma_f32_16x16x32_bf16 v[76:79], v[176:179], v[236:239], v[76:79]
	v_mfma_f32_16x16x32_bf16 v[72:75], v[184:187], v[236:239], v[72:75]
	v_mfma_f32_16x16x32_bf16 v[116:119], v[188:191], v[208:211], v[116:119]
	v_mfma_f32_16x16x32_bf16 v[112:115], v[200:203], v[208:211], v[112:115]
	v_mfma_f32_16x16x32_bf16 v[100:103], v[188:191], v[216:219], v[100:103]
	v_mfma_f32_16x16x32_bf16 v[96:99], v[200:203], v[216:219], v[96:99]
	v_mfma_f32_16x16x32_bf16 v[84:87], v[188:191], v[224:227], v[84:87]
	v_mfma_f32_16x16x32_bf16 v[80:83], v[200:203], v[224:227], v[80:83]
	v_mfma_f32_16x16x32_bf16 v[68:71], v[188:191], v[232:235], v[68:71]
	v_mfma_f32_16x16x32_bf16 v[64:67], v[200:203], v[232:235], v[64:67]
	v_mfma_f32_16x16x32_bf16 v[116:119], v[196:199], v[212:215], v[116:119]
	v_mfma_f32_16x16x32_bf16 v[112:115], v[204:207], v[212:215], v[112:115]
	v_mfma_f32_16x16x32_bf16 v[100:103], v[196:199], v[220:223], v[100:103]
	v_mfma_f32_16x16x32_bf16 v[96:99], v[204:207], v[220:223], v[96:99]
	v_mfma_f32_16x16x32_bf16 v[84:87], v[196:199], v[228:231], v[84:87]
	v_mfma_f32_16x16x32_bf16 v[80:83], v[204:207], v[228:231], v[80:83]
	v_mfma_f32_16x16x32_bf16 v[68:71], v[196:199], v[236:239], v[68:71]
	v_mfma_f32_16x16x32_bf16 v[64:67], v[204:207], v[236:239], v[64:67]
	s_barrier
	s_add_u32 s98, s26, s10
	s_addc_u32 s99, s27, s11
	s_add_u32 s100, s36, s10
	s_addc_u32 s101, s37, s11
	s_mov_b32 m0, s23
	s_add_u32 s54, s26, 0x40000
	ds_read_b128 v[208:211], v141 offset:16384
	ds_read_b128 v[212:215], v141 offset:17408
	ds_read_b128 v[216:219], v141 offset:18432
	ds_read_b128 v[220:223], v141 offset:19456
	ds_read_b128 v[224:227], v141 offset:20480
	ds_read_b128 v[228:231], v141 offset:21504
	ds_read_b128 v[232:235], v141 offset:22528
	ds_read_b128 v[236:239], v141 offset:23552
	global_load_lds_dwordx4 v130, s[26:27]
	s_mov_b32 m0, s28
	s_addc_u32 s55, s27, 0
	global_load_lds_dwordx4 v128, s[26:27]
	s_mov_b32 m0, s29
	s_nop 0
	global_load_lds_dwordx4 v130, s[54:55]
	s_mov_b32 m0, s30
	s_nop 0
	global_load_lds_dwordx4 v128, s[54:55]
	s_mov_b32 m0, s2
	s_nop 0
	global_load_lds_dwordx4 v130, s[36:37]
	s_mov_b32 m0, s31
	s_nop 0
	global_load_lds_dwordx4 v128, s[36:37]
	s_waitcnt vmcnt(8)
	s_waitcnt lgkmcnt(0)
	s_barrier
	v_mfma_f32_16x16x32_bf16 v[60:63], v[172:175], v[208:211], v[60:63]
	v_mfma_f32_16x16x32_bf16 v[56:59], v[180:183], v[208:211], v[56:59]
	v_mfma_f32_16x16x32_bf16 v[44:47], v[172:175], v[216:219], v[44:47]
	v_mfma_f32_16x16x32_bf16 v[40:43], v[180:183], v[216:219], v[40:43]
	v_mfma_f32_16x16x32_bf16 v[28:31], v[172:175], v[224:227], v[28:31]
	v_mfma_f32_16x16x32_bf16 v[24:27], v[180:183], v[224:227], v[24:27]
	v_mfma_f32_16x16x32_bf16 v[12:15], v[172:175], v[232:235], v[12:15]
	v_mfma_f32_16x16x32_bf16 v[8:11], v[180:183], v[232:235], v[8:11]
	v_mfma_f32_16x16x32_bf16 v[60:63], v[176:179], v[212:215], v[60:63]
	v_mfma_f32_16x16x32_bf16 v[56:59], v[184:187], v[212:215], v[56:59]
	v_mfma_f32_16x16x32_bf16 v[44:47], v[176:179], v[220:223], v[44:47]
	v_mfma_f32_16x16x32_bf16 v[40:43], v[184:187], v[220:223], v[40:43]
	v_mfma_f32_16x16x32_bf16 v[28:31], v[176:179], v[228:231], v[28:31]
	v_mfma_f32_16x16x32_bf16 v[24:27], v[184:187], v[228:231], v[24:27]
	v_mfma_f32_16x16x32_bf16 v[12:15], v[176:179], v[236:239], v[12:15]
	v_mfma_f32_16x16x32_bf16 v[8:11], v[184:187], v[236:239], v[8:11]
	v_mfma_f32_16x16x32_bf16 v[52:55], v[188:191], v[208:211], v[52:55]
	v_mfma_f32_16x16x32_bf16 v[48:51], v[200:203], v[208:211], v[48:51]
	v_mfma_f32_16x16x32_bf16 v[36:39], v[188:191], v[216:219], v[36:39]
	v_mfma_f32_16x16x32_bf16 v[32:35], v[200:203], v[216:219], v[32:35]
	v_mfma_f32_16x16x32_bf16 v[20:23], v[188:191], v[224:227], v[20:23]
	v_mfma_f32_16x16x32_bf16 v[16:19], v[200:203], v[224:227], v[16:19]
	v_mfma_f32_16x16x32_bf16 v[4:7], v[188:191], v[232:235], v[4:7]
	v_mfma_f32_16x16x32_bf16 v[0:3], v[200:203], v[232:235], v[0:3]
	v_mfma_f32_16x16x32_bf16 v[52:55], v[196:199], v[212:215], v[52:55]
	v_mfma_f32_16x16x32_bf16 v[48:51], v[204:207], v[212:215], v[48:51]
	v_mfma_f32_16x16x32_bf16 v[36:39], v[196:199], v[220:223], v[36:39]
	v_mfma_f32_16x16x32_bf16 v[32:35], v[204:207], v[220:223], v[32:35]
	v_mfma_f32_16x16x32_bf16 v[20:23], v[196:199], v[228:231], v[20:23]
	v_mfma_f32_16x16x32_bf16 v[16:19], v[204:207], v[228:231], v[16:19]
	v_mfma_f32_16x16x32_bf16 v[4:7], v[196:199], v[236:239], v[4:7]
	v_mfma_f32_16x16x32_bf16 v[0:3], v[204:207], v[236:239], v[0:3]
	s_barrier
	ds_read_b128 v[172:175], v164
	ds_read_b128 v[176:179], v165
	ds_read_b128 v[180:183], v166
	ds_read_b128 v[184:187], v167
	ds_read_b128 v[188:191], v168
	ds_read_b128 v[196:199], v169
	ds_read_b128 v[200:203], v170
	ds_read_b128 v[204:207], v171
	s_add_u32 s36, s36, 0x40000
	s_addc_u32 s37, s37, 0
	s_mov_b32 m0, s33
	ds_read_b128 v[208:211], v141 offset:32768
	ds_read_b128 v[212:215], v141 offset:33792
	ds_read_b128 v[216:219], v141 offset:34816
	ds_read_b128 v[220:223], v141 offset:35840
	ds_read_b128 v[224:227], v141 offset:36864
	ds_read_b128 v[228:231], v141 offset:37888
	ds_read_b128 v[232:235], v141 offset:38912
	ds_read_b128 v[236:239], v141 offset:39936
	global_load_lds_dwordx4 v130, s[36:37]
	s_mov_b32 m0, s34
	s_nop 0
	global_load_lds_dwordx4 v128, s[36:37]
	s_waitcnt vmcnt(8)
	s_waitcnt lgkmcnt(0)
	s_barrier
	v_mfma_f32_16x16x32_bf16 v[124:127], v[172:175], v[208:211], v[124:127]
	v_mfma_f32_16x16x32_bf16 v[120:123], v[180:183], v[208:211], v[120:123]
	v_mfma_f32_16x16x32_bf16 v[108:111], v[172:175], v[216:219], v[108:111]
	v_mfma_f32_16x16x32_bf16 v[104:107], v[180:183], v[216:219], v[104:107]
	v_mfma_f32_16x16x32_bf16 v[92:95], v[172:175], v[224:227], v[92:95]
	v_mfma_f32_16x16x32_bf16 v[88:91], v[180:183], v[224:227], v[88:91]
	v_mfma_f32_16x16x32_bf16 v[76:79], v[172:175], v[232:235], v[76:79]
	v_mfma_f32_16x16x32_bf16 v[72:75], v[180:183], v[232:235], v[72:75]
	v_mfma_f32_16x16x32_bf16 v[124:127], v[176:179], v[212:215], v[124:127]
	v_mfma_f32_16x16x32_bf16 v[120:123], v[184:187], v[212:215], v[120:123]
	v_mfma_f32_16x16x32_bf16 v[108:111], v[176:179], v[220:223], v[108:111]
	v_mfma_f32_16x16x32_bf16 v[104:107], v[184:187], v[220:223], v[104:107]
	v_mfma_f32_16x16x32_bf16 v[92:95], v[176:179], v[228:231], v[92:95]
	v_mfma_f32_16x16x32_bf16 v[88:91], v[184:187], v[228:231], v[88:91]
	v_mfma_f32_16x16x32_bf16 v[76:79], v[176:179], v[236:239], v[76:79]
	v_mfma_f32_16x16x32_bf16 v[72:75], v[184:187], v[236:239], v[72:75]
	v_mfma_f32_16x16x32_bf16 v[116:119], v[188:191], v[208:211], v[116:119]
	v_mfma_f32_16x16x32_bf16 v[112:115], v[200:203], v[208:211], v[112:115]
	v_mfma_f32_16x16x32_bf16 v[100:103], v[188:191], v[216:219], v[100:103]
	v_mfma_f32_16x16x32_bf16 v[96:99], v[200:203], v[216:219], v[96:99]
	v_mfma_f32_16x16x32_bf16 v[84:87], v[188:191], v[224:227], v[84:87]
	v_mfma_f32_16x16x32_bf16 v[80:83], v[200:203], v[224:227], v[80:83]
	v_mfma_f32_16x16x32_bf16 v[68:71], v[188:191], v[232:235], v[68:71]
	v_mfma_f32_16x16x32_bf16 v[64:67], v[200:203], v[232:235], v[64:67]
	v_mfma_f32_16x16x32_bf16 v[116:119], v[196:199], v[212:215], v[116:119]
	v_mfma_f32_16x16x32_bf16 v[112:115], v[204:207], v[212:215], v[112:115]
	v_mfma_f32_16x16x32_bf16 v[100:103], v[196:199], v[220:223], v[100:103]
	v_mfma_f32_16x16x32_bf16 v[96:99], v[204:207], v[220:223], v[96:99]
	v_mfma_f32_16x16x32_bf16 v[84:87], v[196:199], v[228:231], v[84:87]
	v_mfma_f32_16x16x32_bf16 v[80:83], v[204:207], v[228:231], v[80:83]
	v_mfma_f32_16x16x32_bf16 v[68:71], v[196:199], v[236:239], v[68:71]
	v_mfma_f32_16x16x32_bf16 v[64:67], v[204:207], v[236:239], v[64:67]
	s_barrier
	s_mov_b32 m0, s39
	s_add_u32 s26, s26, 0x40080
	ds_read_b128 v[208:211], v141 offset:49152
	ds_read_b128 v[212:215], v141 offset:50176
	ds_read_b128 v[216:219], v141 offset:51200
	ds_read_b128 v[220:223], v141 offset:52224
	ds_read_b128 v[224:227], v141 offset:53248
	ds_read_b128 v[228:231], v141 offset:54272
	ds_read_b128 v[232:235], v141 offset:55296
	ds_read_b128 v[236:239], v141 offset:56320
	global_load_lds_dwordx4 v130, s[98:99]
	s_mov_b32 m0, s40
	s_addc_u32 s27, s27, 0
	global_load_lds_dwordx4 v128, s[98:99]
	s_mov_b32 m0, s43
	s_nop 0
	global_load_lds_dwordx4 v130, s[26:27]
	s_mov_b32 m0, s44
	s_nop 0
	global_load_lds_dwordx4 v128, s[26:27]
	s_mov_b32 m0, s41
	s_nop 0
	global_load_lds_dwordx4 v130, s[100:101]
	s_mov_b32 m0, s42
	s_nop 0
	global_load_lds_dwordx4 v128, s[100:101]
	s_waitcnt vmcnt(8)
	s_waitcnt lgkmcnt(0)
	s_barrier
	v_mfma_f32_16x16x32_bf16 v[60:63], v[172:175], v[208:211], v[60:63]
	v_mfma_f32_16x16x32_bf16 v[56:59], v[180:183], v[208:211], v[56:59]
	v_mfma_f32_16x16x32_bf16 v[44:47], v[172:175], v[216:219], v[44:47]
	v_mfma_f32_16x16x32_bf16 v[40:43], v[180:183], v[216:219], v[40:43]
	v_mfma_f32_16x16x32_bf16 v[28:31], v[172:175], v[224:227], v[28:31]
	v_mfma_f32_16x16x32_bf16 v[24:27], v[180:183], v[224:227], v[24:27]
	v_mfma_f32_16x16x32_bf16 v[12:15], v[172:175], v[232:235], v[12:15]
	v_mfma_f32_16x16x32_bf16 v[8:11], v[180:183], v[232:235], v[8:11]
	v_mfma_f32_16x16x32_bf16 v[60:63], v[176:179], v[212:215], v[60:63]
	v_mfma_f32_16x16x32_bf16 v[56:59], v[184:187], v[212:215], v[56:59]
	v_mfma_f32_16x16x32_bf16 v[44:47], v[176:179], v[220:223], v[44:47]
	v_mfma_f32_16x16x32_bf16 v[40:43], v[184:187], v[220:223], v[40:43]
	v_mfma_f32_16x16x32_bf16 v[28:31], v[176:179], v[228:231], v[28:31]
	v_mfma_f32_16x16x32_bf16 v[24:27], v[184:187], v[228:231], v[24:27]
	v_mfma_f32_16x16x32_bf16 v[12:15], v[176:179], v[236:239], v[12:15]
	v_mfma_f32_16x16x32_bf16 v[8:11], v[184:187], v[236:239], v[8:11]
	v_mfma_f32_16x16x32_bf16 v[52:55], v[188:191], v[208:211], v[52:55]
	v_mfma_f32_16x16x32_bf16 v[48:51], v[200:203], v[208:211], v[48:51]
	v_mfma_f32_16x16x32_bf16 v[36:39], v[188:191], v[216:219], v[36:39]
	v_mfma_f32_16x16x32_bf16 v[32:35], v[200:203], v[216:219], v[32:35]
	v_mfma_f32_16x16x32_bf16 v[20:23], v[188:191], v[224:227], v[20:23]
	v_mfma_f32_16x16x32_bf16 v[16:19], v[200:203], v[224:227], v[16:19]
	v_mfma_f32_16x16x32_bf16 v[4:7], v[188:191], v[232:235], v[4:7]
	v_mfma_f32_16x16x32_bf16 v[0:3], v[200:203], v[232:235], v[0:3]
	v_mfma_f32_16x16x32_bf16 v[52:55], v[196:199], v[212:215], v[52:55]
	v_mfma_f32_16x16x32_bf16 v[48:51], v[204:207], v[212:215], v[48:51]
	v_mfma_f32_16x16x32_bf16 v[36:39], v[196:199], v[220:223], v[36:39]
	v_mfma_f32_16x16x32_bf16 v[32:35], v[204:207], v[220:223], v[32:35]
	v_mfma_f32_16x16x32_bf16 v[20:23], v[196:199], v[228:231], v[20:23]
	v_mfma_f32_16x16x32_bf16 v[16:19], v[204:207], v[228:231], v[16:19]
	v_mfma_f32_16x16x32_bf16 v[4:7], v[196:199], v[236:239], v[4:7]
	v_mfma_f32_16x16x32_bf16 v[0:3], v[204:207], v[236:239], v[0:3]
	s_barrier
	s_add_i32 s53, s53, 2
	s_add_u32 s24, s24, 0x100
	s_addc_u32 s25, s25, 0
	s_add_u32 s51, s51, 0x100
	s_addc_u32 s52, s52, 0
	s_cmp_gt_u32 s53, 13
	s_cbranch_scc0 .LBB0_2949
	s_and_b64 vcc, exec, s[12:13]
	s_cbranch_vccz .LBB0_2952
	s_barrier

.LBB0_3029:
	ds_read_b128 v[128:131], v195
	ds_read_b128 v[132:135], v196
	ds_read_b128 v[136:139], v197
	ds_read_b128 v[140:143], v198
	ds_read_b128 v[170:173], v199
	ds_read_b128 v[174:177], v200
	ds_read_b128 v[178:181], v201
	ds_read_b128 v[182:185], v202
	s_add_u32 s34, s26, 0x100
	s_addc_u32 s35, s27, 0
	s_cmp_eq_u32 s64, 40
	s_cselect_b32 s39, s11, s35
	s_cselect_b32 s38, s10, s34
	s_cselect_b32 s37, s25, s5
	s_cselect_b32 s36, s24, s4
	s_mov_b32 m0, s50
	ds_read_b128 v[186:189], v192
	ds_read_b128 v[212:215], v192 offset:1024
	ds_read_b128 v[216:219], v192 offset:2048
	ds_read_b128 v[220:223], v192 offset:3072
	ds_read_b128 v[224:227], v192 offset:4096
	ds_read_b128 v[228:231], v192 offset:5120
	ds_read_b128 v[232:235], v192 offset:6144
	ds_read_b128 v[236:239], v192 offset:7168
	global_load_lds_dwordx4 v162, s[26:27]
	s_mov_b32 m0, s51
	s_nop 0
	global_load_lds_dwordx4 v164, s[26:27]
	s_waitcnt vmcnt(8)
	s_waitcnt lgkmcnt(0)
	s_barrier
	v_mfma_f32_16x16x32_bf16 v[124:127], v[128:131], v[186:189], v[124:127]
	v_mfma_f32_16x16x32_bf16 v[120:123], v[136:139], v[186:189], v[120:123]
	v_mfma_f32_16x16x32_bf16 v[108:111], v[128:131], v[216:219], v[108:111]
	v_mfma_f32_16x16x32_bf16 v[104:107], v[136:139], v[216:219], v[104:107]
	v_mfma_f32_16x16x32_bf16 v[92:95], v[128:131], v[224:227], v[92:95]
	v_mfma_f32_16x16x32_bf16 v[88:91], v[136:139], v[224:227], v[88:91]
	v_mfma_f32_16x16x32_bf16 v[76:79], v[128:131], v[232:235], v[76:79]
	v_mfma_f32_16x16x32_bf16 v[72:75], v[136:139], v[232:235], v[72:75]
	v_mfma_f32_16x16x32_bf16 v[124:127], v[132:135], v[212:215], v[124:127]
	v_mfma_f32_16x16x32_bf16 v[120:123], v[140:143], v[212:215], v[120:123]
	v_mfma_f32_16x16x32_bf16 v[108:111], v[132:135], v[220:223], v[108:111]
	v_mfma_f32_16x16x32_bf16 v[104:107], v[140:143], v[220:223], v[104:107]
	v_mfma_f32_16x16x32_bf16 v[92:95], v[132:135], v[228:231], v[92:95]
	v_mfma_f32_16x16x32_bf16 v[88:91], v[140:143], v[228:231], v[88:91]
	v_mfma_f32_16x16x32_bf16 v[76:79], v[132:135], v[236:239], v[76:79]
	v_mfma_f32_16x16x32_bf16 v[72:75], v[140:143], v[236:239], v[72:75]
	v_mfma_f32_16x16x32_bf16 v[116:119], v[170:173], v[186:189], v[116:119]
	v_mfma_f32_16x16x32_bf16 v[112:115], v[178:181], v[186:189], v[112:115]
	v_mfma_f32_16x16x32_bf16 v[100:103], v[170:173], v[216:219], v[100:103]
	v_mfma_f32_16x16x32_bf16 v[96:99], v[178:181], v[216:219], v[96:99]
	v_mfma_f32_16x16x32_bf16 v[84:87], v[170:173], v[224:227], v[84:87]
	v_mfma_f32_16x16x32_bf16 v[80:83], v[178:181], v[224:227], v[80:83]
	v_mfma_f32_16x16x32_bf16 v[68:71], v[170:173], v[232:235], v[68:71]
	v_mfma_f32_16x16x32_bf16 v[64:67], v[178:181], v[232:235], v[64:67]
	v_mfma_f32_16x16x32_bf16 v[116:119], v[174:177], v[212:215], v[116:119]
	v_mfma_f32_16x16x32_bf16 v[112:115], v[182:185], v[212:215], v[112:115]
	v_mfma_f32_16x16x32_bf16 v[100:103], v[174:177], v[220:223], v[100:103]
	v_mfma_f32_16x16x32_bf16 v[96:99], v[182:185], v[220:223], v[96:99]
	v_mfma_f32_16x16x32_bf16 v[84:87], v[174:177], v[228:231], v[84:87]
	v_mfma_f32_16x16x32_bf16 v[80:83], v[182:185], v[228:231], v[80:83]
	v_mfma_f32_16x16x32_bf16 v[68:71], v[174:177], v[236:239], v[68:71]
	v_mfma_f32_16x16x32_bf16 v[64:67], v[182:185], v[236:239], v[64:67]
	s_barrier
	s_add_u32 s98, s36, s18
	s_addc_u32 s99, s37, s19
	s_add_u32 s100, s38, s18
	s_addc_u32 s101, s39, s19
	s_mov_b32 m0, s7
	s_add_u32 s26, s36, 0xb0000
	ds_read_b128 v[186:189], v192 offset:16384
	ds_read_b128 v[212:215], v192 offset:17408
	ds_read_b128 v[216:219], v192 offset:18432
	ds_read_b128 v[220:223], v192 offset:19456
	ds_read_b128 v[224:227], v192 offset:20480
	ds_read_b128 v[228:231], v192 offset:21504
	ds_read_b128 v[232:235], v192 offset:22528
	ds_read_b128 v[236:239], v192 offset:23552
	global_load_lds_dwordx4 v158, s[36:37]
	s_mov_b32 m0, s23
	s_addc_u32 s27, s37, 0
	global_load_lds_dwordx4 v160, s[36:37]
	s_mov_b32 m0, s28
	s_nop 0
	global_load_lds_dwordx4 v158, s[26:27]
	s_mov_b32 m0, s29
	s_nop 0
	global_load_lds_dwordx4 v160, s[26:27]
	s_mov_b32 m0, s6
	s_nop 0
	global_load_lds_dwordx4 v158, s[38:39]
	s_mov_b32 m0, s30
	s_nop 0
	global_load_lds_dwordx4 v160, s[38:39]
	s_waitcnt vmcnt(8)
	s_waitcnt lgkmcnt(0)
	s_barrier
	v_mfma_f32_16x16x32_bf16 v[60:63], v[128:131], v[186:189], v[60:63]
	v_mfma_f32_16x16x32_bf16 v[56:59], v[136:139], v[186:189], v[56:59]
	v_mfma_f32_16x16x32_bf16 v[44:47], v[128:131], v[216:219], v[44:47]
	v_mfma_f32_16x16x32_bf16 v[40:43], v[136:139], v[216:219], v[40:43]
	v_mfma_f32_16x16x32_bf16 v[28:31], v[128:131], v[224:227], v[28:31]
	v_mfma_f32_16x16x32_bf16 v[24:27], v[136:139], v[224:227], v[24:27]
	v_mfma_f32_16x16x32_bf16 v[12:15], v[128:131], v[232:235], v[12:15]
	v_mfma_f32_16x16x32_bf16 v[8:11], v[136:139], v[232:235], v[8:11]
	v_mfma_f32_16x16x32_bf16 v[60:63], v[132:135], v[212:215], v[60:63]
	v_mfma_f32_16x16x32_bf16 v[56:59], v[140:143], v[212:215], v[56:59]
	v_mfma_f32_16x16x32_bf16 v[44:47], v[132:135], v[220:223], v[44:47]
	v_mfma_f32_16x16x32_bf16 v[40:43], v[140:143], v[220:223], v[40:43]
	v_mfma_f32_16x16x32_bf16 v[28:31], v[132:135], v[228:231], v[28:31]
	v_mfma_f32_16x16x32_bf16 v[24:27], v[140:143], v[228:231], v[24:27]
	v_mfma_f32_16x16x32_bf16 v[12:15], v[132:135], v[236:239], v[12:15]
	v_mfma_f32_16x16x32_bf16 v[8:11], v[140:143], v[236:239], v[8:11]
	v_mfma_f32_16x16x32_bf16 v[52:55], v[170:173], v[186:189], v[52:55]
	v_mfma_f32_16x16x32_bf16 v[48:51], v[178:181], v[186:189], v[48:51]
	v_mfma_f32_16x16x32_bf16 v[36:39], v[170:173], v[216:219], v[36:39]
	v_mfma_f32_16x16x32_bf16 v[32:35], v[178:181], v[216:219], v[32:35]
	v_mfma_f32_16x16x32_bf16 v[20:23], v[170:173], v[224:227], v[20:23]
	v_mfma_f32_16x16x32_bf16 v[16:19], v[178:181], v[224:227], v[16:19]
	v_mfma_f32_16x16x32_bf16 v[4:7], v[170:173], v[232:235], v[4:7]
	v_mfma_f32_16x16x32_bf16 v[0:3], v[178:181], v[232:235], v[0:3]
	v_mfma_f32_16x16x32_bf16 v[52:55], v[174:177], v[212:215], v[52:55]
	v_mfma_f32_16x16x32_bf16 v[48:51], v[182:185], v[212:215], v[48:51]
	v_mfma_f32_16x16x32_bf16 v[36:39], v[174:177], v[220:223], v[36:39]
	v_mfma_f32_16x16x32_bf16 v[32:35], v[182:185], v[220:223], v[32:35]
	v_mfma_f32_16x16x32_bf16 v[20:23], v[174:177], v[228:231], v[20:23]
	v_mfma_f32_16x16x32_bf16 v[16:19], v[182:185], v[228:231], v[16:19]
	v_mfma_f32_16x16x32_bf16 v[4:7], v[174:177], v[236:239], v[4:7]
	v_mfma_f32_16x16x32_bf16 v[0:3], v[182:185], v[236:239], v[0:3]
	s_barrier
	ds_read_b128 v[128:131], v203
	ds_read_b128 v[132:135], v204
	ds_read_b128 v[136:139], v205
	ds_read_b128 v[140:143], v206
	ds_read_b128 v[170:173], v207
	ds_read_b128 v[174:177], v208
	ds_read_b128 v[178:181], v209
	ds_read_b128 v[182:185], v210
	s_add_u32 s26, s38, 0xb0000
	s_addc_u32 s27, s39, 0
	s_mov_b32 m0, s31
	ds_read_b128 v[186:189], v192 offset:32768
	ds_read_b128 v[212:215], v192 offset:33792
	ds_read_b128 v[216:219], v192 offset:34816
	ds_read_b128 v[220:223], v192 offset:35840
	ds_read_b128 v[224:227], v192 offset:36864
	ds_read_b128 v[228:231], v192 offset:37888
	ds_read_b128 v[232:235], v192 offset:38912
	ds_read_b128 v[236:239], v192 offset:39936
	global_load_lds_dwordx4 v158, s[26:27]
	s_mov_b32 m0, s33
	s_nop 0
	global_load_lds_dwordx4 v160, s[26:27]
	s_waitcnt vmcnt(8)
	s_waitcnt lgkmcnt(0)
	s_barrier
	v_mfma_f32_16x16x32_bf16 v[124:127], v[128:131], v[186:189], v[124:127]
	v_mfma_f32_16x16x32_bf16 v[120:123], v[136:139], v[186:189], v[120:123]
	v_mfma_f32_16x16x32_bf16 v[108:111], v[128:131], v[216:219], v[108:111]
	v_mfma_f32_16x16x32_bf16 v[104:107], v[136:139], v[216:219], v[104:107]
	v_mfma_f32_16x16x32_bf16 v[92:95], v[128:131], v[224:227], v[92:95]
	v_mfma_f32_16x16x32_bf16 v[88:91], v[136:139], v[224:227], v[88:91]
	v_mfma_f32_16x16x32_bf16 v[76:79], v[128:131], v[232:235], v[76:79]
	v_mfma_f32_16x16x32_bf16 v[72:75], v[136:139], v[232:235], v[72:75]
	v_mfma_f32_16x16x32_bf16 v[124:127], v[132:135], v[212:215], v[124:127]
	v_mfma_f32_16x16x32_bf16 v[120:123], v[140:143], v[212:215], v[120:123]
	v_mfma_f32_16x16x32_bf16 v[108:111], v[132:135], v[220:223], v[108:111]
	v_mfma_f32_16x16x32_bf16 v[104:107], v[140:143], v[220:223], v[104:107]
	v_mfma_f32_16x16x32_bf16 v[92:95], v[132:135], v[228:231], v[92:95]
	v_mfma_f32_16x16x32_bf16 v[88:91], v[140:143], v[228:231], v[88:91]
	v_mfma_f32_16x16x32_bf16 v[76:79], v[132:135], v[236:239], v[76:79]
	v_mfma_f32_16x16x32_bf16 v[72:75], v[140:143], v[236:239], v[72:75]
	v_mfma_f32_16x16x32_bf16 v[116:119], v[170:173], v[186:189], v[116:119]
	v_mfma_f32_16x16x32_bf16 v[112:115], v[178:181], v[186:189], v[112:115]
	v_mfma_f32_16x16x32_bf16 v[100:103], v[170:173], v[216:219], v[100:103]
	v_mfma_f32_16x16x32_bf16 v[96:99], v[178:181], v[216:219], v[96:99]
	v_mfma_f32_16x16x32_bf16 v[84:87], v[170:173], v[224:227], v[84:87]
	v_mfma_f32_16x16x32_bf16 v[80:83], v[178:181], v[224:227], v[80:83]
	v_mfma_f32_16x16x32_bf16 v[68:71], v[170:173], v[232:235], v[68:71]
	v_mfma_f32_16x16x32_bf16 v[64:67], v[178:181], v[232:235], v[64:67]
	v_mfma_f32_16x16x32_bf16 v[116:119], v[174:177], v[212:215], v[116:119]
	v_mfma_f32_16x16x32_bf16 v[112:115], v[182:185], v[212:215], v[112:115]
	v_mfma_f32_16x16x32_bf16 v[100:103], v[174:177], v[220:223], v[100:103]
	v_mfma_f32_16x16x32_bf16 v[96:99], v[182:185], v[220:223], v[96:99]
	v_mfma_f32_16x16x32_bf16 v[84:87], v[174:177], v[228:231], v[84:87]
	v_mfma_f32_16x16x32_bf16 v[80:83], v[182:185], v[228:231], v[80:83]
	v_mfma_f32_16x16x32_bf16 v[68:71], v[174:177], v[236:239], v[68:71]
	v_mfma_f32_16x16x32_bf16 v[64:67], v[182:185], v[236:239], v[64:67]
	s_barrier
	s_mov_b32 m0, s40
	s_add_u32 s26, s36, 0xb0080
	ds_read_b128 v[186:189], v192 offset:49152
	ds_read_b128 v[212:215], v192 offset:50176
	ds_read_b128 v[216:219], v192 offset:51200
	ds_read_b128 v[220:223], v192 offset:52224
	ds_read_b128 v[224:227], v192 offset:53248
	ds_read_b128 v[228:231], v192 offset:54272
	ds_read_b128 v[232:235], v192 offset:55296
	ds_read_b128 v[236:239], v192 offset:56320
	global_load_lds_dwordx4 v158, s[98:99]
	s_mov_b32 m0, s41
	s_addc_u32 s27, s37, 0
	global_load_lds_dwordx4 v160, s[98:99]
	s_mov_b32 m0, s44
	s_nop 0
	global_load_lds_dwordx4 v158, s[26:27]
	s_mov_b32 m0, s45
	s_nop 0
	global_load_lds_dwordx4 v160, s[26:27]
	s_mov_b32 m0, s42
	s_nop 0
	global_load_lds_dwordx4 v158, s[100:101]
	s_mov_b32 m0, s43
	s_nop 0
	global_load_lds_dwordx4 v160, s[100:101]
	s_waitcnt vmcnt(8)
	s_waitcnt lgkmcnt(0)
	s_barrier
	v_mfma_f32_16x16x32_bf16 v[60:63], v[128:131], v[186:189], v[60:63]
	v_mfma_f32_16x16x32_bf16 v[56:59], v[136:139], v[186:189], v[56:59]
	v_mfma_f32_16x16x32_bf16 v[44:47], v[128:131], v[216:219], v[44:47]
	v_mfma_f32_16x16x32_bf16 v[40:43], v[136:139], v[216:219], v[40:43]
	v_mfma_f32_16x16x32_bf16 v[28:31], v[128:131], v[224:227], v[28:31]
	v_mfma_f32_16x16x32_bf16 v[24:27], v[136:139], v[224:227], v[24:27]
	v_mfma_f32_16x16x32_bf16 v[12:15], v[128:131], v[232:235], v[12:15]
	v_mfma_f32_16x16x32_bf16 v[8:11], v[136:139], v[232:235], v[8:11]
	v_mfma_f32_16x16x32_bf16 v[60:63], v[132:135], v[212:215], v[60:63]
	v_mfma_f32_16x16x32_bf16 v[56:59], v[140:143], v[212:215], v[56:59]
	v_mfma_f32_16x16x32_bf16 v[44:47], v[132:135], v[220:223], v[44:47]
	v_mfma_f32_16x16x32_bf16 v[40:43], v[140:143], v[220:223], v[40:43]
	v_mfma_f32_16x16x32_bf16 v[28:31], v[132:135], v[228:231], v[28:31]
	v_mfma_f32_16x16x32_bf16 v[24:27], v[140:143], v[228:231], v[24:27]
	v_mfma_f32_16x16x32_bf16 v[12:15], v[132:135], v[236:239], v[12:15]
	v_mfma_f32_16x16x32_bf16 v[8:11], v[140:143], v[236:239], v[8:11]
	v_mfma_f32_16x16x32_bf16 v[52:55], v[170:173], v[186:189], v[52:55]
	v_mfma_f32_16x16x32_bf16 v[48:51], v[178:181], v[186:189], v[48:51]
	v_mfma_f32_16x16x32_bf16 v[36:39], v[170:173], v[216:219], v[36:39]
	v_mfma_f32_16x16x32_bf16 v[32:35], v[178:181], v[216:219], v[32:35]
	v_mfma_f32_16x16x32_bf16 v[20:23], v[170:173], v[224:227], v[20:23]
	v_mfma_f32_16x16x32_bf16 v[16:19], v[178:181], v[224:227], v[16:19]
	v_mfma_f32_16x16x32_bf16 v[4:7], v[170:173], v[232:235], v[4:7]
	v_mfma_f32_16x16x32_bf16 v[0:3], v[178:181], v[232:235], v[0:3]
	v_mfma_f32_16x16x32_bf16 v[52:55], v[174:177], v[212:215], v[52:55]
	v_mfma_f32_16x16x32_bf16 v[48:51], v[182:185], v[212:215], v[48:51]
	v_mfma_f32_16x16x32_bf16 v[36:39], v[174:177], v[220:223], v[36:39]
	v_mfma_f32_16x16x32_bf16 v[32:35], v[182:185], v[220:223], v[32:35]
	v_mfma_f32_16x16x32_bf16 v[20:23], v[174:177], v[228:231], v[20:23]
	v_mfma_f32_16x16x32_bf16 v[16:19], v[182:185], v[228:231], v[16:19]
	v_mfma_f32_16x16x32_bf16 v[4:7], v[174:177], v[236:239], v[4:7]
	v_mfma_f32_16x16x32_bf16 v[0:3], v[182:185], v[236:239], v[0:3]
	s_barrier
	s_add_i32 s64, s64, 2
	s_add_u32 s4, s4, 0x100
	s_addc_u32 s5, s5, 0
	s_cmp_gt_u32 s64, 41
	s_mov_b64 s[26:27], s[34:35]
	s_cbranch_scc0 .LBB0_3029
	s_and_b64 vcc, exec, s[20:21]
	s_cbranch_vccz .LBB0_3032
	s_barrier

.LBB0_3179:
	ds_read_b128 v[140:143], v154
	ds_read_b128 v[170:173], v155
	ds_read_b128 v[174:177], v156
	ds_read_b128 v[178:181], v157
	ds_read_b128 v[182:185], v158
	ds_read_b128 v[186:189], v159
	ds_read_b128 v[190:193], v160
	ds_read_b128 v[194:197], v161
	s_add_u32 s34, s14, 0xfffc0080
	s_addc_u32 s35, s15, -1
	s_cmp_eq_u32 s54, 12
	s_cselect_b32 s37, s4, s35
	s_cselect_b32 s36, s5, s34
	s_cselect_b32 s35, s11, s25
	s_cselect_b32 s34, s13, s23
	s_mov_b32 m0, s51
	ds_read_b128 v[198:201], v149
	ds_read_b128 v[202:205], v149 offset:1024
	ds_read_b128 v[206:209], v149 offset:2048
	ds_read_b128 v[210:213], v149 offset:3072
	ds_read_b128 v[214:217], v149 offset:4096
	ds_read_b128 v[218:221], v149 offset:5120
	ds_read_b128 v[222:225], v149 offset:6144
	ds_read_b128 v[226:229], v149 offset:7168
	global_load_lds_dwordx4 v132, s[14:15]
	s_mov_b32 m0, s52
	s_nop 0
	global_load_lds_dwordx4 v134, s[14:15]
	s_waitcnt vmcnt(8)
	s_waitcnt lgkmcnt(0)
	s_barrier
	v_mfma_f32_16x16x32_bf16 v[124:127], v[140:143], v[198:201], v[124:127]
	v_mfma_f32_16x16x32_bf16 v[120:123], v[174:177], v[198:201], v[120:123]
	v_mfma_f32_16x16x32_bf16 v[108:111], v[140:143], v[206:209], v[108:111]
	v_mfma_f32_16x16x32_bf16 v[104:107], v[174:177], v[206:209], v[104:107]
	v_mfma_f32_16x16x32_bf16 v[92:95], v[140:143], v[214:217], v[92:95]
	v_mfma_f32_16x16x32_bf16 v[88:91], v[174:177], v[214:217], v[88:91]
	v_mfma_f32_16x16x32_bf16 v[76:79], v[140:143], v[222:225], v[76:79]
	v_mfma_f32_16x16x32_bf16 v[72:75], v[174:177], v[222:225], v[72:75]
	v_mfma_f32_16x16x32_bf16 v[124:127], v[170:173], v[202:205], v[124:127]
	v_mfma_f32_16x16x32_bf16 v[120:123], v[178:181], v[202:205], v[120:123]
	v_mfma_f32_16x16x32_bf16 v[108:111], v[170:173], v[210:213], v[108:111]
	v_mfma_f32_16x16x32_bf16 v[104:107], v[178:181], v[210:213], v[104:107]
	v_mfma_f32_16x16x32_bf16 v[92:95], v[170:173], v[218:221], v[92:95]
	v_mfma_f32_16x16x32_bf16 v[88:91], v[178:181], v[218:221], v[88:91]
	v_mfma_f32_16x16x32_bf16 v[76:79], v[170:173], v[226:229], v[76:79]
	v_mfma_f32_16x16x32_bf16 v[72:75], v[178:181], v[226:229], v[72:75]
	v_mfma_f32_16x16x32_bf16 v[116:119], v[182:185], v[198:201], v[116:119]
	v_mfma_f32_16x16x32_bf16 v[112:115], v[190:193], v[198:201], v[112:115]
	v_mfma_f32_16x16x32_bf16 v[100:103], v[182:185], v[206:209], v[100:103]
	v_mfma_f32_16x16x32_bf16 v[96:99], v[190:193], v[206:209], v[96:99]
	v_mfma_f32_16x16x32_bf16 v[84:87], v[182:185], v[214:217], v[84:87]
	v_mfma_f32_16x16x32_bf16 v[80:83], v[190:193], v[214:217], v[80:83]
	v_mfma_f32_16x16x32_bf16 v[68:71], v[182:185], v[222:225], v[68:71]
	v_mfma_f32_16x16x32_bf16 v[64:67], v[190:193], v[222:225], v[64:67]
	v_mfma_f32_16x16x32_bf16 v[116:119], v[186:189], v[202:205], v[116:119]
	v_mfma_f32_16x16x32_bf16 v[112:115], v[194:197], v[202:205], v[112:115]
	v_mfma_f32_16x16x32_bf16 v[100:103], v[186:189], v[210:213], v[100:103]
	v_mfma_f32_16x16x32_bf16 v[96:99], v[194:197], v[210:213], v[96:99]
	v_mfma_f32_16x16x32_bf16 v[84:87], v[186:189], v[218:221], v[84:87]
	v_mfma_f32_16x16x32_bf16 v[80:83], v[194:197], v[218:221], v[80:83]
	v_mfma_f32_16x16x32_bf16 v[68:71], v[186:189], v[226:229], v[68:71]
	v_mfma_f32_16x16x32_bf16 v[64:67], v[194:197], v[226:229], v[64:67]
	s_barrier
	s_add_u32 s98, s34, s16
	s_addc_u32 s99, s35, s17
	s_add_u32 s100, s36, s16
	s_addc_u32 s101, s37, s17
	s_mov_b32 m0, s6
	s_add_u32 s60, s34, 0x40000
	ds_read_b128 v[198:201], v149 offset:16384
	ds_read_b128 v[202:205], v149 offset:17408
	ds_read_b128 v[206:209], v149 offset:18432
	ds_read_b128 v[210:213], v149 offset:19456
	ds_read_b128 v[214:217], v149 offset:20480
	ds_read_b128 v[218:221], v149 offset:21504
	ds_read_b128 v[222:225], v149 offset:22528
	ds_read_b128 v[226:229], v149 offset:23552
	global_load_lds_dwordx4 v128, s[34:35]
	s_mov_b32 m0, s7
	s_addc_u32 s61, s35, 0
	global_load_lds_dwordx4 v130, s[34:35]
	s_mov_b32 m0, s21
	s_nop 0
	global_load_lds_dwordx4 v128, s[60:61]
	s_mov_b32 m0, s28
	s_nop 0
	global_load_lds_dwordx4 v130, s[60:61]
	s_mov_b32 m0, s2
	s_nop 0
	global_load_lds_dwordx4 v128, s[36:37]
	s_mov_b32 m0, s29
	s_nop 0
	global_load_lds_dwordx4 v130, s[36:37]
	s_waitcnt vmcnt(8)
	s_waitcnt lgkmcnt(0)
	s_barrier
	v_mfma_f32_16x16x32_bf16 v[60:63], v[140:143], v[198:201], v[60:63]
	v_mfma_f32_16x16x32_bf16 v[56:59], v[174:177], v[198:201], v[56:59]
	v_mfma_f32_16x16x32_bf16 v[44:47], v[140:143], v[206:209], v[44:47]
	v_mfma_f32_16x16x32_bf16 v[40:43], v[174:177], v[206:209], v[40:43]
	v_mfma_f32_16x16x32_bf16 v[28:31], v[140:143], v[214:217], v[28:31]
	v_mfma_f32_16x16x32_bf16 v[24:27], v[174:177], v[214:217], v[24:27]
	v_mfma_f32_16x16x32_bf16 v[12:15], v[140:143], v[222:225], v[12:15]
	v_mfma_f32_16x16x32_bf16 v[8:11], v[174:177], v[222:225], v[8:11]
	v_mfma_f32_16x16x32_bf16 v[60:63], v[170:173], v[202:205], v[60:63]
	v_mfma_f32_16x16x32_bf16 v[56:59], v[178:181], v[202:205], v[56:59]
	v_mfma_f32_16x16x32_bf16 v[44:47], v[170:173], v[210:213], v[44:47]
	v_mfma_f32_16x16x32_bf16 v[40:43], v[178:181], v[210:213], v[40:43]
	v_mfma_f32_16x16x32_bf16 v[28:31], v[170:173], v[218:221], v[28:31]
	v_mfma_f32_16x16x32_bf16 v[24:27], v[178:181], v[218:221], v[24:27]
	v_mfma_f32_16x16x32_bf16 v[12:15], v[170:173], v[226:229], v[12:15]
	v_mfma_f32_16x16x32_bf16 v[8:11], v[178:181], v[226:229], v[8:11]
	v_mfma_f32_16x16x32_bf16 v[52:55], v[182:185], v[198:201], v[52:55]
	v_mfma_f32_16x16x32_bf16 v[48:51], v[190:193], v[198:201], v[48:51]
	v_mfma_f32_16x16x32_bf16 v[36:39], v[182:185], v[206:209], v[36:39]
	v_mfma_f32_16x16x32_bf16 v[32:35], v[190:193], v[206:209], v[32:35]
	v_mfma_f32_16x16x32_bf16 v[20:23], v[182:185], v[214:217], v[20:23]
	v_mfma_f32_16x16x32_bf16 v[16:19], v[190:193], v[214:217], v[16:19]
	v_mfma_f32_16x16x32_bf16 v[4:7], v[182:185], v[222:225], v[4:7]
	v_mfma_f32_16x16x32_bf16 v[0:3], v[190:193], v[222:225], v[0:3]
	v_mfma_f32_16x16x32_bf16 v[52:55], v[186:189], v[202:205], v[52:55]
	v_mfma_f32_16x16x32_bf16 v[48:51], v[194:197], v[202:205], v[48:51]
	v_mfma_f32_16x16x32_bf16 v[36:39], v[186:189], v[210:213], v[36:39]
	v_mfma_f32_16x16x32_bf16 v[32:35], v[194:197], v[210:213], v[32:35]
	v_mfma_f32_16x16x32_bf16 v[20:23], v[186:189], v[218:221], v[20:23]
	v_mfma_f32_16x16x32_bf16 v[16:19], v[194:197], v[218:221], v[16:19]
	v_mfma_f32_16x16x32_bf16 v[4:7], v[186:189], v[226:229], v[4:7]
	v_mfma_f32_16x16x32_bf16 v[0:3], v[194:197], v[226:229], v[0:3]
	s_barrier
	ds_read_b128 v[140:143], v162
	ds_read_b128 v[170:173], v163
	ds_read_b128 v[174:177], v164
	ds_read_b128 v[178:181], v165
	ds_read_b128 v[182:185], v166
	ds_read_b128 v[186:189], v167
	ds_read_b128 v[190:193], v168
	ds_read_b128 v[194:197], v169
	s_add_u32 s36, s36, 0x40000
	s_addc_u32 s37, s37, 0
	s_mov_b32 m0, s33
	ds_read_b128 v[198:201], v149 offset:32768
	ds_read_b128 v[202:205], v149 offset:33792
	ds_read_b128 v[206:209], v149 offset:34816
	ds_read_b128 v[210:213], v149 offset:35840
	ds_read_b128 v[214:217], v149 offset:36864
	ds_read_b128 v[218:221], v149 offset:37888
	ds_read_b128 v[222:225], v149 offset:38912
	ds_read_b128 v[226:229], v149 offset:39936
	global_load_lds_dwordx4 v128, s[36:37]
	s_mov_b32 m0, s38
	s_nop 0
	global_load_lds_dwordx4 v130, s[36:37]
	s_waitcnt vmcnt(8)
	s_waitcnt lgkmcnt(0)
	s_barrier
	v_mfma_f32_16x16x32_bf16 v[124:127], v[140:143], v[198:201], v[124:127]
	v_mfma_f32_16x16x32_bf16 v[120:123], v[174:177], v[198:201], v[120:123]
	v_mfma_f32_16x16x32_bf16 v[108:111], v[140:143], v[206:209], v[108:111]
	v_mfma_f32_16x16x32_bf16 v[104:107], v[174:177], v[206:209], v[104:107]
	v_mfma_f32_16x16x32_bf16 v[92:95], v[140:143], v[214:217], v[92:95]
	v_mfma_f32_16x16x32_bf16 v[88:91], v[174:177], v[214:217], v[88:91]
	v_mfma_f32_16x16x32_bf16 v[76:79], v[140:143], v[222:225], v[76:79]
	v_mfma_f32_16x16x32_bf16 v[72:75], v[174:177], v[222:225], v[72:75]
	v_mfma_f32_16x16x32_bf16 v[124:127], v[170:173], v[202:205], v[124:127]
	v_mfma_f32_16x16x32_bf16 v[120:123], v[178:181], v[202:205], v[120:123]
	v_mfma_f32_16x16x32_bf16 v[108:111], v[170:173], v[210:213], v[108:111]
	v_mfma_f32_16x16x32_bf16 v[104:107], v[178:181], v[210:213], v[104:107]
	v_mfma_f32_16x16x32_bf16 v[92:95], v[170:173], v[218:221], v[92:95]
	v_mfma_f32_16x16x32_bf16 v[88:91], v[178:181], v[218:221], v[88:91]
	v_mfma_f32_16x16x32_bf16 v[76:79], v[170:173], v[226:229], v[76:79]
	v_mfma_f32_16x16x32_bf16 v[72:75], v[178:181], v[226:229], v[72:75]
	v_mfma_f32_16x16x32_bf16 v[116:119], v[182:185], v[198:201], v[116:119]
	v_mfma_f32_16x16x32_bf16 v[112:115], v[190:193], v[198:201], v[112:115]
	v_mfma_f32_16x16x32_bf16 v[100:103], v[182:185], v[206:209], v[100:103]
	v_mfma_f32_16x16x32_bf16 v[96:99], v[190:193], v[206:209], v[96:99]
	v_mfma_f32_16x16x32_bf16 v[84:87], v[182:185], v[214:217], v[84:87]
	v_mfma_f32_16x16x32_bf16 v[80:83], v[190:193], v[214:217], v[80:83]
	v_mfma_f32_16x16x32_bf16 v[68:71], v[182:185], v[222:225], v[68:71]
	v_mfma_f32_16x16x32_bf16 v[64:67], v[190:193], v[222:225], v[64:67]
	v_mfma_f32_16x16x32_bf16 v[116:119], v[186:189], v[202:205], v[116:119]
	v_mfma_f32_16x16x32_bf16 v[112:115], v[194:197], v[202:205], v[112:115]
	v_mfma_f32_16x16x32_bf16 v[100:103], v[186:189], v[210:213], v[100:103]
	v_mfma_f32_16x16x32_bf16 v[96:99], v[194:197], v[210:213], v[96:99]
	v_mfma_f32_16x16x32_bf16 v[84:87], v[186:189], v[218:221], v[84:87]
	v_mfma_f32_16x16x32_bf16 v[80:83], v[194:197], v[218:221], v[80:83]
	v_mfma_f32_16x16x32_bf16 v[68:71], v[186:189], v[226:229], v[68:71]
	v_mfma_f32_16x16x32_bf16 v[64:67], v[194:197], v[226:229], v[64:67]
	s_barrier
	s_mov_b32 m0, s40
	s_add_u32 s34, s34, 0x40080
	ds_read_b128 v[198:201], v149 offset:49152
	ds_read_b128 v[202:205], v149 offset:50176
	ds_read_b128 v[206:209], v149 offset:51200
	ds_read_b128 v[210:213], v149 offset:52224
	ds_read_b128 v[214:217], v149 offset:53248
	ds_read_b128 v[218:221], v149 offset:54272
	ds_read_b128 v[222:225], v149 offset:55296
	ds_read_b128 v[226:229], v149 offset:56320
	global_load_lds_dwordx4 v128, s[98:99]
	s_mov_b32 m0, s41
	s_addc_u32 s35, s35, 0
	global_load_lds_dwordx4 v130, s[98:99]
	s_mov_b32 m0, s44
	s_nop 0
	global_load_lds_dwordx4 v128, s[34:35]
	s_mov_b32 m0, s45
	s_nop 0
	global_load_lds_dwordx4 v130, s[34:35]
	s_mov_b32 m0, s42
	s_nop 0
	global_load_lds_dwordx4 v128, s[100:101]
	s_mov_b32 m0, s43
	s_nop 0
	global_load_lds_dwordx4 v130, s[100:101]
	s_waitcnt vmcnt(8)
	s_waitcnt lgkmcnt(0)
	s_barrier
	v_mfma_f32_16x16x32_bf16 v[60:63], v[140:143], v[198:201], v[60:63]
	v_mfma_f32_16x16x32_bf16 v[56:59], v[174:177], v[198:201], v[56:59]
	v_mfma_f32_16x16x32_bf16 v[44:47], v[140:143], v[206:209], v[44:47]
	v_mfma_f32_16x16x32_bf16 v[40:43], v[174:177], v[206:209], v[40:43]
	v_mfma_f32_16x16x32_bf16 v[28:31], v[140:143], v[214:217], v[28:31]
	v_mfma_f32_16x16x32_bf16 v[24:27], v[174:177], v[214:217], v[24:27]
	v_mfma_f32_16x16x32_bf16 v[12:15], v[140:143], v[222:225], v[12:15]
	v_mfma_f32_16x16x32_bf16 v[8:11], v[174:177], v[222:225], v[8:11]
	v_mfma_f32_16x16x32_bf16 v[60:63], v[170:173], v[202:205], v[60:63]
	v_mfma_f32_16x16x32_bf16 v[56:59], v[178:181], v[202:205], v[56:59]
	v_mfma_f32_16x16x32_bf16 v[44:47], v[170:173], v[210:213], v[44:47]
	v_mfma_f32_16x16x32_bf16 v[40:43], v[178:181], v[210:213], v[40:43]
	v_mfma_f32_16x16x32_bf16 v[28:31], v[170:173], v[218:221], v[28:31]
	v_mfma_f32_16x16x32_bf16 v[24:27], v[178:181], v[218:221], v[24:27]
	v_mfma_f32_16x16x32_bf16 v[12:15], v[170:173], v[226:229], v[12:15]
	v_mfma_f32_16x16x32_bf16 v[8:11], v[178:181], v[226:229], v[8:11]
	v_mfma_f32_16x16x32_bf16 v[52:55], v[182:185], v[198:201], v[52:55]
	v_mfma_f32_16x16x32_bf16 v[48:51], v[190:193], v[198:201], v[48:51]
	v_mfma_f32_16x16x32_bf16 v[36:39], v[182:185], v[206:209], v[36:39]
	v_mfma_f32_16x16x32_bf16 v[32:35], v[190:193], v[206:209], v[32:35]
	v_mfma_f32_16x16x32_bf16 v[20:23], v[182:185], v[214:217], v[20:23]
	v_mfma_f32_16x16x32_bf16 v[16:19], v[190:193], v[214:217], v[16:19]
	v_mfma_f32_16x16x32_bf16 v[4:7], v[182:185], v[222:225], v[4:7]
	v_mfma_f32_16x16x32_bf16 v[0:3], v[190:193], v[222:225], v[0:3]
	v_mfma_f32_16x16x32_bf16 v[52:55], v[186:189], v[202:205], v[52:55]
	v_mfma_f32_16x16x32_bf16 v[48:51], v[194:197], v[202:205], v[48:51]
	v_mfma_f32_16x16x32_bf16 v[36:39], v[186:189], v[210:213], v[36:39]
	v_mfma_f32_16x16x32_bf16 v[32:35], v[194:197], v[210:213], v[32:35]
	v_mfma_f32_16x16x32_bf16 v[20:23], v[186:189], v[218:221], v[20:23]
	v_mfma_f32_16x16x32_bf16 v[16:19], v[194:197], v[218:221], v[16:19]
	v_mfma_f32_16x16x32_bf16 v[4:7], v[186:189], v[226:229], v[4:7]
	v_mfma_f32_16x16x32_bf16 v[0:3], v[194:197], v[226:229], v[0:3]
	s_barrier
	s_add_i32 s54, s54, 2
	s_add_u32 s14, s14, 0x100
	s_addc_u32 s15, s15, 0
	s_add_u32 s23, s23, 0x100
	s_addc_u32 s25, s25, 0
	s_cmp_gt_u32 s54, 13
	s_cbranch_scc0 .LBB0_3179
	s_and_b64 vcc, exec, s[18:19]
	s_cbranch_vccz .LBB0_3182
	s_barrier

.LBB0_3534:
	ds_read_b128 v[128:131], v188
	ds_read_b128 v[132:135], v189
	ds_read_b128 v[136:139], v190
	ds_read_b128 v[140:143], v191
	ds_read_b128 v[166:169], v192
	ds_read_b128 v[170:173], v193
	ds_read_b128 v[174:177], v194
	ds_read_b128 v[178:181], v195
	s_add_u32 s34, s30, 0x100
	s_addc_u32 s35, s31, 0
	s_cmp_eq_u32 s68, 12
	s_cselect_b32 s39, s4, s35
	s_cselect_b32 s38, s5, s34
	s_cselect_b32 s37, s21, s67
	s_cselect_b32 s36, s23, s66
	s_mov_b32 m0, s55
	ds_read_b128 v[182:185], v149
	ds_read_b128 v[206:209], v149 offset:1024
	ds_read_b128 v[210:213], v149 offset:2048
	ds_read_b128 v[214:217], v149 offset:3072
	ds_read_b128 v[218:221], v149 offset:4096
	ds_read_b128 v[222:225], v149 offset:5120
	ds_read_b128 v[226:229], v149 offset:6144
	ds_read_b128 v[230:233], v149 offset:7168
	global_load_lds_dwordx4 v158, s[30:31]
	s_mov_b32 m0, s60
	s_nop 0
	global_load_lds_dwordx4 v160, s[30:31]
	s_waitcnt vmcnt(8)
	s_waitcnt lgkmcnt(0)
	s_barrier
	v_mfma_f32_16x16x32_bf16 v[124:127], v[128:131], v[182:185], v[124:127]
	v_mfma_f32_16x16x32_bf16 v[120:123], v[136:139], v[182:185], v[120:123]
	v_mfma_f32_16x16x32_bf16 v[108:111], v[128:131], v[210:213], v[108:111]
	v_mfma_f32_16x16x32_bf16 v[104:107], v[136:139], v[210:213], v[104:107]
	v_mfma_f32_16x16x32_bf16 v[92:95], v[128:131], v[218:221], v[92:95]
	v_mfma_f32_16x16x32_bf16 v[88:91], v[136:139], v[218:221], v[88:91]
	v_mfma_f32_16x16x32_bf16 v[76:79], v[128:131], v[226:229], v[76:79]
	v_mfma_f32_16x16x32_bf16 v[72:75], v[136:139], v[226:229], v[72:75]
	v_mfma_f32_16x16x32_bf16 v[124:127], v[132:135], v[206:209], v[124:127]
	v_mfma_f32_16x16x32_bf16 v[120:123], v[140:143], v[206:209], v[120:123]
	v_mfma_f32_16x16x32_bf16 v[108:111], v[132:135], v[214:217], v[108:111]
	v_mfma_f32_16x16x32_bf16 v[104:107], v[140:143], v[214:217], v[104:107]
	v_mfma_f32_16x16x32_bf16 v[92:95], v[132:135], v[222:225], v[92:95]
	v_mfma_f32_16x16x32_bf16 v[88:91], v[140:143], v[222:225], v[88:91]
	v_mfma_f32_16x16x32_bf16 v[76:79], v[132:135], v[230:233], v[76:79]
	v_mfma_f32_16x16x32_bf16 v[72:75], v[140:143], v[230:233], v[72:75]
	v_mfma_f32_16x16x32_bf16 v[116:119], v[166:169], v[182:185], v[116:119]
	v_mfma_f32_16x16x32_bf16 v[112:115], v[174:177], v[182:185], v[112:115]
	v_mfma_f32_16x16x32_bf16 v[100:103], v[166:169], v[210:213], v[100:103]
	v_mfma_f32_16x16x32_bf16 v[96:99], v[174:177], v[210:213], v[96:99]
	v_mfma_f32_16x16x32_bf16 v[84:87], v[166:169], v[218:221], v[84:87]
	v_mfma_f32_16x16x32_bf16 v[80:83], v[174:177], v[218:221], v[80:83]
	v_mfma_f32_16x16x32_bf16 v[68:71], v[166:169], v[226:229], v[68:71]
	v_mfma_f32_16x16x32_bf16 v[64:67], v[174:177], v[226:229], v[64:67]
	v_mfma_f32_16x16x32_bf16 v[116:119], v[170:173], v[206:209], v[116:119]
	v_mfma_f32_16x16x32_bf16 v[112:115], v[178:181], v[206:209], v[112:115]
	v_mfma_f32_16x16x32_bf16 v[100:103], v[170:173], v[214:217], v[100:103]
	v_mfma_f32_16x16x32_bf16 v[96:99], v[178:181], v[214:217], v[96:99]
	v_mfma_f32_16x16x32_bf16 v[84:87], v[170:173], v[222:225], v[84:87]
	v_mfma_f32_16x16x32_bf16 v[80:83], v[178:181], v[222:225], v[80:83]
	v_mfma_f32_16x16x32_bf16 v[68:71], v[170:173], v[230:233], v[68:71]
	v_mfma_f32_16x16x32_bf16 v[64:67], v[178:181], v[230:233], v[64:67]
	s_barrier
	s_add_u32 s98, s36, s14
	s_addc_u32 s99, s37, s15
	s_add_u32 s100, s38, s14
	s_addc_u32 s101, s39, s15
	s_mov_b32 m0, s29
	s_add_u32 s30, s36, 0x40000
	ds_read_b128 v[182:185], v149 offset:16384
	ds_read_b128 v[206:209], v149 offset:17408
	ds_read_b128 v[210:213], v149 offset:18432
	ds_read_b128 v[214:217], v149 offset:19456
	ds_read_b128 v[218:221], v149 offset:20480
	ds_read_b128 v[222:225], v149 offset:21504
	ds_read_b128 v[226:229], v149 offset:22528
	ds_read_b128 v[230:233], v149 offset:23552
	global_load_lds_dwordx4 v154, s[36:37]
	s_mov_b32 m0, s33
	s_addc_u32 s31, s37, 0
	global_load_lds_dwordx4 v156, s[36:37]
	s_mov_b32 m0, s40
	s_nop 0
	global_load_lds_dwordx4 v154, s[30:31]
	s_mov_b32 m0, s41
	s_nop 0
	global_load_lds_dwordx4 v156, s[30:31]
	s_mov_b32 m0, s19
	s_nop 0
	global_load_lds_dwordx4 v154, s[38:39]
	s_mov_b32 m0, s42
	s_nop 0
	global_load_lds_dwordx4 v156, s[38:39]
	s_waitcnt vmcnt(8)
	s_waitcnt lgkmcnt(0)
	s_barrier
	v_mfma_f32_16x16x32_bf16 v[60:63], v[128:131], v[182:185], v[60:63]
	v_mfma_f32_16x16x32_bf16 v[56:59], v[136:139], v[182:185], v[56:59]
	v_mfma_f32_16x16x32_bf16 v[44:47], v[128:131], v[210:213], v[44:47]
	v_mfma_f32_16x16x32_bf16 v[40:43], v[136:139], v[210:213], v[40:43]
	v_mfma_f32_16x16x32_bf16 v[28:31], v[128:131], v[218:221], v[28:31]
	v_mfma_f32_16x16x32_bf16 v[24:27], v[136:139], v[218:221], v[24:27]
	v_mfma_f32_16x16x32_bf16 v[12:15], v[128:131], v[226:229], v[12:15]
	v_mfma_f32_16x16x32_bf16 v[8:11], v[136:139], v[226:229], v[8:11]
	v_mfma_f32_16x16x32_bf16 v[60:63], v[132:135], v[206:209], v[60:63]
	v_mfma_f32_16x16x32_bf16 v[56:59], v[140:143], v[206:209], v[56:59]
	v_mfma_f32_16x16x32_bf16 v[44:47], v[132:135], v[214:217], v[44:47]
	v_mfma_f32_16x16x32_bf16 v[40:43], v[140:143], v[214:217], v[40:43]
	v_mfma_f32_16x16x32_bf16 v[28:31], v[132:135], v[222:225], v[28:31]
	v_mfma_f32_16x16x32_bf16 v[24:27], v[140:143], v[222:225], v[24:27]
	v_mfma_f32_16x16x32_bf16 v[12:15], v[132:135], v[230:233], v[12:15]
	v_mfma_f32_16x16x32_bf16 v[8:11], v[140:143], v[230:233], v[8:11]
	v_mfma_f32_16x16x32_bf16 v[52:55], v[166:169], v[182:185], v[52:55]
	v_mfma_f32_16x16x32_bf16 v[48:51], v[174:177], v[182:185], v[48:51]
	v_mfma_f32_16x16x32_bf16 v[36:39], v[166:169], v[210:213], v[36:39]
	v_mfma_f32_16x16x32_bf16 v[32:35], v[174:177], v[210:213], v[32:35]
	v_mfma_f32_16x16x32_bf16 v[20:23], v[166:169], v[218:221], v[20:23]
	v_mfma_f32_16x16x32_bf16 v[16:19], v[174:177], v[218:221], v[16:19]
	v_mfma_f32_16x16x32_bf16 v[4:7], v[166:169], v[226:229], v[4:7]
	v_mfma_f32_16x16x32_bf16 v[0:3], v[174:177], v[226:229], v[0:3]
	v_mfma_f32_16x16x32_bf16 v[52:55], v[170:173], v[206:209], v[52:55]
	v_mfma_f32_16x16x32_bf16 v[48:51], v[178:181], v[206:209], v[48:51]
	v_mfma_f32_16x16x32_bf16 v[36:39], v[170:173], v[214:217], v[36:39]
	v_mfma_f32_16x16x32_bf16 v[32:35], v[178:181], v[214:217], v[32:35]
	v_mfma_f32_16x16x32_bf16 v[20:23], v[170:173], v[222:225], v[20:23]
	v_mfma_f32_16x16x32_bf16 v[16:19], v[178:181], v[222:225], v[16:19]
	v_mfma_f32_16x16x32_bf16 v[4:7], v[170:173], v[230:233], v[4:7]
	v_mfma_f32_16x16x32_bf16 v[0:3], v[178:181], v[230:233], v[0:3]
	s_barrier
	ds_read_b128 v[128:131], v196
	ds_read_b128 v[132:135], v197
	ds_read_b128 v[136:139], v198
	ds_read_b128 v[140:143], v199
	ds_read_b128 v[166:169], v200
	ds_read_b128 v[170:173], v201
	ds_read_b128 v[174:177], v202
	ds_read_b128 v[178:181], v203
	s_add_u32 s30, s38, 0x40000
	s_addc_u32 s31, s39, 0
	s_mov_b32 m0, s43
	ds_read_b128 v[182:185], v149 offset:32768
	ds_read_b128 v[206:209], v149 offset:33792
	ds_read_b128 v[210:213], v149 offset:34816
	ds_read_b128 v[214:217], v149 offset:35840
	ds_read_b128 v[218:221], v149 offset:36864
	ds_read_b128 v[222:225], v149 offset:37888
	ds_read_b128 v[226:229], v149 offset:38912
	ds_read_b128 v[230:233], v149 offset:39936
	global_load_lds_dwordx4 v154, s[30:31]
	s_mov_b32 m0, s44
	s_nop 0
	global_load_lds_dwordx4 v156, s[30:31]
	s_waitcnt vmcnt(8)
	s_waitcnt lgkmcnt(0)
	s_barrier
	v_mfma_f32_16x16x32_bf16 v[124:127], v[128:131], v[182:185], v[124:127]
	v_mfma_f32_16x16x32_bf16 v[120:123], v[136:139], v[182:185], v[120:123]
	v_mfma_f32_16x16x32_bf16 v[108:111], v[128:131], v[210:213], v[108:111]
	v_mfma_f32_16x16x32_bf16 v[104:107], v[136:139], v[210:213], v[104:107]
	v_mfma_f32_16x16x32_bf16 v[92:95], v[128:131], v[218:221], v[92:95]
	v_mfma_f32_16x16x32_bf16 v[88:91], v[136:139], v[218:221], v[88:91]
	v_mfma_f32_16x16x32_bf16 v[76:79], v[128:131], v[226:229], v[76:79]
	v_mfma_f32_16x16x32_bf16 v[72:75], v[136:139], v[226:229], v[72:75]
	v_mfma_f32_16x16x32_bf16 v[124:127], v[132:135], v[206:209], v[124:127]
	v_mfma_f32_16x16x32_bf16 v[120:123], v[140:143], v[206:209], v[120:123]
	v_mfma_f32_16x16x32_bf16 v[108:111], v[132:135], v[214:217], v[108:111]
	v_mfma_f32_16x16x32_bf16 v[104:107], v[140:143], v[214:217], v[104:107]
	v_mfma_f32_16x16x32_bf16 v[92:95], v[132:135], v[222:225], v[92:95]
	v_mfma_f32_16x16x32_bf16 v[88:91], v[140:143], v[222:225], v[88:91]
	v_mfma_f32_16x16x32_bf16 v[76:79], v[132:135], v[230:233], v[76:79]
	v_mfma_f32_16x16x32_bf16 v[72:75], v[140:143], v[230:233], v[72:75]
	v_mfma_f32_16x16x32_bf16 v[116:119], v[166:169], v[182:185], v[116:119]
	v_mfma_f32_16x16x32_bf16 v[112:115], v[174:177], v[182:185], v[112:115]
	v_mfma_f32_16x16x32_bf16 v[100:103], v[166:169], v[210:213], v[100:103]
	v_mfma_f32_16x16x32_bf16 v[96:99], v[174:177], v[210:213], v[96:99]
	v_mfma_f32_16x16x32_bf16 v[84:87], v[166:169], v[218:221], v[84:87]
	v_mfma_f32_16x16x32_bf16 v[80:83], v[174:177], v[218:221], v[80:83]
	v_mfma_f32_16x16x32_bf16 v[68:71], v[166:169], v[226:229], v[68:71]
	v_mfma_f32_16x16x32_bf16 v[64:67], v[174:177], v[226:229], v[64:67]
	v_mfma_f32_16x16x32_bf16 v[116:119], v[170:173], v[206:209], v[116:119]
	v_mfma_f32_16x16x32_bf16 v[112:115], v[178:181], v[206:209], v[112:115]
	v_mfma_f32_16x16x32_bf16 v[100:103], v[170:173], v[214:217], v[100:103]
	v_mfma_f32_16x16x32_bf16 v[96:99], v[178:181], v[214:217], v[96:99]
	v_mfma_f32_16x16x32_bf16 v[84:87], v[170:173], v[222:225], v[84:87]
	v_mfma_f32_16x16x32_bf16 v[80:83], v[178:181], v[222:225], v[80:83]
	v_mfma_f32_16x16x32_bf16 v[68:71], v[170:173], v[230:233], v[68:71]
	v_mfma_f32_16x16x32_bf16 v[64:67], v[178:181], v[230:233], v[64:67]
	s_barrier
	s_mov_b32 m0, s45
	s_add_u32 s30, s36, 0x40080
	ds_read_b128 v[182:185], v149 offset:49152
	ds_read_b128 v[206:209], v149 offset:50176
	ds_read_b128 v[210:213], v149 offset:51200
	ds_read_b128 v[214:217], v149 offset:52224
	ds_read_b128 v[218:221], v149 offset:53248
	ds_read_b128 v[222:225], v149 offset:54272
	ds_read_b128 v[226:229], v149 offset:55296
	ds_read_b128 v[230:233], v149 offset:56320
	global_load_lds_dwordx4 v154, s[98:99]
	s_mov_b32 m0, s46
	s_addc_u32 s31, s37, 0
	global_load_lds_dwordx4 v156, s[98:99]
	s_mov_b32 m0, s49
	s_nop 0
	global_load_lds_dwordx4 v154, s[30:31]
	s_mov_b32 m0, s50
	s_nop 0
	global_load_lds_dwordx4 v156, s[30:31]
	s_mov_b32 m0, s47
	s_nop 0
	global_load_lds_dwordx4 v154, s[100:101]
	s_mov_b32 m0, s48
	s_nop 0
	global_load_lds_dwordx4 v156, s[100:101]
	s_waitcnt vmcnt(8)
	s_waitcnt lgkmcnt(0)
	s_barrier
	v_mfma_f32_16x16x32_bf16 v[60:63], v[128:131], v[182:185], v[60:63]
	v_mfma_f32_16x16x32_bf16 v[56:59], v[136:139], v[182:185], v[56:59]
	v_mfma_f32_16x16x32_bf16 v[44:47], v[128:131], v[210:213], v[44:47]
	v_mfma_f32_16x16x32_bf16 v[40:43], v[136:139], v[210:213], v[40:43]
	v_mfma_f32_16x16x32_bf16 v[28:31], v[128:131], v[218:221], v[28:31]
	v_mfma_f32_16x16x32_bf16 v[24:27], v[136:139], v[218:221], v[24:27]
	v_mfma_f32_16x16x32_bf16 v[12:15], v[128:131], v[226:229], v[12:15]
	v_mfma_f32_16x16x32_bf16 v[8:11], v[136:139], v[226:229], v[8:11]
	v_mfma_f32_16x16x32_bf16 v[60:63], v[132:135], v[206:209], v[60:63]
	v_mfma_f32_16x16x32_bf16 v[56:59], v[140:143], v[206:209], v[56:59]
	v_mfma_f32_16x16x32_bf16 v[44:47], v[132:135], v[214:217], v[44:47]
	v_mfma_f32_16x16x32_bf16 v[40:43], v[140:143], v[214:217], v[40:43]
	v_mfma_f32_16x16x32_bf16 v[28:31], v[132:135], v[222:225], v[28:31]
	v_mfma_f32_16x16x32_bf16 v[24:27], v[140:143], v[222:225], v[24:27]
	v_mfma_f32_16x16x32_bf16 v[12:15], v[132:135], v[230:233], v[12:15]
	v_mfma_f32_16x16x32_bf16 v[8:11], v[140:143], v[230:233], v[8:11]
	v_mfma_f32_16x16x32_bf16 v[52:55], v[166:169], v[182:185], v[52:55]
	v_mfma_f32_16x16x32_bf16 v[48:51], v[174:177], v[182:185], v[48:51]
	v_mfma_f32_16x16x32_bf16 v[36:39], v[166:169], v[210:213], v[36:39]
	v_mfma_f32_16x16x32_bf16 v[32:35], v[174:177], v[210:213], v[32:35]
	v_mfma_f32_16x16x32_bf16 v[20:23], v[166:169], v[218:221], v[20:23]
	v_mfma_f32_16x16x32_bf16 v[16:19], v[174:177], v[218:221], v[16:19]
	v_mfma_f32_16x16x32_bf16 v[4:7], v[166:169], v[226:229], v[4:7]
	v_mfma_f32_16x16x32_bf16 v[0:3], v[174:177], v[226:229], v[0:3]
	v_mfma_f32_16x16x32_bf16 v[52:55], v[170:173], v[206:209], v[52:55]
	v_mfma_f32_16x16x32_bf16 v[48:51], v[178:181], v[206:209], v[48:51]
	v_mfma_f32_16x16x32_bf16 v[36:39], v[170:173], v[214:217], v[36:39]
	v_mfma_f32_16x16x32_bf16 v[32:35], v[178:181], v[214:217], v[32:35]
	v_mfma_f32_16x16x32_bf16 v[20:23], v[170:173], v[222:225], v[20:23]
	v_mfma_f32_16x16x32_bf16 v[16:19], v[178:181], v[222:225], v[16:19]
	v_mfma_f32_16x16x32_bf16 v[4:7], v[170:173], v[230:233], v[4:7]
	v_mfma_f32_16x16x32_bf16 v[0:3], v[178:181], v[230:233], v[0:3]
	s_barrier
	s_add_i32 s68, s68, 2
	s_add_u32 s66, s66, 0x100
	s_addc_u32 s67, s67, 0
	s_cmp_gt_u32 s68, 13
	s_mov_b64 s[30:31], s[34:35]
	s_cbranch_scc0 .LBB0_3534
	s_and_b64 vcc, exec, s[16:17]
	s_cbranch_vccz .LBB0_3537
	s_barrier

.LBB0_3663:
	ds_read_b128 v[164:167], v143
	ds_read_b128 v[168:171], v147
	ds_read_b128 v[172:175], v148
	ds_read_b128 v[176:179], v149
	ds_read_b128 v[180:183], v151
	ds_read_b128 v[184:187], v153
	ds_read_b128 v[188:191], v154
	ds_read_b128 v[192:195], v155
	s_add_u32 s24, s22, 0xfffc0080
	s_addc_u32 s25, s23, -1
	s_cmp_eq_u32 s53, 12
	s_cselect_b32 s27, s4, s25
	s_cselect_b32 s26, s5, s24
	s_cselect_b32 s25, s13, s52
	s_cselect_b32 s24, s15, s51
	s_mov_b32 m0, s47
	ds_read_b128 v[196:199], v141
	ds_read_b128 v[200:203], v141 offset:1024
	ds_read_b128 v[204:207], v141 offset:2048
	ds_read_b128 v[208:211], v141 offset:3072
	ds_read_b128 v[212:215], v141 offset:4096
	ds_read_b128 v[216:219], v141 offset:5120
	ds_read_b128 v[220:223], v141 offset:6144
	ds_read_b128 v[224:227], v141 offset:7168
	global_load_lds_dwordx4 v132, s[22:23]
	s_mov_b32 m0, s48
	s_nop 0
	global_load_lds_dwordx4 v134, s[22:23]
	s_waitcnt vmcnt(8)
	s_waitcnt lgkmcnt(0)
	s_barrier
	v_mfma_f32_16x16x32_bf16 v[124:127], v[164:167], v[196:199], v[124:127]
	v_mfma_f32_16x16x32_bf16 v[120:123], v[172:175], v[196:199], v[120:123]
	v_mfma_f32_16x16x32_bf16 v[108:111], v[164:167], v[204:207], v[108:111]
	v_mfma_f32_16x16x32_bf16 v[104:107], v[172:175], v[204:207], v[104:107]
	v_mfma_f32_16x16x32_bf16 v[92:95], v[164:167], v[212:215], v[92:95]
	v_mfma_f32_16x16x32_bf16 v[88:91], v[172:175], v[212:215], v[88:91]
	v_mfma_f32_16x16x32_bf16 v[76:79], v[164:167], v[220:223], v[76:79]
	v_mfma_f32_16x16x32_bf16 v[72:75], v[172:175], v[220:223], v[72:75]
	v_mfma_f32_16x16x32_bf16 v[124:127], v[168:171], v[200:203], v[124:127]
	v_mfma_f32_16x16x32_bf16 v[120:123], v[176:179], v[200:203], v[120:123]
	v_mfma_f32_16x16x32_bf16 v[108:111], v[168:171], v[208:211], v[108:111]
	v_mfma_f32_16x16x32_bf16 v[104:107], v[176:179], v[208:211], v[104:107]
	v_mfma_f32_16x16x32_bf16 v[92:95], v[168:171], v[216:219], v[92:95]
	v_mfma_f32_16x16x32_bf16 v[88:91], v[176:179], v[216:219], v[88:91]
	v_mfma_f32_16x16x32_bf16 v[76:79], v[168:171], v[224:227], v[76:79]
	v_mfma_f32_16x16x32_bf16 v[72:75], v[176:179], v[224:227], v[72:75]
	v_mfma_f32_16x16x32_bf16 v[116:119], v[180:183], v[196:199], v[116:119]
	v_mfma_f32_16x16x32_bf16 v[112:115], v[188:191], v[196:199], v[112:115]
	v_mfma_f32_16x16x32_bf16 v[100:103], v[180:183], v[204:207], v[100:103]
	v_mfma_f32_16x16x32_bf16 v[96:99], v[188:191], v[204:207], v[96:99]
	v_mfma_f32_16x16x32_bf16 v[84:87], v[180:183], v[212:215], v[84:87]
	v_mfma_f32_16x16x32_bf16 v[80:83], v[188:191], v[212:215], v[80:83]
	v_mfma_f32_16x16x32_bf16 v[68:71], v[180:183], v[220:223], v[68:71]
	v_mfma_f32_16x16x32_bf16 v[64:67], v[188:191], v[220:223], v[64:67]
	v_mfma_f32_16x16x32_bf16 v[116:119], v[184:187], v[200:203], v[116:119]
	v_mfma_f32_16x16x32_bf16 v[112:115], v[192:195], v[200:203], v[112:115]
	v_mfma_f32_16x16x32_bf16 v[100:103], v[184:187], v[208:211], v[100:103]
	v_mfma_f32_16x16x32_bf16 v[96:99], v[192:195], v[208:211], v[96:99]
	v_mfma_f32_16x16x32_bf16 v[84:87], v[184:187], v[216:219], v[84:87]
	v_mfma_f32_16x16x32_bf16 v[80:83], v[192:195], v[216:219], v[80:83]
	v_mfma_f32_16x16x32_bf16 v[68:71], v[184:187], v[224:227], v[68:71]
	v_mfma_f32_16x16x32_bf16 v[64:67], v[192:195], v[224:227], v[64:67]
	s_barrier
	s_add_u32 s98, s24, s8
	s_addc_u32 s99, s25, s9
	s_add_u32 s100, s26, s8
	s_addc_u32 s101, s27, s9
	s_mov_b32 m0, s21
	s_add_u32 s54, s24, 0x40000
	ds_read_b128 v[196:199], v141 offset:16384
	ds_read_b128 v[200:203], v141 offset:17408
	ds_read_b128 v[204:207], v141 offset:18432
	ds_read_b128 v[208:211], v141 offset:19456
	ds_read_b128 v[212:215], v141 offset:20480
	ds_read_b128 v[216:219], v141 offset:21504
	ds_read_b128 v[220:223], v141 offset:22528
	ds_read_b128 v[224:227], v141 offset:23552
	global_load_lds_dwordx4 v130, s[24:25]
	s_mov_b32 m0, s30
	s_addc_u32 s55, s25, 0
	global_load_lds_dwordx4 v128, s[24:25]
	s_mov_b32 m0, s31
	s_nop 0
	global_load_lds_dwordx4 v130, s[54:55]
	s_mov_b32 m0, s33
	s_nop 0
	global_load_lds_dwordx4 v128, s[54:55]
	s_mov_b32 m0, s2
	s_nop 0
	global_load_lds_dwordx4 v130, s[26:27]
	s_mov_b32 m0, s34
	s_nop 0
	global_load_lds_dwordx4 v128, s[26:27]
	s_waitcnt vmcnt(8)
	s_waitcnt lgkmcnt(0)
	s_barrier
	v_mfma_f32_16x16x32_bf16 v[60:63], v[164:167], v[196:199], v[60:63]
	v_mfma_f32_16x16x32_bf16 v[56:59], v[172:175], v[196:199], v[56:59]
	v_mfma_f32_16x16x32_bf16 v[44:47], v[164:167], v[204:207], v[44:47]
	v_mfma_f32_16x16x32_bf16 v[40:43], v[172:175], v[204:207], v[40:43]
	v_mfma_f32_16x16x32_bf16 v[28:31], v[164:167], v[212:215], v[28:31]
	v_mfma_f32_16x16x32_bf16 v[24:27], v[172:175], v[212:215], v[24:27]
	v_mfma_f32_16x16x32_bf16 v[12:15], v[164:167], v[220:223], v[12:15]
	v_mfma_f32_16x16x32_bf16 v[8:11], v[172:175], v[220:223], v[8:11]
	v_mfma_f32_16x16x32_bf16 v[60:63], v[168:171], v[200:203], v[60:63]
	v_mfma_f32_16x16x32_bf16 v[56:59], v[176:179], v[200:203], v[56:59]
	v_mfma_f32_16x16x32_bf16 v[44:47], v[168:171], v[208:211], v[44:47]
	v_mfma_f32_16x16x32_bf16 v[40:43], v[176:179], v[208:211], v[40:43]
	v_mfma_f32_16x16x32_bf16 v[28:31], v[168:171], v[216:219], v[28:31]
	v_mfma_f32_16x16x32_bf16 v[24:27], v[176:179], v[216:219], v[24:27]
	v_mfma_f32_16x16x32_bf16 v[12:15], v[168:171], v[224:227], v[12:15]
	v_mfma_f32_16x16x32_bf16 v[8:11], v[176:179], v[224:227], v[8:11]
	v_mfma_f32_16x16x32_bf16 v[52:55], v[180:183], v[196:199], v[52:55]
	v_mfma_f32_16x16x32_bf16 v[48:51], v[188:191], v[196:199], v[48:51]
	v_mfma_f32_16x16x32_bf16 v[36:39], v[180:183], v[204:207], v[36:39]
	v_mfma_f32_16x16x32_bf16 v[32:35], v[188:191], v[204:207], v[32:35]
	v_mfma_f32_16x16x32_bf16 v[20:23], v[180:183], v[212:215], v[20:23]
	v_mfma_f32_16x16x32_bf16 v[16:19], v[188:191], v[212:215], v[16:19]
	v_mfma_f32_16x16x32_bf16 v[4:7], v[180:183], v[220:223], v[4:7]
	v_mfma_f32_16x16x32_bf16 v[0:3], v[188:191], v[220:223], v[0:3]
	v_mfma_f32_16x16x32_bf16 v[52:55], v[184:187], v[200:203], v[52:55]
	v_mfma_f32_16x16x32_bf16 v[48:51], v[192:195], v[200:203], v[48:51]
	v_mfma_f32_16x16x32_bf16 v[36:39], v[184:187], v[208:211], v[36:39]
	v_mfma_f32_16x16x32_bf16 v[32:35], v[192:195], v[208:211], v[32:35]
	v_mfma_f32_16x16x32_bf16 v[20:23], v[184:187], v[216:219], v[20:23]
	v_mfma_f32_16x16x32_bf16 v[16:19], v[192:195], v[216:219], v[16:19]
	v_mfma_f32_16x16x32_bf16 v[4:7], v[184:187], v[224:227], v[4:7]
	v_mfma_f32_16x16x32_bf16 v[0:3], v[192:195], v[224:227], v[0:3]
	s_barrier
	ds_read_b128 v[164:167], v156
	ds_read_b128 v[168:171], v157
	ds_read_b128 v[172:175], v158
	ds_read_b128 v[176:179], v159
	ds_read_b128 v[180:183], v160
	ds_read_b128 v[184:187], v161
	ds_read_b128 v[188:191], v162
	ds_read_b128 v[192:195], v163
	s_add_u32 s26, s26, 0x40000
	s_addc_u32 s27, s27, 0
	s_mov_b32 m0, s35
	ds_read_b128 v[196:199], v141 offset:32768
	ds_read_b128 v[200:203], v141 offset:33792
	ds_read_b128 v[204:207], v141 offset:34816
	ds_read_b128 v[208:211], v141 offset:35840
	ds_read_b128 v[212:215], v141 offset:36864
	ds_read_b128 v[216:219], v141 offset:37888
	ds_read_b128 v[220:223], v141 offset:38912
	ds_read_b128 v[224:227], v141 offset:39936
	global_load_lds_dwordx4 v130, s[26:27]
	s_mov_b32 m0, s36
	s_nop 0
	global_load_lds_dwordx4 v128, s[26:27]
	s_waitcnt vmcnt(8)
	s_waitcnt lgkmcnt(0)
	s_barrier
	v_mfma_f32_16x16x32_bf16 v[124:127], v[164:167], v[196:199], v[124:127]
	v_mfma_f32_16x16x32_bf16 v[120:123], v[172:175], v[196:199], v[120:123]
	v_mfma_f32_16x16x32_bf16 v[108:111], v[164:167], v[204:207], v[108:111]
	v_mfma_f32_16x16x32_bf16 v[104:107], v[172:175], v[204:207], v[104:107]
	v_mfma_f32_16x16x32_bf16 v[92:95], v[164:167], v[212:215], v[92:95]
	v_mfma_f32_16x16x32_bf16 v[88:91], v[172:175], v[212:215], v[88:91]
	v_mfma_f32_16x16x32_bf16 v[76:79], v[164:167], v[220:223], v[76:79]
	v_mfma_f32_16x16x32_bf16 v[72:75], v[172:175], v[220:223], v[72:75]
	v_mfma_f32_16x16x32_bf16 v[124:127], v[168:171], v[200:203], v[124:127]
	v_mfma_f32_16x16x32_bf16 v[120:123], v[176:179], v[200:203], v[120:123]
	v_mfma_f32_16x16x32_bf16 v[108:111], v[168:171], v[208:211], v[108:111]
	v_mfma_f32_16x16x32_bf16 v[104:107], v[176:179], v[208:211], v[104:107]
	v_mfma_f32_16x16x32_bf16 v[92:95], v[168:171], v[216:219], v[92:95]
	v_mfma_f32_16x16x32_bf16 v[88:91], v[176:179], v[216:219], v[88:91]
	v_mfma_f32_16x16x32_bf16 v[76:79], v[168:171], v[224:227], v[76:79]
	v_mfma_f32_16x16x32_bf16 v[72:75], v[176:179], v[224:227], v[72:75]
	v_mfma_f32_16x16x32_bf16 v[116:119], v[180:183], v[196:199], v[116:119]
	v_mfma_f32_16x16x32_bf16 v[112:115], v[188:191], v[196:199], v[112:115]
	v_mfma_f32_16x16x32_bf16 v[100:103], v[180:183], v[204:207], v[100:103]
	v_mfma_f32_16x16x32_bf16 v[96:99], v[188:191], v[204:207], v[96:99]
	v_mfma_f32_16x16x32_bf16 v[84:87], v[180:183], v[212:215], v[84:87]
	v_mfma_f32_16x16x32_bf16 v[80:83], v[188:191], v[212:215], v[80:83]
	v_mfma_f32_16x16x32_bf16 v[68:71], v[180:183], v[220:223], v[68:71]
	v_mfma_f32_16x16x32_bf16 v[64:67], v[188:191], v[220:223], v[64:67]
	v_mfma_f32_16x16x32_bf16 v[116:119], v[184:187], v[200:203], v[116:119]
	v_mfma_f32_16x16x32_bf16 v[112:115], v[192:195], v[200:203], v[112:115]
	v_mfma_f32_16x16x32_bf16 v[100:103], v[184:187], v[208:211], v[100:103]
	v_mfma_f32_16x16x32_bf16 v[96:99], v[192:195], v[208:211], v[96:99]
	v_mfma_f32_16x16x32_bf16 v[84:87], v[184:187], v[216:219], v[84:87]
	v_mfma_f32_16x16x32_bf16 v[80:83], v[192:195], v[216:219], v[80:83]
	v_mfma_f32_16x16x32_bf16 v[68:71], v[184:187], v[224:227], v[68:71]
	v_mfma_f32_16x16x32_bf16 v[64:67], v[192:195], v[224:227], v[64:67]
	s_barrier
	s_mov_b32 m0, s39
	s_add_u32 s24, s24, 0x40080
	ds_read_b128 v[196:199], v141 offset:49152
	ds_read_b128 v[200:203], v141 offset:50176
	ds_read_b128 v[204:207], v141 offset:51200
	ds_read_b128 v[208:211], v141 offset:52224
	ds_read_b128 v[212:215], v141 offset:53248
	ds_read_b128 v[216:219], v141 offset:54272
	ds_read_b128 v[220:223], v141 offset:55296
	ds_read_b128 v[224:227], v141 offset:56320
	global_load_lds_dwordx4 v130, s[98:99]
	s_mov_b32 m0, s40
	s_addc_u32 s25, s25, 0
	global_load_lds_dwordx4 v128, s[98:99]
	s_mov_b32 m0, s43
	s_nop 0
	global_load_lds_dwordx4 v130, s[24:25]
	s_mov_b32 m0, s44
	s_nop 0
	global_load_lds_dwordx4 v128, s[24:25]
	s_mov_b32 m0, s41
	s_nop 0
	global_load_lds_dwordx4 v130, s[100:101]
	s_mov_b32 m0, s42
	s_nop 0
	global_load_lds_dwordx4 v128, s[100:101]
	s_waitcnt vmcnt(8)
	s_waitcnt lgkmcnt(0)
	s_barrier
	v_mfma_f32_16x16x32_bf16 v[60:63], v[164:167], v[196:199], v[60:63]
	v_mfma_f32_16x16x32_bf16 v[56:59], v[172:175], v[196:199], v[56:59]
	v_mfma_f32_16x16x32_bf16 v[44:47], v[164:167], v[204:207], v[44:47]
	v_mfma_f32_16x16x32_bf16 v[40:43], v[172:175], v[204:207], v[40:43]
	v_mfma_f32_16x16x32_bf16 v[28:31], v[164:167], v[212:215], v[28:31]
	v_mfma_f32_16x16x32_bf16 v[24:27], v[172:175], v[212:215], v[24:27]
	v_mfma_f32_16x16x32_bf16 v[12:15], v[164:167], v[220:223], v[12:15]
	v_mfma_f32_16x16x32_bf16 v[8:11], v[172:175], v[220:223], v[8:11]
	v_mfma_f32_16x16x32_bf16 v[60:63], v[168:171], v[200:203], v[60:63]
	v_mfma_f32_16x16x32_bf16 v[56:59], v[176:179], v[200:203], v[56:59]
	v_mfma_f32_16x16x32_bf16 v[44:47], v[168:171], v[208:211], v[44:47]
	v_mfma_f32_16x16x32_bf16 v[40:43], v[176:179], v[208:211], v[40:43]
	v_mfma_f32_16x16x32_bf16 v[28:31], v[168:171], v[216:219], v[28:31]
	v_mfma_f32_16x16x32_bf16 v[24:27], v[176:179], v[216:219], v[24:27]
	v_mfma_f32_16x16x32_bf16 v[12:15], v[168:171], v[224:227], v[12:15]
	v_mfma_f32_16x16x32_bf16 v[8:11], v[176:179], v[224:227], v[8:11]
	v_mfma_f32_16x16x32_bf16 v[52:55], v[180:183], v[196:199], v[52:55]
	v_mfma_f32_16x16x32_bf16 v[48:51], v[188:191], v[196:199], v[48:51]
	v_mfma_f32_16x16x32_bf16 v[36:39], v[180:183], v[204:207], v[36:39]
	v_mfma_f32_16x16x32_bf16 v[32:35], v[188:191], v[204:207], v[32:35]
	v_mfma_f32_16x16x32_bf16 v[20:23], v[180:183], v[212:215], v[20:23]
	v_mfma_f32_16x16x32_bf16 v[16:19], v[188:191], v[212:215], v[16:19]
	v_mfma_f32_16x16x32_bf16 v[4:7], v[180:183], v[220:223], v[4:7]
	v_mfma_f32_16x16x32_bf16 v[0:3], v[188:191], v[220:223], v[0:3]
	v_mfma_f32_16x16x32_bf16 v[52:55], v[184:187], v[200:203], v[52:55]
	v_mfma_f32_16x16x32_bf16 v[48:51], v[192:195], v[200:203], v[48:51]
	v_mfma_f32_16x16x32_bf16 v[36:39], v[184:187], v[208:211], v[36:39]
	v_mfma_f32_16x16x32_bf16 v[32:35], v[192:195], v[208:211], v[32:35]
	v_mfma_f32_16x16x32_bf16 v[20:23], v[184:187], v[216:219], v[20:23]
	v_mfma_f32_16x16x32_bf16 v[16:19], v[192:195], v[216:219], v[16:19]
	v_mfma_f32_16x16x32_bf16 v[4:7], v[184:187], v[224:227], v[4:7]
	v_mfma_f32_16x16x32_bf16 v[0:3], v[192:195], v[224:227], v[0:3]
	s_barrier
	s_add_i32 s53, s53, 2
	s_add_u32 s22, s22, 0x100
	s_addc_u32 s23, s23, 0
	s_add_u32 s51, s51, 0x100
	s_addc_u32 s52, s52, 0
	s_cmp_gt_u32 s53, 13
	s_cbranch_scc0 .LBB0_3663
	s_and_b64 vcc, exec, s[10:11]
	s_cbranch_vccz .LBB0_3666
	s_barrier

.LBB0_3743:
	ds_read_b128 v[128:131], v185
	ds_read_b128 v[132:135], v186
	ds_read_b128 v[136:139], v187
	ds_read_b128 v[140:143], v188
	ds_read_b128 v[162:165], v189
	ds_read_b128 v[166:169], v190
	ds_read_b128 v[170:173], v191
	ds_read_b128 v[174:177], v192
	s_add_u32 s26, s24, 0x100
	s_addc_u32 s27, s25, 0
	s_cmp_eq_u32 s60, 40
	s_cselect_b32 s31, s7, s27
	s_cselect_b32 s30, s6, s26
	s_cselect_b32 s29, s23, s59
	s_cselect_b32 s28, s22, s58
	s_mov_b32 m0, s48
	ds_read_b128 v[178:181], v153
	ds_read_b128 v[202:205], v153 offset:1024
	ds_read_b128 v[206:209], v153 offset:2048
	ds_read_b128 v[210:213], v153 offset:3072
	ds_read_b128 v[214:217], v153 offset:4096
	ds_read_b128 v[218:221], v153 offset:5120
	ds_read_b128 v[222:225], v153 offset:6144
	ds_read_b128 v[226:229], v153 offset:7168
	global_load_lds_dwordx4 v146, s[24:25]
	s_mov_b32 m0, s49
	s_nop 0
	global_load_lds_dwordx4 v156, s[24:25]
	s_waitcnt vmcnt(8)
	s_waitcnt lgkmcnt(0)
	s_barrier
	v_mfma_f32_16x16x32_bf16 v[124:127], v[128:131], v[178:181], v[124:127]
	v_mfma_f32_16x16x32_bf16 v[120:123], v[136:139], v[178:181], v[120:123]
	v_mfma_f32_16x16x32_bf16 v[108:111], v[128:131], v[206:209], v[108:111]
	v_mfma_f32_16x16x32_bf16 v[104:107], v[136:139], v[206:209], v[104:107]
	v_mfma_f32_16x16x32_bf16 v[92:95], v[128:131], v[214:217], v[92:95]
	v_mfma_f32_16x16x32_bf16 v[88:91], v[136:139], v[214:217], v[88:91]
	v_mfma_f32_16x16x32_bf16 v[76:79], v[128:131], v[222:225], v[76:79]
	v_mfma_f32_16x16x32_bf16 v[72:75], v[136:139], v[222:225], v[72:75]
	v_mfma_f32_16x16x32_bf16 v[124:127], v[132:135], v[202:205], v[124:127]
	v_mfma_f32_16x16x32_bf16 v[120:123], v[140:143], v[202:205], v[120:123]
	v_mfma_f32_16x16x32_bf16 v[108:111], v[132:135], v[210:213], v[108:111]
	v_mfma_f32_16x16x32_bf16 v[104:107], v[140:143], v[210:213], v[104:107]
	v_mfma_f32_16x16x32_bf16 v[92:95], v[132:135], v[218:221], v[92:95]
	v_mfma_f32_16x16x32_bf16 v[88:91], v[140:143], v[218:221], v[88:91]
	v_mfma_f32_16x16x32_bf16 v[76:79], v[132:135], v[226:229], v[76:79]
	v_mfma_f32_16x16x32_bf16 v[72:75], v[140:143], v[226:229], v[72:75]
	v_mfma_f32_16x16x32_bf16 v[116:119], v[162:165], v[178:181], v[116:119]
	v_mfma_f32_16x16x32_bf16 v[112:115], v[170:173], v[178:181], v[112:115]
	v_mfma_f32_16x16x32_bf16 v[100:103], v[162:165], v[206:209], v[100:103]
	v_mfma_f32_16x16x32_bf16 v[96:99], v[170:173], v[206:209], v[96:99]
	v_mfma_f32_16x16x32_bf16 v[84:87], v[162:165], v[214:217], v[84:87]
	v_mfma_f32_16x16x32_bf16 v[80:83], v[170:173], v[214:217], v[80:83]
	v_mfma_f32_16x16x32_bf16 v[68:71], v[162:165], v[222:225], v[68:71]
	v_mfma_f32_16x16x32_bf16 v[64:67], v[170:173], v[222:225], v[64:67]
	v_mfma_f32_16x16x32_bf16 v[116:119], v[166:169], v[202:205], v[116:119]
	v_mfma_f32_16x16x32_bf16 v[112:115], v[174:177], v[202:205], v[112:115]
	v_mfma_f32_16x16x32_bf16 v[100:103], v[166:169], v[210:213], v[100:103]
	v_mfma_f32_16x16x32_bf16 v[96:99], v[174:177], v[210:213], v[96:99]
	v_mfma_f32_16x16x32_bf16 v[84:87], v[166:169], v[218:221], v[84:87]
	v_mfma_f32_16x16x32_bf16 v[80:83], v[174:177], v[218:221], v[80:83]
	v_mfma_f32_16x16x32_bf16 v[68:71], v[166:169], v[226:229], v[68:71]
	v_mfma_f32_16x16x32_bf16 v[64:67], v[174:177], v[226:229], v[64:67]
	s_barrier
	s_add_u32 s98, s28, s16
	s_addc_u32 s99, s29, s17
	s_add_u32 s100, s30, s16
	s_addc_u32 s101, s31, s17
	s_mov_b32 m0, s5
	s_add_u32 s24, s28, 0xb0000
	ds_read_b128 v[178:181], v153 offset:16384
	ds_read_b128 v[202:205], v153 offset:17408
	ds_read_b128 v[206:209], v153 offset:18432
	ds_read_b128 v[210:213], v153 offset:19456
	ds_read_b128 v[214:217], v153 offset:20480
	ds_read_b128 v[218:221], v153 offset:21504
	ds_read_b128 v[222:225], v153 offset:22528
	ds_read_b128 v[226:229], v153 offset:23552
	global_load_lds_dwordx4 v148, s[28:29]
	s_mov_b32 m0, s21
	s_addc_u32 s25, s29, 0
	global_load_lds_dwordx4 v154, s[28:29]
	s_mov_b32 m0, s33
	s_nop 0
	global_load_lds_dwordx4 v148, s[24:25]
	s_mov_b32 m0, s34
	s_nop 0
	global_load_lds_dwordx4 v154, s[24:25]
	s_mov_b32 m0, s4
	s_nop 0
	global_load_lds_dwordx4 v148, s[30:31]
	s_mov_b32 m0, s35
	s_nop 0
	global_load_lds_dwordx4 v154, s[30:31]
	s_waitcnt vmcnt(8)
	s_waitcnt lgkmcnt(0)
	s_barrier
	v_mfma_f32_16x16x32_bf16 v[60:63], v[128:131], v[178:181], v[60:63]
	v_mfma_f32_16x16x32_bf16 v[56:59], v[136:139], v[178:181], v[56:59]
	v_mfma_f32_16x16x32_bf16 v[44:47], v[128:131], v[206:209], v[44:47]
	v_mfma_f32_16x16x32_bf16 v[40:43], v[136:139], v[206:209], v[40:43]
	v_mfma_f32_16x16x32_bf16 v[28:31], v[128:131], v[214:217], v[28:31]
	v_mfma_f32_16x16x32_bf16 v[24:27], v[136:139], v[214:217], v[24:27]
	v_mfma_f32_16x16x32_bf16 v[12:15], v[128:131], v[222:225], v[12:15]
	v_mfma_f32_16x16x32_bf16 v[8:11], v[136:139], v[222:225], v[8:11]
	v_mfma_f32_16x16x32_bf16 v[60:63], v[132:135], v[202:205], v[60:63]
	v_mfma_f32_16x16x32_bf16 v[56:59], v[140:143], v[202:205], v[56:59]
	v_mfma_f32_16x16x32_bf16 v[44:47], v[132:135], v[210:213], v[44:47]
	v_mfma_f32_16x16x32_bf16 v[40:43], v[140:143], v[210:213], v[40:43]
	v_mfma_f32_16x16x32_bf16 v[28:31], v[132:135], v[218:221], v[28:31]
	v_mfma_f32_16x16x32_bf16 v[24:27], v[140:143], v[218:221], v[24:27]
	v_mfma_f32_16x16x32_bf16 v[12:15], v[132:135], v[226:229], v[12:15]
	v_mfma_f32_16x16x32_bf16 v[8:11], v[140:143], v[226:229], v[8:11]
	v_mfma_f32_16x16x32_bf16 v[52:55], v[162:165], v[178:181], v[52:55]
	v_mfma_f32_16x16x32_bf16 v[48:51], v[170:173], v[178:181], v[48:51]
	v_mfma_f32_16x16x32_bf16 v[36:39], v[162:165], v[206:209], v[36:39]
	v_mfma_f32_16x16x32_bf16 v[32:35], v[170:173], v[206:209], v[32:35]
	v_mfma_f32_16x16x32_bf16 v[20:23], v[162:165], v[214:217], v[20:23]
	v_mfma_f32_16x16x32_bf16 v[16:19], v[170:173], v[214:217], v[16:19]
	v_mfma_f32_16x16x32_bf16 v[4:7], v[162:165], v[222:225], v[4:7]
	v_mfma_f32_16x16x32_bf16 v[0:3], v[170:173], v[222:225], v[0:3]
	v_mfma_f32_16x16x32_bf16 v[52:55], v[166:169], v[202:205], v[52:55]
	v_mfma_f32_16x16x32_bf16 v[48:51], v[174:177], v[202:205], v[48:51]
	v_mfma_f32_16x16x32_bf16 v[36:39], v[166:169], v[210:213], v[36:39]
	v_mfma_f32_16x16x32_bf16 v[32:35], v[174:177], v[210:213], v[32:35]
	v_mfma_f32_16x16x32_bf16 v[20:23], v[166:169], v[218:221], v[20:23]
	v_mfma_f32_16x16x32_bf16 v[16:19], v[174:177], v[218:221], v[16:19]
	v_mfma_f32_16x16x32_bf16 v[4:7], v[166:169], v[226:229], v[4:7]
	v_mfma_f32_16x16x32_bf16 v[0:3], v[174:177], v[226:229], v[0:3]
	s_barrier
	ds_read_b128 v[128:131], v193
	ds_read_b128 v[132:135], v194
	ds_read_b128 v[136:139], v195
	ds_read_b128 v[140:143], v196
	ds_read_b128 v[162:165], v197
	ds_read_b128 v[166:169], v198
	ds_read_b128 v[170:173], v199
	ds_read_b128 v[174:177], v200
	s_add_u32 s24, s30, 0xb0000
	s_addc_u32 s25, s31, 0
	s_mov_b32 m0, s36
	ds_read_b128 v[178:181], v153 offset:32768
	ds_read_b128 v[202:205], v153 offset:33792
	ds_read_b128 v[206:209], v153 offset:34816
	ds_read_b128 v[210:213], v153 offset:35840
	ds_read_b128 v[214:217], v153 offset:36864
	ds_read_b128 v[218:221], v153 offset:37888
	ds_read_b128 v[222:225], v153 offset:38912
	ds_read_b128 v[226:229], v153 offset:39936
	global_load_lds_dwordx4 v148, s[24:25]
	s_mov_b32 m0, s37
	s_nop 0
	global_load_lds_dwordx4 v154, s[24:25]
	s_waitcnt vmcnt(8)
	s_waitcnt lgkmcnt(0)
	s_barrier
	v_mfma_f32_16x16x32_bf16 v[124:127], v[128:131], v[178:181], v[124:127]
	v_mfma_f32_16x16x32_bf16 v[120:123], v[136:139], v[178:181], v[120:123]
	v_mfma_f32_16x16x32_bf16 v[108:111], v[128:131], v[206:209], v[108:111]
	v_mfma_f32_16x16x32_bf16 v[104:107], v[136:139], v[206:209], v[104:107]
	v_mfma_f32_16x16x32_bf16 v[92:95], v[128:131], v[214:217], v[92:95]
	v_mfma_f32_16x16x32_bf16 v[88:91], v[136:139], v[214:217], v[88:91]
	v_mfma_f32_16x16x32_bf16 v[76:79], v[128:131], v[222:225], v[76:79]
	v_mfma_f32_16x16x32_bf16 v[72:75], v[136:139], v[222:225], v[72:75]
	v_mfma_f32_16x16x32_bf16 v[124:127], v[132:135], v[202:205], v[124:127]
	v_mfma_f32_16x16x32_bf16 v[120:123], v[140:143], v[202:205], v[120:123]
	v_mfma_f32_16x16x32_bf16 v[108:111], v[132:135], v[210:213], v[108:111]
	v_mfma_f32_16x16x32_bf16 v[104:107], v[140:143], v[210:213], v[104:107]
	v_mfma_f32_16x16x32_bf16 v[92:95], v[132:135], v[218:221], v[92:95]
	v_mfma_f32_16x16x32_bf16 v[88:91], v[140:143], v[218:221], v[88:91]
	v_mfma_f32_16x16x32_bf16 v[76:79], v[132:135], v[226:229], v[76:79]
	v_mfma_f32_16x16x32_bf16 v[72:75], v[140:143], v[226:229], v[72:75]
	v_mfma_f32_16x16x32_bf16 v[116:119], v[162:165], v[178:181], v[116:119]
	v_mfma_f32_16x16x32_bf16 v[112:115], v[170:173], v[178:181], v[112:115]
	v_mfma_f32_16x16x32_bf16 v[100:103], v[162:165], v[206:209], v[100:103]
	v_mfma_f32_16x16x32_bf16 v[96:99], v[170:173], v[206:209], v[96:99]
	v_mfma_f32_16x16x32_bf16 v[84:87], v[162:165], v[214:217], v[84:87]
	v_mfma_f32_16x16x32_bf16 v[80:83], v[170:173], v[214:217], v[80:83]
	v_mfma_f32_16x16x32_bf16 v[68:71], v[162:165], v[222:225], v[68:71]
	v_mfma_f32_16x16x32_bf16 v[64:67], v[170:173], v[222:225], v[64:67]
	v_mfma_f32_16x16x32_bf16 v[116:119], v[166:169], v[202:205], v[116:119]
	v_mfma_f32_16x16x32_bf16 v[112:115], v[174:177], v[202:205], v[112:115]
	v_mfma_f32_16x16x32_bf16 v[100:103], v[166:169], v[210:213], v[100:103]
	v_mfma_f32_16x16x32_bf16 v[96:99], v[174:177], v[210:213], v[96:99]
	v_mfma_f32_16x16x32_bf16 v[84:87], v[166:169], v[218:221], v[84:87]
	v_mfma_f32_16x16x32_bf16 v[80:83], v[174:177], v[218:221], v[80:83]
	v_mfma_f32_16x16x32_bf16 v[68:71], v[166:169], v[226:229], v[68:71]
	v_mfma_f32_16x16x32_bf16 v[64:67], v[174:177], v[226:229], v[64:67]
	s_barrier
	s_mov_b32 m0, s38
	s_add_u32 s24, s28, 0xb0080
	ds_read_b128 v[178:181], v153 offset:49152
	ds_read_b128 v[202:205], v153 offset:50176
	ds_read_b128 v[206:209], v153 offset:51200
	ds_read_b128 v[210:213], v153 offset:52224
	ds_read_b128 v[214:217], v153 offset:53248
	ds_read_b128 v[218:221], v153 offset:54272
	ds_read_b128 v[222:225], v153 offset:55296
	ds_read_b128 v[226:229], v153 offset:56320
	global_load_lds_dwordx4 v148, s[98:99]
	s_mov_b32 m0, s39
	s_addc_u32 s25, s29, 0
	global_load_lds_dwordx4 v154, s[98:99]
	s_mov_b32 m0, s42
	s_nop 0
	global_load_lds_dwordx4 v148, s[24:25]
	s_mov_b32 m0, s43
	s_nop 0
	global_load_lds_dwordx4 v154, s[24:25]
	s_mov_b32 m0, s40
	s_nop 0
	global_load_lds_dwordx4 v148, s[100:101]
	s_mov_b32 m0, s41
	s_nop 0
	global_load_lds_dwordx4 v154, s[100:101]
	s_waitcnt vmcnt(8)
	s_waitcnt lgkmcnt(0)
	s_barrier
	v_mfma_f32_16x16x32_bf16 v[60:63], v[128:131], v[178:181], v[60:63]
	v_mfma_f32_16x16x32_bf16 v[56:59], v[136:139], v[178:181], v[56:59]
	v_mfma_f32_16x16x32_bf16 v[44:47], v[128:131], v[206:209], v[44:47]
	v_mfma_f32_16x16x32_bf16 v[40:43], v[136:139], v[206:209], v[40:43]
	v_mfma_f32_16x16x32_bf16 v[28:31], v[128:131], v[214:217], v[28:31]
	v_mfma_f32_16x16x32_bf16 v[24:27], v[136:139], v[214:217], v[24:27]
	v_mfma_f32_16x16x32_bf16 v[12:15], v[128:131], v[222:225], v[12:15]
	v_mfma_f32_16x16x32_bf16 v[8:11], v[136:139], v[222:225], v[8:11]
	v_mfma_f32_16x16x32_bf16 v[60:63], v[132:135], v[202:205], v[60:63]
	v_mfma_f32_16x16x32_bf16 v[56:59], v[140:143], v[202:205], v[56:59]
	v_mfma_f32_16x16x32_bf16 v[44:47], v[132:135], v[210:213], v[44:47]
	v_mfma_f32_16x16x32_bf16 v[40:43], v[140:143], v[210:213], v[40:43]
	v_mfma_f32_16x16x32_bf16 v[28:31], v[132:135], v[218:221], v[28:31]
	v_mfma_f32_16x16x32_bf16 v[24:27], v[140:143], v[218:221], v[24:27]
	v_mfma_f32_16x16x32_bf16 v[12:15], v[132:135], v[226:229], v[12:15]
	v_mfma_f32_16x16x32_bf16 v[8:11], v[140:143], v[226:229], v[8:11]
	v_mfma_f32_16x16x32_bf16 v[52:55], v[162:165], v[178:181], v[52:55]
	v_mfma_f32_16x16x32_bf16 v[48:51], v[170:173], v[178:181], v[48:51]
	v_mfma_f32_16x16x32_bf16 v[36:39], v[162:165], v[206:209], v[36:39]
	v_mfma_f32_16x16x32_bf16 v[32:35], v[170:173], v[206:209], v[32:35]
	v_mfma_f32_16x16x32_bf16 v[20:23], v[162:165], v[214:217], v[20:23]
	v_mfma_f32_16x16x32_bf16 v[16:19], v[170:173], v[214:217], v[16:19]
	v_mfma_f32_16x16x32_bf16 v[4:7], v[162:165], v[222:225], v[4:7]
	v_mfma_f32_16x16x32_bf16 v[0:3], v[170:173], v[222:225], v[0:3]
	v_mfma_f32_16x16x32_bf16 v[52:55], v[166:169], v[202:205], v[52:55]
	v_mfma_f32_16x16x32_bf16 v[48:51], v[174:177], v[202:205], v[48:51]
	v_mfma_f32_16x16x32_bf16 v[36:39], v[166:169], v[210:213], v[36:39]
	v_mfma_f32_16x16x32_bf16 v[32:35], v[174:177], v[210:213], v[32:35]
	v_mfma_f32_16x16x32_bf16 v[20:23], v[166:169], v[218:221], v[20:23]
	v_mfma_f32_16x16x32_bf16 v[16:19], v[174:177], v[218:221], v[16:19]
	v_mfma_f32_16x16x32_bf16 v[4:7], v[166:169], v[226:229], v[4:7]
	v_mfma_f32_16x16x32_bf16 v[0:3], v[174:177], v[226:229], v[0:3]
	s_barrier
	s_add_i32 s60, s60, 2
	s_add_u32 s58, s58, 0x100
	s_addc_u32 s59, s59, 0
	s_cmp_gt_u32 s60, 41
	s_mov_b64 s[24:25], s[26:27]
	s_cbranch_scc0 .LBB0_3743
	s_and_b64 vcc, exec, s[18:19]
	s_cbranch_vccz .LBB0_3746
	s_barrier
